# counted-wait placement in the peeled last k-stage of all GEMM loops: hipcc's lgkmcnt(0) waits replaced by minimal counted waits at each fragment's first consumer
# baseline (speedup 1.0000x reference)
; template <bool SWAP, class Epi, bool THIN = false> ...
;     ...
;     for (int st = 0; st < ns; ++st) {
;       asm volatile("s_waitcnt vmcnt(0)" ::: "memory");
;       __builtin_amdgcn_s_barrier();
;       asm volatile("" ::: "memory");
;       if (st + 1 < ns) {
;         char* nb = smem + ((st + 1) & 1) * 65536;
;         const int ko = (st + 1) * 64;
; #pragma unroll
;         for (int i = 0; i < 4; ++i) { GLDS16(A + (size_t)(ap[i] + ko), nb + tid * 16 + i * 8192); GLDS16(Bt + (size_t)(bp[i] + ko), nb + 32768 + tid * 16 + i * 8192); }
;       }
;       const char* sa = smem + (st & 1) * 65536 + (wr * 64 + fr) * 128;
;       const char* sb = smem + (st & 1) * 65536 + 32768 + (wc * 128 + fr) * 128;
;       if constexpr (THIN) {
;         if (wc == 0) {
; #pragma unroll
;           for (int ks = 0; ks < 2; ++ks) {
;             bf16x8 af[4], bf[2];
; #pragma unroll
;             for (int m = 0; m < 4; ++m) af[m] = *(const bf16x8*)(sa + m * 2048 + (((ks * 4 + fq) ^ swz) << 4));
; #pragma unroll
;             for (int n = 0; n < 2; ++n) bf[n] = *(const bf16x8*)(sb + n * 2048 + (((ks * 4 + fq) ^ swz) << 4));
; #pragma unroll
;             for (int m = 0; m < 4; ++m)
; #pragma unroll
;               for (int n = 0; n < 2; ++n)
;                 acc[m][n] = SWAP ? __builtin_amdgcn_mfma_f32_16x16x32_bf16(bf[n], af[m], acc[m][n], 0, 0, 0)
;                                  : __builtin_amdgcn_mfma_f32_16x16x32_bf16(af[m], bf[n], acc[m][n], 0, 0, 0);
;           }
;         }
;       } else {
;       bf16x8 afA[4], afB[4], bfb[2][2];
; #pragma unroll
;       for (int m = 0; m < 4; ++m) afA[m] = *(const bf16x8*)(sa + m * 2048 + ((fq ^ swz) << 4));
; #pragma unroll
;       for (int n = 0; n < 2; ++n) bfb[0][n] = *(const bf16x8*)(sb + n * 2048 + ((fq ^ swz) << 4));
; #pragma unroll
;       for (int gq = 0; gq < 8; ++gq) {
;         const int ks = gq >> 2, nh = gq & 3;
;         if (gq < 7) {
;           const int ks2 = (gq + 1) >> 2, nh2 = (gq + 1) & 3;
; #pragma unroll
;           for (int n = 0; n < 2; ++n) bfb[(gq + 1) & 1][n] = *(const bf16x8*)(sb + (nh2 * 2 + n) * 2048 + (((ks2 * 4 + fq) ^ swz) << 4));
;         }
;         if (gq == 3) {
; #pragma unroll
;           for (int m = 0; m < 4; ++m) afB[m] = *(const bf16x8*)(sa + m * 2048 + (((4 + fq) ^ swz) << 4));
;         }
;         __builtin_amdgcn_sched_barrier(0);
; #pragma unroll
.LBB0_339:
	s_add_i32 s8, s7, 0x10000
	s_and_b32 s9, s8, 0x10000
	v_add_u32_e32 v171, s9, v144
	s_nop 0
	v_readfirstlane_b32 s9, v171
	s_and_b32 s7, s7, 0x10000
	v_add_u32_e32 v130, s7, v145
	v_add_u32_e32 v140, v130, v147
	s_waitcnt vmcnt(0)
	s_barrier
	ds_read_b128 v[172:175], v140
	ds_read_b128 v[176:179], v140 offset:2048
	ds_read_b128 v[180:183], v140 offset:4096
	ds_read_b128 v[184:187], v140 offset:6144
	v_or_b32_e32 v140, s7, v146
	v_add_u32_e32 v141, v140, v147
	ds_read_b128 v[188:191], v141 offset:32768
	ds_read_b128 v[192:195], v141 offset:34816
	ds_read_b128 v[196:199], v141 offset:36864
	ds_read_b128 v[200:203], v141 offset:38912
	v_add_u32_e32 v130, v130, v148
	s_waitcnt lgkmcnt(3)
	v_mfma_f32_16x16x32_bf16 v[126:129], v[188:191], v[172:175], v[126:129]
	s_mov_b32 m0, s9
	v_mfma_f32_16x16x32_bf16 v[110:113], v[188:191], v[176:179], v[110:113]
	global_load_lds_dwordx4 v139, s[36:37]
	v_add_u32_e32 v139, 0x80, v139
	v_mfma_f32_16x16x32_bf16 v[82:85], v[188:191], v[180:183], v[82:85]
	v_mfma_f32_16x16x32_bf16 v[50:53], v[188:191], v[184:187], v[50:53]
	ds_read_b128 v[188:191], v141 offset:40960
	ds_read_b128 v[204:207], v141 offset:43008
	s_waitcnt lgkmcnt(4)
	v_mfma_f32_16x16x32_bf16 v[122:125], v[192:195], v[172:175], v[122:125]
	s_add_u32 m0, s9, 0x8000
	v_mfma_f32_16x16x32_bf16 v[106:109], v[192:195], v[176:179], v[106:109]
	global_load_lds_dwordx4 v138, s[22:23]
	v_add_u32_e32 v138, 0x80, v138
	v_mfma_f32_16x16x32_bf16 v[78:81], v[192:195], v[180:183], v[78:81]
	v_mfma_f32_16x16x32_bf16 v[42:45], v[192:195], v[184:187], v[42:45]
	s_waitcnt lgkmcnt(3)
	v_mfma_f32_16x16x32_bf16 v[118:121], v[196:199], v[172:175], v[118:121]
	s_add_u32 m0, s9, 0x2000
	v_mfma_f32_16x16x32_bf16 v[94:97], v[196:199], v[176:179], v[94:97]
	global_load_lds_dwordx4 v137, s[36:37]
	v_add_u32_e32 v137, 0x80, v137
	v_mfma_f32_16x16x32_bf16 v[58:61], v[196:199], v[180:183], v[58:61]
	v_mfma_f32_16x16x32_bf16 v[26:29], v[196:199], v[184:187], v[26:29]
	ds_read_b128 v[192:195], v141 offset:45056
	ds_read_b128 v[196:199], v141 offset:47104
	s_waitcnt lgkmcnt(4)
	v_mfma_f32_16x16x32_bf16 v[114:117], v[200:203], v[172:175], v[114:117]
	s_add_u32 m0, s9, 0xa000
	v_mfma_f32_16x16x32_bf16 v[86:89], v[200:203], v[176:179], v[86:89]
	global_load_lds_dwordx4 v136, s[22:23]
	v_add_u32_e32 v136, 0x80, v136
	v_mfma_f32_16x16x32_bf16 v[54:57], v[200:203], v[180:183], v[54:57]
	v_mfma_f32_16x16x32_bf16 v[22:25], v[200:203], v[184:187], v[22:25]
	v_add_u32_e32 v140, v140, v148
	s_waitcnt lgkmcnt(3)
	v_mfma_f32_16x16x32_bf16 v[102:105], v[188:191], v[172:175], v[102:105]
	ds_read_b128 v[200:203], v140 offset:32768
	ds_read_b128 v[208:211], v140 offset:34816
	s_add_u32 m0, s9, 0x4000
	v_mfma_f32_16x16x32_bf16 v[74:77], v[188:191], v[176:179], v[74:77]
	global_load_lds_dwordx4 v135, s[36:37]
	v_add_u32_e32 v135, 0x80, v135
	v_mfma_f32_16x16x32_bf16 v[46:49], v[188:191], v[180:183], v[46:49]
	v_mfma_f32_16x16x32_bf16 v[10:13], v[188:191], v[184:187], v[10:13]
	ds_read_b128 v[188:191], v130
	ds_read_b128 v[212:215], v130 offset:2048
	ds_read_b128 v[216:219], v130 offset:4096
	ds_read_b128 v[220:223], v130 offset:6144
	s_waitcnt lgkmcnt(8)
	v_mfma_f32_16x16x32_bf16 v[98:101], v[204:207], v[172:175], v[98:101]
	s_add_u32 m0, s9, 0xc000
	v_mfma_f32_16x16x32_bf16 v[66:69], v[204:207], v[176:179], v[66:69]
	global_load_lds_dwordx4 v134, s[22:23]
	v_add_u32_e32 v134, 0x80, v134
	v_mfma_f32_16x16x32_bf16 v[30:33], v[204:207], v[180:183], v[30:33]
	v_mfma_f32_16x16x32_bf16 v[6:9], v[204:207], v[184:187], v[6:9]
	s_waitcnt lgkmcnt(7)
	v_mfma_f32_16x16x32_bf16 v[70:73], v[192:195], v[172:175], v[70:73]
	s_add_u32 m0, s9, 0x6000
	s_waitcnt lgkmcnt(6)
	v_mfma_f32_16x16x32_bf16 v[62:65], v[196:199], v[172:175], v[62:65]
	global_load_lds_dwordx4 v133, s[36:37]
	v_add_u32_e32 v133, 0x80, v133
	v_mfma_f32_16x16x32_bf16 v[38:41], v[192:195], v[176:179], v[38:41]
	v_mfma_f32_16x16x32_bf16 v[34:37], v[196:199], v[176:179], v[34:37]
	ds_read_b128 v[172:175], v140 offset:36864
	ds_read_b128 v[176:179], v140 offset:38912
	v_mfma_f32_16x16x32_bf16 v[18:21], v[192:195], v[180:183], v[18:21]
	s_add_u32 m0, s9, 0xe000
	v_mfma_f32_16x16x32_bf16 v[14:17], v[196:199], v[180:183], v[14:17]
	global_load_lds_dwordx4 v132, s[22:23]
	v_add_u32_e32 v132, 0x80, v132
	v_mfma_f32_16x16x32_bf16 v[2:5], v[192:195], v[184:187], v[2:5]
	v_mfma_f32_16x16x32_bf16 v[90:93], v[196:199], v[184:187], v[90:93]
	ds_read_b128 v[180:183], v140 offset:40960
	ds_read_b128 v[184:187], v140 offset:43008
	s_waitcnt lgkmcnt(7)
	v_mfma_f32_16x16x32_bf16 v[126:129], v[200:203], v[188:191], v[126:129]
	v_mfma_f32_16x16x32_bf16 v[122:125], v[208:211], v[188:191], v[122:125]
	s_waitcnt lgkmcnt(6)
	v_mfma_f32_16x16x32_bf16 v[110:113], v[200:203], v[212:215], v[110:113]
	v_mfma_f32_16x16x32_bf16 v[106:109], v[208:211], v[212:215], v[106:109]
	s_waitcnt lgkmcnt(5)
	v_mfma_f32_16x16x32_bf16 v[82:85], v[200:203], v[216:219], v[82:85]
	v_mfma_f32_16x16x32_bf16 v[78:81], v[208:211], v[216:219], v[78:81]
	s_waitcnt lgkmcnt(4)
	v_mfma_f32_16x16x32_bf16 v[50:53], v[200:203], v[220:223], v[50:53]
	v_mfma_f32_16x16x32_bf16 v[42:45], v[208:211], v[220:223], v[42:45]
	s_waitcnt lgkmcnt(3)
	v_mfma_f32_16x16x32_bf16 v[118:121], v[172:175], v[188:191], v[118:121]
	v_mfma_f32_16x16x32_bf16 v[94:97], v[172:175], v[212:215], v[94:97]
	v_mfma_f32_16x16x32_bf16 v[58:61], v[172:175], v[216:219], v[58:61]
	v_mfma_f32_16x16x32_bf16 v[26:29], v[172:175], v[220:223], v[26:29]
	ds_read_b128 v[172:175], v140 offset:45056
	ds_read_b128 v[192:195], v140 offset:47104
	s_waitcnt lgkmcnt(4)
; template <bool SWAP, class Epi, bool THIN = false> ...
;     ...
;     for (int st = 0; st < ns; ++st) {
;       asm volatile("s_waitcnt vmcnt(0)" ::: "memory");
;       __builtin_amdgcn_s_barrier();
;       asm volatile("" ::: "memory");
;       if (st + 1 < ns) {
;         char* nb = smem + ((st + 1) & 1) * 65536;
;         const int ko = (st + 1) * 64;
; #pragma unroll
;         for (int i = 0; i < 4; ++i) { GLDS16(A + (size_t)(ap[i] + ko), nb + tid * 16 + i * 8192); GLDS16(Bt + (size_t)(bp[i] + ko), nb + 32768 + tid * 16 + i * 8192); }
;       }
;       const char* sa = smem + (st & 1) * 65536 + (wr * 64 + fr) * 128;
;       const char* sb = smem + (st & 1) * 65536 + 32768 + (wc * 128 + fr) * 128;
;       if constexpr (THIN) {
;         if (wc == 0) {
; #pragma unroll
;           for (int ks = 0; ks < 2; ++ks) {
;             bf16x8 af[4], bf[2];
; #pragma unroll
;             for (int m = 0; m < 4; ++m) af[m] = *(const bf16x8*)(sa + m * 2048 + (((ks * 4 + fq) ^ swz) << 4));
; #pragma unroll
;             for (int n = 0; n < 2; ++n) bf[n] = *(const bf16x8*)(sb + n * 2048 + (((ks * 4 + fq) ^ swz) << 4));
; #pragma unroll
;             for (int m = 0; m < 4; ++m)
; #pragma unroll
;               for (int n = 0; n < 2; ++n)
;                 acc[m][n] = SWAP ? __builtin_amdgcn_mfma_f32_16x16x32_bf16(bf[n], af[m], acc[m][n], 0, 0, 0)
;                                  : __builtin_amdgcn_mfma_f32_16x16x32_bf16(af[m], bf[n], acc[m][n], 0, 0, 0);
;           }
;         }
;       } else {
;       bf16x8 afA[4], afB[4], bfb[2][2];
; #pragma unroll
;       for (int m = 0; m < 4; ++m) afA[m] = *(const bf16x8*)(sa + m * 2048 + ((fq ^ swz) << 4));
; #pragma unroll
;       for (int n = 0; n < 2; ++n) bfb[0][n] = *(const bf16x8*)(sb + n * 2048 + ((fq ^ swz) << 4));
; #pragma unroll
;       for (int gq = 0; gq < 8; ++gq) {
;         const int ks = gq >> 2, nh = gq & 3;
;         if (gq < 7) {
;           const int ks2 = (gq + 1) >> 2, nh2 = (gq + 1) & 3;
; #pragma unroll
;           for (int n = 0; n < 2; ++n) bfb[(gq + 1) & 1][n] = *(const bf16x8*)(sb + (nh2 * 2 + n) * 2048 + (((ks2 * 4 + fq) ^ swz) << 4));
;         }
;         if (gq == 3) {
; #pragma unroll
;           for (int m = 0; m < 4; ++m) afB[m] = *(const bf16x8*)(sa + m * 2048 + (((4 + fq) ^ swz) << 4));
;         }
;         __builtin_amdgcn_sched_barrier(0);
; #pragma unroll
	v_mfma_f32_16x16x32_bf16 v[114:117], v[176:179], v[188:191], v[114:117]
	v_mfma_f32_16x16x32_bf16 v[86:89], v[176:179], v[212:215], v[86:89]
	v_mfma_f32_16x16x32_bf16 v[54:57], v[176:179], v[216:219], v[54:57]
	v_mfma_f32_16x16x32_bf16 v[22:25], v[176:179], v[220:223], v[22:25]
	s_waitcnt lgkmcnt(3)
	v_mfma_f32_16x16x32_bf16 v[102:105], v[180:183], v[188:191], v[102:105]
	s_waitcnt lgkmcnt(2)
	v_mfma_f32_16x16x32_bf16 v[98:101], v[184:187], v[188:191], v[98:101]
	v_mfma_f32_16x16x32_bf16 v[74:77], v[180:183], v[212:215], v[74:77]
	v_mfma_f32_16x16x32_bf16 v[66:69], v[184:187], v[212:215], v[66:69]
	v_mfma_f32_16x16x32_bf16 v[46:49], v[180:183], v[216:219], v[46:49]
	v_mfma_f32_16x16x32_bf16 v[30:33], v[184:187], v[216:219], v[30:33]
	v_mfma_f32_16x16x32_bf16 v[10:13], v[180:183], v[220:223], v[10:13]
	v_mfma_f32_16x16x32_bf16 v[6:9], v[184:187], v[220:223], v[6:9]
	s_waitcnt lgkmcnt(1)
	v_mfma_f32_16x16x32_bf16 v[70:73], v[172:175], v[188:191], v[70:73]
	s_add_i32 s6, s6, 64
	s_cmpk_eq_i32 s6, 0x3c0
	s_mov_b32 s7, s8
	s_waitcnt lgkmcnt(0)
	v_mfma_f32_16x16x32_bf16 v[62:65], v[192:195], v[188:191], v[62:65]
	v_mfma_f32_16x16x32_bf16 v[38:41], v[172:175], v[212:215], v[38:41]
	v_mfma_f32_16x16x32_bf16 v[34:37], v[192:195], v[212:215], v[34:37]
	v_mfma_f32_16x16x32_bf16 v[18:21], v[172:175], v[216:219], v[18:21]
	v_mfma_f32_16x16x32_bf16 v[14:17], v[192:195], v[216:219], v[14:17]
	v_mfma_f32_16x16x32_bf16 v[2:5], v[172:175], v[220:223], v[2:5]
	v_mfma_f32_16x16x32_bf16 v[90:93], v[192:195], v[220:223], v[90:93]
	s_cbranch_scc0 .LBB0_339
	s_waitcnt vmcnt(0)
	s_barrier
	v_add_u32_e32 v130, v159, v147
	ds_read_b128 v[132:135], v130
	ds_read_b128 v[136:139], v130 offset:2048
	ds_read_b128 v[172:175], v130 offset:4096
	ds_read_b128 v[176:179], v130 offset:6144
	v_add_u32_e32 v130, v160, v147
	ds_read_b128 v[180:183], v130
	ds_read_b128 v[184:187], v130 offset:2048
	ds_read_b128 v[188:191], v130 offset:4096
	ds_read_b128 v[192:195], v130 offset:6144
	s_waitcnt lgkmcnt(3)
	v_mfma_f32_16x16x32_bf16 v[126:129], v[180:183], v[132:135], v[126:129]
	v_mfma_f32_16x16x32_bf16 v[110:113], v[180:183], v[136:139], v[110:113]
	v_mfma_f32_16x16x32_bf16 v[82:85], v[180:183], v[172:175], v[82:85]
	v_mfma_f32_16x16x32_bf16 v[50:53], v[180:183], v[176:179], v[50:53]
	ds_read_b128 v[180:183], v130 offset:8192
	ds_read_b128 v[196:199], v130 offset:10240
	s_waitcnt lgkmcnt(4)
	v_mfma_f32_16x16x32_bf16 v[122:125], v[184:187], v[132:135], v[122:125]
	v_mfma_f32_16x16x32_bf16 v[106:109], v[184:187], v[136:139], v[106:109]
	v_mfma_f32_16x16x32_bf16 v[78:81], v[184:187], v[172:175], v[78:81]
	v_mfma_f32_16x16x32_bf16 v[42:45], v[184:187], v[176:179], v[42:45]
	s_waitcnt lgkmcnt(3)
	v_mfma_f32_16x16x32_bf16 v[118:121], v[188:191], v[132:135], v[118:121]
	v_mfma_f32_16x16x32_bf16 v[184:187], v[188:191], v[136:139], v[94:97]
	v_mfma_f32_16x16x32_bf16 v[204:207], v[188:191], v[172:175], v[58:61]
	s_waitcnt lgkmcnt(2)
	v_mfma_f32_16x16x32_bf16 v[208:211], v[192:195], v[172:175], v[54:57]
	v_mfma_f32_16x16x32_bf16 v[188:191], v[188:191], v[176:179], v[26:29]
	s_nop 2
	ds_read_b128 v[26:29], v130 offset:12288
	ds_read_b128 v[54:57], v130 offset:14336
	v_mfma_f32_16x16x32_bf16 v[114:117], v[192:195], v[132:135], v[114:117]
	v_mfma_f32_16x16x32_bf16 v[200:203], v[192:195], v[136:139], v[86:89]
	v_mfma_f32_16x16x32_bf16 v[192:195], v[192:195], v[176:179], v[22:25]
	v_add_u32_e32 v130, v160, v148
	s_waitcnt lgkmcnt(2)
	v_mfma_f32_16x16x32_bf16 v[212:215], v[196:199], v[172:175], v[30:33]
	ds_read_b128 v[22:25], v130
	ds_read_b128 v[86:89], v130 offset:2048
	s_nop 0
	v_add_u32_e32 v30, v159, v148
	v_mfma_f32_16x16x32_bf16 v[102:105], v[180:183], v[132:135], v[102:105]
	v_mfma_f32_16x16x32_bf16 v[74:77], v[180:183], v[136:139], v[74:77]
	v_mfma_f32_16x16x32_bf16 v[46:49], v[180:183], v[172:175], v[46:49]
	v_mfma_f32_16x16x32_bf16 v[10:13], v[180:183], v[176:179], v[10:13]
	ds_read_b128 v[180:183], v30
	ds_read_b128 v[216:219], v30 offset:2048
	ds_read_b128 v[220:223], v30 offset:4096
	ds_read_b128 v[224:227], v30 offset:6144
	v_mfma_f32_16x16x32_bf16 v[98:101], v[196:199], v[132:135], v[98:101]
	v_mfma_f32_16x16x32_bf16 v[66:69], v[196:199], v[136:139], v[66:69]
	v_mfma_f32_16x16x32_bf16 v[6:9], v[196:199], v[176:179], v[6:9]
	s_waitcnt lgkmcnt(7)
	v_mfma_f32_16x16x32_bf16 v[196:199], v[26:29], v[172:175], v[18:21]
	s_waitcnt lgkmcnt(6)
	v_mfma_f32_16x16x32_bf16 v[172:175], v[54:57], v[172:175], v[14:17]
	s_nop 2
	ds_read_b128 v[14:17], v130 offset:4096
	ds_read_b128 v[18:21], v130 offset:6144
	v_mfma_f32_16x16x32_bf16 v[70:73], v[26:29], v[132:135], v[70:73]
	v_mfma_f32_16x16x32_bf16 v[132:135], v[54:57], v[132:135], v[62:65]
	v_mfma_f32_16x16x32_bf16 v[38:41], v[26:29], v[136:139], v[38:41]
	v_mfma_f32_16x16x32_bf16 v[34:37], v[54:57], v[136:139], v[34:37]
	v_mfma_f32_16x16x32_bf16 v[2:5], v[26:29], v[176:179], v[2:5]
	v_mfma_f32_16x16x32_bf16 v[176:179], v[54:57], v[176:179], v[90:93]
	ds_read_b128 v[136:139], v130 offset:8192
	ds_read_b128 v[228:231], v130 offset:10240
	s_waitcnt lgkmcnt(7)
	v_mfma_f32_16x16x32_bf16 v[126:129], v[22:25], v[180:183], v[126:129]
	v_mfma_f32_16x16x32_bf16 v[122:125], v[86:89], v[180:183], v[122:125]
	s_waitcnt lgkmcnt(6)
	v_mfma_f32_16x16x32_bf16 v[94:97], v[22:25], v[216:219], v[110:113]
	v_mfma_f32_16x16x32_bf16 v[90:93], v[86:89], v[216:219], v[106:109]
	s_waitcnt lgkmcnt(5)
	v_mfma_f32_16x16x32_bf16 v[62:65], v[22:25], v[220:223], v[82:85]
	v_mfma_f32_16x16x32_bf16 v[58:61], v[86:89], v[220:223], v[78:81]
	s_waitcnt lgkmcnt(4)
	v_mfma_f32_16x16x32_bf16 v[30:33], v[22:25], v[224:227], v[50:53]
	v_mfma_f32_16x16x32_bf16 v[26:29], v[86:89], v[224:227], v[42:45]
	s_waitcnt lgkmcnt(3)
	v_mfma_f32_16x16x32_bf16 v[86:89], v[14:17], v[216:219], v[184:187]
	v_mfma_f32_16x16x32_bf16 v[22:25], v[14:17], v[224:227], v[188:191]
	s_nop 1
	ds_read_b128 v[184:187], v130 offset:12288
	ds_read_b128 v[188:191], v130 offset:14336
	v_mfma_f32_16x16x32_bf16 v[118:121], v[14:17], v[180:183], v[118:121]
	s_waitcnt lgkmcnt(4)
	v_mfma_f32_16x16x32_bf16 v[114:117], v[18:21], v[180:183], v[114:117]
	v_mfma_f32_16x16x32_bf16 v[82:85], v[18:21], v[216:219], v[200:203]
	v_mfma_f32_16x16x32_bf16 v[54:57], v[14:17], v[220:223], v[204:207]
	v_mfma_f32_16x16x32_bf16 v[50:53], v[18:21], v[220:223], v[208:211]
	v_mfma_f32_16x16x32_bf16 v[18:21], v[18:21], v[224:227], v[192:195]
	s_waitcnt lgkmcnt(3)
	v_mfma_f32_16x16x32_bf16 v[110:113], v[136:139], v[180:183], v[102:105]
	s_waitcnt lgkmcnt(2)
	v_mfma_f32_16x16x32_bf16 v[106:109], v[228:231], v[180:183], v[98:101]
	v_mfma_f32_16x16x32_bf16 v[78:81], v[136:139], v[216:219], v[74:77]
	v_mfma_f32_16x16x32_bf16 v[74:77], v[228:231], v[216:219], v[66:69]
	v_mfma_f32_16x16x32_bf16 v[46:49], v[136:139], v[220:223], v[46:49]
	v_mfma_f32_16x16x32_bf16 v[42:45], v[228:231], v[220:223], v[212:215]
	v_mfma_f32_16x16x32_bf16 v[14:17], v[136:139], v[224:227], v[10:13]
	v_mfma_f32_16x16x32_bf16 v[6:9], v[228:231], v[224:227], v[6:9]
	s_nop 1
	v_mov_b32_e32 v10, v1
	s_waitcnt vmcnt(0) lgkmcnt(0)
	s_barrier
; __device__ __forceinline__ int get_tid512() { int t = threadIdx.x; asm volatile("" : "+v"(t)); return t; }
; __device__ __forceinline__ unsigned pack2(float a, float b) { unsigned r; asm("v_cvt_pk_bf16_f32 %0, %1, %2" : "=v"(r) : "v"(a), "v"(b)); return r; }
;   __device__ __forceinline__ float c4(int g, int rig, int col, f32x4 v) const {
;     ...
;     uint2 u; u.x = pack2(v[0], v[1]); u.y = pack2(v[2], v[3]);
;     *(uint2*)(out + row * ld + col) = u;
;     return v[0] * v[0] + v[1] * v[1] + v[2] * v[2] + v[3] * v[3];
;   }
;   __device__ __forceinline__ void rowsum(int g, int rig, int slot, float ss) const {
;     if (slot < nslots) part[(size_t)slot * ((size_t)8 * ostride) + (size_t)g * ostride + rig] = ss;
; template <bool SWAP, class Epi, bool THIN = false> ...
;     ...
;     __syncthreads();
;     const int te = get_tid512();
;     const int fr_e = te & 15, fq_e = (te & 63) >> 4, wr_e = te >> 7, wc_e = (te >> 6) & 1;
;     const int sub = 2 * mt + (wr_e >> 1);
;     const int g = sub / tpg, ti = sub - g * tpg;
;     const int rig0 = ti * step - halo;
;     const int rw = (wr_e & 1) * 64;
;     if constexpr (Epi::KIND == 0) {
; #pragma unroll
;       for (int m = 0; m < 4; ++m) {
;         const int rig = rig0 + rw + m * 16 + fr_e;
;         if constexpr (Epi::ROWSUM) {
;           float ss = 0.f;
; #pragma unroll
;           for (int n = 0; n < 8; ++n) {
;             const int col = nt * 256 + wc_e * 128 + n * 16 + fq_e * 4;
;             if (col < N) ss += epi.c4(g, rig, col, acc[m][n]);
;           }
;           ss += __shfl_xor(ss, 16); ss += __shfl_xor(ss, 32);
;           if (fq_e == 0) epi.rowsum(g, rig, nt * 2 + wc_e, ss);
	v_mfma_f32_16x16x32_bf16 v[98:101], v[188:191], v[180:183], v[132:135]
	v_ashrrev_i32_e32 v11, 8, v10
	v_add_u32_e32 v11, s5, v11
	v_ashrrev_i32_e32 v12, 31, v11
	v_lshrrev_b32_e32 v12, 28, v12
	v_add_u32_e32 v12, v11, v12
	v_ashrrev_i32_e32 v138, 4, v12
	v_and_b32_e32 v132, 15, v10
	v_bfe_u32 v130, v10, 4, 2
	v_bfe_u32 v171, v10, 6, 1
	v_lshlrev_b32_e32 v12, 11, v138
	v_lshlrev_b32_e32 v11, 7, v11
	v_lshrrev_b32_e32 v10, 1, v10
	v_sub_u32_e32 v133, v11, v12
	v_and_b32_e32 v135, 64, v10
	v_lshlrev_b32_e32 v134, 7, v171
	v_mfma_f32_16x16x32_bf16 v[10:13], v[184:187], v[224:227], v[2:5]
	v_ashrrev_i32_e32 v139, 31, v138
	v_or3_b32 v132, v133, v135, v132
	v_ashrrev_i32_e32 v133, 31, v132
	v_lshlrev_b32_e32 v2, 2, v130
	v_mfma_f32_16x16x32_bf16 v[102:105], v[184:187], v[180:183], v[70:73]
	v_or3_b32 v134, v134, v2, s4
	v_lshlrev_b64 v[136:137], 21, v[138:139]
	v_cmp_gt_i32_e32 vcc, s29, v134
	v_mfma_f32_16x16x32_bf16 v[70:73], v[184:187], v[216:219], v[38:41]
	v_lshlrev_b64 v[140:141], 10, v[132:133]
	v_ashrrev_i32_e32 v135, 31, v134
	v_lshl_add_u64 v[136:137], s[38:39], 0, v[136:137]
	v_mfma_f32_16x16x32_bf16 v[66:69], v[188:191], v[216:219], v[34:37]
	v_mfma_f32_16x16x32_bf16 v[38:41], v[184:187], v[220:223], v[196:199]
	v_mfma_f32_16x16x32_bf16 v[34:37], v[188:191], v[220:223], v[172:175]
	v_mfma_f32_16x16x32_bf16 v[2:5], v[188:191], v[224:227], v[176:179]
	s_nop 1
	v_bfe_u32 v246, v1, 4, 1
	v_mul_u32_u24_e32 v246, 24, v246
	v_mov_b32_e32 v247, 0
	v_xor_b32_e32 v254, 16, v170
	v_lshlrev_b32_e32 v254, 2, v254
	v_xor_b32_e32 v255, 32, v170
	v_lshlrev_b32_e32 v255, 2, v255
	v_lshl_or_b32 v252, s20, 1, v171
	v_ashrrev_i32_e32 v253, 31, v252
	v_cmp_eq_u32_e64 s[18:19], 0, v130
	v_cmp_gt_i32_e64 s[20:21], 4, v252
	s_and_b64 s[18:19], s[18:19], s[20:21]
	v_lshlrev_b64 v[252:253], 16, v[252:253]
	v_lshl_add_u64 v[252:253], s[24:25], 0, v[252:253]
	v_lshlrev_b64 v[248:249], 13, v[138:139]
	v_lshl_add_u64 v[252:253], v[252:253], 0, v[248:249]
	v_lshl_add_u64 v[252:253], v[132:133], 2, v[252:253]
	v_lshl_add_u64 v[248:249], v[136:137], 0, v[140:141]
	v_lshl_add_u64 v[248:249], v[134:135], 1, v[248:249]
	v_lshl_add_u64 v[248:249], v[248:249], 0, v[246:247]
	v_cvt_pk_bf16_f32 v232, v126, v127
	v_cvt_pk_bf16_f32 v233, v128, v129
	v_mul_f32_e32 v240, v126, v126
	v_mul_f32_e32 v241, v127, v127
	v_mul_f32_e32 v242, v128, v128
	v_mul_f32_e32 v243, v129, v129
	v_add_f32_e32 v245, v240, v241
	v_add_f32_e32 v245, v242, v245
	v_add_f32_e32 v244, v243, v245
	v_cvt_pk_bf16_f32 v234, v122, v123
	v_cvt_pk_bf16_f32 v235, v124, v125
	v_mul_f32_e32 v240, v122, v122
	v_mul_f32_e32 v241, v123, v123
	v_mul_f32_e32 v242, v124, v124
	v_mul_f32_e32 v243, v125, v125
	v_add_f32_e32 v245, v240, v241
	v_add_f32_e32 v245, v242, v245
	v_add_f32_e32 v245, v243, v245
	v_add_f32_e32 v244, v245, v244
	s_nop 1
	v_permlane16_swap_b32 v232, v234
	v_permlane16_swap_b32 v233, v235
	global_store_dwordx4 v[248:249], v[232:235], off
	v_cvt_pk_bf16_f32 v236, v118, v119
	v_cvt_pk_bf16_f32 v237, v120, v121
	v_mul_f32_e32 v240, v118, v118
	v_mul_f32_e32 v241, v119, v119
	v_mul_f32_e32 v242, v120, v120
	v_mul_f32_e32 v243, v121, v121
	v_add_f32_e32 v245, v240, v241
	v_add_f32_e32 v245, v242, v245
	v_add_f32_e32 v245, v243, v245
	v_add_f32_e32 v244, v245, v244
	v_cvt_pk_bf16_f32 v238, v114, v115
	v_cvt_pk_bf16_f32 v239, v116, v117
	v_mul_f32_e32 v240, v114, v114
	v_mul_f32_e32 v241, v115, v115
	v_mul_f32_e32 v242, v116, v116
	v_mul_f32_e32 v243, v117, v117
	v_add_f32_e32 v245, v240, v241
	v_add_f32_e32 v245, v242, v245
	v_add_f32_e32 v245, v243, v245
	v_add_f32_e32 v244, v245, v244
	s_nop 1
	v_permlane16_swap_b32 v236, v238
	v_permlane16_swap_b32 v237, v239
	global_store_dwordx4 v[248:249], v[236:239], off offset:64
	v_cvt_pk_bf16_f32 v232, v110, v111
	v_cvt_pk_bf16_f32 v233, v112, v113
	v_mul_f32_e32 v240, v110, v110
	v_mul_f32_e32 v241, v111, v111
	v_mul_f32_e32 v242, v112, v112
	v_mul_f32_e32 v243, v113, v113
	v_add_f32_e32 v245, v240, v241
	v_add_f32_e32 v245, v242, v245
	v_add_f32_e32 v245, v243, v245
	v_add_f32_e32 v244, v245, v244
	v_cvt_pk_bf16_f32 v234, v106, v107
	v_cvt_pk_bf16_f32 v235, v108, v109
	v_mul_f32_e32 v240, v106, v106
	v_mul_f32_e32 v241, v107, v107
	v_mul_f32_e32 v242, v108, v108
	v_mul_f32_e32 v243, v109, v109
	v_add_f32_e32 v245, v240, v241
	v_add_f32_e32 v245, v242, v245
	v_add_f32_e32 v245, v243, v245
	v_add_f32_e32 v244, v245, v244
	s_nop 1
	v_permlane16_swap_b32 v232, v234
	v_permlane16_swap_b32 v233, v235
	global_store_dwordx4 v[248:249], v[232:235], off offset:128
	v_cvt_pk_bf16_f32 v236, v102, v103
	v_cvt_pk_bf16_f32 v237, v104, v105
	v_mul_f32_e32 v240, v102, v102
	v_mul_f32_e32 v241, v103, v103
	v_mul_f32_e32 v242, v104, v104
	v_mul_f32_e32 v243, v105, v105
	v_add_f32_e32 v245, v240, v241
	v_add_f32_e32 v245, v242, v245
	v_add_f32_e32 v245, v243, v245
	v_add_f32_e32 v244, v245, v244
	v_cvt_pk_bf16_f32 v238, v98, v99
	v_cvt_pk_bf16_f32 v239, v100, v101
	v_mul_f32_e32 v240, v98, v98
	v_mul_f32_e32 v241, v99, v99
	v_mul_f32_e32 v242, v100, v100
	v_mul_f32_e32 v243, v101, v101
	v_add_f32_e32 v245, v240, v241
	v_add_f32_e32 v245, v242, v245
	v_add_f32_e32 v245, v243, v245
	v_add_f32_e32 v244, v245, v244
	s_nop 1
	v_permlane16_swap_b32 v236, v238
	v_permlane16_swap_b32 v237, v239
	global_store_dwordx4 v[248:249], v[236:239], off offset:192
	ds_bpermute_b32 v251, v254, v244
	s_waitcnt lgkmcnt(0)
	v_add_f32_e32 v245, v244, v251
	ds_bpermute_b32 v251, v255, v245
	s_waitcnt lgkmcnt(0)
; __device__ __forceinline__ unsigned pack2(float a, float b) { unsigned r; asm("v_cvt_pk_bf16_f32 %0, %1, %2" : "=v"(r) : "v"(a), "v"(b)); return r; }
;   __device__ __forceinline__ float c4(int g, int rig, int col, f32x4 v) const {
;     ...
;     uint2 u; u.x = pack2(v[0], v[1]); u.y = pack2(v[2], v[3]);
;     *(uint2*)(out + row * ld + col) = u;
;     return v[0] * v[0] + v[1] * v[1] + v[2] * v[2] + v[3] * v[3];
;   }
;   __device__ __forceinline__ void rowsum(int g, int rig, int slot, float ss) const {
;     if (slot < nslots) part[(size_t)slot * ((size_t)8 * ostride) + (size_t)g * ostride + rig] = ss;
; template <bool SWAP, class Epi, bool THIN = false> ...
;     ...
;           for (int n = 0; n < 8; ++n) {
;             const int col = nt * 256 + wc_e * 128 + n * 16 + fq_e * 4;
;             if (col < N) ss += epi.c4(g, rig, col, acc[m][n]);
;           }
;           ss += __shfl_xor(ss, 16); ss += __shfl_xor(ss, 32);
;           if (fq_e == 0) epi.rowsum(g, rig, nt * 2 + wc_e, ss);
	v_add_f32_e32 v245, v245, v251
	s_and_saveexec_b64 s[20:21], s[18:19]
	global_store_dword v[252:253], v245, off
	s_or_b64 exec, exec, s[20:21]
	v_or_b32_e32 v248, 16, v132
	v_ashrrev_i32_e32 v249, 31, v248
	v_lshlrev_b64 v[248:249], 10, v[248:249]
	v_lshl_add_u64 v[248:249], v[136:137], 0, v[248:249]
	v_lshl_add_u64 v[248:249], v[134:135], 1, v[248:249]
	v_lshl_add_u64 v[248:249], v[248:249], 0, v[246:247]
	v_cvt_pk_bf16_f32 v232, v94, v95
	v_cvt_pk_bf16_f32 v233, v96, v97
	v_mul_f32_e32 v240, v94, v94
	v_mul_f32_e32 v241, v95, v95
	v_mul_f32_e32 v242, v96, v96
	v_mul_f32_e32 v243, v97, v97
	v_add_f32_e32 v245, v240, v241
	v_add_f32_e32 v245, v242, v245
	v_add_f32_e32 v244, v243, v245
	v_cvt_pk_bf16_f32 v234, v90, v91
	v_cvt_pk_bf16_f32 v235, v92, v93
	v_mul_f32_e32 v240, v90, v90
	v_mul_f32_e32 v241, v91, v91
	v_mul_f32_e32 v242, v92, v92
	v_mul_f32_e32 v243, v93, v93
	v_add_f32_e32 v245, v240, v241
	v_add_f32_e32 v245, v242, v245
	v_add_f32_e32 v245, v243, v245
	v_add_f32_e32 v244, v245, v244
	s_nop 1
	v_permlane16_swap_b32 v232, v234
	v_permlane16_swap_b32 v233, v235
	global_store_dwordx4 v[248:249], v[232:235], off
	v_cvt_pk_bf16_f32 v236, v86, v87
	v_cvt_pk_bf16_f32 v237, v88, v89
	v_mul_f32_e32 v240, v86, v86
	v_mul_f32_e32 v241, v87, v87
	v_mul_f32_e32 v242, v88, v88
	v_mul_f32_e32 v243, v89, v89
	v_add_f32_e32 v245, v240, v241
	v_add_f32_e32 v245, v242, v245
	v_add_f32_e32 v245, v243, v245
	v_add_f32_e32 v244, v245, v244
	v_cvt_pk_bf16_f32 v238, v82, v83
	v_cvt_pk_bf16_f32 v239, v84, v85
	v_mul_f32_e32 v240, v82, v82
	v_mul_f32_e32 v241, v83, v83
	v_mul_f32_e32 v242, v84, v84
	v_mul_f32_e32 v243, v85, v85
	v_add_f32_e32 v245, v240, v241
	v_add_f32_e32 v245, v242, v245
	v_add_f32_e32 v245, v243, v245
	v_add_f32_e32 v244, v245, v244
	s_nop 1
	v_permlane16_swap_b32 v236, v238
	v_permlane16_swap_b32 v237, v239
	global_store_dwordx4 v[248:249], v[236:239], off offset:64
	v_cvt_pk_bf16_f32 v232, v78, v79
	v_cvt_pk_bf16_f32 v233, v80, v81
	v_mul_f32_e32 v240, v78, v78
	v_mul_f32_e32 v241, v79, v79
	v_mul_f32_e32 v242, v80, v80
	v_mul_f32_e32 v243, v81, v81
	v_add_f32_e32 v245, v240, v241
	v_add_f32_e32 v245, v242, v245
	v_add_f32_e32 v245, v243, v245
	v_add_f32_e32 v244, v245, v244
	v_cvt_pk_bf16_f32 v234, v74, v75
	v_cvt_pk_bf16_f32 v235, v76, v77
	v_mul_f32_e32 v240, v74, v74
	v_mul_f32_e32 v241, v75, v75
	v_mul_f32_e32 v242, v76, v76
	v_mul_f32_e32 v243, v77, v77
	v_add_f32_e32 v245, v240, v241
	v_add_f32_e32 v245, v242, v245
	v_add_f32_e32 v245, v243, v245
	v_add_f32_e32 v244, v245, v244
	s_nop 1
	v_permlane16_swap_b32 v232, v234
	v_permlane16_swap_b32 v233, v235
	global_store_dwordx4 v[248:249], v[232:235], off offset:128
	v_cvt_pk_bf16_f32 v236, v70, v71
	v_cvt_pk_bf16_f32 v237, v72, v73
	v_mul_f32_e32 v240, v70, v70
	v_mul_f32_e32 v241, v71, v71
	v_mul_f32_e32 v242, v72, v72
	v_mul_f32_e32 v243, v73, v73
	v_add_f32_e32 v245, v240, v241
	v_add_f32_e32 v245, v242, v245
	v_add_f32_e32 v245, v243, v245
	v_add_f32_e32 v244, v245, v244
	v_cvt_pk_bf16_f32 v238, v66, v67
	v_cvt_pk_bf16_f32 v239, v68, v69
	v_mul_f32_e32 v240, v66, v66
	v_mul_f32_e32 v241, v67, v67
	v_mul_f32_e32 v242, v68, v68
	v_mul_f32_e32 v243, v69, v69
	v_add_f32_e32 v245, v240, v241
	v_add_f32_e32 v245, v242, v245
	v_add_f32_e32 v245, v243, v245
	v_add_f32_e32 v244, v245, v244
	s_nop 1
	v_permlane16_swap_b32 v236, v238
	v_permlane16_swap_b32 v237, v239
	global_store_dwordx4 v[248:249], v[236:239], off offset:192
	ds_bpermute_b32 v251, v254, v244
	s_waitcnt lgkmcnt(0)
	v_add_f32_e32 v245, v244, v251
	ds_bpermute_b32 v251, v255, v245
	s_waitcnt lgkmcnt(0)
	v_add_f32_e32 v245, v245, v251
	s_and_saveexec_b64 s[20:21], s[18:19]
	global_store_dword v[252:253], v245, off offset:64
	s_or_b64 exec, exec, s[20:21]
	v_or_b32_e32 v248, 32, v132
	v_ashrrev_i32_e32 v249, 31, v248
	v_lshlrev_b64 v[248:249], 10, v[248:249]
	v_lshl_add_u64 v[248:249], v[136:137], 0, v[248:249]
	v_lshl_add_u64 v[248:249], v[134:135], 1, v[248:249]
	v_lshl_add_u64 v[248:249], v[248:249], 0, v[246:247]
	v_cvt_pk_bf16_f32 v232, v62, v63
	v_cvt_pk_bf16_f32 v233, v64, v65
	v_mul_f32_e32 v240, v62, v62
	v_mul_f32_e32 v241, v63, v63
	v_mul_f32_e32 v242, v64, v64
	v_mul_f32_e32 v243, v65, v65
	v_add_f32_e32 v245, v240, v241
	v_add_f32_e32 v245, v242, v245
	v_add_f32_e32 v244, v243, v245
	v_cvt_pk_bf16_f32 v234, v58, v59
	v_cvt_pk_bf16_f32 v235, v60, v61
	v_mul_f32_e32 v240, v58, v58
	v_mul_f32_e32 v241, v59, v59
	v_mul_f32_e32 v242, v60, v60
	v_mul_f32_e32 v243, v61, v61
	v_add_f32_e32 v245, v240, v241
	v_add_f32_e32 v245, v242, v245
	v_add_f32_e32 v245, v243, v245
	v_add_f32_e32 v244, v245, v244
	s_nop 1
	v_permlane16_swap_b32 v232, v234
	v_permlane16_swap_b32 v233, v235
	global_store_dwordx4 v[248:249], v[232:235], off
	v_cvt_pk_bf16_f32 v236, v54, v55
	v_cvt_pk_bf16_f32 v237, v56, v57
	v_mul_f32_e32 v240, v54, v54
	v_mul_f32_e32 v241, v55, v55
	v_mul_f32_e32 v242, v56, v56
	v_mul_f32_e32 v243, v57, v57
	v_add_f32_e32 v245, v240, v241
	v_add_f32_e32 v245, v242, v245
	v_add_f32_e32 v245, v243, v245
	v_add_f32_e32 v244, v245, v244
	v_cvt_pk_bf16_f32 v238, v50, v51
	v_cvt_pk_bf16_f32 v239, v52, v53
	v_mul_f32_e32 v240, v50, v50
	v_mul_f32_e32 v241, v51, v51
	v_mul_f32_e32 v242, v52, v52
	v_mul_f32_e32 v243, v53, v53
	v_add_f32_e32 v245, v240, v241
	v_add_f32_e32 v245, v242, v245
	v_add_f32_e32 v245, v243, v245
	v_add_f32_e32 v244, v245, v244
	s_nop 1
	v_permlane16_swap_b32 v236, v238
	v_permlane16_swap_b32 v237, v239
	global_store_dwordx4 v[248:249], v[236:239], off offset:64
; __device__ __forceinline__ unsigned pack2(float a, float b) { unsigned r; asm("v_cvt_pk_bf16_f32 %0, %1, %2" : "=v"(r) : "v"(a), "v"(b)); return r; }
;   __device__ __forceinline__ float c4(int g, int rig, int col, f32x4 v) const {
;     ...
;     uint2 u; u.x = pack2(v[0], v[1]); u.y = pack2(v[2], v[3]);
;     *(uint2*)(out + row * ld + col) = u;
;     return v[0] * v[0] + v[1] * v[1] + v[2] * v[2] + v[3] * v[3];
;   }
;   __device__ __forceinline__ void rowsum(int g, int rig, int slot, float ss) const {
;     if (slot < nslots) part[(size_t)slot * ((size_t)8 * ostride) + (size_t)g * ostride + rig] = ss;
; template <bool SWAP, class Epi, bool THIN = false> ...
;     ...
;     if constexpr (Epi::KIND == 0) {
; #pragma unroll
;       for (int m = 0; m < 4; ++m) {
;         const int rig = rig0 + rw + m * 16 + fr_e;
;         if constexpr (Epi::ROWSUM) {
;           float ss = 0.f;
; #pragma unroll
;           for (int n = 0; n < 8; ++n) {
;             const int col = nt * 256 + wc_e * 128 + n * 16 + fq_e * 4;
;             if (col < N) ss += epi.c4(g, rig, col, acc[m][n]);
;           }
;           ss += __shfl_xor(ss, 16); ss += __shfl_xor(ss, 32);
;           if (fq_e == 0) epi.rowsum(g, rig, nt * 2 + wc_e, ss);
;         } else {
	v_cvt_pk_bf16_f32 v232, v46, v47
	v_cvt_pk_bf16_f32 v233, v48, v49
	v_mul_f32_e32 v240, v46, v46
	v_mul_f32_e32 v241, v47, v47
	v_mul_f32_e32 v242, v48, v48
	v_mul_f32_e32 v243, v49, v49
	v_add_f32_e32 v245, v240, v241
	v_add_f32_e32 v245, v242, v245
	v_add_f32_e32 v245, v243, v245
	v_add_f32_e32 v244, v245, v244
	v_cvt_pk_bf16_f32 v234, v42, v43
	v_cvt_pk_bf16_f32 v235, v44, v45
	v_mul_f32_e32 v240, v42, v42
	v_mul_f32_e32 v241, v43, v43
	v_mul_f32_e32 v242, v44, v44
	v_mul_f32_e32 v243, v45, v45
	v_add_f32_e32 v245, v240, v241
	v_add_f32_e32 v245, v242, v245
	v_add_f32_e32 v245, v243, v245
	v_add_f32_e32 v244, v245, v244
	s_nop 1
	v_permlane16_swap_b32 v232, v234
	v_permlane16_swap_b32 v233, v235
	global_store_dwordx4 v[248:249], v[232:235], off offset:128
	v_cvt_pk_bf16_f32 v236, v38, v39
	v_cvt_pk_bf16_f32 v237, v40, v41
	v_mul_f32_e32 v240, v38, v38
	v_mul_f32_e32 v241, v39, v39
	v_mul_f32_e32 v242, v40, v40
	v_mul_f32_e32 v243, v41, v41
	v_add_f32_e32 v245, v240, v241
	v_add_f32_e32 v245, v242, v245
	v_add_f32_e32 v245, v243, v245
	v_add_f32_e32 v244, v245, v244
	v_cvt_pk_bf16_f32 v238, v34, v35
	v_cvt_pk_bf16_f32 v239, v36, v37
	v_mul_f32_e32 v240, v34, v34
	v_mul_f32_e32 v241, v35, v35
	v_mul_f32_e32 v242, v36, v36
	v_mul_f32_e32 v243, v37, v37
	v_add_f32_e32 v245, v240, v241
	v_add_f32_e32 v245, v242, v245
	v_add_f32_e32 v245, v243, v245
	v_add_f32_e32 v244, v245, v244
	s_nop 1
	v_permlane16_swap_b32 v236, v238
	v_permlane16_swap_b32 v237, v239
	global_store_dwordx4 v[248:249], v[236:239], off offset:192
	ds_bpermute_b32 v251, v254, v244
	s_waitcnt lgkmcnt(0)
	v_add_f32_e32 v245, v244, v251
	ds_bpermute_b32 v251, v255, v245
	s_waitcnt lgkmcnt(0)
	v_add_f32_e32 v245, v245, v251
	s_and_saveexec_b64 s[20:21], s[18:19]
	global_store_dword v[252:253], v245, off offset:128
	s_or_b64 exec, exec, s[20:21]
	v_or_b32_e32 v248, 48, v132
	v_ashrrev_i32_e32 v249, 31, v248
	v_lshlrev_b64 v[248:249], 10, v[248:249]
	v_lshl_add_u64 v[248:249], v[136:137], 0, v[248:249]
	v_lshl_add_u64 v[248:249], v[134:135], 1, v[248:249]
	v_lshl_add_u64 v[248:249], v[248:249], 0, v[246:247]
	v_cvt_pk_bf16_f32 v232, v30, v31
	v_cvt_pk_bf16_f32 v233, v32, v33
	v_mul_f32_e32 v240, v30, v30
	v_mul_f32_e32 v241, v31, v31
	v_mul_f32_e32 v242, v32, v32
	v_mul_f32_e32 v243, v33, v33
	v_add_f32_e32 v245, v240, v241
	v_add_f32_e32 v245, v242, v245
	v_add_f32_e32 v244, v243, v245
	v_cvt_pk_bf16_f32 v234, v26, v27
	v_cvt_pk_bf16_f32 v235, v28, v29
	v_mul_f32_e32 v240, v26, v26
	v_mul_f32_e32 v241, v27, v27
	v_mul_f32_e32 v242, v28, v28
	v_mul_f32_e32 v243, v29, v29
	v_add_f32_e32 v245, v240, v241
	v_add_f32_e32 v245, v242, v245
	v_add_f32_e32 v245, v243, v245
	v_add_f32_e32 v244, v245, v244
	s_nop 1
	v_permlane16_swap_b32 v232, v234
	v_permlane16_swap_b32 v233, v235
	global_store_dwordx4 v[248:249], v[232:235], off
	v_cvt_pk_bf16_f32 v236, v22, v23
	v_cvt_pk_bf16_f32 v237, v24, v25
	v_mul_f32_e32 v240, v22, v22
	v_mul_f32_e32 v241, v23, v23
	v_mul_f32_e32 v242, v24, v24
	v_mul_f32_e32 v243, v25, v25
	v_add_f32_e32 v245, v240, v241
	v_add_f32_e32 v245, v242, v245
	v_add_f32_e32 v245, v243, v245
	v_add_f32_e32 v244, v245, v244
	v_cvt_pk_bf16_f32 v238, v18, v19
	v_cvt_pk_bf16_f32 v239, v20, v21
	v_mul_f32_e32 v240, v18, v18
	v_mul_f32_e32 v241, v19, v19
	v_mul_f32_e32 v242, v20, v20
	v_mul_f32_e32 v243, v21, v21
	v_add_f32_e32 v245, v240, v241
	v_add_f32_e32 v245, v242, v245
	v_add_f32_e32 v245, v243, v245
	v_add_f32_e32 v244, v245, v244
	s_nop 1
	v_permlane16_swap_b32 v236, v238
	v_permlane16_swap_b32 v237, v239
	global_store_dwordx4 v[248:249], v[236:239], off offset:64
	v_cvt_pk_bf16_f32 v232, v14, v15
	v_cvt_pk_bf16_f32 v233, v16, v17
	v_mul_f32_e32 v240, v14, v14
	v_mul_f32_e32 v241, v15, v15
	v_mul_f32_e32 v242, v16, v16
	v_mul_f32_e32 v243, v17, v17
	v_add_f32_e32 v245, v240, v241
	v_add_f32_e32 v245, v242, v245
	v_add_f32_e32 v245, v243, v245
	v_add_f32_e32 v244, v245, v244
	v_cvt_pk_bf16_f32 v234, v6, v7
	v_cvt_pk_bf16_f32 v235, v8, v9
	v_mul_f32_e32 v240, v6, v6
	v_mul_f32_e32 v241, v7, v7
	v_mul_f32_e32 v242, v8, v8
	v_mul_f32_e32 v243, v9, v9
	v_add_f32_e32 v245, v240, v241
	v_add_f32_e32 v245, v242, v245
	v_add_f32_e32 v245, v243, v245
	v_add_f32_e32 v244, v245, v244
	s_nop 1
	v_permlane16_swap_b32 v232, v234
	v_permlane16_swap_b32 v233, v235
	global_store_dwordx4 v[248:249], v[232:235], off offset:128
	v_cvt_pk_bf16_f32 v236, v10, v11
	v_cvt_pk_bf16_f32 v237, v12, v13
	v_mul_f32_e32 v240, v10, v10
	v_mul_f32_e32 v241, v11, v11
	v_mul_f32_e32 v242, v12, v12
	v_mul_f32_e32 v243, v13, v13
	v_add_f32_e32 v245, v240, v241
	v_add_f32_e32 v245, v242, v245
	v_add_f32_e32 v245, v243, v245
	v_add_f32_e32 v244, v245, v244
	v_cvt_pk_bf16_f32 v238, v2, v3
	v_cvt_pk_bf16_f32 v239, v4, v5
	v_mul_f32_e32 v240, v2, v2
	v_mul_f32_e32 v241, v3, v3
	v_mul_f32_e32 v242, v4, v4
	v_mul_f32_e32 v243, v5, v5
	v_add_f32_e32 v245, v240, v241
	v_add_f32_e32 v245, v242, v245
	v_add_f32_e32 v245, v243, v245
	v_add_f32_e32 v244, v245, v244
	s_nop 1
	v_permlane16_swap_b32 v236, v238
	v_permlane16_swap_b32 v237, v239
	global_store_dwordx4 v[248:249], v[236:239], off offset:192
	ds_bpermute_b32 v251, v254, v244
	s_waitcnt lgkmcnt(0)
	v_add_f32_e32 v245, v244, v251
	ds_bpermute_b32 v251, v255, v245
	s_waitcnt lgkmcnt(0)
	v_add_f32_e32 v245, v245, v251
	s_and_saveexec_b64 s[20:21], s[18:19]
	global_store_dword v[252:253], v245, off offset:192
	s_or_b64 exec, exec, s[20:21]
	s_mov_b64 s[4:5], exec
	s_branch .LBB0_337

; template <bool SWAP, class Epi, bool THIN = false> ...
;     ...
;     for (int st = 0; st < ns; ++st) {
;       asm volatile("s_waitcnt vmcnt(0)" ::: "memory");
;       __builtin_amdgcn_s_barrier();
;       asm volatile("" ::: "memory");
;       if (st + 1 < ns) {
;         char* nb = smem + ((st + 1) & 1) * 65536;
;         const int ko = (st + 1) * 64;
; #pragma unroll
;         for (int i = 0; i < 4; ++i) { GLDS16(A + (size_t)(ap[i] + ko), nb + tid * 16 + i * 8192); GLDS16(Bt + (size_t)(bp[i] + ko), nb + 32768 + tid * 16 + i * 8192); }
;       }
;       const char* sa = smem + (st & 1) * 65536 + (wr * 64 + fr) * 128;
;       const char* sb = smem + (st & 1) * 65536 + 32768 + (wc * 128 + fr) * 128;
;       if constexpr (THIN) {
;         if (wc == 0) {
; #pragma unroll
;           for (int ks = 0; ks < 2; ++ks) {
;             bf16x8 af[4], bf[2];
; #pragma unroll
;             for (int m = 0; m < 4; ++m) af[m] = *(const bf16x8*)(sa + m * 2048 + (((ks * 4 + fq) ^ swz) << 4));
; #pragma unroll
;             for (int n = 0; n < 2; ++n) bf[n] = *(const bf16x8*)(sb + n * 2048 + (((ks * 4 + fq) ^ swz) << 4));
; #pragma unroll
;             for (int m = 0; m < 4; ++m)
; #pragma unroll
;               for (int n = 0; n < 2; ++n)
;                 acc[m][n] = SWAP ? __builtin_amdgcn_mfma_f32_16x16x32_bf16(bf[n], af[m], acc[m][n], 0, 0, 0)
;                                  : __builtin_amdgcn_mfma_f32_16x16x32_bf16(af[m], bf[n], acc[m][n], 0, 0, 0);
;           }
;         }
;       } else {
;       bf16x8 afA[4], afB[4], bfb[2][2];
; #pragma unroll
;       for (int m = 0; m < 4; ++m) afA[m] = *(const bf16x8*)(sa + m * 2048 + ((fq ^ swz) << 4));
; #pragma unroll
;       for (int n = 0; n < 2; ++n) bfb[0][n] = *(const bf16x8*)(sb + n * 2048 + ((fq ^ swz) << 4));
; #pragma unroll
;       for (int gq = 0; gq < 8; ++gq) {
;         const int ks = gq >> 2, nh = gq & 3;
;         if (gq < 7) {
;           const int ks2 = (gq + 1) >> 2, nh2 = (gq + 1) & 3;
; #pragma unroll
;           for (int n = 0; n < 2; ++n) bfb[(gq + 1) & 1][n] = *(const bf16x8*)(sb + (nh2 * 2 + n) * 2048 + (((ks2 * 4 + fq) ^ swz) << 4));
;         }
;         if (gq == 3) {
; #pragma unroll
;           for (int m = 0; m < 4; ++m) afB[m] = *(const bf16x8*)(sa + m * 2048 + (((4 + fq) ^ swz) << 4));
;         }
;         __builtin_amdgcn_sched_barrier(0);
; #pragma unroll
.LBB0_418:
	s_add_i32 s8, s7, 0x10000
	s_and_b32 s9, s8, 0x10000
	v_add_u32_e32 v170, s9, v138
	s_nop 0
	v_readfirstlane_b32 s9, v170
	s_and_b32 s7, s7, 0x10000
	v_or_b32_e32 v204, s7, v140
	v_add_u32_e32 v205, v204, v141
	v_add_u32_e32 v130, s7, v139
	v_add_u32_e32 v180, v130, v141
	s_waitcnt vmcnt(0)
	s_barrier
	ds_read_b128 v[168:171], v180
	ds_read_b128 v[172:175], v180 offset:2048
	ds_read_b128 v[176:179], v180 offset:4096
	ds_read_b128 v[180:183], v180 offset:6144
	ds_read_b128 v[184:187], v205 offset:32768
	ds_read_b128 v[188:191], v205 offset:34816
	ds_read_b128 v[192:195], v205 offset:36864
	ds_read_b128 v[196:199], v205 offset:38912
	v_add_u32_e32 v130, v130, v142
	s_waitcnt lgkmcnt(3)
	v_mfma_f32_16x16x32_bf16 v[126:129], v[184:187], v[168:171], v[126:129]
	s_mov_b32 m0, s9
	v_mfma_f32_16x16x32_bf16 v[110:113], v[184:187], v[172:175], v[110:113]
	global_load_lds_dwordx4 v167, s[36:37]
	v_add_u32_e32 v167, 0x80, v167
	v_mfma_f32_16x16x32_bf16 v[82:85], v[184:187], v[176:179], v[82:85]
	v_mfma_f32_16x16x32_bf16 v[50:53], v[184:187], v[180:183], v[50:53]
	ds_read_b128 v[184:187], v205 offset:40960
	ds_read_b128 v[200:203], v205 offset:43008
	s_waitcnt lgkmcnt(4)
	v_mfma_f32_16x16x32_bf16 v[122:125], v[188:191], v[168:171], v[122:125]
	s_add_u32 m0, s9, 0x8000
	v_mfma_f32_16x16x32_bf16 v[106:109], v[188:191], v[172:175], v[106:109]
	global_load_lds_dwordx4 v166, s[38:39]
	v_add_u32_e32 v166, 0x80, v166
	v_mfma_f32_16x16x32_bf16 v[78:81], v[188:191], v[176:179], v[78:81]
	v_mfma_f32_16x16x32_bf16 v[42:45], v[188:191], v[180:183], v[42:45]
	s_waitcnt lgkmcnt(3)
	v_mfma_f32_16x16x32_bf16 v[118:121], v[192:195], v[168:171], v[118:121]
	s_add_u32 m0, s9, 0x2000
	v_mfma_f32_16x16x32_bf16 v[94:97], v[192:195], v[172:175], v[94:97]
	global_load_lds_dwordx4 v165, s[36:37]
	v_add_u32_e32 v165, 0x80, v165
	v_mfma_f32_16x16x32_bf16 v[58:61], v[192:195], v[176:179], v[58:61]
	v_mfma_f32_16x16x32_bf16 v[26:29], v[192:195], v[180:183], v[26:29]
	ds_read_b128 v[188:191], v205 offset:45056
	ds_read_b128 v[192:195], v205 offset:47104
	s_waitcnt lgkmcnt(4)
	v_mfma_f32_16x16x32_bf16 v[114:117], v[196:199], v[168:171], v[114:117]
	s_add_u32 m0, s9, 0xa000
	v_mfma_f32_16x16x32_bf16 v[86:89], v[196:199], v[172:175], v[86:89]
	global_load_lds_dwordx4 v164, s[38:39]
	v_add_u32_e32 v164, 0x80, v164
	v_mfma_f32_16x16x32_bf16 v[54:57], v[196:199], v[176:179], v[54:57]
	v_mfma_f32_16x16x32_bf16 v[22:25], v[196:199], v[180:183], v[22:25]
	v_add_u32_e32 v220, v204, v142
	s_waitcnt lgkmcnt(3)
	v_mfma_f32_16x16x32_bf16 v[102:105], v[184:187], v[168:171], v[102:105]
	ds_read_b128 v[196:199], v220 offset:32768
	ds_read_b128 v[204:207], v220 offset:34816
	s_add_u32 m0, s9, 0x4000
	v_mfma_f32_16x16x32_bf16 v[74:77], v[184:187], v[172:175], v[74:77]
	global_load_lds_dwordx4 v135, s[36:37]
	v_add_u32_e32 v135, 0x80, v135
	v_mfma_f32_16x16x32_bf16 v[46:49], v[184:187], v[176:179], v[46:49]
	v_mfma_f32_16x16x32_bf16 v[10:13], v[184:187], v[180:183], v[10:13]
	ds_read_b128 v[184:187], v130
	ds_read_b128 v[208:211], v130 offset:2048
	ds_read_b128 v[212:215], v130 offset:4096
	ds_read_b128 v[216:219], v130 offset:6144
	s_waitcnt lgkmcnt(8)
	v_mfma_f32_16x16x32_bf16 v[98:101], v[200:203], v[168:171], v[98:101]
	s_add_u32 m0, s9, 0xc000
	v_mfma_f32_16x16x32_bf16 v[66:69], v[200:203], v[172:175], v[66:69]
	global_load_lds_dwordx4 v134, s[38:39]
	v_add_u32_e32 v134, 0x80, v134
	v_mfma_f32_16x16x32_bf16 v[30:33], v[200:203], v[176:179], v[30:33]
	v_mfma_f32_16x16x32_bf16 v[6:9], v[200:203], v[180:183], v[6:9]
	s_waitcnt lgkmcnt(7)
	v_mfma_f32_16x16x32_bf16 v[70:73], v[188:191], v[168:171], v[70:73]
	s_add_u32 m0, s9, 0x6000
	s_waitcnt lgkmcnt(6)
	v_mfma_f32_16x16x32_bf16 v[62:65], v[192:195], v[168:171], v[62:65]
	global_load_lds_dwordx4 v133, s[36:37]
	v_add_u32_e32 v133, 0x80, v133
	v_mfma_f32_16x16x32_bf16 v[38:41], v[188:191], v[172:175], v[38:41]
	v_mfma_f32_16x16x32_bf16 v[34:37], v[192:195], v[172:175], v[34:37]
	ds_read_b128 v[168:171], v220 offset:36864
	ds_read_b128 v[172:175], v220 offset:38912
	v_mfma_f32_16x16x32_bf16 v[18:21], v[188:191], v[176:179], v[18:21]
	s_add_u32 m0, s9, 0xe000
	v_mfma_f32_16x16x32_bf16 v[14:17], v[192:195], v[176:179], v[14:17]
	global_load_lds_dwordx4 v132, s[38:39]
	v_add_u32_e32 v132, 0x80, v132
	v_mfma_f32_16x16x32_bf16 v[2:5], v[188:191], v[180:183], v[2:5]
	v_mfma_f32_16x16x32_bf16 v[90:93], v[192:195], v[180:183], v[90:93]
	ds_read_b128 v[176:179], v220 offset:40960
	ds_read_b128 v[180:183], v220 offset:43008
	s_waitcnt lgkmcnt(7)
	v_mfma_f32_16x16x32_bf16 v[126:129], v[196:199], v[184:187], v[126:129]
	v_mfma_f32_16x16x32_bf16 v[122:125], v[204:207], v[184:187], v[122:125]
	s_waitcnt lgkmcnt(6)
	v_mfma_f32_16x16x32_bf16 v[110:113], v[196:199], v[208:211], v[110:113]
	v_mfma_f32_16x16x32_bf16 v[106:109], v[204:207], v[208:211], v[106:109]
	s_waitcnt lgkmcnt(5)
	v_mfma_f32_16x16x32_bf16 v[82:85], v[196:199], v[212:215], v[82:85]
	v_mfma_f32_16x16x32_bf16 v[78:81], v[204:207], v[212:215], v[78:81]
	s_waitcnt lgkmcnt(4)
	v_mfma_f32_16x16x32_bf16 v[50:53], v[196:199], v[216:219], v[50:53]
	v_mfma_f32_16x16x32_bf16 v[42:45], v[204:207], v[216:219], v[42:45]
	s_waitcnt lgkmcnt(3)
	v_mfma_f32_16x16x32_bf16 v[118:121], v[168:171], v[184:187], v[118:121]
	v_mfma_f32_16x16x32_bf16 v[94:97], v[168:171], v[208:211], v[94:97]
	v_mfma_f32_16x16x32_bf16 v[58:61], v[168:171], v[212:215], v[58:61]
	v_mfma_f32_16x16x32_bf16 v[26:29], v[168:171], v[216:219], v[26:29]
	ds_read_b128 v[168:171], v220 offset:45056
	ds_read_b128 v[188:191], v220 offset:47104
	s_waitcnt lgkmcnt(4)
; template <bool SWAP, class Epi, bool THIN = false> ...
;     ...
;     for (int st = 0; st < ns; ++st) {
;       asm volatile("s_waitcnt vmcnt(0)" ::: "memory");
;       __builtin_amdgcn_s_barrier();
;       asm volatile("" ::: "memory");
;       if (st + 1 < ns) {
;         char* nb = smem + ((st + 1) & 1) * 65536;
;         const int ko = (st + 1) * 64;
; #pragma unroll
;         for (int i = 0; i < 4; ++i) { GLDS16(A + (size_t)(ap[i] + ko), nb + tid * 16 + i * 8192); GLDS16(Bt + (size_t)(bp[i] + ko), nb + 32768 + tid * 16 + i * 8192); }
;       }
;       const char* sa = smem + (st & 1) * 65536 + (wr * 64 + fr) * 128;
;       const char* sb = smem + (st & 1) * 65536 + 32768 + (wc * 128 + fr) * 128;
;       if constexpr (THIN) {
;         if (wc == 0) {
; #pragma unroll
;           for (int ks = 0; ks < 2; ++ks) {
;             bf16x8 af[4], bf[2];
; #pragma unroll
;             for (int m = 0; m < 4; ++m) af[m] = *(const bf16x8*)(sa + m * 2048 + (((ks * 4 + fq) ^ swz) << 4));
; #pragma unroll
;             for (int n = 0; n < 2; ++n) bf[n] = *(const bf16x8*)(sb + n * 2048 + (((ks * 4 + fq) ^ swz) << 4));
; #pragma unroll
;             for (int m = 0; m < 4; ++m)
; #pragma unroll
;               for (int n = 0; n < 2; ++n)
;                 acc[m][n] = SWAP ? __builtin_amdgcn_mfma_f32_16x16x32_bf16(bf[n], af[m], acc[m][n], 0, 0, 0)
;                                  : __builtin_amdgcn_mfma_f32_16x16x32_bf16(af[m], bf[n], acc[m][n], 0, 0, 0);
;           }
;         }
;       } else {
;       bf16x8 afA[4], afB[4], bfb[2][2];
; #pragma unroll
;       for (int m = 0; m < 4; ++m) afA[m] = *(const bf16x8*)(sa + m * 2048 + ((fq ^ swz) << 4));
; #pragma unroll
;       for (int n = 0; n < 2; ++n) bfb[0][n] = *(const bf16x8*)(sb + n * 2048 + ((fq ^ swz) << 4));
; #pragma unroll
;       for (int gq = 0; gq < 8; ++gq) {
;         const int ks = gq >> 2, nh = gq & 3;
;         if (gq < 7) {
;           const int ks2 = (gq + 1) >> 2, nh2 = (gq + 1) & 3;
; #pragma unroll
;           for (int n = 0; n < 2; ++n) bfb[(gq + 1) & 1][n] = *(const bf16x8*)(sb + (nh2 * 2 + n) * 2048 + (((ks2 * 4 + fq) ^ swz) << 4));
;         }
;         if (gq == 3) {
; #pragma unroll
;           for (int m = 0; m < 4; ++m) afB[m] = *(const bf16x8*)(sa + m * 2048 + (((4 + fq) ^ swz) << 4));
;         }
;         __builtin_amdgcn_sched_barrier(0);
; #pragma unroll
	v_mfma_f32_16x16x32_bf16 v[114:117], v[172:175], v[184:187], v[114:117]
	v_mfma_f32_16x16x32_bf16 v[86:89], v[172:175], v[208:211], v[86:89]
	v_mfma_f32_16x16x32_bf16 v[54:57], v[172:175], v[212:215], v[54:57]
	v_mfma_f32_16x16x32_bf16 v[22:25], v[172:175], v[216:219], v[22:25]
	s_waitcnt lgkmcnt(3)
	v_mfma_f32_16x16x32_bf16 v[102:105], v[176:179], v[184:187], v[102:105]
	s_waitcnt lgkmcnt(2)
	v_mfma_f32_16x16x32_bf16 v[98:101], v[180:183], v[184:187], v[98:101]
	v_mfma_f32_16x16x32_bf16 v[74:77], v[176:179], v[208:211], v[74:77]
	v_mfma_f32_16x16x32_bf16 v[66:69], v[180:183], v[208:211], v[66:69]
	v_mfma_f32_16x16x32_bf16 v[46:49], v[176:179], v[212:215], v[46:49]
	v_mfma_f32_16x16x32_bf16 v[30:33], v[180:183], v[212:215], v[30:33]
	v_mfma_f32_16x16x32_bf16 v[10:13], v[176:179], v[216:219], v[10:13]
	v_mfma_f32_16x16x32_bf16 v[6:9], v[180:183], v[216:219], v[6:9]
	s_waitcnt lgkmcnt(1)
	v_mfma_f32_16x16x32_bf16 v[70:73], v[168:171], v[184:187], v[70:73]
	s_add_i32 s6, s6, 64
	s_cmpk_eq_i32 s6, 0x3c0
	s_mov_b32 s7, s8
	s_waitcnt lgkmcnt(0)
	v_mfma_f32_16x16x32_bf16 v[62:65], v[188:191], v[184:187], v[62:65]
	v_mfma_f32_16x16x32_bf16 v[38:41], v[168:171], v[208:211], v[38:41]
	v_mfma_f32_16x16x32_bf16 v[34:37], v[188:191], v[208:211], v[34:37]
	v_mfma_f32_16x16x32_bf16 v[18:21], v[168:171], v[212:215], v[18:21]
	v_mfma_f32_16x16x32_bf16 v[14:17], v[188:191], v[212:215], v[14:17]
	v_mfma_f32_16x16x32_bf16 v[2:5], v[168:171], v[216:219], v[2:5]
	v_mfma_f32_16x16x32_bf16 v[90:93], v[188:191], v[216:219], v[90:93]
	s_cbranch_scc0 .LBB0_418
	s_waitcnt vmcnt(0)
	s_barrier
	v_add_u32_e32 v130, v153, v141
	ds_read_b128 v[132:135], v130
	ds_read_b128 v[164:167], v130 offset:2048
	ds_read_b128 v[168:171], v130 offset:4096
	ds_read_b128 v[172:175], v130 offset:6144
	v_add_u32_e32 v130, v154, v141
	ds_read_b128 v[176:179], v130
	ds_read_b128 v[180:183], v130 offset:2048
	ds_read_b128 v[184:187], v130 offset:4096
	ds_read_b128 v[188:191], v130 offset:6144
	s_waitcnt lgkmcnt(3)
	v_mfma_f32_16x16x32_bf16 v[126:129], v[176:179], v[132:135], v[126:129]
	v_mfma_f32_16x16x32_bf16 v[110:113], v[176:179], v[164:167], v[110:113]
	v_mfma_f32_16x16x32_bf16 v[82:85], v[176:179], v[168:171], v[82:85]
	v_mfma_f32_16x16x32_bf16 v[50:53], v[176:179], v[172:175], v[50:53]
	ds_read_b128 v[176:179], v130 offset:8192
	ds_read_b128 v[192:195], v130 offset:10240
	s_waitcnt lgkmcnt(4)
	v_mfma_f32_16x16x32_bf16 v[122:125], v[180:183], v[132:135], v[122:125]
	v_mfma_f32_16x16x32_bf16 v[106:109], v[180:183], v[164:167], v[106:109]
	v_mfma_f32_16x16x32_bf16 v[78:81], v[180:183], v[168:171], v[78:81]
	v_mfma_f32_16x16x32_bf16 v[42:45], v[180:183], v[172:175], v[42:45]
	s_waitcnt lgkmcnt(3)
	v_mfma_f32_16x16x32_bf16 v[118:121], v[184:187], v[132:135], v[118:121]
	v_mfma_f32_16x16x32_bf16 v[180:183], v[184:187], v[164:167], v[94:97]
	v_mfma_f32_16x16x32_bf16 v[200:203], v[184:187], v[168:171], v[58:61]
	s_waitcnt lgkmcnt(2)
	v_mfma_f32_16x16x32_bf16 v[204:207], v[188:191], v[168:171], v[54:57]
	v_mfma_f32_16x16x32_bf16 v[184:187], v[184:187], v[172:175], v[26:29]
	s_nop 2
	ds_read_b128 v[26:29], v130 offset:12288
	ds_read_b128 v[54:57], v130 offset:14336
	v_mfma_f32_16x16x32_bf16 v[114:117], v[188:191], v[132:135], v[114:117]
	v_mfma_f32_16x16x32_bf16 v[196:199], v[188:191], v[164:167], v[86:89]
	v_mfma_f32_16x16x32_bf16 v[188:191], v[188:191], v[172:175], v[22:25]
	v_add_u32_e32 v130, v154, v142
	s_waitcnt lgkmcnt(2)
	v_mfma_f32_16x16x32_bf16 v[208:211], v[192:195], v[168:171], v[30:33]
	ds_read_b128 v[22:25], v130
	ds_read_b128 v[86:89], v130 offset:2048
	s_nop 0
	v_add_u32_e32 v30, v153, v142
	v_mfma_f32_16x16x32_bf16 v[102:105], v[176:179], v[132:135], v[102:105]
	v_mfma_f32_16x16x32_bf16 v[74:77], v[176:179], v[164:167], v[74:77]
	v_mfma_f32_16x16x32_bf16 v[46:49], v[176:179], v[168:171], v[46:49]
	v_mfma_f32_16x16x32_bf16 v[10:13], v[176:179], v[172:175], v[10:13]
	ds_read_b128 v[176:179], v30
	ds_read_b128 v[212:215], v30 offset:2048
	ds_read_b128 v[216:219], v30 offset:4096
	ds_read_b128 v[220:223], v30 offset:6144
	v_mfma_f32_16x16x32_bf16 v[98:101], v[192:195], v[132:135], v[98:101]
	v_mfma_f32_16x16x32_bf16 v[66:69], v[192:195], v[164:167], v[66:69]
	v_mfma_f32_16x16x32_bf16 v[6:9], v[192:195], v[172:175], v[6:9]
	s_waitcnt lgkmcnt(7)
	v_mfma_f32_16x16x32_bf16 v[38:41], v[26:29], v[164:167], v[38:41]
	s_waitcnt lgkmcnt(6)
	v_mfma_f32_16x16x32_bf16 v[34:37], v[54:57], v[164:167], v[34:37]
	v_mfma_f32_16x16x32_bf16 v[192:195], v[26:29], v[168:171], v[18:21]
	v_mfma_f32_16x16x32_bf16 v[166:169], v[54:57], v[168:171], v[14:17]
	s_nop 2
	ds_read_b128 v[14:17], v130 offset:4096
	ds_read_b128 v[18:21], v130 offset:6144
	v_mfma_f32_16x16x32_bf16 v[70:73], v[26:29], v[132:135], v[70:73]
	v_mfma_f32_16x16x32_bf16 v[132:135], v[54:57], v[132:135], v[62:65]
	v_mfma_f32_16x16x32_bf16 v[2:5], v[26:29], v[172:175], v[2:5]
	v_mfma_f32_16x16x32_bf16 v[170:173], v[54:57], v[172:175], v[90:93]
	ds_read_b128 v[224:227], v130 offset:8192
	ds_read_b128 v[228:231], v130 offset:10240
	s_waitcnt lgkmcnt(7)
	v_mfma_f32_16x16x32_bf16 v[126:129], v[22:25], v[176:179], v[126:129]
	v_mfma_f32_16x16x32_bf16 v[122:125], v[86:89], v[176:179], v[122:125]
	s_waitcnt lgkmcnt(6)
	v_mfma_f32_16x16x32_bf16 v[94:97], v[22:25], v[212:215], v[110:113]
	v_mfma_f32_16x16x32_bf16 v[90:93], v[86:89], v[212:215], v[106:109]
	s_waitcnt lgkmcnt(5)
	v_mfma_f32_16x16x32_bf16 v[62:65], v[22:25], v[216:219], v[82:85]
	v_mfma_f32_16x16x32_bf16 v[58:61], v[86:89], v[216:219], v[78:81]
	s_waitcnt lgkmcnt(4)
	v_mfma_f32_16x16x32_bf16 v[30:33], v[22:25], v[220:223], v[50:53]
	v_mfma_f32_16x16x32_bf16 v[26:29], v[86:89], v[220:223], v[42:45]
	s_waitcnt lgkmcnt(3)
	v_mfma_f32_16x16x32_bf16 v[86:89], v[14:17], v[212:215], v[180:183]
	v_mfma_f32_16x16x32_bf16 v[22:25], v[14:17], v[220:223], v[184:187]
	s_nop 1
	ds_read_b128 v[180:183], v130 offset:12288
	ds_read_b128 v[184:187], v130 offset:14336
	v_mfma_f32_16x16x32_bf16 v[118:121], v[14:17], v[176:179], v[118:121]
	s_waitcnt lgkmcnt(4)
	v_mfma_f32_16x16x32_bf16 v[114:117], v[18:21], v[176:179], v[114:117]
	v_mfma_f32_16x16x32_bf16 v[82:85], v[18:21], v[212:215], v[196:199]
	v_mfma_f32_16x16x32_bf16 v[54:57], v[14:17], v[216:219], v[200:203]
	v_mfma_f32_16x16x32_bf16 v[50:53], v[18:21], v[216:219], v[204:207]
	v_mfma_f32_16x16x32_bf16 v[18:21], v[18:21], v[220:223], v[188:191]
	s_waitcnt lgkmcnt(3)
	v_mfma_f32_16x16x32_bf16 v[110:113], v[224:227], v[176:179], v[102:105]
	s_waitcnt lgkmcnt(2)
	v_mfma_f32_16x16x32_bf16 v[106:109], v[228:231], v[176:179], v[98:101]
	v_mfma_f32_16x16x32_bf16 v[78:81], v[224:227], v[212:215], v[74:77]
	v_mfma_f32_16x16x32_bf16 v[74:77], v[228:231], v[212:215], v[66:69]
	v_mfma_f32_16x16x32_bf16 v[46:49], v[224:227], v[216:219], v[46:49]
	v_mfma_f32_16x16x32_bf16 v[42:45], v[228:231], v[216:219], v[208:211]
	v_mfma_f32_16x16x32_bf16 v[14:17], v[224:227], v[220:223], v[10:13]
	v_mfma_f32_16x16x32_bf16 v[10:13], v[228:231], v[220:223], v[6:9]
	s_nop 2
	v_mov_b32_e32 v6, v1
	s_waitcnt vmcnt(0) lgkmcnt(0)
	s_barrier
; __device__ __forceinline__ int get_tid512() { int t = threadIdx.x; asm volatile("" : "+v"(t)); return t; }
; __device__ __forceinline__ unsigned pack2(float a, float b) { unsigned r; asm("v_cvt_pk_bf16_f32 %0, %1, %2" : "=v"(r) : "v"(a), "v"(b)); return r; }
;   __device__ __forceinline__ float c4(int g, int rig, int col, f32x4 v) const {
;     ...
;     uint2 u; u.x = pack2(v[0], v[1]); u.y = pack2(v[2], v[3]);
;     *(uint2*)(out + row * ld + col) = u;
;     return v[0] * v[0] + v[1] * v[1] + v[2] * v[2] + v[3] * v[3];
; template <bool SWAP, class Epi, bool THIN = false> ...
;     ...
;     __syncthreads();
;     const int te = get_tid512();
;     const int fr_e = te & 15, fq_e = (te & 63) >> 4, wr_e = te >> 7, wc_e = (te >> 6) & 1;
;     const int sub = 2 * mt + (wr_e >> 1);
;     const int g = sub / tpg, ti = sub - g * tpg;
;     const int rig0 = ti * step - halo;
;     const int rw = (wr_e & 1) * 64;
;     if constexpr (Epi::KIND == 0) {
; #pragma unroll
;       for (int m = 0; m < 4; ++m) {
;         const int rig = rig0 + rw + m * 16 + fr_e;
;         if constexpr (Epi::ROWSUM) {
;           float ss = 0.f;
; #pragma unroll
;           for (int n = 0; n < 8; ++n) {
;             const int col = nt * 256 + wc_e * 128 + n * 16 + fq_e * 4;
;             if (col < N) ss += epi.c4(g, rig, col, acc[m][n]);
	v_mfma_f32_16x16x32_bf16 v[98:101], v[184:187], v[176:179], v[132:135]
	v_ashrrev_i32_e32 v7, 8, v6
	v_add_u32_e32 v7, s5, v7
	v_mul_hi_i32 v8, v7, s23
	v_lshrrev_b32_e32 v9, 31, v8
	v_ashrrev_i32_e32 v8, 2, v8
	v_add_u32_e32 v130, v8, v9
	v_and_b32_e32 v132, 15, v6
	v_bfe_u32 v164, v6, 4, 2
	v_bfe_u32 v165, v6, 6, 1
	v_mul_lo_u32 v8, v130, s24
	v_lshrrev_b32_e32 v6, 1, v6
	v_mfma_f32_16x16x32_bf16 v[102:105], v[180:183], v[176:179], v[70:73]
	v_add_lshl_u32 v133, v8, v7, 7
	v_and_b32_e32 v135, 64, v6
	v_lshlrev_b32_e32 v134, 7, v165
	v_mfma_f32_16x16x32_bf16 v[70:73], v[180:183], v[212:215], v[38:41]
	v_or3_b32 v132, v133, v135, v132
	v_ashrrev_i32_e32 v133, 31, v132
	v_mfma_f32_16x16x32_bf16 v[66:69], v[184:187], v[212:215], v[34:37]
	v_mfma_f32_16x16x32_bf16 v[38:41], v[180:183], v[216:219], v[192:195]
	v_mfma_f32_16x16x32_bf16 v[34:37], v[184:187], v[216:219], v[166:169]
	v_mfma_f32_16x16x32_bf16 v[6:9], v[180:183], v[220:223], v[2:5]
	s_nop 1
	v_lshlrev_b32_e32 v166, 2, v164
	v_or3_b32 v134, v134, v166, s4
	v_cmp_gt_i32_e32 vcc, s27, v134
	v_mfma_f32_16x16x32_bf16 v[2:5], v[184:187], v[220:223], v[170:173]
	v_mov_b32_e32 v166, 0
	v_ashrrev_i32_e32 v135, 31, v134
	s_and_saveexec_b64 s[4:5], vcc
	s_cbranch_execz .LBB0_421
	v_mad_i64_i32 v[166:167], s[6:7], v130, s25, v[132:133]
	v_mov_b64_e32 v[170:171], s[30:31]
	v_cvt_pk_bf16_f32 v168, v126, v127
	v_mad_u64_u32 v[170:171], s[6:7], v166, s28, v[170:171]
	v_pk_mul_f32 v[126:127], v[126:127], v[126:127]
	v_cvt_pk_bf16_f32 v169, v128, v129
	v_mad_i32_i24 v171, v167, s28, v171
	v_pk_mul_f32 v[128:129], v[128:129], v[128:129]
	v_add_f32_e32 v126, v126, v127
	v_lshl_add_u64 v[166:167], v[134:135], 1, v[170:171]
	v_add_f32_e32 v126, v128, v126
	global_store_dwordx2 v[166:167], v[168:169], off
	v_add_f32_e32 v166, v129, v126

; template <bool SWAP, class Epi, bool THIN = false> ...
;     ...
;     for (int st = 0; st < ns; ++st) {
;       asm volatile("s_waitcnt vmcnt(0)" ::: "memory");
;       __builtin_amdgcn_s_barrier();
;       asm volatile("" ::: "memory");
;       if (st + 1 < ns) {
;         char* nb = smem + ((st + 1) & 1) * 65536;
;         const int ko = (st + 1) * 64;
; #pragma unroll
;         for (int i = 0; i < 4; ++i) { GLDS16(A + (size_t)(ap[i] + ko), nb + tid * 16 + i * 8192); GLDS16(Bt + (size_t)(bp[i] + ko), nb + 32768 + tid * 16 + i * 8192); }
;       }
;       const char* sa = smem + (st & 1) * 65536 + (wr * 64 + fr) * 128;
;       const char* sb = smem + (st & 1) * 65536 + 32768 + (wc * 128 + fr) * 128;
;       if constexpr (THIN) {
;         if (wc == 0) {
; #pragma unroll
;           for (int ks = 0; ks < 2; ++ks) {
;             bf16x8 af[4], bf[2];
; #pragma unroll
;             for (int m = 0; m < 4; ++m) af[m] = *(const bf16x8*)(sa + m * 2048 + (((ks * 4 + fq) ^ swz) << 4));
; #pragma unroll
;             for (int n = 0; n < 2; ++n) bf[n] = *(const bf16x8*)(sb + n * 2048 + (((ks * 4 + fq) ^ swz) << 4));
; #pragma unroll
;             for (int m = 0; m < 4; ++m)
; #pragma unroll
;               for (int n = 0; n < 2; ++n)
;                 acc[m][n] = SWAP ? __builtin_amdgcn_mfma_f32_16x16x32_bf16(bf[n], af[m], acc[m][n], 0, 0, 0)
;                                  : __builtin_amdgcn_mfma_f32_16x16x32_bf16(af[m], bf[n], acc[m][n], 0, 0, 0);
;           }
;         }
;       } else {
;       bf16x8 afA[4], afB[4], bfb[2][2];
; #pragma unroll
;       for (int m = 0; m < 4; ++m) afA[m] = *(const bf16x8*)(sa + m * 2048 + ((fq ^ swz) << 4));
; #pragma unroll
;       for (int n = 0; n < 2; ++n) bfb[0][n] = *(const bf16x8*)(sb + n * 2048 + ((fq ^ swz) << 4));
; #pragma unroll
;       for (int gq = 0; gq < 8; ++gq) {
;         const int ks = gq >> 2, nh = gq & 3;
;         if (gq < 7) {
;           const int ks2 = (gq + 1) >> 2, nh2 = (gq + 1) & 3;
; #pragma unroll
;           for (int n = 0; n < 2; ++n) bfb[(gq + 1) & 1][n] = *(const bf16x8*)(sb + (nh2 * 2 + n) * 2048 + (((ks2 * 4 + fq) ^ swz) << 4));
;         }
;         if (gq == 3) {
; #pragma unroll
;           for (int m = 0; m < 4; ++m) afB[m] = *(const bf16x8*)(sa + m * 2048 + (((4 + fq) ^ swz) << 4));
;         }
;         __builtin_amdgcn_sched_barrier(0);
; #pragma unroll
.LBB0_2116:
	s_add_i32 s8, s7, 0x10000
	s_and_b32 s9, s8, 0x10000
	v_add_u32_e32 v169, s9, v144
	s_nop 0
	v_readfirstlane_b32 s9, v169
	s_and_b32 s7, s7, 0x10000
	v_add_u32_e32 v130, s7, v145
	v_add_u32_e32 v140, v130, v147
	s_waitcnt vmcnt(0)
	s_barrier
	ds_read_b128 v[170:173], v140
	ds_read_b128 v[174:177], v140 offset:2048
	ds_read_b128 v[178:181], v140 offset:4096
	ds_read_b128 v[182:185], v140 offset:6144
	v_or_b32_e32 v140, s7, v146
	v_add_u32_e32 v141, v140, v147
	ds_read_b128 v[186:189], v141 offset:32768
	ds_read_b128 v[190:193], v141 offset:34816
	ds_read_b128 v[194:197], v141 offset:36864
	ds_read_b128 v[198:201], v141 offset:38912
	v_add_u32_e32 v130, v130, v148
	s_waitcnt lgkmcnt(3)
	v_mfma_f32_16x16x32_bf16 v[126:129], v[186:189], v[170:173], v[126:129]
	s_mov_b32 m0, s9
	v_mfma_f32_16x16x32_bf16 v[110:113], v[186:189], v[174:177], v[110:113]
	global_load_lds_dwordx4 v139, s[18:19]
	v_add_u32_e32 v139, 0x80, v139
	v_mfma_f32_16x16x32_bf16 v[82:85], v[186:189], v[178:181], v[82:85]
	v_mfma_f32_16x16x32_bf16 v[50:53], v[186:189], v[182:185], v[50:53]
	ds_read_b128 v[186:189], v141 offset:40960
	ds_read_b128 v[202:205], v141 offset:43008
	s_waitcnt lgkmcnt(4)
	v_mfma_f32_16x16x32_bf16 v[122:125], v[190:193], v[170:173], v[122:125]
	s_add_u32 m0, s9, 0x8000
	v_mfma_f32_16x16x32_bf16 v[106:109], v[190:193], v[174:177], v[106:109]
	global_load_lds_dwordx4 v138, s[24:25]
	v_add_u32_e32 v138, 0x80, v138
	v_mfma_f32_16x16x32_bf16 v[78:81], v[190:193], v[178:181], v[78:81]
	v_mfma_f32_16x16x32_bf16 v[42:45], v[190:193], v[182:185], v[42:45]
	s_waitcnt lgkmcnt(3)
	v_mfma_f32_16x16x32_bf16 v[118:121], v[194:197], v[170:173], v[118:121]
	s_add_u32 m0, s9, 0x2000
	v_mfma_f32_16x16x32_bf16 v[94:97], v[194:197], v[174:177], v[94:97]
	global_load_lds_dwordx4 v137, s[18:19]
	v_add_u32_e32 v137, 0x80, v137
	v_mfma_f32_16x16x32_bf16 v[58:61], v[194:197], v[178:181], v[58:61]
	v_mfma_f32_16x16x32_bf16 v[26:29], v[194:197], v[182:185], v[26:29]
	ds_read_b128 v[190:193], v141 offset:45056
	ds_read_b128 v[194:197], v141 offset:47104
	s_waitcnt lgkmcnt(4)
	v_mfma_f32_16x16x32_bf16 v[114:117], v[198:201], v[170:173], v[114:117]
	s_add_u32 m0, s9, 0xa000
	v_mfma_f32_16x16x32_bf16 v[86:89], v[198:201], v[174:177], v[86:89]
	global_load_lds_dwordx4 v136, s[24:25]
	v_add_u32_e32 v136, 0x80, v136
	v_mfma_f32_16x16x32_bf16 v[54:57], v[198:201], v[178:181], v[54:57]
	v_mfma_f32_16x16x32_bf16 v[22:25], v[198:201], v[182:185], v[22:25]
	v_add_u32_e32 v140, v140, v148
	s_waitcnt lgkmcnt(3)
	v_mfma_f32_16x16x32_bf16 v[102:105], v[186:189], v[170:173], v[102:105]
	ds_read_b128 v[198:201], v140 offset:32768
	ds_read_b128 v[206:209], v140 offset:34816
	s_add_u32 m0, s9, 0x4000
	v_mfma_f32_16x16x32_bf16 v[74:77], v[186:189], v[174:177], v[74:77]
	global_load_lds_dwordx4 v135, s[18:19]
	v_add_u32_e32 v135, 0x80, v135
	v_mfma_f32_16x16x32_bf16 v[46:49], v[186:189], v[178:181], v[46:49]
	v_mfma_f32_16x16x32_bf16 v[10:13], v[186:189], v[182:185], v[10:13]
	ds_read_b128 v[186:189], v130
	ds_read_b128 v[210:213], v130 offset:2048
	ds_read_b128 v[214:217], v130 offset:4096
	ds_read_b128 v[218:221], v130 offset:6144
	s_waitcnt lgkmcnt(8)
	v_mfma_f32_16x16x32_bf16 v[98:101], v[202:205], v[170:173], v[98:101]
	s_add_u32 m0, s9, 0xc000
	v_mfma_f32_16x16x32_bf16 v[66:69], v[202:205], v[174:177], v[66:69]
	global_load_lds_dwordx4 v134, s[24:25]
	v_add_u32_e32 v134, 0x80, v134
	v_mfma_f32_16x16x32_bf16 v[30:33], v[202:205], v[178:181], v[30:33]
	v_mfma_f32_16x16x32_bf16 v[6:9], v[202:205], v[182:185], v[6:9]
	s_waitcnt lgkmcnt(7)
	v_mfma_f32_16x16x32_bf16 v[70:73], v[190:193], v[170:173], v[70:73]
	s_add_u32 m0, s9, 0x6000
	s_waitcnt lgkmcnt(6)
	v_mfma_f32_16x16x32_bf16 v[62:65], v[194:197], v[170:173], v[62:65]
	global_load_lds_dwordx4 v133, s[18:19]
	v_add_u32_e32 v133, 0x80, v133
	v_mfma_f32_16x16x32_bf16 v[38:41], v[190:193], v[174:177], v[38:41]
	v_mfma_f32_16x16x32_bf16 v[34:37], v[194:197], v[174:177], v[34:37]
	ds_read_b128 v[170:173], v140 offset:36864
	ds_read_b128 v[174:177], v140 offset:38912
	v_mfma_f32_16x16x32_bf16 v[18:21], v[190:193], v[178:181], v[18:21]
	s_add_u32 m0, s9, 0xe000
	v_mfma_f32_16x16x32_bf16 v[14:17], v[194:197], v[178:181], v[14:17]
	global_load_lds_dwordx4 v132, s[24:25]
	v_add_u32_e32 v132, 0x80, v132
	v_mfma_f32_16x16x32_bf16 v[2:5], v[190:193], v[182:185], v[2:5]
	v_mfma_f32_16x16x32_bf16 v[90:93], v[194:197], v[182:185], v[90:93]
	ds_read_b128 v[178:181], v140 offset:40960
	ds_read_b128 v[182:185], v140 offset:43008
	s_waitcnt lgkmcnt(7)
	v_mfma_f32_16x16x32_bf16 v[126:129], v[198:201], v[186:189], v[126:129]
	v_mfma_f32_16x16x32_bf16 v[122:125], v[206:209], v[186:189], v[122:125]
	s_waitcnt lgkmcnt(6)
	v_mfma_f32_16x16x32_bf16 v[110:113], v[198:201], v[210:213], v[110:113]
	v_mfma_f32_16x16x32_bf16 v[106:109], v[206:209], v[210:213], v[106:109]
	s_waitcnt lgkmcnt(5)
	v_mfma_f32_16x16x32_bf16 v[82:85], v[198:201], v[214:217], v[82:85]
	v_mfma_f32_16x16x32_bf16 v[78:81], v[206:209], v[214:217], v[78:81]
	s_waitcnt lgkmcnt(4)
	v_mfma_f32_16x16x32_bf16 v[50:53], v[198:201], v[218:221], v[50:53]
	v_mfma_f32_16x16x32_bf16 v[42:45], v[206:209], v[218:221], v[42:45]
	s_waitcnt lgkmcnt(3)
	v_mfma_f32_16x16x32_bf16 v[118:121], v[170:173], v[186:189], v[118:121]
	v_mfma_f32_16x16x32_bf16 v[94:97], v[170:173], v[210:213], v[94:97]
	v_mfma_f32_16x16x32_bf16 v[58:61], v[170:173], v[214:217], v[58:61]
	v_mfma_f32_16x16x32_bf16 v[26:29], v[170:173], v[218:221], v[26:29]
	ds_read_b128 v[170:173], v140 offset:45056
	ds_read_b128 v[190:193], v140 offset:47104
	s_waitcnt lgkmcnt(4)
; template <bool SWAP, class Epi, bool THIN = false> ...
;     ...
;     for (int st = 0; st < ns; ++st) {
;       asm volatile("s_waitcnt vmcnt(0)" ::: "memory");
;       __builtin_amdgcn_s_barrier();
;       asm volatile("" ::: "memory");
;       if (st + 1 < ns) {
;         char* nb = smem + ((st + 1) & 1) * 65536;
;         const int ko = (st + 1) * 64;
; #pragma unroll
;         for (int i = 0; i < 4; ++i) { GLDS16(A + (size_t)(ap[i] + ko), nb + tid * 16 + i * 8192); GLDS16(Bt + (size_t)(bp[i] + ko), nb + 32768 + tid * 16 + i * 8192); }
;       }
;       const char* sa = smem + (st & 1) * 65536 + (wr * 64 + fr) * 128;
;       const char* sb = smem + (st & 1) * 65536 + 32768 + (wc * 128 + fr) * 128;
;       if constexpr (THIN) {
;         if (wc == 0) {
; #pragma unroll
;           for (int ks = 0; ks < 2; ++ks) {
;             bf16x8 af[4], bf[2];
; #pragma unroll
;             for (int m = 0; m < 4; ++m) af[m] = *(const bf16x8*)(sa + m * 2048 + (((ks * 4 + fq) ^ swz) << 4));
; #pragma unroll
;             for (int n = 0; n < 2; ++n) bf[n] = *(const bf16x8*)(sb + n * 2048 + (((ks * 4 + fq) ^ swz) << 4));
; #pragma unroll
;             for (int m = 0; m < 4; ++m)
; #pragma unroll
;               for (int n = 0; n < 2; ++n)
;                 acc[m][n] = SWAP ? __builtin_amdgcn_mfma_f32_16x16x32_bf16(bf[n], af[m], acc[m][n], 0, 0, 0)
;                                  : __builtin_amdgcn_mfma_f32_16x16x32_bf16(af[m], bf[n], acc[m][n], 0, 0, 0);
;           }
;         }
;       } else {
;       bf16x8 afA[4], afB[4], bfb[2][2];
; #pragma unroll
;       for (int m = 0; m < 4; ++m) afA[m] = *(const bf16x8*)(sa + m * 2048 + ((fq ^ swz) << 4));
; #pragma unroll
;       for (int n = 0; n < 2; ++n) bfb[0][n] = *(const bf16x8*)(sb + n * 2048 + ((fq ^ swz) << 4));
; #pragma unroll
;       for (int gq = 0; gq < 8; ++gq) {
;         const int ks = gq >> 2, nh = gq & 3;
;         if (gq < 7) {
;           const int ks2 = (gq + 1) >> 2, nh2 = (gq + 1) & 3;
; #pragma unroll
;           for (int n = 0; n < 2; ++n) bfb[(gq + 1) & 1][n] = *(const bf16x8*)(sb + (nh2 * 2 + n) * 2048 + (((ks2 * 4 + fq) ^ swz) << 4));
;         }
;         if (gq == 3) {
; #pragma unroll
;           for (int m = 0; m < 4; ++m) afB[m] = *(const bf16x8*)(sa + m * 2048 + (((4 + fq) ^ swz) << 4));
;         }
;         __builtin_amdgcn_sched_barrier(0);
; #pragma unroll
	v_mfma_f32_16x16x32_bf16 v[114:117], v[174:177], v[186:189], v[114:117]
	v_mfma_f32_16x16x32_bf16 v[86:89], v[174:177], v[210:213], v[86:89]
	v_mfma_f32_16x16x32_bf16 v[54:57], v[174:177], v[214:217], v[54:57]
	v_mfma_f32_16x16x32_bf16 v[22:25], v[174:177], v[218:221], v[22:25]
	s_waitcnt lgkmcnt(3)
	v_mfma_f32_16x16x32_bf16 v[102:105], v[178:181], v[186:189], v[102:105]
	s_waitcnt lgkmcnt(2)
	v_mfma_f32_16x16x32_bf16 v[98:101], v[182:185], v[186:189], v[98:101]
	v_mfma_f32_16x16x32_bf16 v[74:77], v[178:181], v[210:213], v[74:77]
	v_mfma_f32_16x16x32_bf16 v[66:69], v[182:185], v[210:213], v[66:69]
	v_mfma_f32_16x16x32_bf16 v[46:49], v[178:181], v[214:217], v[46:49]
	v_mfma_f32_16x16x32_bf16 v[30:33], v[182:185], v[214:217], v[30:33]
	v_mfma_f32_16x16x32_bf16 v[10:13], v[178:181], v[218:221], v[10:13]
	v_mfma_f32_16x16x32_bf16 v[6:9], v[182:185], v[218:221], v[6:9]
	s_waitcnt lgkmcnt(1)
	v_mfma_f32_16x16x32_bf16 v[70:73], v[170:173], v[186:189], v[70:73]
	s_add_i32 s6, s6, 64
	s_cmpk_eq_i32 s6, 0x3c0
	s_mov_b32 s7, s8
	s_waitcnt lgkmcnt(0)
	v_mfma_f32_16x16x32_bf16 v[62:65], v[190:193], v[186:189], v[62:65]
	v_mfma_f32_16x16x32_bf16 v[38:41], v[170:173], v[210:213], v[38:41]
	v_mfma_f32_16x16x32_bf16 v[34:37], v[190:193], v[210:213], v[34:37]
	v_mfma_f32_16x16x32_bf16 v[18:21], v[170:173], v[214:217], v[18:21]
	v_mfma_f32_16x16x32_bf16 v[14:17], v[190:193], v[214:217], v[14:17]
	v_mfma_f32_16x16x32_bf16 v[2:5], v[170:173], v[218:221], v[2:5]
	v_mfma_f32_16x16x32_bf16 v[90:93], v[190:193], v[218:221], v[90:93]
	s_cbranch_scc0 .LBB0_2116
	s_waitcnt vmcnt(0)
	s_barrier
	v_add_u32_e32 v130, v159, v147
	ds_read_b128 v[132:135], v130
	ds_read_b128 v[136:139], v130 offset:2048
	ds_read_b128 v[170:173], v130 offset:4096
	ds_read_b128 v[174:177], v130 offset:6144
	v_add_u32_e32 v130, v160, v147
	ds_read_b128 v[178:181], v130
	ds_read_b128 v[182:185], v130 offset:2048
	ds_read_b128 v[186:189], v130 offset:4096
	ds_read_b128 v[190:193], v130 offset:6144
	s_waitcnt lgkmcnt(3)
	v_mfma_f32_16x16x32_bf16 v[126:129], v[178:181], v[132:135], v[126:129]
	v_mfma_f32_16x16x32_bf16 v[110:113], v[178:181], v[136:139], v[110:113]
	v_mfma_f32_16x16x32_bf16 v[82:85], v[178:181], v[170:173], v[82:85]
	v_mfma_f32_16x16x32_bf16 v[50:53], v[178:181], v[174:177], v[50:53]
	ds_read_b128 v[178:181], v130 offset:8192
	ds_read_b128 v[194:197], v130 offset:10240
	s_waitcnt lgkmcnt(4)
	v_mfma_f32_16x16x32_bf16 v[122:125], v[182:185], v[132:135], v[122:125]
	v_mfma_f32_16x16x32_bf16 v[106:109], v[182:185], v[136:139], v[106:109]
	v_mfma_f32_16x16x32_bf16 v[78:81], v[182:185], v[170:173], v[78:81]
	v_mfma_f32_16x16x32_bf16 v[42:45], v[182:185], v[174:177], v[42:45]
	s_waitcnt lgkmcnt(3)
	v_mfma_f32_16x16x32_bf16 v[118:121], v[186:189], v[132:135], v[118:121]
	v_mfma_f32_16x16x32_bf16 v[182:185], v[186:189], v[136:139], v[94:97]
	v_mfma_f32_16x16x32_bf16 v[202:205], v[186:189], v[170:173], v[58:61]
	s_waitcnt lgkmcnt(2)
	v_mfma_f32_16x16x32_bf16 v[206:209], v[190:193], v[170:173], v[54:57]
	v_mfma_f32_16x16x32_bf16 v[186:189], v[186:189], v[174:177], v[26:29]
	s_nop 2
	ds_read_b128 v[26:29], v130 offset:12288
	ds_read_b128 v[54:57], v130 offset:14336
	v_mfma_f32_16x16x32_bf16 v[114:117], v[190:193], v[132:135], v[114:117]
	v_mfma_f32_16x16x32_bf16 v[198:201], v[190:193], v[136:139], v[86:89]
	v_mfma_f32_16x16x32_bf16 v[190:193], v[190:193], v[174:177], v[22:25]
	v_add_u32_e32 v130, v160, v148
	s_waitcnt lgkmcnt(2)
	v_mfma_f32_16x16x32_bf16 v[210:213], v[194:197], v[170:173], v[30:33]
	ds_read_b128 v[22:25], v130
	ds_read_b128 v[86:89], v130 offset:2048
	s_nop 0
	v_add_u32_e32 v30, v159, v148
	v_mfma_f32_16x16x32_bf16 v[102:105], v[178:181], v[132:135], v[102:105]
	v_mfma_f32_16x16x32_bf16 v[74:77], v[178:181], v[136:139], v[74:77]
	v_mfma_f32_16x16x32_bf16 v[46:49], v[178:181], v[170:173], v[46:49]
	v_mfma_f32_16x16x32_bf16 v[10:13], v[178:181], v[174:177], v[10:13]
	ds_read_b128 v[178:181], v30
	ds_read_b128 v[214:217], v30 offset:2048
	ds_read_b128 v[218:221], v30 offset:4096
	ds_read_b128 v[222:225], v30 offset:6144
	v_mfma_f32_16x16x32_bf16 v[98:101], v[194:197], v[132:135], v[98:101]
	v_mfma_f32_16x16x32_bf16 v[66:69], v[194:197], v[136:139], v[66:69]
	v_mfma_f32_16x16x32_bf16 v[6:9], v[194:197], v[174:177], v[6:9]
	s_waitcnt lgkmcnt(7)
	v_mfma_f32_16x16x32_bf16 v[38:41], v[26:29], v[136:139], v[38:41]
	s_waitcnt lgkmcnt(6)
	v_mfma_f32_16x16x32_bf16 v[34:37], v[54:57], v[136:139], v[34:37]
	v_mfma_f32_16x16x32_bf16 v[136:139], v[26:29], v[170:173], v[18:21]
	v_mfma_f32_16x16x32_bf16 v[170:173], v[54:57], v[170:173], v[14:17]
	s_nop 2
	ds_read_b128 v[14:17], v130 offset:4096
	ds_read_b128 v[18:21], v130 offset:6144
	v_mfma_f32_16x16x32_bf16 v[70:73], v[26:29], v[132:135], v[70:73]
	v_mfma_f32_16x16x32_bf16 v[132:135], v[54:57], v[132:135], v[62:65]
	v_mfma_f32_16x16x32_bf16 v[2:5], v[26:29], v[174:177], v[2:5]
	v_mfma_f32_16x16x32_bf16 v[174:177], v[54:57], v[174:177], v[90:93]
	ds_read_b128 v[194:197], v130 offset:8192
	ds_read_b128 v[226:229], v130 offset:10240
	s_waitcnt lgkmcnt(7)
	v_mfma_f32_16x16x32_bf16 v[126:129], v[22:25], v[178:181], v[126:129]
	v_mfma_f32_16x16x32_bf16 v[122:125], v[86:89], v[178:181], v[122:125]
	s_waitcnt lgkmcnt(6)
	v_mfma_f32_16x16x32_bf16 v[94:97], v[22:25], v[214:217], v[110:113]
	v_mfma_f32_16x16x32_bf16 v[90:93], v[86:89], v[214:217], v[106:109]
	s_waitcnt lgkmcnt(5)
	v_mfma_f32_16x16x32_bf16 v[62:65], v[22:25], v[218:221], v[82:85]
	v_mfma_f32_16x16x32_bf16 v[58:61], v[86:89], v[218:221], v[78:81]
	s_waitcnt lgkmcnt(4)
	v_mfma_f32_16x16x32_bf16 v[30:33], v[22:25], v[222:225], v[50:53]
	v_mfma_f32_16x16x32_bf16 v[26:29], v[86:89], v[222:225], v[42:45]
	s_waitcnt lgkmcnt(3)
	v_mfma_f32_16x16x32_bf16 v[86:89], v[14:17], v[214:217], v[182:185]
	v_mfma_f32_16x16x32_bf16 v[22:25], v[14:17], v[222:225], v[186:189]
	s_nop 1
	ds_read_b128 v[182:185], v130 offset:12288
	ds_read_b128 v[186:189], v130 offset:14336
	v_mfma_f32_16x16x32_bf16 v[118:121], v[14:17], v[178:181], v[118:121]
	s_waitcnt lgkmcnt(4)
	v_mfma_f32_16x16x32_bf16 v[114:117], v[18:21], v[178:181], v[114:117]
	v_mfma_f32_16x16x32_bf16 v[82:85], v[18:21], v[214:217], v[198:201]
	v_mfma_f32_16x16x32_bf16 v[54:57], v[14:17], v[218:221], v[202:205]
	v_mfma_f32_16x16x32_bf16 v[50:53], v[18:21], v[218:221], v[206:209]
	v_mfma_f32_16x16x32_bf16 v[18:21], v[18:21], v[222:225], v[190:193]
	s_waitcnt lgkmcnt(3)
	v_mfma_f32_16x16x32_bf16 v[110:113], v[194:197], v[178:181], v[102:105]
	s_waitcnt lgkmcnt(2)
	v_mfma_f32_16x16x32_bf16 v[106:109], v[226:229], v[178:181], v[98:101]
	v_mfma_f32_16x16x32_bf16 v[78:81], v[194:197], v[214:217], v[74:77]
	v_mfma_f32_16x16x32_bf16 v[74:77], v[226:229], v[214:217], v[66:69]
	v_mfma_f32_16x16x32_bf16 v[46:49], v[194:197], v[218:221], v[46:49]
	v_mfma_f32_16x16x32_bf16 v[42:45], v[226:229], v[218:221], v[210:213]
	v_mfma_f32_16x16x32_bf16 v[14:17], v[194:197], v[222:225], v[10:13]
	v_mfma_f32_16x16x32_bf16 v[6:9], v[226:229], v[222:225], v[6:9]
	v_mov_b32_e32 v130, v1
	s_waitcnt vmcnt(0) lgkmcnt(0)
	s_barrier
; __device__ __forceinline__ int get_tid512() { int t = threadIdx.x; asm volatile("" : "+v"(t)); return t; }
; __device__ __forceinline__ unsigned pack2(float a, float b) { unsigned r; asm("v_cvt_pk_bf16_f32 %0, %1, %2" : "=v"(r) : "v"(a), "v"(b)); return r; }
; __device__ __forceinline__ float bf2f(bf16_t h) { return __uint_as_float(((unsigned)h) << 16); }
;   __device__ __forceinline__ void c4(int g, int rig, int col, f32x4 v) const {
;     const size_t o = ((size_t)g * 2048 + rig) * 1024 + col;
;     f32x4 bs;
;     if (BASE_F32) bs = __builtin_nontemporal_load((const f32x4*)((const float*)base + o));
;     else {
;       const uint2 u = *(const uint2*)((const bf16_t*)base + o);
;       bs[0] = bf2f((bf16_t)(u.x & 0xffff)); bs[1] = bf2f((bf16_t)(u.x >> 16)); bs[2] = bf2f((bf16_t)(u.y & 0xffff)); bs[3] = bf2f((bf16_t)(u.y >> 16));
;     }
;     const f32x4 gt = *(const f32x4*)(gate + (size_t)g * 6144 + col);
;     f32x4 bi = {0.f, 0.f, 0.f, 0.f};
;     if (bias) bi = *(const f32x4*)(bias + col);
;     f32x4 r;
; #pragma unroll
;     for (int j = 0; j < 4; ++j) r[j] = bs[j] + gt[j] * (v[j] + bi[j]);
;     uint2 w; w.x = pack2(r[0], r[1]); w.y = pack2(r[2], r[3]);
;     *(uint2*)(X16 + o) = w;
; template <bool SWAP, class Epi, bool THIN = false> ...
;     ...
;     __syncthreads();
;     const int te = get_tid512();
;     const int fr_e = te & 15, fq_e = (te & 63) >> 4, wr_e = te >> 7, wc_e = (te >> 6) & 1;
;     const int sub = 2 * mt + (wr_e >> 1);
;     const int g = sub / tpg, ti = sub - g * tpg;
;     const int rig0 = ti * step - halo;
;     const int rw = (wr_e & 1) * 64;
;     if constexpr (Epi::KIND == 0) {
; #pragma unroll
;       for (int m = 0; m < 4; ++m) {
;         const int rig = rig0 + rw + m * 16 + fr_e;
;         if constexpr (Epi::ROWSUM) {
;           float ss = 0.f;
; #pragma unroll
;           for (int n = 0; n < 8; ++n) {
;             const int col = nt * 256 + wc_e * 128 + n * 16 + fq_e * 4;
;             if (col < N) ss += epi.c4(g, rig, col, acc[m][n]);
;           }
	v_mfma_f32_16x16x32_bf16 v[98:101], v[186:189], v[178:181], v[132:135]
	v_ashrrev_i32_e32 v11, 8, v130
	v_add_u32_e32 v11, s5, v11
	v_ashrrev_i32_e32 v12, 31, v11
	v_lshrrev_b32_e32 v12, 28, v12
	v_add_u32_e32 v12, v11, v12
	v_ashrrev_i32_e32 v134, 4, v12
	v_lshlrev_b32_e32 v12, 11, v134
	v_lshlrev_b32_e32 v11, 7, v11
	v_sub_u32_e32 v11, v11, v12
	v_lshrrev_b32_e32 v12, 1, v130
	v_and_b32_e32 v10, 15, v130
	v_and_b32_e32 v12, 64, v12
	v_mfma_f32_16x16x32_bf16 v[102:105], v[182:185], v[178:181], v[70:73]
	v_ashrrev_i32_e32 v135, 31, v134
	v_mfma_f32_16x16x32_bf16 v[70:73], v[182:185], v[214:217], v[38:41]
	v_mfma_f32_16x16x32_bf16 v[38:41], v[182:185], v[218:221], v[136:139]
	s_nop 2
	v_or3_b32 v136, v11, v12, v10
	v_lshlrev_b32_e32 v10, 1, v130
	v_and_b32_e32 v132, 0x80, v10
	v_mfma_f32_16x16x32_bf16 v[10:13], v[182:185], v[222:225], v[2:5]
	v_ashrrev_i32_e32 v137, 31, v136
	v_lshlrev_b64 v[138:139], 21, v[134:135]
	v_lshlrev_b64 v[140:141], 10, v[136:137]
	v_lshrrev_b32_e32 v2, 2, v130
	v_and_b32_e32 v2, 12, v2
	v_mfma_f32_16x16x32_bf16 v[66:69], v[186:189], v[214:217], v[34:37]
	v_or3_b32 v132, v2, v132, s4
	v_bfe_u32 v246, v130, 4, 1
	v_mul_u32_u24_e32 v246, 24, v246
	v_mov_b32_e32 v247, 0
	v_mad_i64_i32 v[134:135], s[4:5], v134, s33, 0
	v_mfma_f32_16x16x32_bf16 v[34:37], v[186:189], v[218:221], v[170:173]
	v_lshl_add_u64 v[140:141], v[140:141], 0, v[138:139]
	v_cmp_gt_i32_e32 vcc, s34, v132
	v_ashrrev_i32_e32 v133, 31, v132
	v_mfma_f32_16x16x32_bf16 v[2:5], v[186:189], v[222:225], v[174:177]
	v_lshl_add_u64 v[134:135], s[26:27], 0, v[134:135]
	v_lshl_add_u64 v[168:169], v[132:133], 2, v[134:135]
	global_load_dwordx4 v[180:183], v[168:169], off
	global_load_dwordx4 v[184:187], v[168:169], off offset:64
	global_load_dwordx4 v[188:191], v[168:169], off offset:128
	global_load_dwordx4 v[192:195], v[168:169], off offset:192
	global_load_dwordx4 v[196:199], v[168:169], off offset:256
	global_load_dwordx4 v[200:203], v[168:169], off offset:320
	global_load_dwordx4 v[204:207], v[168:169], off offset:384
	global_load_dwordx4 v[208:211], v[168:169], off offset:448
	v_lshl_add_u64 v[178:179], v[140:141], 0, v[132:133]
	v_lshl_add_u64 v[244:245], v[140:141], 0, v[132:133]
	v_lshl_add_u64 v[244:245], v[244:245], 2, s[22:23]
	global_load_dwordx4 v[212:215], v[244:245], off nt
	global_load_dwordx4 v[216:219], v[244:245], off offset:64 nt
	global_load_dwordx4 v[220:223], v[244:245], off offset:128 nt
	global_load_dwordx4 v[224:227], v[244:245], off offset:192 nt
	global_load_dwordx4 v[228:231], v[244:245], off offset:256 nt
	global_load_dwordx4 v[232:235], v[244:245], off offset:320 nt
	global_load_dwordx4 v[236:239], v[244:245], off offset:384 nt
	global_load_dwordx4 v[240:243], v[244:245], off offset:448 nt
	s_nop 0
	v_add_f32_e32 v126, 0, v126
	v_add_f32_e32 v127, 0, v127
	v_add_f32_e32 v128, 0, v128
	v_add_f32_e32 v129, 0, v129
	s_waitcnt vmcnt(7)
	v_fma_f32 v126, v126, v180, v212
	v_fma_f32 v127, v127, v181, v213
	v_fma_f32 v128, v128, v182, v214
	v_fma_f32 v177, v129, v183, v215
	v_cvt_pk_bf16_f32 v126, v126, v127
	v_cvt_pk_bf16_f32 v127, v128, v177
	v_lshl_add_u64 v[174:175], v[140:141], 0, v[132:133]
	s_nop 0
	v_add_f32_e32 v122, 0, v122
	v_add_f32_e32 v123, 0, v123
	v_add_f32_e32 v124, 0, v124
	v_add_f32_e32 v125, 0, v125
	s_waitcnt vmcnt(6)
	v_fma_f32 v122, v122, v184, v216
	v_fma_f32 v123, v123, v185, v217
	v_fma_f32 v124, v124, v186, v218
	v_fma_f32 v173, v125, v187, v219
	v_cvt_pk_bf16_f32 v128, v122, v123
	v_cvt_pk_bf16_f32 v129, v124, v173
	v_lshl_add_u64 v[124:125], v[174:175], 1, s[20:21]
	s_nop 1
	v_permlane16_swap_b32 v126, v128
	v_permlane16_swap_b32 v127, v129
	v_lshl_add_u64 v[248:249], v[124:125], 0, v[246:247]
	s_nop 0
	global_store_dwordx4 v[248:249], v[126:129], off
	s_nop 1
	v_or_b32_e32 v122, 32, v132
	v_lshl_add_u64 v[170:171], v[140:141], 0, v[132:133]
	s_nop 0
	v_add_f32_e32 v118, 0, v118
	v_add_f32_e32 v119, 0, v119
	v_add_f32_e32 v120, 0, v120
	v_add_f32_e32 v121, 0, v121
	s_waitcnt vmcnt(6)
	v_fma_f32 v118, v118, v188, v220
	v_fma_f32 v119, v119, v189, v221
	v_fma_f32 v120, v120, v190, v222
	v_fma_f32 v129, v121, v191, v223
	v_cvt_pk_bf16_f32 v118, v118, v119
	v_cvt_pk_bf16_f32 v119, v120, v129
	v_lshl_add_u64 v[126:127], v[140:141], 0, v[132:133]
	s_nop 0
	v_add_f32_e32 v114, 0, v114
	v_add_f32_e32 v115, 0, v115
	v_add_f32_e32 v116, 0, v116
	v_add_f32_e32 v117, 0, v117
	s_waitcnt vmcnt(5)
	v_fma_f32 v114, v114, v192, v224
	v_fma_f32 v115, v115, v193, v225
	v_fma_f32 v116, v116, v194, v226
	v_fma_f32 v125, v117, v195, v227
	v_cvt_pk_bf16_f32 v120, v114, v115
	v_cvt_pk_bf16_f32 v121, v116, v125
	v_lshl_add_u64 v[116:117], v[126:127], 1, s[20:21]
	s_nop 1
	v_permlane16_swap_b32 v118, v120
	v_permlane16_swap_b32 v119, v121
	v_lshl_add_u64 v[248:249], v[116:117], 0, v[246:247]
	s_nop 0
	global_store_dwordx4 v[248:249], v[118:121], off offset:64
	s_nop 1
	v_or_b32_e32 v114, 64, v132
	v_lshl_add_u64 v[122:123], v[140:141], 0, v[132:133]
	s_nop 0
	v_add_f32_e32 v110, 0, v110
	v_add_f32_e32 v111, 0, v111
	v_add_f32_e32 v112, 0, v112
	v_add_f32_e32 v113, 0, v113
	s_waitcnt vmcnt(5)
	v_fma_f32 v110, v110, v196, v228
	v_fma_f32 v111, v111, v197, v229
	v_fma_f32 v112, v112, v198, v230
	v_fma_f32 v121, v113, v199, v231
	v_cvt_pk_bf16_f32 v110, v110, v111
	v_cvt_pk_bf16_f32 v111, v112, v121
	v_lshl_add_u64 v[118:119], v[140:141], 0, v[132:133]
	s_nop 0
	v_add_f32_e32 v106, 0, v106
	v_add_f32_e32 v107, 0, v107
	v_add_f32_e32 v108, 0, v108
	v_add_f32_e32 v109, 0, v109
	s_waitcnt vmcnt(4)
; __device__ __forceinline__ unsigned pack2(float a, float b) { unsigned r; asm("v_cvt_pk_bf16_f32 %0, %1, %2" : "=v"(r) : "v"(a), "v"(b)); return r; }
; __device__ __forceinline__ float bf2f(bf16_t h) { return __uint_as_float(((unsigned)h) << 16); }
;   __device__ __forceinline__ void c4(int g, int rig, int col, f32x4 v) const {
;     const size_t o = ((size_t)g * 2048 + rig) * 1024 + col;
;     f32x4 bs;
;     if (BASE_F32) bs = __builtin_nontemporal_load((const f32x4*)((const float*)base + o));
;     else {
;       const uint2 u = *(const uint2*)((const bf16_t*)base + o);
;       bs[0] = bf2f((bf16_t)(u.x & 0xffff)); bs[1] = bf2f((bf16_t)(u.x >> 16)); bs[2] = bf2f((bf16_t)(u.y & 0xffff)); bs[3] = bf2f((bf16_t)(u.y >> 16));
;     }
;     const f32x4 gt = *(const f32x4*)(gate + (size_t)g * 6144 + col);
;     f32x4 bi = {0.f, 0.f, 0.f, 0.f};
;     if (bias) bi = *(const f32x4*)(bias + col);
;     f32x4 r;
; #pragma unroll
;     for (int j = 0; j < 4; ++j) r[j] = bs[j] + gt[j] * (v[j] + bi[j]);
;     uint2 w; w.x = pack2(r[0], r[1]); w.y = pack2(r[2], r[3]);
;     *(uint2*)(X16 + o) = w;
; template <bool SWAP, class Epi, bool THIN = false> ...
;     ...
;     if constexpr (Epi::KIND == 0) {
; #pragma unroll
;       for (int m = 0; m < 4; ++m) {
;         const int rig = rig0 + rw + m * 16 + fr_e;
;         if constexpr (Epi::ROWSUM) {
;           float ss = 0.f;
; #pragma unroll
;           for (int n = 0; n < 8; ++n) {
;             const int col = nt * 256 + wc_e * 128 + n * 16 + fq_e * 4;
;             if (col < N) ss += epi.c4(g, rig, col, acc[m][n]);
;           }
;           ss += __shfl_xor(ss, 16); ss += __shfl_xor(ss, 32);
;           if (fq_e == 0) epi.rowsum(g, rig, nt * 2 + wc_e, ss);
;         } else {
; #pragma unroll
;           for (int n = 0; n < 8; ++n) {
;             const int col = nt * 256 + wc_e * 128 + n * 16 + fq_e * 4;
;             if (col < N) epi.c4(g, rig, col, acc[m][n]);
;           }
	v_fma_f32 v106, v106, v200, v232
	v_fma_f32 v107, v107, v201, v233
	v_fma_f32 v108, v108, v202, v234
	v_fma_f32 v117, v109, v203, v235
	v_cvt_pk_bf16_f32 v112, v106, v107
	v_cvt_pk_bf16_f32 v113, v108, v117
	v_lshl_add_u64 v[108:109], v[118:119], 1, s[20:21]
	s_nop 1
	v_permlane16_swap_b32 v110, v112
	v_permlane16_swap_b32 v111, v113
	v_lshl_add_u64 v[248:249], v[108:109], 0, v[246:247]
	s_nop 0
	global_store_dwordx4 v[248:249], v[110:113], off offset:128
	s_nop 1
	v_or_b32_e32 v106, 0x60, v132
	v_lshl_add_u64 v[114:115], v[140:141], 0, v[132:133]
	s_nop 0
	v_add_f32_e32 v102, 0, v102
	v_add_f32_e32 v103, 0, v103
	v_add_f32_e32 v104, 0, v104
	v_add_f32_e32 v105, 0, v105
	s_waitcnt vmcnt(4)
	v_fma_f32 v102, v102, v204, v236
	v_fma_f32 v103, v103, v205, v237
	v_fma_f32 v104, v104, v206, v238
	v_fma_f32 v113, v105, v207, v239
	v_cvt_pk_bf16_f32 v102, v102, v103
	v_cvt_pk_bf16_f32 v103, v104, v113
	v_lshl_add_u64 v[110:111], v[140:141], 0, v[132:133]
	s_nop 0
	v_add_f32_e32 v98, 0, v98
	v_add_f32_e32 v99, 0, v99
	v_add_f32_e32 v100, 0, v100
	v_add_f32_e32 v101, 0, v101
	s_waitcnt vmcnt(3)
	v_fma_f32 v98, v98, v208, v240
	v_fma_f32 v99, v99, v209, v241
	v_fma_f32 v100, v100, v210, v242
	v_fma_f32 v109, v101, v211, v243
	v_cvt_pk_bf16_f32 v104, v98, v99
	v_cvt_pk_bf16_f32 v105, v100, v109
	v_lshl_add_u64 v[100:101], v[110:111], 1, s[20:21]
	s_nop 1
	v_permlane16_swap_b32 v102, v104
	v_permlane16_swap_b32 v103, v105
	v_lshl_add_u64 v[248:249], v[100:101], 0, v[246:247]
	s_nop 0
	global_store_dwordx4 v[248:249], v[102:105], off offset:192
	s_nop 1
	v_or_b32_e32 v98, 16, v136
	v_ashrrev_i32_e32 v99, 31, v98
	v_lshlrev_b64 v[98:99], 10, v[98:99]
	v_lshl_add_u64 v[98:99], v[98:99], 0, v[138:139]
	v_lshl_add_u64 v[108:109], v[98:99], 0, v[132:133]
	v_lshl_add_u64 v[244:245], v[98:99], 0, v[132:133]
	v_lshl_add_u64 v[244:245], v[244:245], 2, s[22:23]
	global_load_dwordx4 v[212:215], v[244:245], off nt
	global_load_dwordx4 v[216:219], v[244:245], off offset:64 nt
	global_load_dwordx4 v[220:223], v[244:245], off offset:128 nt
	global_load_dwordx4 v[224:227], v[244:245], off offset:192 nt
	global_load_dwordx4 v[228:231], v[244:245], off offset:256 nt
	global_load_dwordx4 v[232:235], v[244:245], off offset:320 nt
	global_load_dwordx4 v[236:239], v[244:245], off offset:384 nt
	global_load_dwordx4 v[240:243], v[244:245], off offset:448 nt
	s_nop 0
	v_add_f32_e32 v94, 0, v94
	v_add_f32_e32 v95, 0, v95
	v_add_f32_e32 v96, 0, v96
	v_add_f32_e32 v97, 0, v97
	s_waitcnt vmcnt(7)
	v_fma_f32 v94, v94, v180, v212
	v_fma_f32 v95, v95, v181, v213
	v_fma_f32 v96, v96, v182, v214
	v_fma_f32 v107, v97, v183, v215
	v_cvt_pk_bf16_f32 v94, v94, v95
	v_cvt_pk_bf16_f32 v95, v96, v107
	v_lshl_add_u64 v[104:105], v[98:99], 0, v[132:133]
	s_nop 0
	v_add_f32_e32 v90, 0, v90
	v_add_f32_e32 v91, 0, v91
	v_add_f32_e32 v92, 0, v92
	v_add_f32_e32 v93, 0, v93
	s_waitcnt vmcnt(6)
	v_fma_f32 v90, v90, v184, v216
	v_fma_f32 v91, v91, v185, v217
	v_fma_f32 v92, v92, v186, v218
	v_fma_f32 v103, v93, v187, v219
	v_cvt_pk_bf16_f32 v96, v90, v91
	v_cvt_pk_bf16_f32 v97, v92, v103
	v_lshl_add_u64 v[92:93], v[104:105], 1, s[20:21]
	s_nop 1
	v_permlane16_swap_b32 v94, v96
	v_permlane16_swap_b32 v95, v97
	v_lshl_add_u64 v[248:249], v[92:93], 0, v[246:247]
	s_nop 0
	global_store_dwordx4 v[248:249], v[94:97], off
	s_nop 1
	v_lshl_add_u64 v[100:101], v[98:99], 0, v[132:133]
	s_nop 0
	v_add_f32_e32 v86, 0, v86
	v_add_f32_e32 v87, 0, v87
	v_add_f32_e32 v88, 0, v88
	v_add_f32_e32 v89, 0, v89
	s_waitcnt vmcnt(6)
	v_fma_f32 v86, v86, v188, v220
	v_fma_f32 v87, v87, v189, v221
	v_fma_f32 v88, v88, v190, v222
	v_fma_f32 v97, v89, v191, v223
	v_cvt_pk_bf16_f32 v86, v86, v87
	v_cvt_pk_bf16_f32 v87, v88, v97
	v_lshl_add_u64 v[94:95], v[98:99], 0, v[132:133]
	s_nop 0
	v_add_f32_e32 v82, 0, v82
	v_add_f32_e32 v83, 0, v83
	v_add_f32_e32 v84, 0, v84
	v_add_f32_e32 v85, 0, v85
	s_waitcnt vmcnt(5)
	v_fma_f32 v82, v82, v192, v224
	v_fma_f32 v83, v83, v193, v225
	v_fma_f32 v84, v84, v194, v226
	v_fma_f32 v93, v85, v195, v227
	v_cvt_pk_bf16_f32 v88, v82, v83
	v_cvt_pk_bf16_f32 v89, v84, v93
	v_lshl_add_u64 v[84:85], v[94:95], 1, s[20:21]
	s_nop 1
	v_permlane16_swap_b32 v86, v88
	v_permlane16_swap_b32 v87, v89
	v_lshl_add_u64 v[248:249], v[84:85], 0, v[246:247]
	s_nop 0
	global_store_dwordx4 v[248:249], v[86:89], off offset:64
	s_nop 1
	v_lshl_add_u64 v[90:91], v[98:99], 0, v[132:133]
	s_nop 0
	v_add_f32_e32 v78, 0, v78
	v_add_f32_e32 v79, 0, v79
	v_add_f32_e32 v80, 0, v80
	v_add_f32_e32 v81, 0, v81
	s_waitcnt vmcnt(5)
	v_fma_f32 v78, v78, v196, v228
	v_fma_f32 v79, v79, v197, v229
	v_fma_f32 v80, v80, v198, v230
	v_fma_f32 v89, v81, v199, v231
	v_cvt_pk_bf16_f32 v78, v78, v79
	v_cvt_pk_bf16_f32 v79, v80, v89
	v_lshl_add_u64 v[86:87], v[98:99], 0, v[132:133]
	s_nop 0
	v_add_f32_e32 v74, 0, v74
	v_add_f32_e32 v75, 0, v75
	v_add_f32_e32 v76, 0, v76
	v_add_f32_e32 v77, 0, v77
	s_waitcnt vmcnt(4)
	v_fma_f32 v74, v74, v200, v232
	v_fma_f32 v75, v75, v201, v233
	v_fma_f32 v76, v76, v202, v234
	v_fma_f32 v85, v77, v203, v235
	v_cvt_pk_bf16_f32 v80, v74, v75
	v_cvt_pk_bf16_f32 v81, v76, v85
	v_lshl_add_u64 v[76:77], v[86:87], 1, s[20:21]
	s_nop 1
	v_permlane16_swap_b32 v78, v80
	v_permlane16_swap_b32 v79, v81
	v_lshl_add_u64 v[248:249], v[76:77], 0, v[246:247]
	s_nop 0
	global_store_dwordx4 v[248:249], v[78:81], off offset:128
	s_nop 1
	v_lshl_add_u64 v[82:83], v[98:99], 0, v[132:133]
	v_add_f32_e32 v70, 0, v70
	v_add_f32_e32 v71, 0, v71
	v_add_f32_e32 v72, 0, v72
	v_add_f32_e32 v73, 0, v73
	s_waitcnt vmcnt(4)
; __device__ __forceinline__ unsigned pack2(float a, float b) { unsigned r; asm("v_cvt_pk_bf16_f32 %0, %1, %2" : "=v"(r) : "v"(a), "v"(b)); return r; }
; __device__ __forceinline__ float bf2f(bf16_t h) { return __uint_as_float(((unsigned)h) << 16); }
;   __device__ __forceinline__ void c4(int g, int rig, int col, f32x4 v) const {
;     const size_t o = ((size_t)g * 2048 + rig) * 1024 + col;
;     f32x4 bs;
;     if (BASE_F32) bs = __builtin_nontemporal_load((const f32x4*)((const float*)base + o));
;     else {
;       const uint2 u = *(const uint2*)((const bf16_t*)base + o);
;       bs[0] = bf2f((bf16_t)(u.x & 0xffff)); bs[1] = bf2f((bf16_t)(u.x >> 16)); bs[2] = bf2f((bf16_t)(u.y & 0xffff)); bs[3] = bf2f((bf16_t)(u.y >> 16));
;     }
;     const f32x4 gt = *(const f32x4*)(gate + (size_t)g * 6144 + col);
;     f32x4 bi = {0.f, 0.f, 0.f, 0.f};
;     if (bias) bi = *(const f32x4*)(bias + col);
;     f32x4 r;
; #pragma unroll
;     for (int j = 0; j < 4; ++j) r[j] = bs[j] + gt[j] * (v[j] + bi[j]);
;     uint2 w; w.x = pack2(r[0], r[1]); w.y = pack2(r[2], r[3]);
;     *(uint2*)(X16 + o) = w;
; template <bool SWAP, class Epi, bool THIN = false> ...
;     ...
;     if constexpr (Epi::KIND == 0) {
; #pragma unroll
;       for (int m = 0; m < 4; ++m) {
;         const int rig = rig0 + rw + m * 16 + fr_e;
;         if constexpr (Epi::ROWSUM) {
;           float ss = 0.f;
; #pragma unroll
;           for (int n = 0; n < 8; ++n) {
;             const int col = nt * 256 + wc_e * 128 + n * 16 + fq_e * 4;
;             if (col < N) ss += epi.c4(g, rig, col, acc[m][n]);
;           }
;           ss += __shfl_xor(ss, 16); ss += __shfl_xor(ss, 32);
;           if (fq_e == 0) epi.rowsum(g, rig, nt * 2 + wc_e, ss);
;         } else {
; #pragma unroll
;           for (int n = 0; n < 8; ++n) {
;             const int col = nt * 256 + wc_e * 128 + n * 16 + fq_e * 4;
;             if (col < N) epi.c4(g, rig, col, acc[m][n]);
;           }
	v_fma_f32 v70, v70, v204, v236
	v_fma_f32 v71, v71, v205, v237
	v_fma_f32 v72, v72, v206, v238
	v_fma_f32 v81, v73, v207, v239
	v_cvt_pk_bf16_f32 v70, v70, v71
	v_cvt_pk_bf16_f32 v71, v72, v81
	v_lshl_add_u64 v[78:79], v[98:99], 0, v[132:133]
	v_add_f32_e32 v66, 0, v66
	v_add_f32_e32 v67, 0, v67
	v_add_f32_e32 v68, 0, v68
	v_add_f32_e32 v69, 0, v69
	s_waitcnt vmcnt(3)
	v_fma_f32 v66, v66, v208, v240
	v_fma_f32 v67, v67, v209, v241
	v_fma_f32 v68, v68, v210, v242
	v_fma_f32 v77, v69, v211, v243
	v_cvt_pk_bf16_f32 v72, v66, v67
	v_cvt_pk_bf16_f32 v73, v68, v77
	v_lshl_add_u64 v[68:69], v[78:79], 1, s[20:21]
	s_nop 1
	v_permlane16_swap_b32 v70, v72
	v_permlane16_swap_b32 v71, v73
	v_lshl_add_u64 v[248:249], v[68:69], 0, v[246:247]
	s_nop 0
	global_store_dwordx4 v[248:249], v[70:73], off offset:192
	s_nop 1
	v_or_b32_e32 v66, 32, v136
	v_ashrrev_i32_e32 v67, 31, v66
	v_lshlrev_b64 v[66:67], 10, v[66:67]
	v_lshl_add_u64 v[66:67], v[66:67], 0, v[138:139]
	v_lshl_add_u64 v[76:77], v[66:67], 0, v[132:133]
	v_lshl_add_u64 v[244:245], v[66:67], 0, v[132:133]
	v_lshl_add_u64 v[244:245], v[244:245], 2, s[22:23]
	global_load_dwordx4 v[212:215], v[244:245], off nt
	global_load_dwordx4 v[216:219], v[244:245], off offset:64 nt
	global_load_dwordx4 v[220:223], v[244:245], off offset:128 nt
	global_load_dwordx4 v[224:227], v[244:245], off offset:192 nt
	global_load_dwordx4 v[228:231], v[244:245], off offset:256 nt
	global_load_dwordx4 v[232:235], v[244:245], off offset:320 nt
	global_load_dwordx4 v[236:239], v[244:245], off offset:384 nt
	global_load_dwordx4 v[240:243], v[244:245], off offset:448 nt
	v_add_f32_e32 v62, 0, v62
	v_add_f32_e32 v63, 0, v63
	v_add_f32_e32 v64, 0, v64
	v_add_f32_e32 v65, 0, v65
	s_waitcnt vmcnt(7)
	v_fma_f32 v62, v62, v180, v212
	v_fma_f32 v63, v63, v181, v213
	v_fma_f32 v64, v64, v182, v214
	v_fma_f32 v75, v65, v183, v215
	v_cvt_pk_bf16_f32 v62, v62, v63
	v_cvt_pk_bf16_f32 v63, v64, v75
	v_lshl_add_u64 v[72:73], v[66:67], 0, v[132:133]
	v_add_f32_e32 v58, 0, v58
	v_add_f32_e32 v59, 0, v59
	v_add_f32_e32 v60, 0, v60
	v_add_f32_e32 v61, 0, v61
	s_waitcnt vmcnt(6)
	v_fma_f32 v58, v58, v184, v216
	v_fma_f32 v59, v59, v185, v217
	v_fma_f32 v60, v60, v186, v218
	v_fma_f32 v71, v61, v187, v219
	v_cvt_pk_bf16_f32 v64, v58, v59
	v_cvt_pk_bf16_f32 v65, v60, v71
	v_lshl_add_u64 v[60:61], v[72:73], 1, s[20:21]
	s_nop 1
	v_permlane16_swap_b32 v62, v64
	v_permlane16_swap_b32 v63, v65
	v_lshl_add_u64 v[248:249], v[60:61], 0, v[246:247]
	s_nop 0
	global_store_dwordx4 v[248:249], v[62:65], off
	s_nop 1
	v_lshl_add_u64 v[68:69], v[66:67], 0, v[132:133]
	v_add_f32_e32 v54, 0, v54
	v_add_f32_e32 v55, 0, v55
	v_add_f32_e32 v56, 0, v56
	v_add_f32_e32 v57, 0, v57
	s_waitcnt vmcnt(6)
	v_fma_f32 v54, v54, v188, v220
	v_fma_f32 v55, v55, v189, v221
	v_fma_f32 v56, v56, v190, v222
	v_fma_f32 v65, v57, v191, v223
	v_cvt_pk_bf16_f32 v54, v54, v55
	v_cvt_pk_bf16_f32 v55, v56, v65
	v_lshl_add_u64 v[62:63], v[66:67], 0, v[132:133]
	v_add_f32_e32 v50, 0, v50
	v_add_f32_e32 v51, 0, v51
	v_add_f32_e32 v52, 0, v52
	v_add_f32_e32 v53, 0, v53
	s_waitcnt vmcnt(5)
	v_fma_f32 v50, v50, v192, v224
	v_fma_f32 v51, v51, v193, v225
	v_fma_f32 v52, v52, v194, v226
	v_fma_f32 v61, v53, v195, v227
	v_cvt_pk_bf16_f32 v56, v50, v51
	v_cvt_pk_bf16_f32 v57, v52, v61
	v_lshl_add_u64 v[52:53], v[62:63], 1, s[20:21]
	s_nop 1
	v_permlane16_swap_b32 v54, v56
	v_permlane16_swap_b32 v55, v57
	v_lshl_add_u64 v[248:249], v[52:53], 0, v[246:247]
	s_nop 0
	global_store_dwordx4 v[248:249], v[54:57], off offset:64
	s_nop 1
	v_lshl_add_u64 v[58:59], v[66:67], 0, v[132:133]
	v_add_f32_e32 v46, 0, v46
	v_add_f32_e32 v47, 0, v47
	v_add_f32_e32 v48, 0, v48
	v_add_f32_e32 v49, 0, v49
	s_waitcnt vmcnt(5)
	v_fma_f32 v46, v46, v196, v228
	v_fma_f32 v47, v47, v197, v229
	v_fma_f32 v48, v48, v198, v230
	v_fma_f32 v57, v49, v199, v231
	v_cvt_pk_bf16_f32 v46, v46, v47
	v_cvt_pk_bf16_f32 v47, v48, v57
	v_lshl_add_u64 v[54:55], v[66:67], 0, v[132:133]
	v_add_f32_e32 v42, 0, v42
	v_add_f32_e32 v43, 0, v43
	v_add_f32_e32 v44, 0, v44
	v_add_f32_e32 v45, 0, v45
	s_waitcnt vmcnt(4)
	v_fma_f32 v42, v42, v200, v232
	v_fma_f32 v43, v43, v201, v233
	v_fma_f32 v44, v44, v202, v234
	v_fma_f32 v53, v45, v203, v235
	v_cvt_pk_bf16_f32 v48, v42, v43
	v_cvt_pk_bf16_f32 v49, v44, v53
	v_lshl_add_u64 v[44:45], v[54:55], 1, s[20:21]
	s_nop 1
	v_permlane16_swap_b32 v46, v48
	v_permlane16_swap_b32 v47, v49
	v_lshl_add_u64 v[248:249], v[44:45], 0, v[246:247]
	s_nop 0
	global_store_dwordx4 v[248:249], v[46:49], off offset:128
	s_nop 1
	v_lshl_add_u64 v[50:51], v[66:67], 0, v[132:133]
	v_add_f32_e32 v38, 0, v38
	v_add_f32_e32 v39, 0, v39
	v_add_f32_e32 v40, 0, v40
	v_add_f32_e32 v41, 0, v41
	s_waitcnt vmcnt(4)
	v_fma_f32 v38, v38, v204, v236
	v_fma_f32 v39, v39, v205, v237
	v_fma_f32 v40, v40, v206, v238
	v_fma_f32 v49, v41, v207, v239
	v_cvt_pk_bf16_f32 v38, v38, v39
	v_cvt_pk_bf16_f32 v39, v40, v49
	v_lshl_add_u64 v[46:47], v[66:67], 0, v[132:133]
	v_add_f32_e32 v34, 0, v34
	v_add_f32_e32 v35, 0, v35
	v_add_f32_e32 v36, 0, v36
	v_add_f32_e32 v37, 0, v37
	s_waitcnt vmcnt(3)
; __device__ __forceinline__ unsigned pack2(float a, float b) { unsigned r; asm("v_cvt_pk_bf16_f32 %0, %1, %2" : "=v"(r) : "v"(a), "v"(b)); return r; }
; __device__ __forceinline__ float bf2f(bf16_t h) { return __uint_as_float(((unsigned)h) << 16); }
;   __device__ __forceinline__ void c4(int g, int rig, int col, f32x4 v) const {
;     const size_t o = ((size_t)g * 2048 + rig) * 1024 + col;
;     f32x4 bs;
;     if (BASE_F32) bs = __builtin_nontemporal_load((const f32x4*)((const float*)base + o));
;     else {
;       const uint2 u = *(const uint2*)((const bf16_t*)base + o);
;       bs[0] = bf2f((bf16_t)(u.x & 0xffff)); bs[1] = bf2f((bf16_t)(u.x >> 16)); bs[2] = bf2f((bf16_t)(u.y & 0xffff)); bs[3] = bf2f((bf16_t)(u.y >> 16));
;     }
;     const f32x4 gt = *(const f32x4*)(gate + (size_t)g * 6144 + col);
;     f32x4 bi = {0.f, 0.f, 0.f, 0.f};
;     if (bias) bi = *(const f32x4*)(bias + col);
;     f32x4 r;
; #pragma unroll
;     for (int j = 0; j < 4; ++j) r[j] = bs[j] + gt[j] * (v[j] + bi[j]);
;     uint2 w; w.x = pack2(r[0], r[1]); w.y = pack2(r[2], r[3]);
;     *(uint2*)(X16 + o) = w;
; template <bool SWAP, class Epi, bool THIN = false> ...
;     ...
;     if constexpr (Epi::KIND == 0) {
; #pragma unroll
;       for (int m = 0; m < 4; ++m) {
;         const int rig = rig0 + rw + m * 16 + fr_e;
;         if constexpr (Epi::ROWSUM) {
;           float ss = 0.f;
; #pragma unroll
;           for (int n = 0; n < 8; ++n) {
;             const int col = nt * 256 + wc_e * 128 + n * 16 + fq_e * 4;
;             if (col < N) ss += epi.c4(g, rig, col, acc[m][n]);
;           }
;           ss += __shfl_xor(ss, 16); ss += __shfl_xor(ss, 32);
;           if (fq_e == 0) epi.rowsum(g, rig, nt * 2 + wc_e, ss);
;         } else {
; #pragma unroll
;           for (int n = 0; n < 8; ++n) {
;             const int col = nt * 256 + wc_e * 128 + n * 16 + fq_e * 4;
;             if (col < N) epi.c4(g, rig, col, acc[m][n]);
;           }
	v_fma_f32 v34, v34, v208, v240
	v_fma_f32 v35, v35, v209, v241
	v_fma_f32 v36, v36, v210, v242
	v_fma_f32 v45, v37, v211, v243
	v_cvt_pk_bf16_f32 v40, v34, v35
	v_cvt_pk_bf16_f32 v41, v36, v45
	v_lshl_add_u64 v[36:37], v[46:47], 1, s[20:21]
	s_nop 1
	v_permlane16_swap_b32 v38, v40
	v_permlane16_swap_b32 v39, v41
	v_lshl_add_u64 v[248:249], v[36:37], 0, v[246:247]
	s_nop 0
	global_store_dwordx4 v[248:249], v[38:41], off offset:192
	s_nop 1
	v_or_b32_e32 v34, 48, v136
	v_ashrrev_i32_e32 v35, 31, v34
	v_lshlrev_b64 v[34:35], 10, v[34:35]
	v_lshl_add_u64 v[34:35], v[34:35], 0, v[138:139]
	v_lshl_add_u64 v[44:45], v[34:35], 0, v[132:133]
	v_lshl_add_u64 v[244:245], v[34:35], 0, v[132:133]
	v_lshl_add_u64 v[244:245], v[244:245], 2, s[22:23]
	global_load_dwordx4 v[212:215], v[244:245], off nt
	global_load_dwordx4 v[216:219], v[244:245], off offset:64 nt
	global_load_dwordx4 v[220:223], v[244:245], off offset:128 nt
	global_load_dwordx4 v[224:227], v[244:245], off offset:192 nt
	global_load_dwordx4 v[228:231], v[244:245], off offset:256 nt
	global_load_dwordx4 v[232:235], v[244:245], off offset:320 nt
	global_load_dwordx4 v[236:239], v[244:245], off offset:384 nt
	global_load_dwordx4 v[240:243], v[244:245], off offset:448 nt
	v_add_f32_e32 v30, 0, v30
	v_add_f32_e32 v31, 0, v31
	v_add_f32_e32 v32, 0, v32
	v_add_f32_e32 v33, 0, v33
	s_waitcnt vmcnt(7)
	v_fma_f32 v30, v30, v180, v212
	v_fma_f32 v31, v31, v181, v213
	v_fma_f32 v32, v32, v182, v214
	v_fma_f32 v43, v33, v183, v215
	v_cvt_pk_bf16_f32 v30, v30, v31
	v_cvt_pk_bf16_f32 v31, v32, v43
	v_lshl_add_u64 v[40:41], v[34:35], 0, v[132:133]
	v_add_f32_e32 v26, 0, v26
	v_add_f32_e32 v27, 0, v27
	v_add_f32_e32 v28, 0, v28
	v_add_f32_e32 v29, 0, v29
	s_waitcnt vmcnt(6)
	v_fma_f32 v26, v26, v184, v216
	v_fma_f32 v27, v27, v185, v217
	v_fma_f32 v28, v28, v186, v218
	v_fma_f32 v39, v29, v187, v219
	v_cvt_pk_bf16_f32 v32, v26, v27
	v_cvt_pk_bf16_f32 v33, v28, v39
	v_lshl_add_u64 v[28:29], v[40:41], 1, s[20:21]
	s_nop 1
	v_permlane16_swap_b32 v30, v32
	v_permlane16_swap_b32 v31, v33
	v_lshl_add_u64 v[248:249], v[28:29], 0, v[246:247]
	s_nop 0
	global_store_dwordx4 v[248:249], v[30:33], off
	s_nop 1
	v_lshl_add_u64 v[36:37], v[34:35], 0, v[132:133]
	v_add_f32_e32 v22, 0, v22
	v_add_f32_e32 v23, 0, v23
	v_add_f32_e32 v24, 0, v24
	v_add_f32_e32 v25, 0, v25
	s_waitcnt vmcnt(6)
	v_fma_f32 v22, v22, v188, v220
	v_fma_f32 v23, v23, v189, v221
	v_fma_f32 v24, v24, v190, v222
	v_fma_f32 v33, v25, v191, v223
	v_cvt_pk_bf16_f32 v22, v22, v23
	v_cvt_pk_bf16_f32 v23, v24, v33
	v_lshl_add_u64 v[30:31], v[34:35], 0, v[132:133]
	v_add_f32_e32 v18, 0, v18
	v_add_f32_e32 v19, 0, v19
	v_add_f32_e32 v20, 0, v20
	v_add_f32_e32 v21, 0, v21
	s_waitcnt vmcnt(5)
	v_fma_f32 v18, v18, v192, v224
	v_fma_f32 v19, v19, v193, v225
	v_fma_f32 v20, v20, v194, v226
	v_fma_f32 v29, v21, v195, v227
	v_cvt_pk_bf16_f32 v24, v18, v19
	v_cvt_pk_bf16_f32 v25, v20, v29
	v_lshl_add_u64 v[20:21], v[30:31], 1, s[20:21]
	s_nop 1
	v_permlane16_swap_b32 v22, v24
	v_permlane16_swap_b32 v23, v25
	v_lshl_add_u64 v[248:249], v[20:21], 0, v[246:247]
	s_nop 0
	global_store_dwordx4 v[248:249], v[22:25], off offset:64
	s_nop 1
	v_lshl_add_u64 v[26:27], v[34:35], 0, v[132:133]
	v_add_f32_e32 v14, 0, v14
	v_add_f32_e32 v15, 0, v15
	v_add_f32_e32 v16, 0, v16
	v_add_f32_e32 v17, 0, v17
	s_waitcnt vmcnt(5)
	v_fma_f32 v14, v14, v196, v228
	v_fma_f32 v15, v15, v197, v229
	v_fma_f32 v16, v16, v198, v230
	v_fma_f32 v25, v17, v199, v231
	v_cvt_pk_bf16_f32 v14, v14, v15
	v_cvt_pk_bf16_f32 v15, v16, v25
	v_lshl_add_u64 v[22:23], v[34:35], 0, v[132:133]
	v_add_f32_e32 v6, 0, v6
	v_add_f32_e32 v7, 0, v7
	v_add_f32_e32 v8, 0, v8
	v_add_f32_e32 v9, 0, v9
	s_waitcnt vmcnt(4)
	v_fma_f32 v6, v6, v200, v232
	v_fma_f32 v7, v7, v201, v233
	v_fma_f32 v8, v8, v202, v234
	v_fma_f32 v21, v9, v203, v235
	v_cvt_pk_bf16_f32 v16, v6, v7
	v_cvt_pk_bf16_f32 v17, v8, v21
	v_lshl_add_u64 v[8:9], v[22:23], 1, s[20:21]
	s_nop 1
	v_permlane16_swap_b32 v14, v16
	v_permlane16_swap_b32 v15, v17
	v_lshl_add_u64 v[248:249], v[8:9], 0, v[246:247]
	s_nop 0
	global_store_dwordx4 v[248:249], v[14:17], off offset:128
	s_nop 1
	v_lshl_add_u64 v[18:19], v[34:35], 0, v[132:133]
	v_add_f32_e32 v10, 0, v10
	v_add_f32_e32 v11, 0, v11
	v_add_f32_e32 v12, 0, v12
	v_add_f32_e32 v13, 0, v13
	s_waitcnt vmcnt(4)
	v_fma_f32 v6, v10, v204, v236
	v_fma_f32 v7, v11, v205, v237
	v_fma_f32 v8, v12, v206, v238
	v_fma_f32 v17, v13, v207, v239
	v_cvt_pk_bf16_f32 v6, v6, v7
	v_cvt_pk_bf16_f32 v7, v8, v17
	v_lshl_add_u64 v[14:15], v[34:35], 0, v[132:133]
	v_add_f32_e32 v2, 0, v2
	v_add_f32_e32 v3, 0, v3
	v_add_f32_e32 v4, 0, v4
	v_add_f32_e32 v5, 0, v5
	s_waitcnt vmcnt(3)
	v_fma_f32 v2, v2, v208, v240
	v_fma_f32 v3, v3, v209, v241
	v_fma_f32 v4, v4, v210, v242
	v_fma_f32 v13, v5, v211, v243
	v_cvt_pk_bf16_f32 v8, v2, v3
	v_cvt_pk_bf16_f32 v9, v4, v13
	v_lshl_add_u64 v[4:5], v[14:15], 1, s[20:21]
	s_nop 1
	v_permlane16_swap_b32 v6, v8
	v_permlane16_swap_b32 v7, v9
	v_lshl_add_u64 v[248:249], v[4:5], 0, v[246:247]
	s_nop 0
	global_store_dwordx4 v[248:249], v[6:9], off offset:192
	s_nop 1
	s_branch .LBB0_2114

; template <bool SWAP, class Epi, bool THIN = false> ...
;     ...
;     for (int st = 0; st < ns; ++st) {
;       asm volatile("s_waitcnt vmcnt(0)" ::: "memory");
;       __builtin_amdgcn_s_barrier();
;       asm volatile("" ::: "memory");
;       if (st + 1 < ns) {
;         char* nb = smem + ((st + 1) & 1) * 65536;
;         const int ko = (st + 1) * 64;
; #pragma unroll
;         for (int i = 0; i < 4; ++i) { GLDS16(A + (size_t)(ap[i] + ko), nb + tid * 16 + i * 8192); GLDS16(Bt + (size_t)(bp[i] + ko), nb + 32768 + tid * 16 + i * 8192); }
;       }
;       const char* sa = smem + (st & 1) * 65536 + (wr * 64 + fr) * 128;
;       const char* sb = smem + (st & 1) * 65536 + 32768 + (wc * 128 + fr) * 128;
;       if constexpr (THIN) {
;         if (wc == 0) {
; #pragma unroll
;           for (int ks = 0; ks < 2; ++ks) {
;             bf16x8 af[4], bf[2];
; #pragma unroll
;             for (int m = 0; m < 4; ++m) af[m] = *(const bf16x8*)(sa + m * 2048 + (((ks * 4 + fq) ^ swz) << 4));
; #pragma unroll
;             for (int n = 0; n < 2; ++n) bf[n] = *(const bf16x8*)(sb + n * 2048 + (((ks * 4 + fq) ^ swz) << 4));
; #pragma unroll
;             for (int m = 0; m < 4; ++m)
; #pragma unroll
;               for (int n = 0; n < 2; ++n)
;                 acc[m][n] = SWAP ? __builtin_amdgcn_mfma_f32_16x16x32_bf16(bf[n], af[m], acc[m][n], 0, 0, 0)
;                                  : __builtin_amdgcn_mfma_f32_16x16x32_bf16(af[m], bf[n], acc[m][n], 0, 0, 0);
;           }
;         }
;       } else {
;       bf16x8 afA[4], afB[4], bfb[2][2];
; #pragma unroll
;       for (int m = 0; m < 4; ++m) afA[m] = *(const bf16x8*)(sa + m * 2048 + ((fq ^ swz) << 4));
; #pragma unroll
;       for (int n = 0; n < 2; ++n) bfb[0][n] = *(const bf16x8*)(sb + n * 2048 + ((fq ^ swz) << 4));
; #pragma unroll
;       for (int gq = 0; gq < 8; ++gq) {
;         const int ks = gq >> 2, nh = gq & 3;
;         if (gq < 7) {
;           const int ks2 = (gq + 1) >> 2, nh2 = (gq + 1) & 3;
; #pragma unroll
;           for (int n = 0; n < 2; ++n) bfb[(gq + 1) & 1][n] = *(const bf16x8*)(sb + (nh2 * 2 + n) * 2048 + (((ks2 * 4 + fq) ^ swz) << 4));
;         }
;         if (gq == 3) {
; #pragma unroll
;           for (int m = 0; m < 4; ++m) afB[m] = *(const bf16x8*)(sa + m * 2048 + (((4 + fq) ^ swz) << 4));
;         }
;         __builtin_amdgcn_sched_barrier(0);
; #pragma unroll
.LBB0_2334:
	s_add_i32 s8, s7, 0x10000
	s_and_b32 s9, s8, 0x10000
	v_add_u32_e32 v170, s9, v135
	s_nop 0
	v_readfirstlane_b32 s9, v170
	s_and_b32 s7, s7, 0x10000
	v_or_b32_e32 v204, s7, v139
	v_add_u32_e32 v205, v204, v140
	v_add_u32_e32 v136, s7, v138
	v_add_u32_e32 v180, v136, v140
	s_waitcnt vmcnt(0)
	s_barrier
	ds_read_b128 v[168:171], v180
	ds_read_b128 v[172:175], v180 offset:2048
	ds_read_b128 v[176:179], v180 offset:4096
	ds_read_b128 v[180:183], v180 offset:6144
	ds_read_b128 v[184:187], v205 offset:32768
	ds_read_b128 v[188:191], v205 offset:34816
	ds_read_b128 v[192:195], v205 offset:36864
	ds_read_b128 v[196:199], v205 offset:38912
	v_add_u32_e32 v136, v136, v141
	s_waitcnt lgkmcnt(3)
	v_mfma_f32_16x16x32_bf16 v[126:129], v[184:187], v[168:171], v[126:129]
	s_mov_b32 m0, s9
	v_mfma_f32_16x16x32_bf16 v[110:113], v[184:187], v[172:175], v[110:113]
	global_load_lds_dwordx4 v167, s[16:17]
	v_add_u32_e32 v167, 0x80, v167
	v_mfma_f32_16x16x32_bf16 v[82:85], v[184:187], v[176:179], v[82:85]
	v_mfma_f32_16x16x32_bf16 v[50:53], v[184:187], v[180:183], v[50:53]
	ds_read_b128 v[184:187], v205 offset:40960
	ds_read_b128 v[200:203], v205 offset:43008
	s_waitcnt lgkmcnt(4)
	v_mfma_f32_16x16x32_bf16 v[122:125], v[188:191], v[168:171], v[122:125]
	s_add_u32 m0, s9, 0x8000
	v_mfma_f32_16x16x32_bf16 v[106:109], v[188:191], v[172:175], v[106:109]
	global_load_lds_dwordx4 v166, s[18:19]
	v_add_u32_e32 v166, 0x80, v166
	v_mfma_f32_16x16x32_bf16 v[78:81], v[188:191], v[176:179], v[78:81]
	v_mfma_f32_16x16x32_bf16 v[42:45], v[188:191], v[180:183], v[42:45]
	s_waitcnt lgkmcnt(3)
	v_mfma_f32_16x16x32_bf16 v[118:121], v[192:195], v[168:171], v[118:121]
	s_add_u32 m0, s9, 0x2000
	v_mfma_f32_16x16x32_bf16 v[94:97], v[192:195], v[172:175], v[94:97]
	global_load_lds_dwordx4 v165, s[16:17]
	v_add_u32_e32 v165, 0x80, v165
	v_mfma_f32_16x16x32_bf16 v[58:61], v[192:195], v[176:179], v[58:61]
	v_mfma_f32_16x16x32_bf16 v[26:29], v[192:195], v[180:183], v[26:29]
	ds_read_b128 v[188:191], v205 offset:45056
	ds_read_b128 v[192:195], v205 offset:47104
	s_waitcnt lgkmcnt(4)
	v_mfma_f32_16x16x32_bf16 v[114:117], v[196:199], v[168:171], v[114:117]
	s_add_u32 m0, s9, 0xa000
	v_mfma_f32_16x16x32_bf16 v[90:93], v[196:199], v[172:175], v[90:93]
	global_load_lds_dwordx4 v164, s[18:19]
	v_add_u32_e32 v164, 0x80, v164
	v_mfma_f32_16x16x32_bf16 v[54:57], v[196:199], v[176:179], v[54:57]
	v_mfma_f32_16x16x32_bf16 v[22:25], v[196:199], v[180:183], v[22:25]
	v_add_u32_e32 v220, v204, v141
	s_waitcnt lgkmcnt(3)
	v_mfma_f32_16x16x32_bf16 v[102:105], v[184:187], v[168:171], v[102:105]
	ds_read_b128 v[196:199], v220 offset:32768
	ds_read_b128 v[204:207], v220 offset:34816
	s_add_u32 m0, s9, 0x4000
	v_mfma_f32_16x16x32_bf16 v[74:77], v[184:187], v[172:175], v[74:77]
	global_load_lds_dwordx4 v163, s[16:17]
	v_add_u32_e32 v163, 0x80, v163
	v_mfma_f32_16x16x32_bf16 v[46:49], v[184:187], v[176:179], v[46:49]
	v_mfma_f32_16x16x32_bf16 v[10:13], v[184:187], v[180:183], v[10:13]
	ds_read_b128 v[184:187], v136
	ds_read_b128 v[208:211], v136 offset:2048
	ds_read_b128 v[212:215], v136 offset:4096
	ds_read_b128 v[216:219], v136 offset:6144
	s_waitcnt lgkmcnt(8)
	v_mfma_f32_16x16x32_bf16 v[98:101], v[200:203], v[168:171], v[98:101]
	s_add_u32 m0, s9, 0xc000
	v_mfma_f32_16x16x32_bf16 v[66:69], v[200:203], v[172:175], v[66:69]
	global_load_lds_dwordx4 v162, s[18:19]
	v_add_u32_e32 v162, 0x80, v162
	v_mfma_f32_16x16x32_bf16 v[30:33], v[200:203], v[176:179], v[30:33]
	v_mfma_f32_16x16x32_bf16 v[6:9], v[200:203], v[180:183], v[6:9]
	s_waitcnt lgkmcnt(7)
	v_mfma_f32_16x16x32_bf16 v[70:73], v[188:191], v[168:171], v[70:73]
	s_add_u32 m0, s9, 0x6000
	s_waitcnt lgkmcnt(6)
	v_mfma_f32_16x16x32_bf16 v[62:65], v[192:195], v[168:171], v[62:65]
	global_load_lds_dwordx4 v161, s[16:17]
	v_add_u32_e32 v161, 0x80, v161
	v_mfma_f32_16x16x32_bf16 v[38:41], v[188:191], v[172:175], v[38:41]
	v_mfma_f32_16x16x32_bf16 v[34:37], v[192:195], v[172:175], v[34:37]
	ds_read_b128 v[168:171], v220 offset:36864
	ds_read_b128 v[172:175], v220 offset:38912
	v_mfma_f32_16x16x32_bf16 v[18:21], v[188:191], v[176:179], v[18:21]
	s_add_u32 m0, s9, 0xe000
	v_mfma_f32_16x16x32_bf16 v[14:17], v[192:195], v[176:179], v[14:17]
	global_load_lds_dwordx4 v160, s[18:19]
	v_add_u32_e32 v160, 0x80, v160
	v_mfma_f32_16x16x32_bf16 v[2:5], v[188:191], v[180:183], v[2:5]
	v_mfma_f32_16x16x32_bf16 v[86:89], v[192:195], v[180:183], v[86:89]
	ds_read_b128 v[176:179], v220 offset:40960
	ds_read_b128 v[180:183], v220 offset:43008
	s_waitcnt lgkmcnt(7)
	v_mfma_f32_16x16x32_bf16 v[126:129], v[196:199], v[184:187], v[126:129]
	v_mfma_f32_16x16x32_bf16 v[122:125], v[204:207], v[184:187], v[122:125]
	s_waitcnt lgkmcnt(6)
	v_mfma_f32_16x16x32_bf16 v[110:113], v[196:199], v[208:211], v[110:113]
	v_mfma_f32_16x16x32_bf16 v[106:109], v[204:207], v[208:211], v[106:109]
	s_waitcnt lgkmcnt(5)
	v_mfma_f32_16x16x32_bf16 v[82:85], v[196:199], v[212:215], v[82:85]
	v_mfma_f32_16x16x32_bf16 v[78:81], v[204:207], v[212:215], v[78:81]
	s_waitcnt lgkmcnt(4)
	v_mfma_f32_16x16x32_bf16 v[50:53], v[196:199], v[216:219], v[50:53]
	v_mfma_f32_16x16x32_bf16 v[42:45], v[204:207], v[216:219], v[42:45]
	s_waitcnt lgkmcnt(3)
	v_mfma_f32_16x16x32_bf16 v[118:121], v[168:171], v[184:187], v[118:121]
	v_mfma_f32_16x16x32_bf16 v[94:97], v[168:171], v[208:211], v[94:97]
	v_mfma_f32_16x16x32_bf16 v[58:61], v[168:171], v[212:215], v[58:61]
	v_mfma_f32_16x16x32_bf16 v[26:29], v[168:171], v[216:219], v[26:29]
	ds_read_b128 v[168:171], v220 offset:45056
	ds_read_b128 v[188:191], v220 offset:47104
	s_waitcnt lgkmcnt(4)
; template <bool SWAP, class Epi, bool THIN = false> ...
;     ...
;     for (int st = 0; st < ns; ++st) {
;       asm volatile("s_waitcnt vmcnt(0)" ::: "memory");
;       __builtin_amdgcn_s_barrier();
;       asm volatile("" ::: "memory");
;       if (st + 1 < ns) {
;         char* nb = smem + ((st + 1) & 1) * 65536;
;         const int ko = (st + 1) * 64;
; #pragma unroll
;         for (int i = 0; i < 4; ++i) { GLDS16(A + (size_t)(ap[i] + ko), nb + tid * 16 + i * 8192); GLDS16(Bt + (size_t)(bp[i] + ko), nb + 32768 + tid * 16 + i * 8192); }
;       }
;       const char* sa = smem + (st & 1) * 65536 + (wr * 64 + fr) * 128;
;       const char* sb = smem + (st & 1) * 65536 + 32768 + (wc * 128 + fr) * 128;
;       if constexpr (THIN) {
;         if (wc == 0) {
; #pragma unroll
;           for (int ks = 0; ks < 2; ++ks) {
;             bf16x8 af[4], bf[2];
; #pragma unroll
;             for (int m = 0; m < 4; ++m) af[m] = *(const bf16x8*)(sa + m * 2048 + (((ks * 4 + fq) ^ swz) << 4));
; #pragma unroll
;             for (int n = 0; n < 2; ++n) bf[n] = *(const bf16x8*)(sb + n * 2048 + (((ks * 4 + fq) ^ swz) << 4));
; #pragma unroll
;             for (int m = 0; m < 4; ++m)
; #pragma unroll
;               for (int n = 0; n < 2; ++n)
;                 acc[m][n] = SWAP ? __builtin_amdgcn_mfma_f32_16x16x32_bf16(bf[n], af[m], acc[m][n], 0, 0, 0)
;                                  : __builtin_amdgcn_mfma_f32_16x16x32_bf16(af[m], bf[n], acc[m][n], 0, 0, 0);
;           }
;         }
;       } else {
;       bf16x8 afA[4], afB[4], bfb[2][2];
; #pragma unroll
;       for (int m = 0; m < 4; ++m) afA[m] = *(const bf16x8*)(sa + m * 2048 + ((fq ^ swz) << 4));
; #pragma unroll
;       for (int n = 0; n < 2; ++n) bfb[0][n] = *(const bf16x8*)(sb + n * 2048 + ((fq ^ swz) << 4));
; #pragma unroll
;       for (int gq = 0; gq < 8; ++gq) {
;         const int ks = gq >> 2, nh = gq & 3;
;         if (gq < 7) {
;           const int ks2 = (gq + 1) >> 2, nh2 = (gq + 1) & 3;
; #pragma unroll
;           for (int n = 0; n < 2; ++n) bfb[(gq + 1) & 1][n] = *(const bf16x8*)(sb + (nh2 * 2 + n) * 2048 + (((ks2 * 4 + fq) ^ swz) << 4));
;         }
;         if (gq == 3) {
; #pragma unroll
;           for (int m = 0; m < 4; ++m) afB[m] = *(const bf16x8*)(sa + m * 2048 + (((4 + fq) ^ swz) << 4));
;         }
;         __builtin_amdgcn_sched_barrier(0);
; #pragma unroll
	v_mfma_f32_16x16x32_bf16 v[114:117], v[172:175], v[184:187], v[114:117]
	v_mfma_f32_16x16x32_bf16 v[90:93], v[172:175], v[208:211], v[90:93]
	v_mfma_f32_16x16x32_bf16 v[54:57], v[172:175], v[212:215], v[54:57]
	v_mfma_f32_16x16x32_bf16 v[22:25], v[172:175], v[216:219], v[22:25]
	s_waitcnt lgkmcnt(3)
	v_mfma_f32_16x16x32_bf16 v[102:105], v[176:179], v[184:187], v[102:105]
	s_waitcnt lgkmcnt(2)
	v_mfma_f32_16x16x32_bf16 v[98:101], v[180:183], v[184:187], v[98:101]
	v_mfma_f32_16x16x32_bf16 v[74:77], v[176:179], v[208:211], v[74:77]
	v_mfma_f32_16x16x32_bf16 v[66:69], v[180:183], v[208:211], v[66:69]
	v_mfma_f32_16x16x32_bf16 v[46:49], v[176:179], v[212:215], v[46:49]
	v_mfma_f32_16x16x32_bf16 v[30:33], v[180:183], v[212:215], v[30:33]
	v_mfma_f32_16x16x32_bf16 v[10:13], v[176:179], v[216:219], v[10:13]
	v_mfma_f32_16x16x32_bf16 v[6:9], v[180:183], v[216:219], v[6:9]
	s_waitcnt lgkmcnt(1)
	v_mfma_f32_16x16x32_bf16 v[70:73], v[168:171], v[184:187], v[70:73]
	s_add_i32 s5, s5, 64
	s_cmpk_eq_i32 s5, 0x3c0
	s_mov_b32 s7, s8
	s_waitcnt lgkmcnt(0)
	v_mfma_f32_16x16x32_bf16 v[62:65], v[188:191], v[184:187], v[62:65]
	v_mfma_f32_16x16x32_bf16 v[38:41], v[168:171], v[208:211], v[38:41]
	v_mfma_f32_16x16x32_bf16 v[34:37], v[188:191], v[208:211], v[34:37]
	v_mfma_f32_16x16x32_bf16 v[18:21], v[168:171], v[212:215], v[18:21]
	v_mfma_f32_16x16x32_bf16 v[14:17], v[188:191], v[212:215], v[14:17]
	v_mfma_f32_16x16x32_bf16 v[2:5], v[168:171], v[216:219], v[2:5]
	v_mfma_f32_16x16x32_bf16 v[86:89], v[188:191], v[216:219], v[86:89]
	s_cbranch_scc0 .LBB0_2334
	s_waitcnt vmcnt(0)
	s_barrier
	v_add_u32_e32 v136, v150, v140
	ds_read_b128 v[160:163], v136
	ds_read_b128 v[164:167], v136 offset:2048
	ds_read_b128 v[168:171], v136 offset:4096
	ds_read_b128 v[172:175], v136 offset:6144
	v_add_u32_e32 v136, v151, v140
	ds_read_b128 v[176:179], v136
	ds_read_b128 v[180:183], v136 offset:2048
	ds_read_b128 v[184:187], v136 offset:4096
	ds_read_b128 v[188:191], v136 offset:6144
	s_waitcnt lgkmcnt(3)
	v_mfma_f32_16x16x32_bf16 v[126:129], v[176:179], v[160:163], v[126:129]
	v_mfma_f32_16x16x32_bf16 v[110:113], v[176:179], v[164:167], v[110:113]
	v_mfma_f32_16x16x32_bf16 v[82:85], v[176:179], v[168:171], v[82:85]
	v_mfma_f32_16x16x32_bf16 v[50:53], v[176:179], v[172:175], v[50:53]
	ds_read_b128 v[176:179], v136 offset:8192
	ds_read_b128 v[192:195], v136 offset:10240
	s_waitcnt lgkmcnt(4)
	v_mfma_f32_16x16x32_bf16 v[122:125], v[180:183], v[160:163], v[122:125]
	v_mfma_f32_16x16x32_bf16 v[106:109], v[180:183], v[164:167], v[106:109]
	v_mfma_f32_16x16x32_bf16 v[78:81], v[180:183], v[168:171], v[78:81]
	v_mfma_f32_16x16x32_bf16 v[42:45], v[180:183], v[172:175], v[42:45]
	s_waitcnt lgkmcnt(3)
	v_mfma_f32_16x16x32_bf16 v[118:121], v[184:187], v[160:163], v[118:121]
	v_mfma_f32_16x16x32_bf16 v[94:97], v[184:187], v[164:167], v[94:97]
	v_mfma_f32_16x16x32_bf16 v[58:61], v[184:187], v[168:171], v[58:61]
	v_mfma_f32_16x16x32_bf16 v[26:29], v[184:187], v[172:175], v[26:29]
	ds_read_b128 v[180:183], v136 offset:12288
	ds_read_b128 v[184:187], v136 offset:14336
	s_waitcnt lgkmcnt(4)
	v_mfma_f32_16x16x32_bf16 v[114:117], v[188:191], v[160:163], v[114:117]
	v_mfma_f32_16x16x32_bf16 v[90:93], v[188:191], v[164:167], v[90:93]
	v_mfma_f32_16x16x32_bf16 v[54:57], v[188:191], v[168:171], v[54:57]
	v_mfma_f32_16x16x32_bf16 v[22:25], v[188:191], v[172:175], v[22:25]
	v_add_u32_e32 v136, v151, v141
	v_add_u32_e32 v208, v150, v141
	s_waitcnt lgkmcnt(3)
	v_mfma_f32_16x16x32_bf16 v[102:105], v[176:179], v[160:163], v[102:105]
	v_mfma_f32_16x16x32_bf16 v[74:77], v[176:179], v[164:167], v[74:77]
	s_waitcnt lgkmcnt(2)
	v_mfma_f32_16x16x32_bf16 v[188:191], v[192:195], v[164:167], v[66:69]
	v_mfma_f32_16x16x32_bf16 v[196:199], v[176:179], v[168:171], v[46:49]
	s_nop 2
	ds_read_b128 v[46:49], v136
	ds_read_b128 v[66:69], v136 offset:2048
	v_mfma_f32_16x16x32_bf16 v[10:13], v[176:179], v[172:175], v[10:13]
	ds_read_b128 v[176:179], v208
	ds_read_b128 v[200:203], v208 offset:2048
	ds_read_b128 v[204:207], v208 offset:4096
	ds_read_b128 v[208:211], v208 offset:6144
	v_mfma_f32_16x16x32_bf16 v[98:101], v[192:195], v[160:163], v[98:101]
	v_mfma_f32_16x16x32_bf16 v[30:33], v[192:195], v[168:171], v[30:33]
	v_mfma_f32_16x16x32_bf16 v[6:9], v[192:195], v[172:175], v[6:9]
	s_waitcnt lgkmcnt(7)
	v_mfma_f32_16x16x32_bf16 v[192:195], v[180:183], v[164:167], v[38:41]
	s_waitcnt lgkmcnt(6)
	v_mfma_f32_16x16x32_bf16 v[164:167], v[184:187], v[164:167], v[34:37]
	v_mfma_f32_16x16x32_bf16 v[18:21], v[180:183], v[168:171], v[18:21]
	v_mfma_f32_16x16x32_bf16 v[168:171], v[184:187], v[168:171], v[14:17]
	s_nop 2
	ds_read_b128 v[14:17], v136 offset:4096
	ds_read_b128 v[34:37], v136 offset:6144
	v_mfma_f32_16x16x32_bf16 v[70:73], v[180:183], v[160:163], v[70:73]
	v_mfma_f32_16x16x32_bf16 v[2:5], v[180:183], v[172:175], v[2:5]
	v_mfma_f32_16x16x32_bf16 v[160:163], v[184:187], v[160:163], v[62:65]
	v_mfma_f32_16x16x32_bf16 v[86:89], v[184:187], v[172:175], v[86:89]
	s_waitcnt lgkmcnt(2)
	v_mfma_f32_16x16x32_bf16 v[172:175], v[46:49], v[208:211], v[50:53]
	s_nop 2
	ds_read_b128 v[50:53], v136 offset:8192
	ds_read_b128 v[180:183], v136 offset:10240
	v_mfma_f32_16x16x32_bf16 v[126:129], v[46:49], v[176:179], v[126:129]
	v_mfma_f32_16x16x32_bf16 v[122:125], v[66:69], v[176:179], v[122:125]
	v_mfma_f32_16x16x32_bf16 v[110:113], v[46:49], v[200:203], v[110:113]
	v_mfma_f32_16x16x32_bf16 v[106:109], v[66:69], v[200:203], v[106:109]
	v_mfma_f32_16x16x32_bf16 v[82:85], v[46:49], v[204:207], v[82:85]
	v_mfma_f32_16x16x32_bf16 v[78:81], v[66:69], v[204:207], v[78:81]
	v_mfma_f32_16x16x32_bf16 v[184:187], v[66:69], v[208:211], v[42:45]
	ds_read_b128 v[224:227], v136 offset:12288
	ds_read_b128 v[228:231], v136 offset:14336
	s_waitcnt lgkmcnt(5)
; template <bool SWAP, class Epi, bool THIN = false> ...
;     ...
;     for (int st = 0; st < ns; ++st) {
;       asm volatile("s_waitcnt vmcnt(0)" ::: "memory");
;       __builtin_amdgcn_s_barrier();
;       asm volatile("" ::: "memory");
;       if (st + 1 < ns) {
;         char* nb = smem + ((st + 1) & 1) * 65536;
;         const int ko = (st + 1) * 64;
; #pragma unroll
;         for (int i = 0; i < 4; ++i) { GLDS16(A + (size_t)(ap[i] + ko), nb + tid * 16 + i * 8192); GLDS16(Bt + (size_t)(bp[i] + ko), nb + 32768 + tid * 16 + i * 8192); }
;       }
;       const char* sa = smem + (st & 1) * 65536 + (wr * 64 + fr) * 128;
;       const char* sb = smem + (st & 1) * 65536 + 32768 + (wc * 128 + fr) * 128;
;       if constexpr (THIN) {
;         if (wc == 0) {
; #pragma unroll
;           for (int ks = 0; ks < 2; ++ks) {
;             bf16x8 af[4], bf[2];
; #pragma unroll
;             for (int m = 0; m < 4; ++m) af[m] = *(const bf16x8*)(sa + m * 2048 + (((ks * 4 + fq) ^ swz) << 4));
; #pragma unroll
;             for (int n = 0; n < 2; ++n) bf[n] = *(const bf16x8*)(sb + n * 2048 + (((ks * 4 + fq) ^ swz) << 4));
; #pragma unroll
;             for (int m = 0; m < 4; ++m)
; #pragma unroll
;               for (int n = 0; n < 2; ++n)
;                 acc[m][n] = SWAP ? __builtin_amdgcn_mfma_f32_16x16x32_bf16(bf[n], af[m], acc[m][n], 0, 0, 0)
;                                  : __builtin_amdgcn_mfma_f32_16x16x32_bf16(af[m], bf[n], acc[m][n], 0, 0, 0);
;           }
;         }
;       } else {
;       bf16x8 afA[4], afB[4], bfb[2][2];
; #pragma unroll
;       for (int m = 0; m < 4; ++m) afA[m] = *(const bf16x8*)(sa + m * 2048 + ((fq ^ swz) << 4));
; #pragma unroll
;       for (int n = 0; n < 2; ++n) bfb[0][n] = *(const bf16x8*)(sb + n * 2048 + ((fq ^ swz) << 4));
; #pragma unroll
;       for (int gq = 0; gq < 8; ++gq) {
;         const int ks = gq >> 2, nh = gq & 3;
;         if (gq < 7) {
;           const int ks2 = (gq + 1) >> 2, nh2 = (gq + 1) & 3;
; #pragma unroll
;           for (int n = 0; n < 2; ++n) bfb[(gq + 1) & 1][n] = *(const bf16x8*)(sb + (nh2 * 2 + n) * 2048 + (((ks2 * 4 + fq) ^ swz) << 4));
;         }
;         if (gq == 3) {
; #pragma unroll
;           for (int m = 0; m < 4; ++m) afB[m] = *(const bf16x8*)(sa + m * 2048 + (((4 + fq) ^ swz) << 4));
;         }
;         __builtin_amdgcn_sched_barrier(0);
; #pragma unroll
	v_mfma_f32_16x16x32_bf16 v[118:121], v[14:17], v[176:179], v[118:121]
	s_waitcnt lgkmcnt(4)
	v_mfma_f32_16x16x32_bf16 v[114:117], v[34:37], v[176:179], v[114:117]
	v_mfma_f32_16x16x32_bf16 v[94:97], v[14:17], v[200:203], v[94:97]
	v_mfma_f32_16x16x32_bf16 v[90:93], v[34:37], v[200:203], v[90:93]
	v_mfma_f32_16x16x32_bf16 v[212:215], v[14:17], v[204:207], v[58:61]
	v_mfma_f32_16x16x32_bf16 v[216:219], v[34:37], v[204:207], v[54:57]
	v_mfma_f32_16x16x32_bf16 v[220:223], v[14:17], v[208:211], v[26:29]
	v_mfma_f32_16x16x32_bf16 v[66:69], v[34:37], v[208:211], v[22:25]
	s_waitcnt lgkmcnt(2)
	v_mfma_f32_16x16x32_bf16 v[38:41], v[180:183], v[204:207], v[30:33]
	v_mfma_f32_16x16x32_bf16 v[62:65], v[50:53], v[176:179], v[102:105]
	v_mfma_f32_16x16x32_bf16 v[46:49], v[180:183], v[176:179], v[98:101]
	v_mfma_f32_16x16x32_bf16 v[58:61], v[50:53], v[200:203], v[74:77]
	v_mfma_f32_16x16x32_bf16 v[42:45], v[180:183], v[200:203], v[188:191]
	v_mfma_f32_16x16x32_bf16 v[54:57], v[50:53], v[204:207], v[196:199]
	v_mfma_f32_16x16x32_bf16 v[50:53], v[50:53], v[208:211], v[10:13]
	v_mfma_f32_16x16x32_bf16 v[34:37], v[180:183], v[208:211], v[6:9]
	s_nop 2
	v_mov_b32_e32 v8, v1
	s_waitcnt vmcnt(0)
	s_waitcnt lgkmcnt(1)
	v_mfma_f32_16x16x32_bf16 v[30:33], v[224:227], v[176:179], v[70:73]
	s_waitcnt lgkmcnt(0)
	s_barrier
	v_mfma_f32_16x16x32_bf16 v[22:25], v[224:227], v[204:207], v[18:21]
	s_nop 0
	v_ashrrev_i32_e32 v71, 8, v8
	v_add_u32_e32 v6, s4, v71
	v_mul_hi_i32 v7, v6, s26
	v_lshrrev_b32_e32 v9, 31, v7
	v_ashrrev_i32_e32 v7, 3, v7
	v_add_u32_e32 v70, v7, v9
	v_and_b32_e32 v73, 15, v8
	v_mad_u64_u32 v[6:7], s[4:5], v70, s27, v[6:7]
	v_lshrrev_b32_e32 v75, 1, v8
	v_bfe_u32 v74, v8, 6, 1
	v_mul_lo_u32 v72, v6, s28
	v_and_or_b32 v73, v75, 64, v73
	v_add_u32_e32 v98, v72, v73
	v_lshl_or_b32 v74, v71, 1, v74
	v_mul_lo_u32 v74, v74, s29
	v_add_u32_e32 v99, -1, v98
	v_mfma_f32_16x16x32_bf16 v[18:21], v[224:227], v[208:211], v[2:5]
	v_add_f32_e64 v76, v126, 0
	v_add_f32_e64 v77, v127, 0
	v_cmp_gt_u32_e32 vcc, s30, v99
	s_lshl_b32 s24, s6, 7
	v_mfma_f32_16x16x32_bf16 v[2:5], v[228:231], v[208:211], v[86:89]
	v_add_f32_e64 v84, v84, 0
	v_add_f32_e64 v85, v85, 0
	v_pk_add_f32 v[82:83], v[82:83], 0 op_sel_hi:[1,0]
	v_pk_add_f32 v[66:67], v[66:67], 0 op_sel_hi:[1,0]
	v_and_or_b32 v86, v75, 24, v74
	v_pk_add_f32 v[74:75], v[128:129], 0 op_sel_hi:[1,0]
	v_add_u32_e32 v88, 15, v98
	v_cndmask_b32_e32 v87, 0, v74, vcc
	v_cndmask_b32_e32 v75, 0, v75, vcc
	v_cndmask_b32_e32 v74, 0, v76, vcc
	v_cndmask_b32_e32 v76, 0, v77, vcc
	v_cvt_pk_bf16_f32 v74, v74, v76
	v_cvt_pk_bf16_f32 v75, v87, v75
	v_mad_u32_u24 v73, v73, s31, v86
	v_pk_add_f32 v[76:77], v[112:113], 0 op_sel_hi:[1,0]
	v_pk_add_f32 v[86:87], v[110:111], 0 op_sel_hi:[1,0]
	v_cmp_gt_u32_e64 s[4:5], s30, v88
	v_mfma_f32_16x16x32_bf16 v[26:29], v[224:227], v[200:203], v[192:195]
	v_add_f32_e64 v62, v62, 0
	v_add_f32_e64 v63, v63, 0
	v_cndmask_b32_e64 v88, 0, v76, s[4:5]
	v_cndmask_b32_e64 v76, 0, v86, s[4:5]
	v_cndmask_b32_e64 v86, 0, v87, s[4:5]
	v_cvt_pk_bf16_f32 v76, v76, v86
	v_add_u32_e32 v86, 31, v98
	v_cndmask_b32_e64 v77, 0, v77, s[4:5]
	v_cmp_gt_u32_e64 s[6:7], s30, v86
	v_cvt_pk_bf16_f32 v77, v88, v77
	v_add_u32_e32 v88, 47, v98
	v_pk_add_f32 v[86:87], v[172:173], 0 op_sel_hi:[1,0]
	v_cndmask_b32_e64 v84, 0, v84, s[6:7]
	v_cndmask_b32_e64 v85, 0, v85, s[6:7]
	v_cndmask_b32_e64 v82, 0, v82, s[6:7]
	v_cndmask_b32_e64 v83, 0, v83, s[6:7]
	v_cvt_pk_bf16_f32 v82, v82, v83
	v_cvt_pk_bf16_f32 v83, v84, v85
	v_pk_add_f32 v[84:85], v[174:175], 0 op_sel_hi:[1,0]
	v_cmp_gt_u32_e64 s[8:9], s30, v88
	v_mfma_f32_16x16x32_bf16 v[14:17], v[228:231], v[176:179], v[160:163]
	v_add_f32_e64 v28, v28, 0
	v_add_f32_e64 v29, v29, 0
	v_cndmask_b32_e64 v88, 0, v84, s[8:9]
	v_cndmask_b32_e64 v85, 0, v85, s[8:9]
	v_cndmask_b32_e64 v84, 0, v86, s[8:9]
	v_cndmask_b32_e64 v86, 0, v87, s[8:9]
	v_cvt_pk_bf16_f32 v84, v84, v86
	v_cvt_pk_bf16_f32 v85, v88, v85
	v_pk_add_f32 v[86:87], v[124:125], 0 op_sel_hi:[1,0]
	v_pk_add_f32 v[88:89], v[122:123], 0 op_sel_hi:[1,0]
	v_cndmask_b32_e32 v98, 0, v86, vcc
	v_cndmask_b32_e32 v87, 0, v87, vcc
	v_cndmask_b32_e32 v86, 0, v88, vcc
	v_cndmask_b32_e32 v88, 0, v89, vcc
	v_cvt_pk_bf16_f32 v86, v86, v88
	v_cvt_pk_bf16_f32 v87, v98, v87
	ds_write2_b64 v73, v[74:75], v[86:87] offset1:4
	v_pk_add_f32 v[74:75], v[108:109], 0 op_sel_hi:[1,0]
	v_pk_add_f32 v[86:87], v[106:107], 0 op_sel_hi:[1,0]
	v_cndmask_b32_e64 v88, 0, v74, s[4:5]
	v_cndmask_b32_e64 v75, 0, v75, s[4:5]
	v_cndmask_b32_e64 v74, 0, v86, s[4:5]
	v_cndmask_b32_e64 v86, 0, v87, s[4:5]
	v_cvt_pk_bf16_f32 v74, v74, v86
	v_cvt_pk_bf16_f32 v75, v88, v75
	v_add_u32_e32 v86, 0x1000, v73
	ds_write2_b64 v86, v[76:77], v[74:75] offset0:16 offset1:20
	v_pk_add_f32 v[74:75], v[80:81], 0 op_sel_hi:[1,0]
	v_pk_add_f32 v[76:77], v[78:79], 0 op_sel_hi:[1,0]
	v_cndmask_b32_e64 v78, 0, v74, s[6:7]
	v_cndmask_b32_e64 v75, 0, v75, s[6:7]
	v_cndmask_b32_e64 v74, 0, v76, s[6:7]
	v_cndmask_b32_e64 v76, 0, v77, s[6:7]
	v_cvt_pk_bf16_f32 v74, v74, v76
	v_cvt_pk_bf16_f32 v75, v78, v75
	v_add_u32_e32 v87, 0x2000, v73
	ds_write2_b64 v87, v[82:83], v[74:75] offset0:32 offset1:36
	v_pk_add_f32 v[74:75], v[186:187], 0 op_sel_hi:[1,0]
	v_pk_add_f32 v[76:77], v[184:185], 0 op_sel_hi:[1,0]
	v_cndmask_b32_e64 v78, 0, v74, s[8:9]
	v_cndmask_b32_e64 v75, 0, v75, s[8:9]
	v_cndmask_b32_e64 v74, 0, v76, s[8:9]
	v_cndmask_b32_e64 v76, 0, v77, s[8:9]
	v_cvt_pk_bf16_f32 v74, v74, v76
	v_cvt_pk_bf16_f32 v75, v78, v75
	v_add_u32_e32 v88, 0x3000, v73
	ds_write2_b64 v88, v[84:85], v[74:75] offset0:48 offset1:52
	v_pk_add_f32 v[74:75], v[120:121], 0 op_sel_hi:[1,0]
	v_pk_add_f32 v[76:77], v[118:119], 0 op_sel_hi:[1,0]
; __device__ __forceinline__ unsigned pack2(float a, float b) { unsigned r; asm("v_cvt_pk_bf16_f32 %0, %1, %2" : "=v"(r) : "v"(a), "v"(b)); return r; }
; template <bool SWAP, class Epi, bool THIN = false> ...
;     ...
;     } else {
;       bf16_t* Zw = (bf16_t*)smem + ((wr_e >> 1) * 2 + wc_e) * (128 * 132);
;       const int nt2w = nt * 2 + wc_e;
; #pragma unroll
;       for (int n = 0; n < 8; ++n) {
;         const int cl = n * 16 + fq_e * 4;
;         f32x4 b4 = {0.f, 0.f, 0.f, 0.f};
;         if (epi.pre_bias) b4 = *(const f32x4*)(epi.pre_bias + epi.norig(nt2w, cl));
; #pragma unroll
;         for (int m = 0; m < 4; ++m) {
;           const int rl = rw + m * 16 + fr_e;
;           const int pos = rig0 + rl;
;           const bool ok = pos >= 0 && pos < grows;
;           f32x4 vv = acc[m][n] + b4;
;           if (!ok) vv = (f32x4){0.f, 0.f, 0.f, 0.f};
;           uint2 u; u.x = pack2(vv[0], vv[1]); u.y = pack2(vv[2], vv[3]);
;           *(uint2*)(Zw + rl * 132 + cl) = u;
;         }
;       }
	v_cndmask_b32_e32 v78, 0, v74, vcc
	v_cndmask_b32_e32 v75, 0, v75, vcc
	v_cndmask_b32_e32 v74, 0, v76, vcc
	v_cndmask_b32_e32 v76, 0, v77, vcc
	v_cvt_pk_bf16_f32 v74, v74, v76
	v_cvt_pk_bf16_f32 v75, v78, v75
	v_pk_add_f32 v[76:77], v[96:97], 0 op_sel_hi:[1,0]
	v_pk_add_f32 v[78:79], v[94:95], 0 op_sel_hi:[1,0]
	v_cndmask_b32_e64 v80, 0, v76, s[4:5]
	v_cndmask_b32_e64 v77, 0, v77, s[4:5]
	v_cndmask_b32_e64 v76, 0, v78, s[4:5]
	v_cndmask_b32_e64 v78, 0, v79, s[4:5]
	v_cvt_pk_bf16_f32 v76, v76, v78
	v_cvt_pk_bf16_f32 v77, v80, v77
	v_pk_add_f32 v[78:79], v[214:215], 0 op_sel_hi:[1,0]
	v_pk_add_f32 v[80:81], v[212:213], 0 op_sel_hi:[1,0]
	v_cndmask_b32_e64 v82, 0, v78, s[6:7]
	v_cndmask_b32_e64 v79, 0, v79, s[6:7]
	v_cndmask_b32_e64 v78, 0, v80, s[6:7]
	v_cndmask_b32_e64 v80, 0, v81, s[6:7]
	v_cvt_pk_bf16_f32 v78, v78, v80
	v_cvt_pk_bf16_f32 v79, v82, v79
	v_pk_add_f32 v[80:81], v[222:223], 0 op_sel_hi:[1,0]
	v_pk_add_f32 v[82:83], v[220:221], 0 op_sel_hi:[1,0]
	v_cndmask_b32_e64 v84, 0, v80, s[8:9]
	v_cndmask_b32_e64 v81, 0, v81, s[8:9]
	v_cndmask_b32_e64 v80, 0, v82, s[8:9]
	v_cndmask_b32_e64 v82, 0, v83, s[8:9]
	v_cvt_pk_bf16_f32 v80, v80, v82
	v_cvt_pk_bf16_f32 v81, v84, v81
	v_pk_add_f32 v[82:83], v[116:117], 0 op_sel_hi:[1,0]
	v_pk_add_f32 v[84:85], v[114:115], 0 op_sel_hi:[1,0]
	v_cndmask_b32_e32 v89, 0, v82, vcc
	v_cndmask_b32_e32 v83, 0, v83, vcc
	v_cndmask_b32_e32 v82, 0, v84, vcc
	v_mfma_f32_16x16x32_bf16 v[10:13], v[228:231], v[200:203], v[164:167]
	v_cndmask_b32_e32 v84, 0, v85, vcc
	v_cvt_pk_bf16_f32 v82, v82, v84
	v_cvt_pk_bf16_f32 v83, v89, v83
	v_mfma_f32_16x16x32_bf16 v[6:9], v[228:231], v[204:207], v[168:171]
	ds_write2_b64 v73, v[74:75], v[82:83] offset0:8 offset1:12
	v_pk_add_f32 v[74:75], v[92:93], 0 op_sel_hi:[1,0]
	v_pk_add_f32 v[82:83], v[90:91], 0 op_sel_hi:[1,0]
	v_cndmask_b32_e64 v84, 0, v74, s[4:5]
	v_cndmask_b32_e64 v75, 0, v75, s[4:5]
	v_cndmask_b32_e64 v74, 0, v82, s[4:5]
	v_cndmask_b32_e64 v82, 0, v83, s[4:5]
	v_cvt_pk_bf16_f32 v74, v74, v82
	v_cvt_pk_bf16_f32 v75, v84, v75
	v_pk_add_f32 v[26:27], v[26:27], 0 op_sel_hi:[1,0]
	ds_write2_b64 v86, v[76:77], v[74:75] offset0:24 offset1:28
	v_pk_add_f32 v[74:75], v[218:219], 0 op_sel_hi:[1,0]
	v_pk_add_f32 v[76:77], v[216:217], 0 op_sel_hi:[1,0]
	v_pk_add_f32 v[58:59], v[58:59], 0 op_sel_hi:[1,0]
	v_pk_add_f32 v[54:55], v[54:55], 0 op_sel_hi:[1,0]
	v_pk_add_f32 v[50:51], v[50:51], 0 op_sel_hi:[1,0]
	v_pk_add_f32 v[46:47], v[46:47], 0 op_sel_hi:[1,0]
	v_pk_add_f32 v[42:43], v[42:43], 0 op_sel_hi:[1,0]
	v_pk_add_f32 v[38:39], v[38:39], 0 op_sel_hi:[1,0]
	v_pk_add_f32 v[34:35], v[34:35], 0 op_sel_hi:[1,0]
	v_pk_add_f32 v[30:31], v[30:31], 0 op_sel_hi:[1,0]
	v_cndmask_b32_e64 v28, 0, v28, s[4:5]
	v_cndmask_b32_e64 v26, 0, v26, s[4:5]
	v_cndmask_b32_e64 v27, 0, v27, s[4:5]
	v_pk_add_f32 v[22:23], v[22:23], 0 op_sel_hi:[1,0]
	v_pk_add_f32 v[18:19], v[18:19], 0 op_sel_hi:[1,0]
	v_pk_add_f32 v[14:15], v[14:15], 0 op_sel_hi:[1,0]
	v_pk_add_f32 v[10:11], v[10:11], 0 op_sel_hi:[1,0]
	v_pk_add_f32 v[6:7], v[6:7], 0 op_sel_hi:[1,0]
	v_pk_add_f32 v[2:3], v[2:3], 0 op_sel_hi:[1,0]
	v_cndmask_b32_e64 v82, 0, v74, s[6:7]
	v_cndmask_b32_e64 v75, 0, v75, s[6:7]
	v_cndmask_b32_e64 v74, 0, v76, s[6:7]
	v_pk_add_f32 v[68:69], v[68:69], 0 op_sel_hi:[1,0]
	v_cndmask_b32_e64 v66, 0, v66, s[8:9]
	v_cndmask_b32_e64 v67, 0, v67, s[8:9]
	v_pk_add_f32 v[64:65], v[64:65], 0 op_sel_hi:[1,0]
	v_cndmask_b32_e32 v62, 0, v62, vcc
	v_cndmask_b32_e32 v63, 0, v63, vcc
	v_pk_add_f32 v[60:61], v[60:61], 0 op_sel_hi:[1,0]
	v_cndmask_b32_e64 v58, 0, v58, s[4:5]
	v_cndmask_b32_e64 v59, 0, v59, s[4:5]
	v_pk_add_f32 v[56:57], v[56:57], 0 op_sel_hi:[1,0]
	v_cndmask_b32_e64 v54, 0, v54, s[6:7]
	v_cndmask_b32_e64 v55, 0, v55, s[6:7]
	v_pk_add_f32 v[52:53], v[52:53], 0 op_sel_hi:[1,0]
	v_cndmask_b32_e64 v50, 0, v50, s[8:9]
	v_cndmask_b32_e64 v51, 0, v51, s[8:9]
	v_pk_add_f32 v[48:49], v[48:49], 0 op_sel_hi:[1,0]
	v_cndmask_b32_e32 v46, 0, v46, vcc
	v_cndmask_b32_e32 v47, 0, v47, vcc
	v_pk_add_f32 v[44:45], v[44:45], 0 op_sel_hi:[1,0]
	v_cndmask_b32_e64 v42, 0, v42, s[4:5]
	v_cndmask_b32_e64 v43, 0, v43, s[4:5]
	v_pk_add_f32 v[40:41], v[40:41], 0 op_sel_hi:[1,0]
	v_cndmask_b32_e64 v38, 0, v38, s[6:7]
	v_cndmask_b32_e64 v39, 0, v39, s[6:7]
	v_pk_add_f32 v[36:37], v[36:37], 0 op_sel_hi:[1,0]
	v_cndmask_b32_e64 v34, 0, v34, s[8:9]
	v_cndmask_b32_e64 v35, 0, v35, s[8:9]
	v_pk_add_f32 v[32:33], v[32:33], 0 op_sel_hi:[1,0]
	v_cndmask_b32_e32 v30, 0, v30, vcc
	v_cndmask_b32_e32 v31, 0, v31, vcc
	v_cndmask_b32_e64 v29, 0, v29, s[4:5]
	v_cvt_pk_bf16_f32 v26, v26, v27
	v_cvt_pk_bf16_f32 v27, v28, v29
	v_pk_add_f32 v[24:25], v[24:25], 0 op_sel_hi:[1,0]
	v_cndmask_b32_e64 v22, 0, v22, s[6:7]
	v_cndmask_b32_e64 v23, 0, v23, s[6:7]
	v_pk_add_f32 v[20:21], v[20:21], 0 op_sel_hi:[1,0]
	v_cndmask_b32_e64 v18, 0, v18, s[8:9]
	v_cndmask_b32_e64 v19, 0, v19, s[8:9]
	v_pk_add_f32 v[16:17], v[16:17], 0 op_sel_hi:[1,0]
	v_cndmask_b32_e32 v14, 0, v14, vcc
	v_cndmask_b32_e32 v15, 0, v15, vcc
	v_pk_add_f32 v[12:13], v[12:13], 0 op_sel_hi:[1,0]
	v_cndmask_b32_e64 v10, 0, v10, s[4:5]
	v_cndmask_b32_e64 v11, 0, v11, s[4:5]
	v_pk_add_f32 v[8:9], v[8:9], 0 op_sel_hi:[1,0]
	v_cndmask_b32_e64 v6, 0, v6, s[6:7]
	v_cndmask_b32_e64 v7, 0, v7, s[6:7]
	v_pk_add_f32 v[4:5], v[4:5], 0 op_sel_hi:[1,0]
	v_cndmask_b32_e64 v2, 0, v2, s[8:9]
	v_cndmask_b32_e64 v3, 0, v3, s[8:9]
	v_mov_b32_e32 v28, v142
	v_cndmask_b32_e64 v76, 0, v77, s[6:7]
	v_cvt_pk_bf16_f32 v74, v74, v76
	v_cvt_pk_bf16_f32 v75, v82, v75
	ds_write2_b64 v87, v[78:79], v[74:75] offset0:40 offset1:44
	v_cndmask_b32_e64 v68, 0, v68, s[8:9]
	v_cndmask_b32_e64 v69, 0, v69, s[8:9]
;   template <class F>
;   __device__ __forceinline__ void finish(const bf16_t* Z, int g, int rig0, int nt, F&& pre) const {
;     typedef f32x2_t f32x2;
;     const int tid = get_tid();
;     if (MODE == 0 || nt < 8) {
;       if (MODE == 0) {
;         const int f2 = (tid & 31) * 2, q8 = tid >> 5;
;         const int q0 = 1 + 16 * q8, q1 = (q0 + 16 < 127) ? q0 + 16 : 127;
;         const int na = norig(nt, f2), ng = norig(nt, 64 + f2);
;         const f32x2 a0 = *(const f32x2*)(cw + na), a1 = *(const f32x2*)(cw + NC + na), a2 = *(const f32x2*)(cw + 2 * NC + na), ab = *(const f32x2*)(cb + na);
;         const f32x2 g0 = *(const f32x2*)(cw + ng), g1 = *(const f32x2*)(cw + NC + ng), g2 = *(const f32x2*)(cw + 2 * NC + ng), gb = *(const f32x2*)(cb + ng);
;         pre();
;         f32x2 am = ldz(Z, q0 - 1, f2), ac = ldz(Z, q0, f2);
;         f32x2 gm = ldz(Z, q0 - 1, 64 + f2), gc = ldz(Z, q0, 64 + f2);
; #pragma unroll 4
;         for (int pl = q0; pl < q1; ++pl) {
;           const f32x2 an = ldz(Z, pl + 1, f2), gn = ldz(Z, pl + 1, 64 + f2);
;           const int pos = rig0 + pl;
;           if (pos < 2048) {
;             const f32x2 av = a0 * am + a1 * ac + a2 * an + ab;
; template <bool SWAP, class Epi, bool THIN = false> ...
;     ...
;     } else {
;       bf16_t* Zw = (bf16_t*)smem + ((wr_e >> 1) * 2 + wc_e) * (128 * 132);
;       const int nt2w = nt * 2 + wc_e;
; #pragma unroll
;       for (int n = 0; n < 8; ++n) {
;         const int cl = n * 16 + fq_e * 4;
;         f32x4 b4 = {0.f, 0.f, 0.f, 0.f};
;         if (epi.pre_bias) b4 = *(const f32x4*)(epi.pre_bias + epi.norig(nt2w, cl));
; #pragma unroll
;         for (int m = 0; m < 4; ++m) {
;           const int rl = rw + m * 16 + fr_e;
;           const int pos = rig0 + rl;
;           const bool ok = pos >= 0 && pos < grows;
;           f32x4 vv = acc[m][n] + b4;
;           if (!ok) vv = (f32x4){0.f, 0.f, 0.f, 0.f};
;           uint2 u; u.x = pack2(vv[0], vv[1]); u.y = pack2(vv[2], vv[3]);
;           *(uint2*)(Zw + rl * 132 + cl) = u;
;         }
;       }
;       __syncthreads();
;       {
;         auto no_pre = []() {};
;         const bf16_t* Zr = (const bf16_t*)smem + ((wr_e >> 1) * 2) * (128 * 132);
;         epi.finish(Zr, g, rig0, nt * 2, no_pre);
;         epi.finish(Zr + 128 * 132, g, rig0, nt * 2 + 1, no_pre);
;       }
;       __syncthreads();
	v_cvt_pk_bf16_f32 v66, v66, v67
	v_cvt_pk_bf16_f32 v67, v68, v69
	ds_write2_b64 v88, v[80:81], v[66:67] offset0:56 offset1:60
	v_cndmask_b32_e32 v64, 0, v64, vcc
	v_cndmask_b32_e32 v65, 0, v65, vcc
	v_cvt_pk_bf16_f32 v62, v62, v63
	v_cvt_pk_bf16_f32 v63, v64, v65
	v_cndmask_b32_e64 v60, 0, v60, s[4:5]
	v_cndmask_b32_e64 v61, 0, v61, s[4:5]
	v_cvt_pk_bf16_f32 v58, v58, v59
	v_cvt_pk_bf16_f32 v59, v60, v61
	v_cndmask_b32_e64 v56, 0, v56, s[6:7]
	v_cndmask_b32_e64 v57, 0, v57, s[6:7]
	v_cvt_pk_bf16_f32 v54, v54, v55
	v_cvt_pk_bf16_f32 v55, v56, v57
	v_cndmask_b32_e64 v52, 0, v52, s[8:9]
	v_cndmask_b32_e64 v53, 0, v53, s[8:9]
	v_cvt_pk_bf16_f32 v50, v50, v51
	v_cvt_pk_bf16_f32 v51, v52, v53
	v_cndmask_b32_e32 v48, 0, v48, vcc
	v_cndmask_b32_e32 v49, 0, v49, vcc
	v_cvt_pk_bf16_f32 v46, v46, v47
	v_cvt_pk_bf16_f32 v47, v48, v49
	ds_write2_b64 v73, v[62:63], v[46:47] offset0:16 offset1:20
	v_cndmask_b32_e64 v44, 0, v44, s[4:5]
	v_cndmask_b32_e64 v45, 0, v45, s[4:5]
	v_cvt_pk_bf16_f32 v42, v42, v43
	v_cvt_pk_bf16_f32 v43, v44, v45
	ds_write2_b64 v86, v[58:59], v[42:43] offset0:32 offset1:36
	v_cndmask_b32_e64 v40, 0, v40, s[6:7]
	v_cndmask_b32_e64 v41, 0, v41, s[6:7]
	v_cvt_pk_bf16_f32 v38, v38, v39
	v_cvt_pk_bf16_f32 v39, v40, v41
	ds_write2_b64 v87, v[54:55], v[38:39] offset0:48 offset1:52
	v_cndmask_b32_e64 v36, 0, v36, s[8:9]
	v_cndmask_b32_e64 v37, 0, v37, s[8:9]
	v_cvt_pk_bf16_f32 v34, v34, v35
	v_cvt_pk_bf16_f32 v35, v36, v37
	ds_write2_b64 v88, v[50:51], v[34:35] offset0:64 offset1:68
	v_cndmask_b32_e32 v32, 0, v32, vcc
	v_cndmask_b32_e32 v33, 0, v33, vcc
	v_cvt_pk_bf16_f32 v30, v30, v31
	v_cvt_pk_bf16_f32 v31, v32, v33
	v_cndmask_b32_e64 v24, 0, v24, s[6:7]
	v_cndmask_b32_e64 v25, 0, v25, s[6:7]
	v_cvt_pk_bf16_f32 v22, v22, v23
	v_cvt_pk_bf16_f32 v23, v24, v25
	v_cndmask_b32_e64 v20, 0, v20, s[8:9]
	v_cndmask_b32_e64 v21, 0, v21, s[8:9]
	v_cvt_pk_bf16_f32 v18, v18, v19
	v_cvt_pk_bf16_f32 v19, v20, v21
	v_cndmask_b32_e32 v16, 0, v16, vcc
	v_cndmask_b32_e32 v17, 0, v17, vcc
	v_cvt_pk_bf16_f32 v14, v14, v15
	v_cvt_pk_bf16_f32 v15, v16, v17
	ds_write2_b64 v73, v[30:31], v[14:15] offset0:24 offset1:28
	v_cndmask_b32_e64 v12, 0, v12, s[4:5]
	v_cndmask_b32_e64 v13, 0, v13, s[4:5]
	v_cvt_pk_bf16_f32 v10, v10, v11
	v_cvt_pk_bf16_f32 v11, v12, v13
	ds_write2_b64 v86, v[26:27], v[10:11] offset0:40 offset1:44
	v_cndmask_b32_e64 v8, 0, v8, s[6:7]
	v_cndmask_b32_e64 v9, 0, v9, s[6:7]
	v_cvt_pk_bf16_f32 v6, v6, v7
	v_cvt_pk_bf16_f32 v7, v8, v9
	ds_write2_b64 v87, v[22:23], v[6:7] offset0:56 offset1:60
	v_cndmask_b32_e64 v4, 0, v4, s[8:9]
	v_cndmask_b32_e64 v5, 0, v5, s[8:9]
	v_cvt_pk_bf16_f32 v2, v2, v3
	v_cvt_pk_bf16_f32 v3, v4, v5
	ds_write2_b64 v88, v[18:19], v[2:3] offset0:72 offset1:76
	s_waitcnt lgkmcnt(0)
	s_barrier
	s_nop 0
	v_ashrrev_i32_e32 v29, 1, v28
	v_and_b32_e32 v38, -16, v29
	v_min_i32_e32 v2, 0x6e, v38
	v_or_b32_e32 v20, 1, v38
	v_add_u32_e32 v3, 17, v2
	v_cmp_ge_i32_e32 vcc, v20, v3
	s_and_saveexec_b64 s[4:5], vcc
	s_xor_b64 s[4:5], exec, s[4:5]
	s_ashr_i32 s25, s24, 31
	s_or_saveexec_b64 s[4:5], s[4:5]
	v_mul_i32_i24_e32 v2, 0x10800, v71
	v_mov_b64_e32 v[22:23], s[24:25]
	v_ashrrev_i32_e32 v71, 31, v70
	s_xor_b64 exec, exec, s[4:5]
	s_cbranch_execz .LBB0_2345
	v_lshlrev_b32_e32 v4, 1, v28
	v_and_b32_e32 v21, 62, v4
	v_or_b32_e32 v4, s24, v21
	s_add_i32 s6, s24, 0xb00
	v_ashrrev_i32_e32 v5, 31, v4
	v_or_b32_e32 v12, s6, v21
	v_lshlrev_b64 v[10:11], 2, v[4:5]
	v_lshl_add_u64 v[14:15], s[12:13], 0, v[10:11]
	v_lshl_add_u64 v[18:19], s[22:23], 0, v[10:11]
	v_ashrrev_i32_e32 v13, 31, v12
	v_lshl_add_u64 v[16:17], s[20:21], 0, v[10:11]
	global_load_dwordx2 v[4:5], v[14:15], off
	global_load_dwordx2 v[6:7], v[16:17], off
	global_load_dwordx2 v[8:9], v[18:19], off
	v_lshlrev_b64 v[18:19], 2, v[12:13]
	v_lshl_add_u64 v[10:11], s[14:15], 0, v[10:11]
	v_lshl_add_u64 v[22:23], s[12:13], 0, v[18:19]
	global_load_dwordx2 v[10:11], v[10:11], off
	v_lshl_add_u64 v[24:25], s[20:21], 0, v[18:19]
	v_lshl_add_u64 v[26:27], s[22:23], 0, v[18:19]
	global_load_dwordx2 v[12:13], v[22:23], off
	global_load_dwordx2 v[14:15], v[24:25], off
	global_load_dwordx2 v[16:17], v[26:27], off
	v_lshl_add_u64 v[18:19], s[14:15], 0, v[18:19]
	global_load_dwordx2 v[18:19], v[18:19], off
	s_ashr_i32 s25, s24, 31
	v_mov_b64_e32 v[106:107], s[24:25]
	v_mov_b32_e32 v117, 0
	v_lshlrev_b32_e32 v88, 1, v142
	v_and_b32_e32 v116, 62, v88
	v_add3_u32 v88, v116, s24, 64
	s_add_i32 s38, s24, 0xb40
	v_ashrrev_i32_e32 v89, 31, v88
	v_lshl_add_u64 v[90:91], v[116:117], 0, v[106:107]
	v_or_b32_e32 v96, s38, v116
	v_lshlrev_b64 v[94:95], 2, v[90:91]
	v_lshlrev_b64 v[88:89], 2, v[88:89]
	v_lshl_add_u64 v[98:99], s[12:13], 0, v[94:95]
	v_lshl_add_u64 v[102:103], s[22:23], 0, v[88:89]
	v_ashrrev_i32_e32 v97, 31, v96
	v_lshl_add_u64 v[100:101], s[20:21], 0, v[88:89]
	global_load_dwordx2 v[88:89], v[98:99], off offset:256
	global_load_dwordx2 v[90:91], v[100:101], off
	global_load_dwordx2 v[92:93], v[102:103], off
	v_lshlrev_b64 v[102:103], 2, v[96:97]
	v_lshl_add_u64 v[94:95], s[14:15], 0, v[94:95]
	v_lshl_add_u64 v[108:109], s[12:13], 0, v[102:103]
	global_load_dwordx2 v[94:95], v[94:95], off offset:256
	v_lshl_add_u64 v[110:111], s[20:21], 0, v[102:103]
	v_lshl_add_u64 v[114:115], s[22:23], 0, v[102:103]
	global_load_dwordx2 v[96:97], v[108:109], off
	global_load_dwordx2 v[98:99], v[110:111], off
	global_load_dwordx2 v[100:101], v[114:115], off
	v_lshl_add_u64 v[102:103], s[14:15], 0, v[102:103]
	global_load_dwordx2 v[102:103], v[102:103], off
	v_lshlrev_b32_e32 v136, 1, v21
	v_mul_lo_u32 v22, v38, s31
	v_mul_lo_u32 v20, v20, s31
	v_add3_u32 v22, v2, v22, v136
	v_add3_u32 v20, v2, v20, v136
	ds_read2_b32 v[22:23], v22 offset1:32
	ds_read2_b32 v[20:21], v20 offset1:32
	s_ashr_i32 s25, s24, 31
	s_lshl_b64 s[6:7], s[24:25], 1
	s_add_u32 s6, s10, s6
	s_addc_u32 s7, s11, s7
	v_lshrrev_b32_e32 v29, 4, v29
	v_and_b32_e32 v28, 31, v28
	s_waitcnt lgkmcnt(1)
	v_lshlrev_b32_e32 v32, 16, v23
	v_and_b32_e32 v33, 0xffff0000, v23
	v_lshlrev_b32_e32 v34, 16, v22
	v_and_b32_e32 v35, 0xffff0000, v22
	v_lshl_add_u64 v[22:23], s[6:7], 0, v[136:137]
	v_mad_u64_u32 v[30:31], s[6:7], v29, s33, v[2:3]
	v_lshlrev_b32_e32 v28, 2, v28
	s_waitcnt lgkmcnt(0)
	v_lshlrev_b32_e32 v24, 16, v21
	v_and_b32_e32 v25, 0xffff0000, v21
	v_lshlrev_b32_e32 v26, 16, v20
	v_and_b32_e32 v27, 0xffff0000, v20
	v_lshlrev_b64 v[20:21], 11, v[70:71]
	v_add3_u32 v39, v30, v28, s34
	s_mov_b32 s98, 0x1600
	s_mov_b32 s99, 0
	v_add_u32_e32 v48, v72, v38
	v_ashrrev_i32_e32 v49, 31, v48
	v_lshl_add_u64 v[48:49], v[20:21], 0, v[48:49]
	v_mad_u64_u32 v[50:51], s[38:39], v48, s35, v[22:23]
	v_mad_i32_i24 v51, v49, s35, v51
	s_mov_b64 s[6:7], 0
	s_waitcnt vmcnt(0)
	ds_read2_b32 v[44:45], v39 offset1:32
	s_branch .LBB0_2340

; template <bool SWAP, class Epi, bool THIN = false> ...
;     ...
;     for (int st = 0; st < ns; ++st) {
;       asm volatile("s_waitcnt vmcnt(0)" ::: "memory");
;       __builtin_amdgcn_s_barrier();
;       asm volatile("" ::: "memory");
;       if (st + 1 < ns) {
;         char* nb = smem + ((st + 1) & 1) * 65536;
;         const int ko = (st + 1) * 64;
; #pragma unroll
;         for (int i = 0; i < 4; ++i) { GLDS16(A + (size_t)(ap[i] + ko), nb + tid * 16 + i * 8192); GLDS16(Bt + (size_t)(bp[i] + ko), nb + 32768 + tid * 16 + i * 8192); }
;       }
;       const char* sa = smem + (st & 1) * 65536 + (wr * 64 + fr) * 128;
;       const char* sb = smem + (st & 1) * 65536 + 32768 + (wc * 128 + fr) * 128;
;       if constexpr (THIN) {
;         if (wc == 0) {
; #pragma unroll
;           for (int ks = 0; ks < 2; ++ks) {
;             bf16x8 af[4], bf[2];
; #pragma unroll
;             for (int m = 0; m < 4; ++m) af[m] = *(const bf16x8*)(sa + m * 2048 + (((ks * 4 + fq) ^ swz) << 4));
; #pragma unroll
;             for (int n = 0; n < 2; ++n) bf[n] = *(const bf16x8*)(sb + n * 2048 + (((ks * 4 + fq) ^ swz) << 4));
; #pragma unroll
;             for (int m = 0; m < 4; ++m)
; #pragma unroll
;               for (int n = 0; n < 2; ++n)
;                 acc[m][n] = SWAP ? __builtin_amdgcn_mfma_f32_16x16x32_bf16(bf[n], af[m], acc[m][n], 0, 0, 0)
;                                  : __builtin_amdgcn_mfma_f32_16x16x32_bf16(af[m], bf[n], acc[m][n], 0, 0, 0);
;           }
;         }
;       } else {
;       bf16x8 afA[4], afB[4], bfb[2][2];
; #pragma unroll
;       for (int m = 0; m < 4; ++m) afA[m] = *(const bf16x8*)(sa + m * 2048 + ((fq ^ swz) << 4));
; #pragma unroll
;       for (int n = 0; n < 2; ++n) bfb[0][n] = *(const bf16x8*)(sb + n * 2048 + ((fq ^ swz) << 4));
; #pragma unroll
;       for (int gq = 0; gq < 8; ++gq) {
;         const int ks = gq >> 2, nh = gq & 3;
;         if (gq < 7) {
;           const int ks2 = (gq + 1) >> 2, nh2 = (gq + 1) & 3;
; #pragma unroll
;           for (int n = 0; n < 2; ++n) bfb[(gq + 1) & 1][n] = *(const bf16x8*)(sb + (nh2 * 2 + n) * 2048 + (((ks2 * 4 + fq) ^ swz) << 4));
;         }
;         if (gq == 3) {
; #pragma unroll
;           for (int m = 0; m < 4; ++m) afB[m] = *(const bf16x8*)(sa + m * 2048 + (((4 + fq) ^ swz) << 4));
;         }
;         __builtin_amdgcn_sched_barrier(0);
; #pragma unroll
.LBB0_2429:
	s_add_i32 s9, s7, 0x10000
	s_and_b32 s8, s9, 0x10000
	v_add_u32_e32 v139, s8, v144
	s_nop 0
	v_readfirstlane_b32 s10, v139
	s_and_b32 s7, s7, 0x10000
	v_add_u32_e32 v130, s7, v145
	v_add_u32_e32 v139, v130, v147
	s_waitcnt vmcnt(0)
	s_barrier
	ds_read_b128 v[168:171], v139
	ds_read_b128 v[172:175], v139 offset:2048
	ds_read_b128 v[176:179], v139 offset:4096
	ds_read_b128 v[180:183], v139 offset:6144
	v_or_b32_e32 v139, s7, v146
	v_add_u32_e32 v141, v139, v147
	ds_read_b128 v[184:187], v141 offset:32768
	ds_read_b128 v[188:191], v141 offset:34816
	ds_read_b128 v[192:195], v141 offset:36864
	ds_read_b128 v[196:199], v141 offset:38912
	v_add_u32_e32 v130, v130, v148
	s_waitcnt lgkmcnt(3)
	v_mfma_f32_16x16x32_bf16 v[126:129], v[184:187], v[168:171], v[126:129]
	s_mov_b32 m0, s10
	v_mfma_f32_16x16x32_bf16 v[110:113], v[184:187], v[172:175], v[110:113]
	global_load_lds_dwordx4 v138, s[22:23]
	v_add_u32_e32 v138, 0x80, v138
	v_mfma_f32_16x16x32_bf16 v[82:85], v[184:187], v[176:179], v[82:85]
	v_mfma_f32_16x16x32_bf16 v[50:53], v[184:187], v[180:183], v[50:53]
	ds_read_b128 v[184:187], v141 offset:40960
	ds_read_b128 v[200:203], v141 offset:43008
	s_waitcnt lgkmcnt(4)
	v_mfma_f32_16x16x32_bf16 v[122:125], v[188:191], v[168:171], v[122:125]
	s_add_u32 m0, s10, 0x8000
	v_mfma_f32_16x16x32_bf16 v[106:109], v[188:191], v[172:175], v[106:109]
	global_load_lds_dwordx4 v137, s[18:19]
	v_add_u32_e32 v137, 0x80, v137
	v_mfma_f32_16x16x32_bf16 v[78:81], v[188:191], v[176:179], v[78:81]
	v_mfma_f32_16x16x32_bf16 v[38:41], v[188:191], v[180:183], v[38:41]
	s_waitcnt lgkmcnt(3)
	v_mfma_f32_16x16x32_bf16 v[118:121], v[192:195], v[168:171], v[118:121]
	s_add_u32 m0, s10, 0x2000
	v_mfma_f32_16x16x32_bf16 v[94:97], v[192:195], v[172:175], v[94:97]
	global_load_lds_dwordx4 v136, s[22:23]
	v_add_u32_e32 v136, 0x80, v136
	v_mfma_f32_16x16x32_bf16 v[58:61], v[192:195], v[176:179], v[58:61]
	v_mfma_f32_16x16x32_bf16 v[26:29], v[192:195], v[180:183], v[26:29]
	ds_read_b128 v[188:191], v141 offset:45056
	ds_read_b128 v[192:195], v141 offset:47104
	s_waitcnt lgkmcnt(4)
	v_mfma_f32_16x16x32_bf16 v[114:117], v[196:199], v[168:171], v[114:117]
	s_add_u32 m0, s10, 0xa000
	v_mfma_f32_16x16x32_bf16 v[86:89], v[196:199], v[172:175], v[86:89]
	global_load_lds_dwordx4 v135, s[18:19]
	v_add_u32_e32 v135, 0x80, v135
	v_mfma_f32_16x16x32_bf16 v[54:57], v[196:199], v[176:179], v[54:57]
	v_mfma_f32_16x16x32_bf16 v[22:25], v[196:199], v[180:183], v[22:25]
	v_add_u32_e32 v139, v139, v148
	s_waitcnt lgkmcnt(3)
	v_mfma_f32_16x16x32_bf16 v[102:105], v[184:187], v[168:171], v[102:105]
	ds_read_b128 v[196:199], v139 offset:32768
	ds_read_b128 v[204:207], v139 offset:34816
	s_add_u32 m0, s10, 0x4000
	v_mfma_f32_16x16x32_bf16 v[74:77], v[184:187], v[172:175], v[74:77]
	global_load_lds_dwordx4 v134, s[22:23]
	v_add_u32_e32 v134, 0x80, v134
	v_mfma_f32_16x16x32_bf16 v[46:49], v[184:187], v[176:179], v[46:49]
	v_mfma_f32_16x16x32_bf16 v[10:13], v[184:187], v[180:183], v[10:13]
	ds_read_b128 v[184:187], v130
	ds_read_b128 v[208:211], v130 offset:2048
	ds_read_b128 v[212:215], v130 offset:4096
	ds_read_b128 v[216:219], v130 offset:6144
	s_waitcnt lgkmcnt(8)
	v_mfma_f32_16x16x32_bf16 v[98:101], v[200:203], v[168:171], v[98:101]
	s_add_u32 m0, s10, 0xc000
	v_mfma_f32_16x16x32_bf16 v[66:69], v[200:203], v[172:175], v[66:69]
	global_load_lds_dwordx4 v133, s[18:19]
	v_add_u32_e32 v133, 0x80, v133
	v_mfma_f32_16x16x32_bf16 v[34:37], v[200:203], v[176:179], v[34:37]
	v_mfma_f32_16x16x32_bf16 v[6:9], v[200:203], v[180:183], v[6:9]
	s_waitcnt lgkmcnt(7)
	v_mfma_f32_16x16x32_bf16 v[70:73], v[188:191], v[168:171], v[70:73]
	s_add_u32 m0, s10, 0x6000
	s_waitcnt lgkmcnt(6)
	v_mfma_f32_16x16x32_bf16 v[62:65], v[192:195], v[168:171], v[62:65]
	global_load_lds_dwordx4 v132, s[22:23]
	v_add_u32_e32 v132, 0x80, v132
	v_mfma_f32_16x16x32_bf16 v[42:45], v[188:191], v[172:175], v[42:45]
	v_mfma_f32_16x16x32_bf16 v[30:33], v[192:195], v[172:175], v[30:33]
	ds_read_b128 v[168:171], v139 offset:36864
	ds_read_b128 v[172:175], v139 offset:38912
	v_mfma_f32_16x16x32_bf16 v[18:21], v[188:191], v[176:179], v[18:21]
	s_add_u32 m0, s10, 0xe000
	v_mfma_f32_16x16x32_bf16 v[14:17], v[192:195], v[176:179], v[14:17]
	global_load_lds_dwordx4 v140, s[18:19]
	v_add_u32_e32 v140, 0x80, v140
	v_mfma_f32_16x16x32_bf16 v[2:5], v[188:191], v[180:183], v[2:5]
	v_mfma_f32_16x16x32_bf16 v[90:93], v[192:195], v[180:183], v[90:93]
	ds_read_b128 v[176:179], v139 offset:40960
	ds_read_b128 v[180:183], v139 offset:43008
	s_waitcnt lgkmcnt(7)
	v_mfma_f32_16x16x32_bf16 v[126:129], v[196:199], v[184:187], v[126:129]
	v_mfma_f32_16x16x32_bf16 v[122:125], v[204:207], v[184:187], v[122:125]
	s_waitcnt lgkmcnt(6)
	v_mfma_f32_16x16x32_bf16 v[110:113], v[196:199], v[208:211], v[110:113]
	v_mfma_f32_16x16x32_bf16 v[106:109], v[204:207], v[208:211], v[106:109]
	s_waitcnt lgkmcnt(5)
	v_mfma_f32_16x16x32_bf16 v[82:85], v[196:199], v[212:215], v[82:85]
	v_mfma_f32_16x16x32_bf16 v[78:81], v[204:207], v[212:215], v[78:81]
	s_waitcnt lgkmcnt(4)
	v_mfma_f32_16x16x32_bf16 v[50:53], v[196:199], v[216:219], v[50:53]
	v_mfma_f32_16x16x32_bf16 v[38:41], v[204:207], v[216:219], v[38:41]
	s_waitcnt lgkmcnt(3)
	v_mfma_f32_16x16x32_bf16 v[118:121], v[168:171], v[184:187], v[118:121]
	v_mfma_f32_16x16x32_bf16 v[94:97], v[168:171], v[208:211], v[94:97]
	v_mfma_f32_16x16x32_bf16 v[58:61], v[168:171], v[212:215], v[58:61]
	v_mfma_f32_16x16x32_bf16 v[26:29], v[168:171], v[216:219], v[26:29]
	ds_read_b128 v[168:171], v139 offset:45056
	ds_read_b128 v[188:191], v139 offset:47104
	s_waitcnt lgkmcnt(4)
; template <bool SWAP, class Epi, bool THIN = false> ...
;     ...
;     for (int st = 0; st < ns; ++st) {
;       asm volatile("s_waitcnt vmcnt(0)" ::: "memory");
;       __builtin_amdgcn_s_barrier();
;       asm volatile("" ::: "memory");
;       if (st + 1 < ns) {
;         char* nb = smem + ((st + 1) & 1) * 65536;
;         const int ko = (st + 1) * 64;
; #pragma unroll
;         for (int i = 0; i < 4; ++i) { GLDS16(A + (size_t)(ap[i] + ko), nb + tid * 16 + i * 8192); GLDS16(Bt + (size_t)(bp[i] + ko), nb + 32768 + tid * 16 + i * 8192); }
;       }
;       const char* sa = smem + (st & 1) * 65536 + (wr * 64 + fr) * 128;
;       const char* sb = smem + (st & 1) * 65536 + 32768 + (wc * 128 + fr) * 128;
;       if constexpr (THIN) {
;         if (wc == 0) {
; #pragma unroll
;           for (int ks = 0; ks < 2; ++ks) {
;             bf16x8 af[4], bf[2];
; #pragma unroll
;             for (int m = 0; m < 4; ++m) af[m] = *(const bf16x8*)(sa + m * 2048 + (((ks * 4 + fq) ^ swz) << 4));
; #pragma unroll
;             for (int n = 0; n < 2; ++n) bf[n] = *(const bf16x8*)(sb + n * 2048 + (((ks * 4 + fq) ^ swz) << 4));
; #pragma unroll
;             for (int m = 0; m < 4; ++m)
; #pragma unroll
;               for (int n = 0; n < 2; ++n)
;                 acc[m][n] = SWAP ? __builtin_amdgcn_mfma_f32_16x16x32_bf16(bf[n], af[m], acc[m][n], 0, 0, 0)
;                                  : __builtin_amdgcn_mfma_f32_16x16x32_bf16(af[m], bf[n], acc[m][n], 0, 0, 0);
;           }
;         }
;       } else {
;       bf16x8 afA[4], afB[4], bfb[2][2];
; #pragma unroll
;       for (int m = 0; m < 4; ++m) afA[m] = *(const bf16x8*)(sa + m * 2048 + ((fq ^ swz) << 4));
; #pragma unroll
;       for (int n = 0; n < 2; ++n) bfb[0][n] = *(const bf16x8*)(sb + n * 2048 + ((fq ^ swz) << 4));
; #pragma unroll
;       for (int gq = 0; gq < 8; ++gq) {
;         const int ks = gq >> 2, nh = gq & 3;
;         if (gq < 7) {
;           const int ks2 = (gq + 1) >> 2, nh2 = (gq + 1) & 3;
; #pragma unroll
;           for (int n = 0; n < 2; ++n) bfb[(gq + 1) & 1][n] = *(const bf16x8*)(sb + (nh2 * 2 + n) * 2048 + (((ks2 * 4 + fq) ^ swz) << 4));
;         }
;         if (gq == 3) {
; #pragma unroll
;           for (int m = 0; m < 4; ++m) afB[m] = *(const bf16x8*)(sa + m * 2048 + (((4 + fq) ^ swz) << 4));
;         }
;         __builtin_amdgcn_sched_barrier(0);
; #pragma unroll
	v_mfma_f32_16x16x32_bf16 v[114:117], v[172:175], v[184:187], v[114:117]
	v_mfma_f32_16x16x32_bf16 v[86:89], v[172:175], v[208:211], v[86:89]
	v_mfma_f32_16x16x32_bf16 v[54:57], v[172:175], v[212:215], v[54:57]
	v_mfma_f32_16x16x32_bf16 v[22:25], v[172:175], v[216:219], v[22:25]
	s_waitcnt lgkmcnt(3)
	v_mfma_f32_16x16x32_bf16 v[102:105], v[176:179], v[184:187], v[102:105]
	s_waitcnt lgkmcnt(2)
	v_mfma_f32_16x16x32_bf16 v[98:101], v[180:183], v[184:187], v[98:101]
	v_mfma_f32_16x16x32_bf16 v[74:77], v[176:179], v[208:211], v[74:77]
	v_mfma_f32_16x16x32_bf16 v[66:69], v[180:183], v[208:211], v[66:69]
	v_mfma_f32_16x16x32_bf16 v[46:49], v[176:179], v[212:215], v[46:49]
	v_mfma_f32_16x16x32_bf16 v[34:37], v[180:183], v[212:215], v[34:37]
	v_mfma_f32_16x16x32_bf16 v[10:13], v[176:179], v[216:219], v[10:13]
	v_mfma_f32_16x16x32_bf16 v[6:9], v[180:183], v[216:219], v[6:9]
	s_waitcnt lgkmcnt(1)
	v_mfma_f32_16x16x32_bf16 v[70:73], v[168:171], v[184:187], v[70:73]
	s_add_i32 s6, s6, 64
	s_cmpk_eq_i32 s6, 0xac0
	s_mov_b32 s7, s9
	s_waitcnt lgkmcnt(0)
	v_mfma_f32_16x16x32_bf16 v[62:65], v[188:191], v[184:187], v[62:65]
	v_mfma_f32_16x16x32_bf16 v[42:45], v[168:171], v[208:211], v[42:45]
	v_mfma_f32_16x16x32_bf16 v[30:33], v[188:191], v[208:211], v[30:33]
	v_mfma_f32_16x16x32_bf16 v[18:21], v[168:171], v[212:215], v[18:21]
	v_mfma_f32_16x16x32_bf16 v[14:17], v[188:191], v[212:215], v[14:17]
	v_mfma_f32_16x16x32_bf16 v[2:5], v[168:171], v[216:219], v[2:5]
	v_mfma_f32_16x16x32_bf16 v[90:93], v[188:191], v[216:219], v[90:93]
	s_cbranch_scc0 .LBB0_2429
	v_add_u32_e32 v130, s8, v145
	s_waitcnt vmcnt(0)
	s_barrier
	v_add_u32_e32 v140, v130, v147
	ds_read_b128 v[132:135], v140
	ds_read_b128 v[136:139], v140 offset:2048
	ds_read_b128 v[168:171], v140 offset:4096
	ds_read_b128 v[172:175], v140 offset:6144
	v_add_u32_e32 v140, s8, v146
	v_add_u32_e32 v141, v140, v147
	ds_read_b128 v[176:179], v141 offset:32768
	ds_read_b128 v[180:183], v141 offset:34816
	ds_read_b128 v[184:187], v141 offset:36864
	ds_read_b128 v[188:191], v141 offset:38912
	v_add_u32_e32 v130, v130, v148
	s_waitcnt lgkmcnt(3)
	v_mfma_f32_16x16x32_bf16 v[126:129], v[176:179], v[132:135], v[126:129]
	v_mfma_f32_16x16x32_bf16 v[110:113], v[176:179], v[136:139], v[110:113]
	v_mfma_f32_16x16x32_bf16 v[82:85], v[176:179], v[168:171], v[82:85]
	v_mfma_f32_16x16x32_bf16 v[50:53], v[176:179], v[172:175], v[50:53]
	ds_read_b128 v[176:179], v141 offset:40960
	ds_read_b128 v[192:195], v141 offset:43008
	s_waitcnt lgkmcnt(4)
	v_mfma_f32_16x16x32_bf16 v[122:125], v[180:183], v[132:135], v[122:125]
	v_mfma_f32_16x16x32_bf16 v[106:109], v[180:183], v[136:139], v[106:109]
	v_mfma_f32_16x16x32_bf16 v[78:81], v[180:183], v[168:171], v[78:81]
	v_mfma_f32_16x16x32_bf16 v[38:41], v[180:183], v[172:175], v[38:41]
	s_waitcnt lgkmcnt(3)
	v_mfma_f32_16x16x32_bf16 v[118:121], v[184:187], v[132:135], v[118:121]
	v_mfma_f32_16x16x32_bf16 v[180:183], v[184:187], v[136:139], v[94:97]
	v_mfma_f32_16x16x32_bf16 v[200:203], v[184:187], v[168:171], v[58:61]
	s_waitcnt lgkmcnt(2)
	v_mfma_f32_16x16x32_bf16 v[204:207], v[188:191], v[168:171], v[54:57]
	v_mfma_f32_16x16x32_bf16 v[184:187], v[184:187], v[172:175], v[26:29]
	s_nop 2
	ds_read_b128 v[26:29], v141 offset:45056
	ds_read_b128 v[54:57], v141 offset:47104
	v_mfma_f32_16x16x32_bf16 v[114:117], v[188:191], v[132:135], v[114:117]
	v_mfma_f32_16x16x32_bf16 v[196:199], v[188:191], v[136:139], v[86:89]
	v_mfma_f32_16x16x32_bf16 v[188:191], v[188:191], v[172:175], v[22:25]
	v_add_u32_e32 v140, v140, v148
	s_waitcnt lgkmcnt(3)
	v_mfma_f32_16x16x32_bf16 v[102:105], v[176:179], v[132:135], v[102:105]
	ds_read_b128 v[22:25], v140 offset:32768
	ds_read_b128 v[86:89], v140 offset:34816
	v_mfma_f32_16x16x32_bf16 v[74:77], v[176:179], v[136:139], v[74:77]
	v_mfma_f32_16x16x32_bf16 v[46:49], v[176:179], v[168:171], v[46:49]
	v_mfma_f32_16x16x32_bf16 v[10:13], v[176:179], v[172:175], v[10:13]
	ds_read_b128 v[176:179], v130
	ds_read_b128 v[208:211], v130 offset:2048
	ds_read_b128 v[212:215], v130 offset:4096
	ds_read_b128 v[216:219], v130 offset:6144
	s_waitcnt lgkmcnt(8)
	v_mfma_f32_16x16x32_bf16 v[98:101], v[192:195], v[132:135], v[98:101]
	v_mfma_f32_16x16x32_bf16 v[66:69], v[192:195], v[136:139], v[66:69]
	v_mfma_f32_16x16x32_bf16 v[34:37], v[192:195], v[168:171], v[34:37]
	v_mfma_f32_16x16x32_bf16 v[6:9], v[192:195], v[172:175], v[6:9]
	s_waitcnt lgkmcnt(7)
	v_mfma_f32_16x16x32_bf16 v[220:223], v[26:29], v[168:171], v[18:21]
	s_waitcnt lgkmcnt(6)
	v_mfma_f32_16x16x32_bf16 v[168:171], v[54:57], v[168:171], v[14:17]
	s_nop 2
	ds_read_b128 v[14:17], v140 offset:36864
	ds_read_b128 v[18:21], v140 offset:38912
	v_mfma_f32_16x16x32_bf16 v[70:73], v[26:29], v[132:135], v[70:73]
	v_mfma_f32_16x16x32_bf16 v[132:135], v[54:57], v[132:135], v[62:65]
	v_mfma_f32_16x16x32_bf16 v[192:195], v[26:29], v[136:139], v[42:45]
	v_mfma_f32_16x16x32_bf16 v[136:139], v[54:57], v[136:139], v[30:33]
	v_mfma_f32_16x16x32_bf16 v[2:5], v[26:29], v[172:175], v[2:5]
	v_mfma_f32_16x16x32_bf16 v[172:175], v[54:57], v[172:175], v[90:93]
	ds_read_b128 v[224:227], v140 offset:40960
	ds_read_b128 v[228:231], v140 offset:43008
	s_waitcnt lgkmcnt(7)
	v_mfma_f32_16x16x32_bf16 v[126:129], v[22:25], v[176:179], v[126:129]
	v_mfma_f32_16x16x32_bf16 v[122:125], v[86:89], v[176:179], v[122:125]
	s_waitcnt lgkmcnt(6)
	v_mfma_f32_16x16x32_bf16 v[94:97], v[22:25], v[208:211], v[110:113]
	v_mfma_f32_16x16x32_bf16 v[90:93], v[86:89], v[208:211], v[106:109]
	s_waitcnt lgkmcnt(5)
	v_mfma_f32_16x16x32_bf16 v[62:65], v[22:25], v[212:215], v[82:85]
	v_mfma_f32_16x16x32_bf16 v[58:61], v[86:89], v[212:215], v[78:81]
	s_waitcnt lgkmcnt(4)
; template <bool SWAP, class Epi, bool THIN = false> ...
;     ...
;       bf16x8 afA[4], afB[4], bfb[2][2];
; #pragma unroll
;       for (int m = 0; m < 4; ++m) afA[m] = *(const bf16x8*)(sa + m * 2048 + ((fq ^ swz) << 4));
; #pragma unroll
;       for (int n = 0; n < 2; ++n) bfb[0][n] = *(const bf16x8*)(sb + n * 2048 + ((fq ^ swz) << 4));
; #pragma unroll
;       for (int gq = 0; gq < 8; ++gq) {
;         const int ks = gq >> 2, nh = gq & 3;
;         if (gq < 7) {
;           const int ks2 = (gq + 1) >> 2, nh2 = (gq + 1) & 3;
; #pragma unroll
;           for (int n = 0; n < 2; ++n) bfb[(gq + 1) & 1][n] = *(const bf16x8*)(sb + (nh2 * 2 + n) * 2048 + (((ks2 * 4 + fq) ^ swz) << 4));
;         }
;         if (gq == 3) {
; #pragma unroll
;           for (int m = 0; m < 4; ++m) afB[m] = *(const bf16x8*)(sa + m * 2048 + (((4 + fq) ^ swz) << 4));
;         }
;         __builtin_amdgcn_sched_barrier(0);
; #pragma unroll
;         for (int m = 0; m < 4; ++m)
; #pragma unroll
;           for (int n = 0; n < 2; ++n) {
;             const bf16x8 av = ks ? afB[m] : afA[m];
;             acc[m][nh * 2 + n] = SWAP ? __builtin_amdgcn_mfma_f32_16x16x32_bf16(bfb[gq & 1][n], av, acc[m][nh * 2 + n], 0, 0, 0)
;                                       : __builtin_amdgcn_mfma_f32_16x16x32_bf16(av, bfb[gq & 1][n], acc[m][nh * 2 + n], 0, 0, 0);
;           }
;       }
;       }
;     }
;     __syncthreads();
;     const int te = get_tid512();
;     const int fr_e = te & 15, fq_e = (te & 63) >> 4, wr_e = te >> 7, wc_e = (te >> 6) & 1;
;     const int sub = 2 * mt + (wr_e >> 1);
;     const int g = sub / tpg, ti = sub - g * tpg;
;     const int rig0 = ti * step - halo;
;     const int rw = (wr_e & 1) * 64;
;     if constexpr (Epi::KIND == 0) {
; #pragma unroll
;       for (int m = 0; m < 4; ++m) {
;         const int rig = rig0 + rw + m * 16 + fr_e;
;         if constexpr (Epi::ROWSUM) {
;           float ss = 0.f;
; #pragma unroll
;           for (int n = 0; n < 8; ++n) {
;             const int col = nt * 256 + wc_e * 128 + n * 16 + fq_e * 4;
;             if (col < N) ss += epi.c4(g, rig, col, acc[m][n]);
;           }
;           ss += __shfl_xor(ss, 16); ss += __shfl_xor(ss, 32);
;           if (fq_e == 0) epi.rowsum(g, rig, nt * 2 + wc_e, ss);
;         } else {
; #pragma unroll
;           for (int n = 0; n < 8; ++n) {
	v_mfma_f32_16x16x32_bf16 v[30:33], v[22:25], v[216:219], v[50:53]
	v_mfma_f32_16x16x32_bf16 v[26:29], v[86:89], v[216:219], v[38:41]
	s_waitcnt lgkmcnt(3)
	v_mfma_f32_16x16x32_bf16 v[86:89], v[14:17], v[208:211], v[180:183]
	v_mfma_f32_16x16x32_bf16 v[22:25], v[14:17], v[216:219], v[184:187]
	s_nop 1
	ds_read_b128 v[180:183], v140 offset:45056
	ds_read_b128 v[184:187], v140 offset:47104
	v_mfma_f32_16x16x32_bf16 v[118:121], v[14:17], v[176:179], v[118:121]
	s_waitcnt lgkmcnt(4)
	v_mfma_f32_16x16x32_bf16 v[114:117], v[18:21], v[176:179], v[114:117]
	v_mfma_f32_16x16x32_bf16 v[82:85], v[18:21], v[208:211], v[196:199]
	v_mfma_f32_16x16x32_bf16 v[54:57], v[14:17], v[212:215], v[200:203]
	v_mfma_f32_16x16x32_bf16 v[50:53], v[18:21], v[212:215], v[204:207]
	v_mfma_f32_16x16x32_bf16 v[18:21], v[18:21], v[216:219], v[188:191]
	s_waitcnt lgkmcnt(3)
	v_mfma_f32_16x16x32_bf16 v[110:113], v[224:227], v[176:179], v[102:105]
	s_waitcnt lgkmcnt(2)
	v_mfma_f32_16x16x32_bf16 v[106:109], v[228:231], v[176:179], v[98:101]
	v_mfma_f32_16x16x32_bf16 v[78:81], v[224:227], v[208:211], v[74:77]
	v_mfma_f32_16x16x32_bf16 v[74:77], v[228:231], v[208:211], v[66:69]
	v_mfma_f32_16x16x32_bf16 v[46:49], v[224:227], v[212:215], v[46:49]
	v_mfma_f32_16x16x32_bf16 v[42:45], v[228:231], v[212:215], v[34:37]
	v_mfma_f32_16x16x32_bf16 v[14:17], v[224:227], v[216:219], v[10:13]
	v_mfma_f32_16x16x32_bf16 v[10:13], v[228:231], v[216:219], v[6:9]
	v_mov_b32_e32 v130, v1
	s_waitcnt vmcnt(0) lgkmcnt(0)
	s_barrier
	v_mfma_f32_16x16x32_bf16 v[98:101], v[184:187], v[176:179], v[132:135]
	v_ashrrev_i32_e32 v7, 8, v130
	v_add_u32_e32 v7, s5, v7
	v_ashrrev_i32_e32 v8, 31, v7
	v_lshrrev_b32_e32 v8, 28, v8
	v_add_u32_e32 v8, v7, v8
	v_ashrrev_i32_e32 v134, 4, v8
	v_lshlrev_b32_e32 v8, 11, v134
	v_lshlrev_b32_e32 v7, 7, v7
	v_sub_u32_e32 v7, v7, v8
	v_lshrrev_b32_e32 v8, 1, v130
	v_and_b32_e32 v6, 15, v130
	v_and_b32_e32 v8, 64, v8
	v_mfma_f32_16x16x32_bf16 v[66:69], v[184:187], v[208:211], v[136:139]
	v_ashrrev_i32_e32 v135, 31, v134
	s_nop 1
	v_or3_b32 v136, v7, v8, v6
	v_lshlrev_b32_e32 v6, 1, v130
	v_and_b32_e32 v132, 0x80, v6
	v_mfma_f32_16x16x32_bf16 v[6:9], v[180:183], v[216:219], v[2:5]
	v_ashrrev_i32_e32 v137, 31, v136
	v_lshlrev_b64 v[138:139], 21, v[134:135]
	v_lshlrev_b64 v[140:141], 10, v[136:137]
	v_lshrrev_b32_e32 v2, 2, v130
	v_and_b32_e32 v2, 12, v2
	v_mfma_f32_16x16x32_bf16 v[102:105], v[180:183], v[176:179], v[70:73]
	v_or3_b32 v132, v2, v132, s4
	v_mad_i64_i32 v[134:135], s[4:5], v134, s31, 0
	v_mfma_f32_16x16x32_bf16 v[70:73], v[180:183], v[208:211], v[192:195]
	v_lshl_add_u64 v[140:141], v[140:141], 0, v[138:139]
	v_cmp_gt_i32_e32 vcc, s34, v132
	v_ashrrev_i32_e32 v133, 31, v132
	v_bfe_u32 v246, v130, 4, 1
	v_mul_u32_u24_e32 v246, 24, v246
	v_mov_b32_e32 v247, 0
	v_mfma_f32_16x16x32_bf16 v[38:41], v[180:183], v[212:215], v[220:223]
	v_lshl_add_u64 v[134:135], s[24:25], 0, v[134:135]
	v_lshl_add_u64 v[140:141], v[140:141], 1, s[20:21]
	v_mfma_f32_16x16x32_bf16 v[34:37], v[184:187], v[212:215], v[168:171]
	v_mfma_f32_16x16x32_bf16 v[2:5], v[184:187], v[216:219], v[172:175]
	v_lshl_add_u64 v[218:219], v[132:133], 2, v[134:135]
	global_load_dwordx4 v[198:201], v[218:219], off
	global_load_dwordx4 v[202:205], v[218:219], off offset:64
	global_load_dwordx4 v[206:209], v[218:219], off offset:128
	global_load_dwordx4 v[210:213], v[218:219], off offset:192
	global_load_dwordx4 v[214:217], v[218:219], off offset:256
	global_load_dwordx4 v[224:227], v[218:219], off offset:320
	global_load_dwordx4 v[228:231], v[218:219], off offset:384
	global_load_dwordx4 v[232:235], v[218:219], off offset:448
	s_nop 0
	v_lshl_add_u64 v[172:173], v[132:133], 1, v[140:141]
	v_lshl_add_u64 v[196:197], v[132:133], 1, v[140:141]
	global_load_dwordx2 v[176:177], v[196:197], off
	global_load_dwordx2 v[178:179], v[196:197], off offset:32
	global_load_dwordx2 v[180:181], v[196:197], off offset:64
	global_load_dwordx2 v[182:183], v[196:197], off offset:96
	global_load_dwordx2 v[184:185], v[196:197], off offset:128
	global_load_dwordx2 v[186:187], v[196:197], off offset:160
	global_load_dwordx2 v[188:189], v[196:197], off offset:192
	global_load_dwordx2 v[190:191], v[196:197], off offset:224
	v_add_f32_e32 v126, 0, v126
	v_add_f32_e32 v127, 0, v127
	v_add_f32_e32 v128, 0, v128
	v_add_f32_e32 v129, 0, v129
	s_waitcnt vmcnt(7)
	v_lshlrev_b32_e32 v130, 16, v176
	v_and_b32_e32 v137, 0xffff0000, v176
	v_lshlrev_b32_e32 v167, 16, v177
	v_and_b32_e32 v174, 0xffff0000, v177
	v_fmac_f32_e32 v130, v126, v198
	v_fmac_f32_e32 v137, v127, v199
	v_fmac_f32_e32 v167, v128, v200
	v_fmac_f32_e32 v174, v129, v201
	v_cvt_pk_bf16_f32 v126, v130, v137
	v_cvt_pk_bf16_f32 v127, v167, v174
	v_lshl_add_u64 v[168:169], v[132:133], 1, v[140:141]
	v_add_f32_e32 v122, 0, v122
	v_add_f32_e32 v123, 0, v123
	v_add_f32_e32 v124, 0, v124
	v_add_f32_e32 v125, 0, v125
	s_waitcnt vmcnt(6)
	v_lshlrev_b32_e32 v130, 16, v178
	v_and_b32_e32 v137, 0xffff0000, v178
	v_lshlrev_b32_e32 v167, 16, v179
	v_and_b32_e32 v170, 0xffff0000, v179
	v_fmac_f32_e32 v130, v122, v202
	v_fmac_f32_e32 v137, v123, v203
	v_fmac_f32_e32 v167, v124, v204
	v_fmac_f32_e32 v170, v125, v205
	v_cvt_pk_bf16_f32 v128, v130, v137
	v_cvt_pk_bf16_f32 v129, v167, v170
	s_nop 1
	v_permlane16_swap_b32 v126, v128
	v_permlane16_swap_b32 v127, v129
	v_lshl_add_u64 v[248:249], v[168:169], 0, v[246:247]
	s_nop 0
	global_store_dwordx4 v[248:249], v[126:129], off
	s_nop 1
	v_or_b32_e32 v122, 32, v132
	v_lshl_add_u64 v[126:127], v[132:133], 1, v[140:141]
	v_add_f32_e32 v118, 0, v118
	v_add_f32_e32 v119, 0, v119
	v_add_f32_e32 v120, 0, v120
	v_add_f32_e32 v121, 0, v121
	s_waitcnt vmcnt(6)
; __device__ __forceinline__ unsigned pack2(float a, float b) { unsigned r; asm("v_cvt_pk_bf16_f32 %0, %1, %2" : "=v"(r) : "v"(a), "v"(b)); return r; }
; __device__ __forceinline__ float bf2f(bf16_t h) { return __uint_as_float(((unsigned)h) << 16); }
;   __device__ __forceinline__ void c4(int g, int rig, int col, f32x4 v) const {
;     const size_t o = ((size_t)g * 2048 + rig) * 1024 + col;
;     f32x4 bs;
;     if (BASE_F32) bs = __builtin_nontemporal_load((const f32x4*)((const float*)base + o));
;     else {
;       const uint2 u = *(const uint2*)((const bf16_t*)base + o);
;       bs[0] = bf2f((bf16_t)(u.x & 0xffff)); bs[1] = bf2f((bf16_t)(u.x >> 16)); bs[2] = bf2f((bf16_t)(u.y & 0xffff)); bs[3] = bf2f((bf16_t)(u.y >> 16));
;     }
;     const f32x4 gt = *(const f32x4*)(gate + (size_t)g * 6144 + col);
;     f32x4 bi = {0.f, 0.f, 0.f, 0.f};
;     if (bias) bi = *(const f32x4*)(bias + col);
;     f32x4 r;
; #pragma unroll
;     for (int j = 0; j < 4; ++j) r[j] = bs[j] + gt[j] * (v[j] + bi[j]);
;     uint2 w; w.x = pack2(r[0], r[1]); w.y = pack2(r[2], r[3]);
;     *(uint2*)(X16 + o) = w;
; template <bool SWAP, class Epi, bool THIN = false> ...
;     ...
;     if constexpr (Epi::KIND == 0) {
; #pragma unroll
;       for (int m = 0; m < 4; ++m) {
;         const int rig = rig0 + rw + m * 16 + fr_e;
;         if constexpr (Epi::ROWSUM) {
;           float ss = 0.f;
; #pragma unroll
;           for (int n = 0; n < 8; ++n) {
;             const int col = nt * 256 + wc_e * 128 + n * 16 + fq_e * 4;
;             if (col < N) ss += epi.c4(g, rig, col, acc[m][n]);
;           }
;           ss += __shfl_xor(ss, 16); ss += __shfl_xor(ss, 32);
;           if (fq_e == 0) epi.rowsum(g, rig, nt * 2 + wc_e, ss);
;         } else {
; #pragma unroll
;           for (int n = 0; n < 8; ++n) {
;             const int col = nt * 256 + wc_e * 128 + n * 16 + fq_e * 4;
;             if (col < N) epi.c4(g, rig, col, acc[m][n]);
;           }
	v_lshlrev_b32_e32 v130, 16, v180
	v_and_b32_e32 v128, 0xffff0000, v180
	v_lshlrev_b32_e32 v137, 16, v181
	v_and_b32_e32 v129, 0xffff0000, v181
	v_fmac_f32_e32 v130, v118, v206
	v_fmac_f32_e32 v128, v119, v207
	v_fmac_f32_e32 v137, v120, v208
	v_fmac_f32_e32 v129, v121, v209
	v_cvt_pk_bf16_f32 v118, v130, v128
	v_cvt_pk_bf16_f32 v119, v137, v129
	v_lshl_add_u64 v[122:123], v[132:133], 1, v[140:141]
	v_add_f32_e32 v114, 0, v114
	v_add_f32_e32 v115, 0, v115
	v_add_f32_e32 v116, 0, v116
	v_add_f32_e32 v117, 0, v117
	s_waitcnt vmcnt(5)
	v_lshlrev_b32_e32 v126, 16, v182
	v_and_b32_e32 v124, 0xffff0000, v182
	v_lshlrev_b32_e32 v127, 16, v183
	v_and_b32_e32 v125, 0xffff0000, v183
	v_fmac_f32_e32 v126, v114, v210
	v_fmac_f32_e32 v124, v115, v211
	v_fmac_f32_e32 v127, v116, v212
	v_fmac_f32_e32 v125, v117, v213
	v_cvt_pk_bf16_f32 v120, v126, v124
	v_cvt_pk_bf16_f32 v121, v127, v125
	s_nop 1
	v_permlane16_swap_b32 v118, v120
	v_permlane16_swap_b32 v119, v121
	v_lshl_add_u64 v[248:249], v[122:123], 0, v[246:247]
	s_nop 0
	global_store_dwordx4 v[248:249], v[118:121], off offset:64
	s_nop 1
	v_or_b32_e32 v114, 64, v132
	v_lshl_add_u64 v[118:119], v[132:133], 1, v[140:141]
	v_add_f32_e32 v110, 0, v110
	v_add_f32_e32 v111, 0, v111
	v_add_f32_e32 v112, 0, v112
	v_add_f32_e32 v113, 0, v113
	s_waitcnt vmcnt(5)
	v_lshlrev_b32_e32 v122, 16, v184
	v_and_b32_e32 v120, 0xffff0000, v184
	v_lshlrev_b32_e32 v123, 16, v185
	v_and_b32_e32 v121, 0xffff0000, v185
	v_fmac_f32_e32 v122, v110, v214
	v_fmac_f32_e32 v120, v111, v215
	v_fmac_f32_e32 v123, v112, v216
	v_fmac_f32_e32 v121, v113, v217
	v_cvt_pk_bf16_f32 v110, v122, v120
	v_cvt_pk_bf16_f32 v111, v123, v121
	v_lshl_add_u64 v[114:115], v[132:133], 1, v[140:141]
	v_add_f32_e32 v106, 0, v106
	v_add_f32_e32 v107, 0, v107
	v_add_f32_e32 v108, 0, v108
	v_add_f32_e32 v109, 0, v109
	s_waitcnt vmcnt(4)
	v_lshlrev_b32_e32 v118, 16, v186
	v_and_b32_e32 v116, 0xffff0000, v186
	v_lshlrev_b32_e32 v119, 16, v187
	v_and_b32_e32 v117, 0xffff0000, v187
	v_fmac_f32_e32 v118, v106, v224
	v_fmac_f32_e32 v116, v107, v225
	v_fmac_f32_e32 v119, v108, v226
	v_fmac_f32_e32 v117, v109, v227
	v_cvt_pk_bf16_f32 v112, v118, v116
	v_cvt_pk_bf16_f32 v113, v119, v117
	s_nop 1
	v_permlane16_swap_b32 v110, v112
	v_permlane16_swap_b32 v111, v113
	v_lshl_add_u64 v[248:249], v[114:115], 0, v[246:247]
	s_nop 0
	global_store_dwordx4 v[248:249], v[110:113], off offset:128
	s_nop 1
	v_or_b32_e32 v106, 0x60, v132
	v_lshl_add_u64 v[110:111], v[132:133], 1, v[140:141]
	v_add_f32_e32 v102, 0, v102
	v_add_f32_e32 v103, 0, v103
	v_add_f32_e32 v104, 0, v104
	v_add_f32_e32 v105, 0, v105
	s_waitcnt vmcnt(4)
	v_lshlrev_b32_e32 v114, 16, v188
	v_and_b32_e32 v112, 0xffff0000, v188
	v_lshlrev_b32_e32 v115, 16, v189
	v_and_b32_e32 v113, 0xffff0000, v189
	v_fmac_f32_e32 v114, v102, v228
	v_fmac_f32_e32 v112, v103, v229
	v_fmac_f32_e32 v115, v104, v230
	v_fmac_f32_e32 v113, v105, v231
	v_cvt_pk_bf16_f32 v102, v114, v112
	v_cvt_pk_bf16_f32 v103, v115, v113
	v_lshl_add_u64 v[106:107], v[132:133], 1, v[140:141]
	v_add_f32_e32 v98, 0, v98
	v_add_f32_e32 v99, 0, v99
	v_add_f32_e32 v100, 0, v100
	v_add_f32_e32 v101, 0, v101
	s_waitcnt vmcnt(3)
	v_lshlrev_b32_e32 v110, 16, v190
	v_and_b32_e32 v108, 0xffff0000, v190
	v_lshlrev_b32_e32 v111, 16, v191
	v_and_b32_e32 v109, 0xffff0000, v191
	v_fmac_f32_e32 v110, v98, v232
	v_fmac_f32_e32 v108, v99, v233
	v_fmac_f32_e32 v111, v100, v234
	v_fmac_f32_e32 v109, v101, v235
	v_cvt_pk_bf16_f32 v104, v110, v108
	v_cvt_pk_bf16_f32 v105, v111, v109
	s_nop 1
	v_permlane16_swap_b32 v102, v104
	v_permlane16_swap_b32 v103, v105
	v_lshl_add_u64 v[248:249], v[106:107], 0, v[246:247]
	s_nop 0
	global_store_dwordx4 v[248:249], v[102:105], off offset:192
	s_nop 1
	v_or_b32_e32 v98, 16, v136
	v_ashrrev_i32_e32 v99, 31, v98
	v_lshlrev_b64 v[98:99], 10, v[98:99]
	v_lshl_add_u64 v[98:99], v[98:99], 0, v[138:139]
	v_lshl_add_u64 v[98:99], v[98:99], 1, s[20:21]
	v_lshl_add_u64 v[104:105], v[132:133], 1, v[98:99]
	v_lshl_add_u64 v[196:197], v[132:133], 1, v[98:99]
	global_load_dwordx2 v[176:177], v[196:197], off
	global_load_dwordx2 v[178:179], v[196:197], off offset:32
	global_load_dwordx2 v[180:181], v[196:197], off offset:64
	global_load_dwordx2 v[182:183], v[196:197], off offset:96
	global_load_dwordx2 v[184:185], v[196:197], off offset:128
	global_load_dwordx2 v[186:187], v[196:197], off offset:160
	global_load_dwordx2 v[188:189], v[196:197], off offset:192
	global_load_dwordx2 v[190:191], v[196:197], off offset:224
	v_add_f32_e32 v94, 0, v94
	v_add_f32_e32 v95, 0, v95
	v_add_f32_e32 v96, 0, v96
	v_add_f32_e32 v97, 0, v97
	s_waitcnt vmcnt(7)
	v_lshlrev_b32_e32 v108, 16, v176
	v_and_b32_e32 v106, 0xffff0000, v176
	v_lshlrev_b32_e32 v109, 16, v177
	v_and_b32_e32 v107, 0xffff0000, v177
	v_fmac_f32_e32 v108, v94, v198
	v_fmac_f32_e32 v106, v95, v199
	v_fmac_f32_e32 v109, v96, v200
	v_fmac_f32_e32 v107, v97, v201
	v_cvt_pk_bf16_f32 v94, v108, v106
	v_cvt_pk_bf16_f32 v95, v109, v107
	v_lshl_add_u64 v[100:101], v[132:133], 1, v[98:99]
	v_add_f32_e32 v90, 0, v90
	v_add_f32_e32 v91, 0, v91
	v_add_f32_e32 v92, 0, v92
	v_add_f32_e32 v93, 0, v93
	s_waitcnt vmcnt(6)
	v_lshlrev_b32_e32 v104, 16, v178
	v_and_b32_e32 v102, 0xffff0000, v178
	v_lshlrev_b32_e32 v105, 16, v179
	v_and_b32_e32 v103, 0xffff0000, v179
	v_fmac_f32_e32 v104, v90, v202
	v_fmac_f32_e32 v102, v91, v203
	v_fmac_f32_e32 v105, v92, v204
	v_fmac_f32_e32 v103, v93, v205
	v_cvt_pk_bf16_f32 v96, v104, v102
	v_cvt_pk_bf16_f32 v97, v105, v103
	s_nop 1
	v_permlane16_swap_b32 v94, v96
	v_permlane16_swap_b32 v95, v97
	v_lshl_add_u64 v[248:249], v[100:101], 0, v[246:247]
	s_nop 0
	global_store_dwordx4 v[248:249], v[94:97], off
	s_nop 1
	v_lshl_add_u64 v[94:95], v[132:133], 1, v[98:99]
	v_add_f32_e32 v86, 0, v86
	v_add_f32_e32 v87, 0, v87
	v_add_f32_e32 v88, 0, v88
	v_add_f32_e32 v89, 0, v89
	s_waitcnt vmcnt(6)
; __device__ __forceinline__ unsigned pack2(float a, float b) { unsigned r; asm("v_cvt_pk_bf16_f32 %0, %1, %2" : "=v"(r) : "v"(a), "v"(b)); return r; }
; __device__ __forceinline__ float bf2f(bf16_t h) { return __uint_as_float(((unsigned)h) << 16); }
;   __device__ __forceinline__ void c4(int g, int rig, int col, f32x4 v) const {
;     const size_t o = ((size_t)g * 2048 + rig) * 1024 + col;
;     f32x4 bs;
;     if (BASE_F32) bs = __builtin_nontemporal_load((const f32x4*)((const float*)base + o));
;     else {
;       const uint2 u = *(const uint2*)((const bf16_t*)base + o);
;       bs[0] = bf2f((bf16_t)(u.x & 0xffff)); bs[1] = bf2f((bf16_t)(u.x >> 16)); bs[2] = bf2f((bf16_t)(u.y & 0xffff)); bs[3] = bf2f((bf16_t)(u.y >> 16));
;     }
;     const f32x4 gt = *(const f32x4*)(gate + (size_t)g * 6144 + col);
;     f32x4 bi = {0.f, 0.f, 0.f, 0.f};
;     if (bias) bi = *(const f32x4*)(bias + col);
;     f32x4 r;
; #pragma unroll
;     for (int j = 0; j < 4; ++j) r[j] = bs[j] + gt[j] * (v[j] + bi[j]);
;     uint2 w; w.x = pack2(r[0], r[1]); w.y = pack2(r[2], r[3]);
;     *(uint2*)(X16 + o) = w;
; template <bool SWAP, class Epi, bool THIN = false> ...
;     ...
;     if constexpr (Epi::KIND == 0) {
; #pragma unroll
;       for (int m = 0; m < 4; ++m) {
;         const int rig = rig0 + rw + m * 16 + fr_e;
;         if constexpr (Epi::ROWSUM) {
;           float ss = 0.f;
; #pragma unroll
;           for (int n = 0; n < 8; ++n) {
;             const int col = nt * 256 + wc_e * 128 + n * 16 + fq_e * 4;
;             if (col < N) ss += epi.c4(g, rig, col, acc[m][n]);
;           }
;           ss += __shfl_xor(ss, 16); ss += __shfl_xor(ss, 32);
;           if (fq_e == 0) epi.rowsum(g, rig, nt * 2 + wc_e, ss);
;         } else {
; #pragma unroll
;           for (int n = 0; n < 8; ++n) {
;             const int col = nt * 256 + wc_e * 128 + n * 16 + fq_e * 4;
;             if (col < N) epi.c4(g, rig, col, acc[m][n]);
;           }
	v_lshlrev_b32_e32 v100, 16, v180
	v_and_b32_e32 v96, 0xffff0000, v180
	v_lshlrev_b32_e32 v101, 16, v181
	v_and_b32_e32 v97, 0xffff0000, v181
	v_fmac_f32_e32 v100, v86, v206
	v_fmac_f32_e32 v96, v87, v207
	v_fmac_f32_e32 v101, v88, v208
	v_fmac_f32_e32 v97, v89, v209
	v_cvt_pk_bf16_f32 v86, v100, v96
	v_cvt_pk_bf16_f32 v87, v101, v97
	v_lshl_add_u64 v[90:91], v[132:133], 1, v[98:99]
	v_add_f32_e32 v82, 0, v82
	v_add_f32_e32 v83, 0, v83
	v_add_f32_e32 v84, 0, v84
	v_add_f32_e32 v85, 0, v85
	s_waitcnt vmcnt(5)
	v_lshlrev_b32_e32 v94, 16, v182
	v_and_b32_e32 v92, 0xffff0000, v182
	v_lshlrev_b32_e32 v95, 16, v183
	v_and_b32_e32 v93, 0xffff0000, v183
	v_fmac_f32_e32 v94, v82, v210
	v_fmac_f32_e32 v92, v83, v211
	v_fmac_f32_e32 v95, v84, v212
	v_fmac_f32_e32 v93, v85, v213
	v_cvt_pk_bf16_f32 v88, v94, v92
	v_cvt_pk_bf16_f32 v89, v95, v93
	s_nop 1
	v_permlane16_swap_b32 v86, v88
	v_permlane16_swap_b32 v87, v89
	v_lshl_add_u64 v[248:249], v[90:91], 0, v[246:247]
	s_nop 0
	global_store_dwordx4 v[248:249], v[86:89], off offset:64
	s_nop 1
	v_lshl_add_u64 v[86:87], v[132:133], 1, v[98:99]
	v_add_f32_e32 v78, 0, v78
	v_add_f32_e32 v79, 0, v79
	v_add_f32_e32 v80, 0, v80
	v_add_f32_e32 v81, 0, v81
	s_waitcnt vmcnt(5)
	v_lshlrev_b32_e32 v90, 16, v184
	v_and_b32_e32 v88, 0xffff0000, v184
	v_lshlrev_b32_e32 v91, 16, v185
	v_and_b32_e32 v89, 0xffff0000, v185
	v_fmac_f32_e32 v90, v78, v214
	v_fmac_f32_e32 v88, v79, v215
	v_fmac_f32_e32 v91, v80, v216
	v_fmac_f32_e32 v89, v81, v217
	v_cvt_pk_bf16_f32 v78, v90, v88
	v_cvt_pk_bf16_f32 v79, v91, v89
	v_lshl_add_u64 v[82:83], v[132:133], 1, v[98:99]
	v_add_f32_e32 v74, 0, v74
	v_add_f32_e32 v75, 0, v75
	v_add_f32_e32 v76, 0, v76
	v_add_f32_e32 v77, 0, v77
	s_waitcnt vmcnt(4)
	v_lshlrev_b32_e32 v86, 16, v186
	v_and_b32_e32 v84, 0xffff0000, v186
	v_lshlrev_b32_e32 v87, 16, v187
	v_and_b32_e32 v85, 0xffff0000, v187
	v_fmac_f32_e32 v86, v74, v224
	v_fmac_f32_e32 v84, v75, v225
	v_fmac_f32_e32 v87, v76, v226
	v_fmac_f32_e32 v85, v77, v227
	v_cvt_pk_bf16_f32 v80, v86, v84
	v_cvt_pk_bf16_f32 v81, v87, v85
	s_nop 1
	v_permlane16_swap_b32 v78, v80
	v_permlane16_swap_b32 v79, v81
	v_lshl_add_u64 v[248:249], v[82:83], 0, v[246:247]
	s_nop 0
	global_store_dwordx4 v[248:249], v[78:81], off offset:128
	s_nop 1
	v_lshl_add_u64 v[78:79], v[132:133], 1, v[98:99]
	v_add_f32_e32 v70, 0, v70
	v_add_f32_e32 v71, 0, v71
	v_add_f32_e32 v72, 0, v72
	v_add_f32_e32 v73, 0, v73
	s_waitcnt vmcnt(4)
	v_lshlrev_b32_e32 v82, 16, v188
	v_and_b32_e32 v80, 0xffff0000, v188
	v_lshlrev_b32_e32 v83, 16, v189
	v_and_b32_e32 v81, 0xffff0000, v189
	v_fmac_f32_e32 v82, v70, v228
	v_fmac_f32_e32 v80, v71, v229
	v_fmac_f32_e32 v83, v72, v230
	v_fmac_f32_e32 v81, v73, v231
	v_cvt_pk_bf16_f32 v70, v82, v80
	v_cvt_pk_bf16_f32 v71, v83, v81
	v_lshl_add_u64 v[74:75], v[132:133], 1, v[98:99]
	v_add_f32_e32 v66, 0, v66
	v_add_f32_e32 v67, 0, v67
	v_add_f32_e32 v68, 0, v68
	v_add_f32_e32 v69, 0, v69
	s_waitcnt vmcnt(3)
	v_lshlrev_b32_e32 v78, 16, v190
	v_and_b32_e32 v76, 0xffff0000, v190
	v_lshlrev_b32_e32 v79, 16, v191
	v_and_b32_e32 v77, 0xffff0000, v191
	v_fmac_f32_e32 v78, v66, v232
	v_fmac_f32_e32 v76, v67, v233
	v_fmac_f32_e32 v79, v68, v234
	v_fmac_f32_e32 v77, v69, v235
	v_cvt_pk_bf16_f32 v72, v78, v76
	v_cvt_pk_bf16_f32 v73, v79, v77
	s_nop 1
	v_permlane16_swap_b32 v70, v72
	v_permlane16_swap_b32 v71, v73
	v_lshl_add_u64 v[248:249], v[74:75], 0, v[246:247]
	s_nop 0
	global_store_dwordx4 v[248:249], v[70:73], off offset:192
	s_nop 1
	v_or_b32_e32 v66, 32, v136
	v_ashrrev_i32_e32 v67, 31, v66
	v_lshlrev_b64 v[66:67], 10, v[66:67]
	v_lshl_add_u64 v[66:67], v[66:67], 0, v[138:139]
	v_lshl_add_u64 v[66:67], v[66:67], 1, s[20:21]
	v_lshl_add_u64 v[72:73], v[132:133], 1, v[66:67]
	v_lshl_add_u64 v[196:197], v[132:133], 1, v[66:67]
	global_load_dwordx2 v[176:177], v[196:197], off
	global_load_dwordx2 v[178:179], v[196:197], off offset:32
	global_load_dwordx2 v[180:181], v[196:197], off offset:64
	global_load_dwordx2 v[182:183], v[196:197], off offset:96
	global_load_dwordx2 v[184:185], v[196:197], off offset:128
	global_load_dwordx2 v[186:187], v[196:197], off offset:160
	global_load_dwordx2 v[188:189], v[196:197], off offset:192
	global_load_dwordx2 v[190:191], v[196:197], off offset:224
	v_add_f32_e32 v62, 0, v62
	v_add_f32_e32 v63, 0, v63
	v_add_f32_e32 v64, 0, v64
	v_add_f32_e32 v65, 0, v65
	s_waitcnt vmcnt(7)
	v_lshlrev_b32_e32 v76, 16, v176
	v_and_b32_e32 v74, 0xffff0000, v176
	v_lshlrev_b32_e32 v77, 16, v177
	v_and_b32_e32 v75, 0xffff0000, v177
	v_fmac_f32_e32 v76, v62, v198
	v_fmac_f32_e32 v74, v63, v199
	v_fmac_f32_e32 v77, v64, v200
	v_fmac_f32_e32 v75, v65, v201
	v_cvt_pk_bf16_f32 v62, v76, v74
	v_cvt_pk_bf16_f32 v63, v77, v75
	v_lshl_add_u64 v[68:69], v[132:133], 1, v[66:67]
	v_add_f32_e32 v58, 0, v58
	v_add_f32_e32 v59, 0, v59
	v_add_f32_e32 v60, 0, v60
	v_add_f32_e32 v61, 0, v61
	s_waitcnt vmcnt(6)
	v_lshlrev_b32_e32 v72, 16, v178
	v_and_b32_e32 v70, 0xffff0000, v178
	v_lshlrev_b32_e32 v73, 16, v179
	v_and_b32_e32 v71, 0xffff0000, v179
	v_fmac_f32_e32 v72, v58, v202
	v_fmac_f32_e32 v70, v59, v203
	v_fmac_f32_e32 v73, v60, v204
	v_fmac_f32_e32 v71, v61, v205
	v_cvt_pk_bf16_f32 v64, v72, v70
	v_cvt_pk_bf16_f32 v65, v73, v71
	s_nop 1
	v_permlane16_swap_b32 v62, v64
	v_permlane16_swap_b32 v63, v65
	v_lshl_add_u64 v[248:249], v[68:69], 0, v[246:247]
	s_nop 0
	global_store_dwordx4 v[248:249], v[62:65], off
	s_nop 1
	v_lshl_add_u64 v[62:63], v[132:133], 1, v[66:67]
	v_add_f32_e32 v54, 0, v54
	v_add_f32_e32 v55, 0, v55
	v_add_f32_e32 v56, 0, v56
	v_add_f32_e32 v57, 0, v57
	s_waitcnt vmcnt(6)
; __device__ __forceinline__ unsigned pack2(float a, float b) { unsigned r; asm("v_cvt_pk_bf16_f32 %0, %1, %2" : "=v"(r) : "v"(a), "v"(b)); return r; }
; __device__ __forceinline__ float bf2f(bf16_t h) { return __uint_as_float(((unsigned)h) << 16); }
;   __device__ __forceinline__ void c4(int g, int rig, int col, f32x4 v) const {
;     const size_t o = ((size_t)g * 2048 + rig) * 1024 + col;
;     f32x4 bs;
;     if (BASE_F32) bs = __builtin_nontemporal_load((const f32x4*)((const float*)base + o));
;     else {
;       const uint2 u = *(const uint2*)((const bf16_t*)base + o);
;       bs[0] = bf2f((bf16_t)(u.x & 0xffff)); bs[1] = bf2f((bf16_t)(u.x >> 16)); bs[2] = bf2f((bf16_t)(u.y & 0xffff)); bs[3] = bf2f((bf16_t)(u.y >> 16));
;     }
;     const f32x4 gt = *(const f32x4*)(gate + (size_t)g * 6144 + col);
;     f32x4 bi = {0.f, 0.f, 0.f, 0.f};
;     if (bias) bi = *(const f32x4*)(bias + col);
;     f32x4 r;
; #pragma unroll
;     for (int j = 0; j < 4; ++j) r[j] = bs[j] + gt[j] * (v[j] + bi[j]);
;     uint2 w; w.x = pack2(r[0], r[1]); w.y = pack2(r[2], r[3]);
;     *(uint2*)(X16 + o) = w;
; template <bool SWAP, class Epi, bool THIN = false> ...
;     ...
;     if constexpr (Epi::KIND == 0) {
; #pragma unroll
;       for (int m = 0; m < 4; ++m) {
;         const int rig = rig0 + rw + m * 16 + fr_e;
;         if constexpr (Epi::ROWSUM) {
;           float ss = 0.f;
; #pragma unroll
;           for (int n = 0; n < 8; ++n) {
;             const int col = nt * 256 + wc_e * 128 + n * 16 + fq_e * 4;
;             if (col < N) ss += epi.c4(g, rig, col, acc[m][n]);
;           }
;           ss += __shfl_xor(ss, 16); ss += __shfl_xor(ss, 32);
;           if (fq_e == 0) epi.rowsum(g, rig, nt * 2 + wc_e, ss);
;         } else {
; #pragma unroll
;           for (int n = 0; n < 8; ++n) {
;             const int col = nt * 256 + wc_e * 128 + n * 16 + fq_e * 4;
;             if (col < N) epi.c4(g, rig, col, acc[m][n]);
;           }
	v_lshlrev_b32_e32 v68, 16, v180
	v_and_b32_e32 v64, 0xffff0000, v180
	v_lshlrev_b32_e32 v69, 16, v181
	v_and_b32_e32 v65, 0xffff0000, v181
	v_fmac_f32_e32 v68, v54, v206
	v_fmac_f32_e32 v64, v55, v207
	v_fmac_f32_e32 v69, v56, v208
	v_fmac_f32_e32 v65, v57, v209
	v_cvt_pk_bf16_f32 v54, v68, v64
	v_cvt_pk_bf16_f32 v55, v69, v65
	v_lshl_add_u64 v[58:59], v[132:133], 1, v[66:67]
	v_add_f32_e32 v50, 0, v50
	v_add_f32_e32 v51, 0, v51
	v_add_f32_e32 v52, 0, v52
	v_add_f32_e32 v53, 0, v53
	s_waitcnt vmcnt(5)
	v_lshlrev_b32_e32 v62, 16, v182
	v_and_b32_e32 v60, 0xffff0000, v182
	v_lshlrev_b32_e32 v63, 16, v183
	v_and_b32_e32 v61, 0xffff0000, v183
	v_fmac_f32_e32 v62, v50, v210
	v_fmac_f32_e32 v60, v51, v211
	v_fmac_f32_e32 v63, v52, v212
	v_fmac_f32_e32 v61, v53, v213
	v_cvt_pk_bf16_f32 v56, v62, v60
	v_cvt_pk_bf16_f32 v57, v63, v61
	s_nop 1
	v_permlane16_swap_b32 v54, v56
	v_permlane16_swap_b32 v55, v57
	v_lshl_add_u64 v[248:249], v[58:59], 0, v[246:247]
	s_nop 0
	global_store_dwordx4 v[248:249], v[54:57], off offset:64
	s_nop 1
	v_lshl_add_u64 v[54:55], v[132:133], 1, v[66:67]
	v_add_f32_e32 v46, 0, v46
	v_add_f32_e32 v47, 0, v47
	v_add_f32_e32 v48, 0, v48
	v_add_f32_e32 v49, 0, v49
	s_waitcnt vmcnt(5)
	v_lshlrev_b32_e32 v58, 16, v184
	v_and_b32_e32 v56, 0xffff0000, v184
	v_lshlrev_b32_e32 v59, 16, v185
	v_and_b32_e32 v57, 0xffff0000, v185
	v_fmac_f32_e32 v58, v46, v214
	v_fmac_f32_e32 v56, v47, v215
	v_fmac_f32_e32 v59, v48, v216
	v_fmac_f32_e32 v57, v49, v217
	v_cvt_pk_bf16_f32 v46, v58, v56
	v_cvt_pk_bf16_f32 v47, v59, v57
	v_lshl_add_u64 v[50:51], v[132:133], 1, v[66:67]
	v_add_f32_e32 v42, 0, v42
	v_add_f32_e32 v43, 0, v43
	v_add_f32_e32 v44, 0, v44
	v_add_f32_e32 v45, 0, v45
	s_waitcnt vmcnt(4)
	v_lshlrev_b32_e32 v54, 16, v186
	v_and_b32_e32 v52, 0xffff0000, v186
	v_lshlrev_b32_e32 v55, 16, v187
	v_and_b32_e32 v53, 0xffff0000, v187
	v_fmac_f32_e32 v54, v42, v224
	v_fmac_f32_e32 v52, v43, v225
	v_fmac_f32_e32 v55, v44, v226
	v_fmac_f32_e32 v53, v45, v227
	v_cvt_pk_bf16_f32 v48, v54, v52
	v_cvt_pk_bf16_f32 v49, v55, v53
	s_nop 1
	v_permlane16_swap_b32 v46, v48
	v_permlane16_swap_b32 v47, v49
	v_lshl_add_u64 v[248:249], v[50:51], 0, v[246:247]
	s_nop 0
	global_store_dwordx4 v[248:249], v[46:49], off offset:128
	s_nop 1
	v_lshl_add_u64 v[46:47], v[132:133], 1, v[66:67]
	v_add_f32_e32 v38, 0, v38
	v_add_f32_e32 v39, 0, v39
	v_add_f32_e32 v40, 0, v40
	v_add_f32_e32 v41, 0, v41
	s_waitcnt vmcnt(4)
	v_lshlrev_b32_e32 v50, 16, v188
	v_and_b32_e32 v48, 0xffff0000, v188
	v_lshlrev_b32_e32 v51, 16, v189
	v_and_b32_e32 v49, 0xffff0000, v189
	v_fmac_f32_e32 v50, v38, v228
	v_fmac_f32_e32 v48, v39, v229
	v_fmac_f32_e32 v51, v40, v230
	v_fmac_f32_e32 v49, v41, v231
	v_cvt_pk_bf16_f32 v38, v50, v48
	v_cvt_pk_bf16_f32 v39, v51, v49
	v_lshl_add_u64 v[42:43], v[132:133], 1, v[66:67]
	v_add_f32_e32 v34, 0, v34
	v_add_f32_e32 v35, 0, v35
	v_add_f32_e32 v36, 0, v36
	v_add_f32_e32 v37, 0, v37
	s_waitcnt vmcnt(3)
	v_lshlrev_b32_e32 v46, 16, v190
	v_and_b32_e32 v44, 0xffff0000, v190
	v_lshlrev_b32_e32 v47, 16, v191
	v_and_b32_e32 v45, 0xffff0000, v191
	v_fmac_f32_e32 v46, v34, v232
	v_fmac_f32_e32 v44, v35, v233
	v_fmac_f32_e32 v47, v36, v234
	v_fmac_f32_e32 v45, v37, v235
	v_cvt_pk_bf16_f32 v40, v46, v44
	v_cvt_pk_bf16_f32 v41, v47, v45
	s_nop 1
	v_permlane16_swap_b32 v38, v40
	v_permlane16_swap_b32 v39, v41
	v_lshl_add_u64 v[248:249], v[42:43], 0, v[246:247]
	s_nop 0
	global_store_dwordx4 v[248:249], v[38:41], off offset:192
	s_nop 1
	v_or_b32_e32 v34, 48, v136
	v_ashrrev_i32_e32 v35, 31, v34
	v_lshlrev_b64 v[34:35], 10, v[34:35]
	v_lshl_add_u64 v[34:35], v[34:35], 0, v[138:139]
	v_lshl_add_u64 v[34:35], v[34:35], 1, s[20:21]
	v_lshl_add_u64 v[40:41], v[132:133], 1, v[34:35]
	v_lshl_add_u64 v[196:197], v[132:133], 1, v[34:35]
	global_load_dwordx2 v[176:177], v[196:197], off
	global_load_dwordx2 v[178:179], v[196:197], off offset:32
	global_load_dwordx2 v[180:181], v[196:197], off offset:64
	global_load_dwordx2 v[182:183], v[196:197], off offset:96
	global_load_dwordx2 v[184:185], v[196:197], off offset:128
	global_load_dwordx2 v[186:187], v[196:197], off offset:160
	global_load_dwordx2 v[188:189], v[196:197], off offset:192
	global_load_dwordx2 v[190:191], v[196:197], off offset:224
	v_add_f32_e32 v30, 0, v30
	v_add_f32_e32 v31, 0, v31
	v_add_f32_e32 v32, 0, v32
	v_add_f32_e32 v33, 0, v33
	s_waitcnt vmcnt(7)
; __device__ __forceinline__ unsigned pack2(float a, float b) { unsigned r; asm("v_cvt_pk_bf16_f32 %0, %1, %2" : "=v"(r) : "v"(a), "v"(b)); return r; }
; __device__ __forceinline__ float bf2f(bf16_t h) { return __uint_as_float(((unsigned)h) << 16); }
;   __device__ __forceinline__ void c4(int g, int rig, int col, f32x4 v) const {
;     const size_t o = ((size_t)g * 2048 + rig) * 1024 + col;
;     f32x4 bs;
;     if (BASE_F32) bs = __builtin_nontemporal_load((const f32x4*)((const float*)base + o));
;     else {
;       const uint2 u = *(const uint2*)((const bf16_t*)base + o);
;       bs[0] = bf2f((bf16_t)(u.x & 0xffff)); bs[1] = bf2f((bf16_t)(u.x >> 16)); bs[2] = bf2f((bf16_t)(u.y & 0xffff)); bs[3] = bf2f((bf16_t)(u.y >> 16));
;     }
;     const f32x4 gt = *(const f32x4*)(gate + (size_t)g * 6144 + col);
;     f32x4 bi = {0.f, 0.f, 0.f, 0.f};
;     if (bias) bi = *(const f32x4*)(bias + col);
;     f32x4 r;
; #pragma unroll
;     for (int j = 0; j < 4; ++j) r[j] = bs[j] + gt[j] * (v[j] + bi[j]);
;     uint2 w; w.x = pack2(r[0], r[1]); w.y = pack2(r[2], r[3]);
;     *(uint2*)(X16 + o) = w;
; template <bool SWAP, class Epi, bool THIN = false> ...
;     ...
;     if constexpr (Epi::KIND == 0) {
; #pragma unroll
;       for (int m = 0; m < 4; ++m) {
;         const int rig = rig0 + rw + m * 16 + fr_e;
;         if constexpr (Epi::ROWSUM) {
;           float ss = 0.f;
; #pragma unroll
;           for (int n = 0; n < 8; ++n) {
;             const int col = nt * 256 + wc_e * 128 + n * 16 + fq_e * 4;
;             if (col < N) ss += epi.c4(g, rig, col, acc[m][n]);
;           }
;           ss += __shfl_xor(ss, 16); ss += __shfl_xor(ss, 32);
;           if (fq_e == 0) epi.rowsum(g, rig, nt * 2 + wc_e, ss);
;         } else {
; #pragma unroll
;           for (int n = 0; n < 8; ++n) {
;             const int col = nt * 256 + wc_e * 128 + n * 16 + fq_e * 4;
;             if (col < N) epi.c4(g, rig, col, acc[m][n]);
;           }
	v_lshlrev_b32_e32 v44, 16, v176
	v_and_b32_e32 v42, 0xffff0000, v176
	v_lshlrev_b32_e32 v45, 16, v177
	v_and_b32_e32 v43, 0xffff0000, v177
	v_fmac_f32_e32 v44, v30, v198
	v_fmac_f32_e32 v42, v31, v199
	v_fmac_f32_e32 v45, v32, v200
	v_fmac_f32_e32 v43, v33, v201
	v_cvt_pk_bf16_f32 v30, v44, v42
	v_cvt_pk_bf16_f32 v31, v45, v43
	v_lshl_add_u64 v[36:37], v[132:133], 1, v[34:35]
	v_add_f32_e32 v26, 0, v26
	v_add_f32_e32 v27, 0, v27
	v_add_f32_e32 v28, 0, v28
	v_add_f32_e32 v29, 0, v29
	s_waitcnt vmcnt(6)
	v_lshlrev_b32_e32 v40, 16, v178
	v_and_b32_e32 v38, 0xffff0000, v178
	v_lshlrev_b32_e32 v41, 16, v179
	v_and_b32_e32 v39, 0xffff0000, v179
	v_fmac_f32_e32 v40, v26, v202
	v_fmac_f32_e32 v38, v27, v203
	v_fmac_f32_e32 v41, v28, v204
	v_fmac_f32_e32 v39, v29, v205
	v_cvt_pk_bf16_f32 v32, v40, v38
	v_cvt_pk_bf16_f32 v33, v41, v39
	s_nop 1
	v_permlane16_swap_b32 v30, v32
	v_permlane16_swap_b32 v31, v33
	v_lshl_add_u64 v[248:249], v[36:37], 0, v[246:247]
	s_nop 0
	global_store_dwordx4 v[248:249], v[30:33], off
	s_nop 1
	v_lshl_add_u64 v[30:31], v[132:133], 1, v[34:35]
	v_add_f32_e32 v22, 0, v22
	v_add_f32_e32 v23, 0, v23
	v_add_f32_e32 v24, 0, v24
	v_add_f32_e32 v25, 0, v25
	s_waitcnt vmcnt(6)
	v_lshlrev_b32_e32 v36, 16, v180
	v_and_b32_e32 v32, 0xffff0000, v180
	v_lshlrev_b32_e32 v37, 16, v181
	v_and_b32_e32 v33, 0xffff0000, v181
	v_fmac_f32_e32 v36, v22, v206
	v_fmac_f32_e32 v32, v23, v207
	v_fmac_f32_e32 v37, v24, v208
	v_fmac_f32_e32 v33, v25, v209
	v_cvt_pk_bf16_f32 v22, v36, v32
	v_cvt_pk_bf16_f32 v23, v37, v33
	v_lshl_add_u64 v[26:27], v[132:133], 1, v[34:35]
	v_add_f32_e32 v18, 0, v18
	v_add_f32_e32 v19, 0, v19
	v_add_f32_e32 v20, 0, v20
	v_add_f32_e32 v21, 0, v21
	s_waitcnt vmcnt(5)
	v_lshlrev_b32_e32 v30, 16, v182
	v_and_b32_e32 v28, 0xffff0000, v182
	v_lshlrev_b32_e32 v31, 16, v183
	v_and_b32_e32 v29, 0xffff0000, v183
	v_fmac_f32_e32 v30, v18, v210
	v_fmac_f32_e32 v28, v19, v211
	v_fmac_f32_e32 v31, v20, v212
	v_fmac_f32_e32 v29, v21, v213
	v_cvt_pk_bf16_f32 v24, v30, v28
	v_cvt_pk_bf16_f32 v25, v31, v29
	s_nop 1
	v_permlane16_swap_b32 v22, v24
	v_permlane16_swap_b32 v23, v25
	v_lshl_add_u64 v[248:249], v[26:27], 0, v[246:247]
	s_nop 0
	global_store_dwordx4 v[248:249], v[22:25], off offset:64
	s_nop 1
	v_lshl_add_u64 v[22:23], v[132:133], 1, v[34:35]
	v_add_f32_e32 v14, 0, v14
	v_add_f32_e32 v15, 0, v15
	v_add_f32_e32 v16, 0, v16
	v_add_f32_e32 v17, 0, v17
	s_waitcnt vmcnt(5)
	v_lshlrev_b32_e32 v26, 16, v184
	v_and_b32_e32 v24, 0xffff0000, v184
	v_lshlrev_b32_e32 v27, 16, v185
	v_and_b32_e32 v25, 0xffff0000, v185
	v_fmac_f32_e32 v26, v14, v214
	v_fmac_f32_e32 v24, v15, v215
	v_fmac_f32_e32 v27, v16, v216
	v_fmac_f32_e32 v25, v17, v217
	v_cvt_pk_bf16_f32 v14, v26, v24
	v_cvt_pk_bf16_f32 v15, v27, v25
	v_lshl_add_u64 v[18:19], v[132:133], 1, v[34:35]
	v_add_f32_e32 v10, 0, v10
	v_add_f32_e32 v11, 0, v11
	v_add_f32_e32 v12, 0, v12
	v_add_f32_e32 v13, 0, v13
	s_waitcnt vmcnt(4)
	v_lshlrev_b32_e32 v22, 16, v186
	v_and_b32_e32 v20, 0xffff0000, v186
	v_lshlrev_b32_e32 v23, 16, v187
	v_and_b32_e32 v21, 0xffff0000, v187
	v_fmac_f32_e32 v22, v10, v224
	v_fmac_f32_e32 v20, v11, v225
	v_fmac_f32_e32 v23, v12, v226
	v_fmac_f32_e32 v21, v13, v227
	v_cvt_pk_bf16_f32 v16, v22, v20
	v_cvt_pk_bf16_f32 v17, v23, v21
	s_nop 1
	v_permlane16_swap_b32 v14, v16
	v_permlane16_swap_b32 v15, v17
	v_lshl_add_u64 v[248:249], v[18:19], 0, v[246:247]
	s_nop 0
	global_store_dwordx4 v[248:249], v[14:17], off offset:128
	s_nop 1
	v_lshl_add_u64 v[14:15], v[132:133], 1, v[34:35]
	v_add_f32_e32 v6, 0, v6
	v_add_f32_e32 v7, 0, v7
	v_add_f32_e32 v8, 0, v8
	v_add_f32_e32 v9, 0, v9
	s_waitcnt vmcnt(4)
	v_lshlrev_b32_e32 v18, 16, v188
	v_and_b32_e32 v16, 0xffff0000, v188
	v_lshlrev_b32_e32 v19, 16, v189
	v_and_b32_e32 v17, 0xffff0000, v189
	v_fmac_f32_e32 v18, v6, v228
	v_fmac_f32_e32 v16, v7, v229
	v_fmac_f32_e32 v19, v8, v230
	v_fmac_f32_e32 v17, v9, v231
	v_cvt_pk_bf16_f32 v6, v18, v16
	v_cvt_pk_bf16_f32 v7, v19, v17
	v_lshl_add_u64 v[10:11], v[132:133], 1, v[34:35]
	v_add_f32_e32 v2, 0, v2
	v_add_f32_e32 v3, 0, v3
	v_add_f32_e32 v4, 0, v4
	v_add_f32_e32 v5, 0, v5
	s_waitcnt vmcnt(3)
	v_lshlrev_b32_e32 v14, 16, v190
	v_and_b32_e32 v12, 0xffff0000, v190
	v_lshlrev_b32_e32 v15, 16, v191
	v_and_b32_e32 v13, 0xffff0000, v191
	v_fmac_f32_e32 v14, v2, v232
	v_fmac_f32_e32 v12, v3, v233
	v_fmac_f32_e32 v15, v4, v234
	v_fmac_f32_e32 v13, v5, v235
	v_cvt_pk_bf16_f32 v8, v14, v12
	v_cvt_pk_bf16_f32 v9, v15, v13
	s_nop 1
	v_permlane16_swap_b32 v6, v8
	v_permlane16_swap_b32 v7, v9
	v_lshl_add_u64 v[248:249], v[10:11], 0, v[246:247]
	s_nop 0
	global_store_dwordx4 v[248:249], v[6:9], off offset:192
	s_nop 1
	s_branch .LBB0_2427

; template <bool SWAP, class Epi, bool THIN = false> ...
;     ...
;     for (int st = 0; st < ns; ++st) {
;       asm volatile("s_waitcnt vmcnt(0)" ::: "memory");
;       __builtin_amdgcn_s_barrier();
;       asm volatile("" ::: "memory");
;       if (st + 1 < ns) {
;         char* nb = smem + ((st + 1) & 1) * 65536;
;         const int ko = (st + 1) * 64;
; #pragma unroll
;         for (int i = 0; i < 4; ++i) { GLDS16(A + (size_t)(ap[i] + ko), nb + tid * 16 + i * 8192); GLDS16(Bt + (size_t)(bp[i] + ko), nb + 32768 + tid * 16 + i * 8192); }
;       }
;       const char* sa = smem + (st & 1) * 65536 + (wr * 64 + fr) * 128;
;       const char* sb = smem + (st & 1) * 65536 + 32768 + (wc * 128 + fr) * 128;
;       if constexpr (THIN) {
;         if (wc == 0) {
; #pragma unroll
;           for (int ks = 0; ks < 2; ++ks) {
;             bf16x8 af[4], bf[2];
; #pragma unroll
;             for (int m = 0; m < 4; ++m) af[m] = *(const bf16x8*)(sa + m * 2048 + (((ks * 4 + fq) ^ swz) << 4));
; #pragma unroll
;             for (int n = 0; n < 2; ++n) bf[n] = *(const bf16x8*)(sb + n * 2048 + (((ks * 4 + fq) ^ swz) << 4));
; #pragma unroll
;             for (int m = 0; m < 4; ++m)
; #pragma unroll
;               for (int n = 0; n < 2; ++n)
;                 acc[m][n] = SWAP ? __builtin_amdgcn_mfma_f32_16x16x32_bf16(bf[n], af[m], acc[m][n], 0, 0, 0)
;                                  : __builtin_amdgcn_mfma_f32_16x16x32_bf16(af[m], bf[n], acc[m][n], 0, 0, 0);
;           }
;         }
;       } else {
;       bf16x8 afA[4], afB[4], bfb[2][2];
; #pragma unroll
;       for (int m = 0; m < 4; ++m) afA[m] = *(const bf16x8*)(sa + m * 2048 + ((fq ^ swz) << 4));
; #pragma unroll
;       for (int n = 0; n < 2; ++n) bfb[0][n] = *(const bf16x8*)(sb + n * 2048 + ((fq ^ swz) << 4));
; #pragma unroll
;       for (int gq = 0; gq < 8; ++gq) {
;         const int ks = gq >> 2, nh = gq & 3;
;         if (gq < 7) {
;           const int ks2 = (gq + 1) >> 2, nh2 = (gq + 1) & 3;
; #pragma unroll
;           for (int n = 0; n < 2; ++n) bfb[(gq + 1) & 1][n] = *(const bf16x8*)(sb + (nh2 * 2 + n) * 2048 + (((ks2 * 4 + fq) ^ swz) << 4));
;         }
;         if (gq == 3) {
; #pragma unroll
;           for (int m = 0; m < 4; ++m) afB[m] = *(const bf16x8*)(sa + m * 2048 + (((4 + fq) ^ swz) << 4));
;         }
;         __builtin_amdgcn_sched_barrier(0);
; #pragma unroll
.LBB0_2643:
	s_add_i32 s8, s7, 0x10000
	s_and_b32 s9, s8, 0x10000
	v_add_u32_e32 v167, s9, v142
	s_nop 0
	v_readfirstlane_b32 s9, v167
	s_and_b32 s7, s7, 0x10000
	v_add_u32_e32 v130, s7, v143
	v_add_u32_e32 v167, v130, v145
	s_waitcnt vmcnt(0)
	s_barrier
	ds_read_b128 v[168:171], v167
	ds_read_b128 v[172:175], v167 offset:2048
	ds_read_b128 v[176:179], v167 offset:4096
	ds_read_b128 v[180:183], v167 offset:6144
	v_or_b32_e32 v167, s7, v144
	v_add_u32_e32 v204, v167, v145
	ds_read_b128 v[184:187], v204 offset:32768
	ds_read_b128 v[188:191], v204 offset:34816
	ds_read_b128 v[192:195], v204 offset:36864
	ds_read_b128 v[196:199], v204 offset:38912
	v_add_u32_e32 v130, v130, v146
	s_waitcnt lgkmcnt(3)
	v_mfma_f32_16x16x32_bf16 v[126:129], v[184:187], v[168:171], v[126:129]
	s_mov_b32 m0, s9
	v_mfma_f32_16x16x32_bf16 v[110:113], v[184:187], v[172:175], v[110:113]
	global_load_lds_dwordx4 v139, s[18:19]
	v_add_u32_e32 v139, 0x80, v139
	v_mfma_f32_16x16x32_bf16 v[82:85], v[184:187], v[176:179], v[82:85]
	v_mfma_f32_16x16x32_bf16 v[50:53], v[184:187], v[180:183], v[50:53]
	ds_read_b128 v[184:187], v204 offset:40960
	ds_read_b128 v[200:203], v204 offset:43008
	s_waitcnt lgkmcnt(4)
	v_mfma_f32_16x16x32_bf16 v[122:125], v[188:191], v[168:171], v[122:125]
	s_add_u32 m0, s9, 0x8000
	v_mfma_f32_16x16x32_bf16 v[106:109], v[188:191], v[172:175], v[106:109]
	global_load_lds_dwordx4 v138, s[24:25]
	v_add_u32_e32 v138, 0x80, v138
	v_mfma_f32_16x16x32_bf16 v[78:81], v[188:191], v[176:179], v[78:81]
	v_mfma_f32_16x16x32_bf16 v[42:45], v[188:191], v[180:183], v[42:45]
	s_waitcnt lgkmcnt(3)
	v_mfma_f32_16x16x32_bf16 v[118:121], v[192:195], v[168:171], v[118:121]
	s_add_u32 m0, s9, 0x2000
	v_mfma_f32_16x16x32_bf16 v[94:97], v[192:195], v[172:175], v[94:97]
	global_load_lds_dwordx4 v137, s[18:19]
	v_add_u32_e32 v137, 0x80, v137
	v_mfma_f32_16x16x32_bf16 v[58:61], v[192:195], v[176:179], v[58:61]
	v_mfma_f32_16x16x32_bf16 v[26:29], v[192:195], v[180:183], v[26:29]
	ds_read_b128 v[188:191], v204 offset:45056
	ds_read_b128 v[192:195], v204 offset:47104
	s_waitcnt lgkmcnt(4)
	v_mfma_f32_16x16x32_bf16 v[114:117], v[196:199], v[168:171], v[114:117]
	s_add_u32 m0, s9, 0xa000
	v_mfma_f32_16x16x32_bf16 v[86:89], v[196:199], v[172:175], v[86:89]
	global_load_lds_dwordx4 v136, s[24:25]
	v_add_u32_e32 v136, 0x80, v136
	v_mfma_f32_16x16x32_bf16 v[54:57], v[196:199], v[176:179], v[54:57]
	v_mfma_f32_16x16x32_bf16 v[22:25], v[196:199], v[180:183], v[22:25]
	v_add_u32_e32 v167, v167, v146
	s_waitcnt lgkmcnt(3)
	v_mfma_f32_16x16x32_bf16 v[102:105], v[184:187], v[168:171], v[102:105]
	ds_read_b128 v[196:199], v167 offset:32768
	ds_read_b128 v[204:207], v167 offset:34816
	s_add_u32 m0, s9, 0x4000
	v_mfma_f32_16x16x32_bf16 v[74:77], v[184:187], v[172:175], v[74:77]
	global_load_lds_dwordx4 v135, s[18:19]
	v_add_u32_e32 v135, 0x80, v135
	v_mfma_f32_16x16x32_bf16 v[46:49], v[184:187], v[176:179], v[46:49]
	v_mfma_f32_16x16x32_bf16 v[10:13], v[184:187], v[180:183], v[10:13]
	ds_read_b128 v[184:187], v130
	ds_read_b128 v[208:211], v130 offset:2048
	ds_read_b128 v[212:215], v130 offset:4096
	ds_read_b128 v[216:219], v130 offset:6144
	s_waitcnt lgkmcnt(8)
	v_mfma_f32_16x16x32_bf16 v[98:101], v[200:203], v[168:171], v[98:101]
	s_add_u32 m0, s9, 0xc000
	v_mfma_f32_16x16x32_bf16 v[66:69], v[200:203], v[172:175], v[66:69]
	global_load_lds_dwordx4 v134, s[24:25]
	v_add_u32_e32 v134, 0x80, v134
	v_mfma_f32_16x16x32_bf16 v[30:33], v[200:203], v[176:179], v[30:33]
	v_mfma_f32_16x16x32_bf16 v[6:9], v[200:203], v[180:183], v[6:9]
	s_waitcnt lgkmcnt(7)
	v_mfma_f32_16x16x32_bf16 v[70:73], v[188:191], v[168:171], v[70:73]
	s_add_u32 m0, s9, 0x6000
	s_waitcnt lgkmcnt(6)
	v_mfma_f32_16x16x32_bf16 v[62:65], v[192:195], v[168:171], v[62:65]
	global_load_lds_dwordx4 v133, s[18:19]
	v_add_u32_e32 v133, 0x80, v133
	v_mfma_f32_16x16x32_bf16 v[38:41], v[188:191], v[172:175], v[38:41]
	v_mfma_f32_16x16x32_bf16 v[34:37], v[192:195], v[172:175], v[34:37]
	ds_read_b128 v[168:171], v167 offset:36864
	ds_read_b128 v[172:175], v167 offset:38912
	v_mfma_f32_16x16x32_bf16 v[18:21], v[188:191], v[176:179], v[18:21]
	s_add_u32 m0, s9, 0xe000
	v_mfma_f32_16x16x32_bf16 v[14:17], v[192:195], v[176:179], v[14:17]
	global_load_lds_dwordx4 v132, s[24:25]
	v_add_u32_e32 v132, 0x80, v132
	v_mfma_f32_16x16x32_bf16 v[2:5], v[188:191], v[180:183], v[2:5]
	v_mfma_f32_16x16x32_bf16 v[90:93], v[192:195], v[180:183], v[90:93]
	ds_read_b128 v[176:179], v167 offset:40960
	ds_read_b128 v[180:183], v167 offset:43008
	s_waitcnt lgkmcnt(7)
	v_mfma_f32_16x16x32_bf16 v[126:129], v[196:199], v[184:187], v[126:129]
	v_mfma_f32_16x16x32_bf16 v[122:125], v[204:207], v[184:187], v[122:125]
	s_waitcnt lgkmcnt(6)
	v_mfma_f32_16x16x32_bf16 v[110:113], v[196:199], v[208:211], v[110:113]
	v_mfma_f32_16x16x32_bf16 v[106:109], v[204:207], v[208:211], v[106:109]
	s_waitcnt lgkmcnt(5)
	v_mfma_f32_16x16x32_bf16 v[82:85], v[196:199], v[212:215], v[82:85]
	v_mfma_f32_16x16x32_bf16 v[78:81], v[204:207], v[212:215], v[78:81]
	s_waitcnt lgkmcnt(4)
	v_mfma_f32_16x16x32_bf16 v[50:53], v[196:199], v[216:219], v[50:53]
	v_mfma_f32_16x16x32_bf16 v[42:45], v[204:207], v[216:219], v[42:45]
	s_waitcnt lgkmcnt(3)
	v_mfma_f32_16x16x32_bf16 v[118:121], v[168:171], v[184:187], v[118:121]
	v_mfma_f32_16x16x32_bf16 v[94:97], v[168:171], v[208:211], v[94:97]
	v_mfma_f32_16x16x32_bf16 v[58:61], v[168:171], v[212:215], v[58:61]
	v_mfma_f32_16x16x32_bf16 v[26:29], v[168:171], v[216:219], v[26:29]
	ds_read_b128 v[168:171], v167 offset:45056
	ds_read_b128 v[188:191], v167 offset:47104
	s_waitcnt lgkmcnt(4)
; template <bool SWAP, class Epi, bool THIN = false> ...
;     ...
;       bf16x8 afA[4], afB[4], bfb[2][2];
; #pragma unroll
;       for (int m = 0; m < 4; ++m) afA[m] = *(const bf16x8*)(sa + m * 2048 + ((fq ^ swz) << 4));
; #pragma unroll
;       for (int n = 0; n < 2; ++n) bfb[0][n] = *(const bf16x8*)(sb + n * 2048 + ((fq ^ swz) << 4));
; #pragma unroll
;       for (int gq = 0; gq < 8; ++gq) {
;         const int ks = gq >> 2, nh = gq & 3;
;         if (gq < 7) {
;           const int ks2 = (gq + 1) >> 2, nh2 = (gq + 1) & 3;
; #pragma unroll
;           for (int n = 0; n < 2; ++n) bfb[(gq + 1) & 1][n] = *(const bf16x8*)(sb + (nh2 * 2 + n) * 2048 + (((ks2 * 4 + fq) ^ swz) << 4));
;         }
;         if (gq == 3) {
; #pragma unroll
;           for (int m = 0; m < 4; ++m) afB[m] = *(const bf16x8*)(sa + m * 2048 + (((4 + fq) ^ swz) << 4));
;         }
;         __builtin_amdgcn_sched_barrier(0);
; #pragma unroll
;         for (int m = 0; m < 4; ++m)
; #pragma unroll
;           for (int n = 0; n < 2; ++n) {
;             const bf16x8 av = ks ? afB[m] : afA[m];
;             acc[m][nh * 2 + n] = SWAP ? __builtin_amdgcn_mfma_f32_16x16x32_bf16(bfb[gq & 1][n], av, acc[m][nh * 2 + n], 0, 0, 0)
;                                       : __builtin_amdgcn_mfma_f32_16x16x32_bf16(av, bfb[gq & 1][n], acc[m][nh * 2 + n], 0, 0, 0);
;           }
;       }
;       }
	v_mfma_f32_16x16x32_bf16 v[114:117], v[172:175], v[184:187], v[114:117]
	v_mfma_f32_16x16x32_bf16 v[86:89], v[172:175], v[208:211], v[86:89]
	v_mfma_f32_16x16x32_bf16 v[54:57], v[172:175], v[212:215], v[54:57]
	v_mfma_f32_16x16x32_bf16 v[22:25], v[172:175], v[216:219], v[22:25]
	s_waitcnt lgkmcnt(3)
	v_mfma_f32_16x16x32_bf16 v[102:105], v[176:179], v[184:187], v[102:105]
	s_waitcnt lgkmcnt(2)
	v_mfma_f32_16x16x32_bf16 v[98:101], v[180:183], v[184:187], v[98:101]
	v_mfma_f32_16x16x32_bf16 v[74:77], v[176:179], v[208:211], v[74:77]
	v_mfma_f32_16x16x32_bf16 v[66:69], v[180:183], v[208:211], v[66:69]
	v_mfma_f32_16x16x32_bf16 v[46:49], v[176:179], v[212:215], v[46:49]
	v_mfma_f32_16x16x32_bf16 v[30:33], v[180:183], v[212:215], v[30:33]
	v_mfma_f32_16x16x32_bf16 v[10:13], v[176:179], v[216:219], v[10:13]
	v_mfma_f32_16x16x32_bf16 v[6:9], v[180:183], v[216:219], v[6:9]
	s_waitcnt lgkmcnt(1)
	v_mfma_f32_16x16x32_bf16 v[70:73], v[168:171], v[184:187], v[70:73]
	s_add_i32 s6, s6, 64
	s_cmpk_eq_i32 s6, 0x3c0
	s_mov_b32 s7, s8
	s_waitcnt lgkmcnt(0)
	v_mfma_f32_16x16x32_bf16 v[62:65], v[188:191], v[184:187], v[62:65]
	v_mfma_f32_16x16x32_bf16 v[38:41], v[168:171], v[208:211], v[38:41]
	v_mfma_f32_16x16x32_bf16 v[34:37], v[188:191], v[208:211], v[34:37]
	v_mfma_f32_16x16x32_bf16 v[18:21], v[168:171], v[212:215], v[18:21]
	v_mfma_f32_16x16x32_bf16 v[14:17], v[188:191], v[212:215], v[14:17]
	v_mfma_f32_16x16x32_bf16 v[2:5], v[168:171], v[216:219], v[2:5]
	v_mfma_f32_16x16x32_bf16 v[90:93], v[188:191], v[216:219], v[90:93]
	s_cbranch_scc0 .LBB0_2643
	s_waitcnt vmcnt(0)
	s_barrier
	v_add_u32_e32 v130, v157, v145
	ds_read_b128 v[132:135], v130
	ds_read_b128 v[136:139], v130 offset:2048
	ds_read_b128 v[168:171], v130 offset:4096
	ds_read_b128 v[172:175], v130 offset:6144
	v_add_u32_e32 v130, v158, v145
	ds_read_b128 v[176:179], v130
	ds_read_b128 v[180:183], v130 offset:2048
	ds_read_b128 v[184:187], v130 offset:4096
	ds_read_b128 v[188:191], v130 offset:6144
	s_waitcnt lgkmcnt(3)
	v_mfma_f32_16x16x32_bf16 v[126:129], v[176:179], v[132:135], v[126:129]
	v_mfma_f32_16x16x32_bf16 v[110:113], v[176:179], v[136:139], v[110:113]
	v_mfma_f32_16x16x32_bf16 v[82:85], v[176:179], v[168:171], v[82:85]
	v_mfma_f32_16x16x32_bf16 v[50:53], v[176:179], v[172:175], v[50:53]
	ds_read_b128 v[176:179], v130 offset:8192
	ds_read_b128 v[192:195], v130 offset:10240
	s_waitcnt lgkmcnt(4)
	v_mfma_f32_16x16x32_bf16 v[122:125], v[180:183], v[132:135], v[122:125]
	v_mfma_f32_16x16x32_bf16 v[106:109], v[180:183], v[136:139], v[106:109]
	v_mfma_f32_16x16x32_bf16 v[78:81], v[180:183], v[168:171], v[78:81]
	v_mfma_f32_16x16x32_bf16 v[42:45], v[180:183], v[172:175], v[42:45]
	s_waitcnt lgkmcnt(3)
	v_mfma_f32_16x16x32_bf16 v[118:121], v[184:187], v[132:135], v[118:121]
	v_mfma_f32_16x16x32_bf16 v[180:183], v[184:187], v[136:139], v[94:97]
	v_mfma_f32_16x16x32_bf16 v[200:203], v[184:187], v[168:171], v[58:61]
	s_waitcnt lgkmcnt(2)
	v_mfma_f32_16x16x32_bf16 v[204:207], v[188:191], v[168:171], v[54:57]
	v_mfma_f32_16x16x32_bf16 v[184:187], v[184:187], v[172:175], v[26:29]
	s_nop 2
	ds_read_b128 v[26:29], v130 offset:12288
	ds_read_b128 v[54:57], v130 offset:14336
	v_mfma_f32_16x16x32_bf16 v[114:117], v[188:191], v[132:135], v[114:117]
	v_mfma_f32_16x16x32_bf16 v[196:199], v[188:191], v[136:139], v[86:89]
	v_mfma_f32_16x16x32_bf16 v[188:191], v[188:191], v[172:175], v[22:25]
	v_add_u32_e32 v130, v158, v146
	s_waitcnt lgkmcnt(2)
	v_mfma_f32_16x16x32_bf16 v[208:211], v[192:195], v[168:171], v[30:33]
	ds_read_b128 v[22:25], v130
	ds_read_b128 v[86:89], v130 offset:2048
	s_nop 0
	v_add_u32_e32 v30, v157, v146
	v_mfma_f32_16x16x32_bf16 v[102:105], v[176:179], v[132:135], v[102:105]
	v_mfma_f32_16x16x32_bf16 v[74:77], v[176:179], v[136:139], v[74:77]
	v_mfma_f32_16x16x32_bf16 v[46:49], v[176:179], v[168:171], v[46:49]
	v_mfma_f32_16x16x32_bf16 v[10:13], v[176:179], v[172:175], v[10:13]
	ds_read_b128 v[176:179], v30
	ds_read_b128 v[212:215], v30 offset:2048
	ds_read_b128 v[216:219], v30 offset:4096
	ds_read_b128 v[220:223], v30 offset:6144
	v_mfma_f32_16x16x32_bf16 v[98:101], v[192:195], v[132:135], v[98:101]
	v_mfma_f32_16x16x32_bf16 v[66:69], v[192:195], v[136:139], v[66:69]
	v_mfma_f32_16x16x32_bf16 v[6:9], v[192:195], v[172:175], v[6:9]
	s_waitcnt lgkmcnt(7)
	v_mfma_f32_16x16x32_bf16 v[224:227], v[26:29], v[136:139], v[38:41]
	s_waitcnt lgkmcnt(6)
	v_mfma_f32_16x16x32_bf16 v[34:37], v[54:57], v[136:139], v[34:37]
	v_mfma_f32_16x16x32_bf16 v[136:139], v[26:29], v[168:171], v[18:21]
	v_mfma_f32_16x16x32_bf16 v[168:171], v[54:57], v[168:171], v[14:17]
	s_nop 2
	ds_read_b128 v[14:17], v130 offset:4096
	ds_read_b128 v[18:21], v130 offset:6144
	v_mfma_f32_16x16x32_bf16 v[192:195], v[26:29], v[132:135], v[70:73]
	v_mfma_f32_16x16x32_bf16 v[132:135], v[54:57], v[132:135], v[62:65]
	v_mfma_f32_16x16x32_bf16 v[2:5], v[26:29], v[172:175], v[2:5]
	v_mfma_f32_16x16x32_bf16 v[172:175], v[54:57], v[172:175], v[90:93]
	ds_read_b128 v[228:231], v130 offset:8192
	ds_read_b128 v[232:235], v130 offset:10240
	s_waitcnt lgkmcnt(7)
	v_mfma_f32_16x16x32_bf16 v[126:129], v[22:25], v[176:179], v[126:129]
	v_mfma_f32_16x16x32_bf16 v[122:125], v[86:89], v[176:179], v[122:125]
	s_waitcnt lgkmcnt(6)
	v_mfma_f32_16x16x32_bf16 v[94:97], v[22:25], v[212:215], v[110:113]
	v_mfma_f32_16x16x32_bf16 v[90:93], v[86:89], v[212:215], v[106:109]
	s_waitcnt lgkmcnt(5)
	v_mfma_f32_16x16x32_bf16 v[62:65], v[22:25], v[216:219], v[82:85]
	v_mfma_f32_16x16x32_bf16 v[58:61], v[86:89], v[216:219], v[78:81]
	s_waitcnt lgkmcnt(4)
	v_mfma_f32_16x16x32_bf16 v[30:33], v[22:25], v[220:223], v[50:53]
	v_mfma_f32_16x16x32_bf16 v[26:29], v[86:89], v[220:223], v[42:45]
	s_waitcnt lgkmcnt(3)
	v_mfma_f32_16x16x32_bf16 v[86:89], v[14:17], v[212:215], v[180:183]
	v_mfma_f32_16x16x32_bf16 v[22:25], v[14:17], v[220:223], v[184:187]
	s_nop 1
	ds_read_b128 v[180:183], v130 offset:12288
	ds_read_b128 v[184:187], v130 offset:14336
	v_mfma_f32_16x16x32_bf16 v[118:121], v[14:17], v[176:179], v[118:121]
	s_waitcnt lgkmcnt(4)
	v_mfma_f32_16x16x32_bf16 v[114:117], v[18:21], v[176:179], v[114:117]
	v_mfma_f32_16x16x32_bf16 v[82:85], v[18:21], v[212:215], v[196:199]
	v_mfma_f32_16x16x32_bf16 v[54:57], v[14:17], v[216:219], v[200:203]
	v_mfma_f32_16x16x32_bf16 v[50:53], v[18:21], v[216:219], v[204:207]
	v_mfma_f32_16x16x32_bf16 v[18:21], v[18:21], v[220:223], v[188:191]
	s_waitcnt lgkmcnt(3)
	v_mfma_f32_16x16x32_bf16 v[110:113], v[228:231], v[176:179], v[102:105]
	s_waitcnt lgkmcnt(2)
	v_mfma_f32_16x16x32_bf16 v[106:109], v[232:235], v[176:179], v[98:101]
	v_mfma_f32_16x16x32_bf16 v[78:81], v[228:231], v[212:215], v[74:77]
	v_mfma_f32_16x16x32_bf16 v[70:73], v[232:235], v[212:215], v[66:69]
	v_mfma_f32_16x16x32_bf16 v[46:49], v[228:231], v[216:219], v[46:49]
	v_mfma_f32_16x16x32_bf16 v[38:41], v[232:235], v[216:219], v[208:211]
	v_mfma_f32_16x16x32_bf16 v[14:17], v[228:231], v[220:223], v[10:13]
	v_mfma_f32_16x16x32_bf16 v[6:9], v[232:235], v[220:223], v[6:9]
	v_mov_b32_e32 v130, v1
	s_waitcnt vmcnt(0) lgkmcnt(0)
	s_barrier
; __device__ __forceinline__ int get_tid512() { int t = threadIdx.x; asm volatile("" : "+v"(t)); return t; }
; __device__ __forceinline__ unsigned pack2(float a, float b) { unsigned r; asm("v_cvt_pk_bf16_f32 %0, %1, %2" : "=v"(r) : "v"(a), "v"(b)); return r; }
;   __device__ __forceinline__ void c4(int g, int rig, int col, f32x4 v) const {
;     const size_t row = (size_t)g * 2048 + rig;
;     const f32x4 b4 = *(const f32x4*)(bias + col);
;     uint2 u; u.x = pack2(v[0] + b4[0], v[1] + b4[1]); u.y = pack2(v[2] + b4[2], v[3] + b4[3]);
;     *(uint2*)(out + row * ld + col) = u;
;   }
; template <bool SWAP, class Epi, bool THIN = false> ...
;     ...
;     __syncthreads();
;     const int te = get_tid512();
;     const int fr_e = te & 15, fq_e = (te & 63) >> 4, wr_e = te >> 7, wc_e = (te >> 6) & 1;
;     const int sub = 2 * mt + (wr_e >> 1);
;     const int g = sub / tpg, ti = sub - g * tpg;
;     const int rig0 = ti * step - halo;
;     const int rw = (wr_e & 1) * 64;
;     if constexpr (Epi::KIND == 0) {
; #pragma unroll
;       for (int m = 0; m < 4; ++m) {
;         const int rig = rig0 + rw + m * 16 + fr_e;
;         if constexpr (Epi::ROWSUM) {
;           float ss = 0.f;
; #pragma unroll
;           for (int n = 0; n < 8; ++n) {
;             const int col = nt * 256 + wc_e * 128 + n * 16 + fq_e * 4;
;             if (col < N) ss += epi.c4(g, rig, col, acc[m][n]);
;           }
;           ss += __shfl_xor(ss, 16); ss += __shfl_xor(ss, 32);
;           if (fq_e == 0) epi.rowsum(g, rig, nt * 2 + wc_e, ss);
;         } else {
; #pragma unroll
;           for (int n = 0; n < 8; ++n) {
;             const int col = nt * 256 + wc_e * 128 + n * 16 + fq_e * 4;
;             if (col < N) epi.c4(g, rig, col, acc[m][n]);
;           }
;         }
;       }
	v_mfma_f32_16x16x32_bf16 v[102:105], v[180:183], v[176:179], v[192:195]
	v_ashrrev_i32_e32 v11, 8, v130
	v_add_u32_e32 v11, s5, v11
	v_ashrrev_i32_e32 v12, 31, v11
	v_lshrrev_b32_e32 v12, 28, v12
	v_add_u32_e32 v12, v11, v12
	v_mfma_f32_16x16x32_bf16 v[98:101], v[184:187], v[176:179], v[132:135]
	v_ashrrev_i32_e32 v176, 4, v12
	v_lshlrev_b32_e32 v12, 11, v176
	v_lshlrev_b32_e32 v11, 7, v11
	v_sub_u32_e32 v11, v11, v12
	v_lshrrev_b32_e32 v12, 1, v130
	v_and_b32_e32 v10, 15, v130
	v_bfe_u32 v246, v130, 4, 1
	v_mul_u32_u24_e32 v246, 24, v246
	v_mov_b32_e32 v247, 0
	v_and_b32_e32 v12, 64, v12
	v_or3_b32 v134, v11, v12, v10
	v_lshlrev_b32_e32 v10, 1, v130
	v_and_b32_e32 v132, 0x80, v10
	v_mfma_f32_16x16x32_bf16 v[10:13], v[180:183], v[220:223], v[2:5]
	v_ashrrev_i32_e32 v177, 31, v176
	v_ashrrev_i32_e32 v135, 31, v134
	s_nop 0
	v_lshrrev_b32_e32 v2, 2, v130
	v_and_b32_e32 v2, 12, v2
	v_mfma_f32_16x16x32_bf16 v[74:77], v[180:183], v[212:215], v[224:227]
	v_or3_b32 v132, v2, v132, s4
	v_cmp_gt_i32_e32 vcc, s31, v132
	v_ashrrev_i32_e32 v133, 31, v132
	v_mfma_f32_16x16x32_bf16 v[66:69], v[184:187], v[212:215], v[34:37]
	v_mfma_f32_16x16x32_bf16 v[42:45], v[180:183], v[216:219], v[136:139]
	v_mfma_f32_16x16x32_bf16 v[34:37], v[184:187], v[216:219], v[168:171]
	s_nop 1
	v_lshlrev_b64 v[136:137], 11, v[176:177]
	v_lshl_add_u64 v[138:139], v[136:137], 0, v[134:135]
	v_lshlrev_b64 v[138:139], 11, v[138:139]
	v_mfma_f32_16x16x32_bf16 v[2:5], v[184:187], v[220:223], v[172:175]
	v_lshl_add_u64 v[138:139], s[20:21], 0, v[138:139]
	v_lshl_add_u64 v[188:189], v[132:133], 2, s[22:23]
	global_load_dwordx4 v[196:199], v[188:189], off
	global_load_dwordx4 v[200:203], v[188:189], off offset:64
	global_load_dwordx4 v[204:207], v[188:189], off offset:128
	global_load_dwordx4 v[208:211], v[188:189], off offset:192
	global_load_dwordx4 v[228:231], v[188:189], off offset:256
	global_load_dwordx4 v[232:235], v[188:189], off offset:320
	global_load_dwordx4 v[236:239], v[188:189], off offset:384
	global_load_dwordx4 v[240:243], v[188:189], off offset:448
	s_waitcnt vmcnt(0)
	v_add_f32_e32 v126, v126, v196
	v_add_f32_e32 v127, v127, v197
	v_add_f32_e32 v128, v128, v198
	v_add_f32_e32 v129, v129, v199
	v_cvt_pk_bf16_f32 v126, v126, v127
	v_cvt_pk_bf16_f32 v127, v128, v129
	v_add_f32_e32 v122, v122, v200
	v_add_f32_e32 v123, v123, v201
	v_add_f32_e32 v124, v124, v202
	v_add_f32_e32 v125, v125, v203
	v_cvt_pk_bf16_f32 v128, v122, v123
	v_cvt_pk_bf16_f32 v129, v124, v125
	v_lshl_add_u64 v[124:125], v[132:133], 1, v[138:139]
	s_nop 1
	v_permlane16_swap_b32 v126, v128
	v_permlane16_swap_b32 v127, v129
	v_lshl_add_u64 v[248:249], v[124:125], 0, v[246:247]
	s_nop 0
	global_store_dwordx4 v[248:249], v[126:129], off
	s_nop 1
	v_or_b32_e32 v122, 32, v132
	v_add_f32_e32 v118, v118, v204
	v_add_f32_e32 v119, v119, v205
	v_add_f32_e32 v120, v120, v206
	v_add_f32_e32 v121, v121, v207
	v_cvt_pk_bf16_f32 v118, v118, v119
	v_cvt_pk_bf16_f32 v119, v120, v121
	v_add_f32_e32 v114, v114, v208
	v_add_f32_e32 v115, v115, v209
	v_add_f32_e32 v116, v116, v210
	v_add_f32_e32 v117, v117, v211
	v_cvt_pk_bf16_f32 v120, v114, v115
	v_cvt_pk_bf16_f32 v121, v116, v117
	v_lshl_add_u64 v[116:117], v[132:133], 1, v[138:139]
	s_nop 1
	v_permlane16_swap_b32 v118, v120
	v_permlane16_swap_b32 v119, v121
	v_lshl_add_u64 v[248:249], v[116:117], 0, v[246:247]
	s_nop 0
	global_store_dwordx4 v[248:249], v[118:121], off offset:64
	s_nop 1
	v_or_b32_e32 v114, 64, v132
	v_add_f32_e32 v110, v110, v228
	v_add_f32_e32 v111, v111, v229
	v_add_f32_e32 v112, v112, v230
	v_add_f32_e32 v113, v113, v231
	v_cvt_pk_bf16_f32 v110, v110, v111
	v_cvt_pk_bf16_f32 v111, v112, v113
	v_add_f32_e32 v106, v106, v232
	v_add_f32_e32 v107, v107, v233
	v_add_f32_e32 v108, v108, v234
	v_add_f32_e32 v109, v109, v235
	v_cvt_pk_bf16_f32 v112, v106, v107
	v_cvt_pk_bf16_f32 v113, v108, v109
	v_lshl_add_u64 v[108:109], v[132:133], 1, v[138:139]
	s_nop 1
	v_permlane16_swap_b32 v110, v112
	v_permlane16_swap_b32 v111, v113
	v_lshl_add_u64 v[248:249], v[108:109], 0, v[246:247]
	s_nop 0
	global_store_dwordx4 v[248:249], v[110:113], off offset:128
	s_nop 1
	v_or_b32_e32 v106, 0x60, v132
	v_add_f32_e32 v102, v102, v236
	v_add_f32_e32 v103, v103, v237
	v_add_f32_e32 v104, v104, v238
	v_add_f32_e32 v105, v105, v239
	v_cvt_pk_bf16_f32 v102, v102, v103
	v_cvt_pk_bf16_f32 v103, v104, v105
	v_add_f32_e32 v98, v98, v240
	v_add_f32_e32 v99, v99, v241
	v_add_f32_e32 v100, v100, v242
	v_add_f32_e32 v101, v101, v243
	v_cvt_pk_bf16_f32 v104, v98, v99
	v_cvt_pk_bf16_f32 v105, v100, v101
	v_lshl_add_u64 v[100:101], v[132:133], 1, v[138:139]
	s_nop 1
	v_permlane16_swap_b32 v102, v104
	v_permlane16_swap_b32 v103, v105
	v_lshl_add_u64 v[248:249], v[100:101], 0, v[246:247]
	s_nop 0
	global_store_dwordx4 v[248:249], v[102:105], off offset:192
	s_nop 1
	v_or_b32_e32 v98, 16, v134
	v_ashrrev_i32_e32 v99, 31, v98
	v_lshl_add_u64 v[98:99], v[136:137], 0, v[98:99]
	v_lshlrev_b64 v[98:99], 11, v[98:99]
	v_lshl_add_u64 v[98:99], s[20:21], 0, v[98:99]
	v_add_f32_e32 v94, v94, v196
	v_add_f32_e32 v95, v95, v197
	v_add_f32_e32 v96, v96, v198
	v_add_f32_e32 v97, v97, v199
	v_cvt_pk_bf16_f32 v94, v94, v95
	v_cvt_pk_bf16_f32 v95, v96, v97
	v_add_f32_e32 v90, v90, v200
	v_add_f32_e32 v91, v91, v201
	v_add_f32_e32 v92, v92, v202
	v_add_f32_e32 v93, v93, v203
	v_cvt_pk_bf16_f32 v96, v90, v91
	v_cvt_pk_bf16_f32 v97, v92, v93
	v_lshl_add_u64 v[92:93], v[132:133], 1, v[98:99]
	s_nop 1
	v_permlane16_swap_b32 v94, v96
	v_permlane16_swap_b32 v95, v97
	v_lshl_add_u64 v[248:249], v[92:93], 0, v[246:247]
	s_nop 0
	global_store_dwordx4 v[248:249], v[94:97], off
	s_nop 1
	v_add_f32_e32 v86, v86, v204
; __device__ __forceinline__ unsigned pack2(float a, float b) { unsigned r; asm("v_cvt_pk_bf16_f32 %0, %1, %2" : "=v"(r) : "v"(a), "v"(b)); return r; }
;   __device__ __forceinline__ void c4(int g, int rig, int col, f32x4 v) const {
;     const size_t row = (size_t)g * 2048 + rig;
;     const f32x4 b4 = *(const f32x4*)(bias + col);
;     uint2 u; u.x = pack2(v[0] + b4[0], v[1] + b4[1]); u.y = pack2(v[2] + b4[2], v[3] + b4[3]);
;     *(uint2*)(out + row * ld + col) = u;
;   }
; template <bool SWAP, class Epi, bool THIN = false> ...
;     ...
;         } else {
; #pragma unroll
;           for (int n = 0; n < 8; ++n) {
;             const int col = nt * 256 + wc_e * 128 + n * 16 + fq_e * 4;
;             if (col < N) epi.c4(g, rig, col, acc[m][n]);
;           }
;         }
	v_add_f32_e32 v87, v87, v205
	v_add_f32_e32 v88, v88, v206
	v_add_f32_e32 v89, v89, v207
	v_cvt_pk_bf16_f32 v86, v86, v87
	v_cvt_pk_bf16_f32 v87, v88, v89
	v_add_f32_e32 v82, v82, v208
	v_add_f32_e32 v83, v83, v209
	v_add_f32_e32 v84, v84, v210
	v_add_f32_e32 v85, v85, v211
	v_cvt_pk_bf16_f32 v88, v82, v83
	v_cvt_pk_bf16_f32 v89, v84, v85
	v_lshl_add_u64 v[84:85], v[132:133], 1, v[98:99]
	s_nop 1
	v_permlane16_swap_b32 v86, v88
	v_permlane16_swap_b32 v87, v89
	v_lshl_add_u64 v[248:249], v[84:85], 0, v[246:247]
	s_nop 0
	global_store_dwordx4 v[248:249], v[86:89], off offset:64
	s_nop 1
	v_add_f32_e32 v78, v78, v228
	v_add_f32_e32 v79, v79, v229
	v_add_f32_e32 v80, v80, v230
	v_add_f32_e32 v81, v81, v231
	v_cvt_pk_bf16_f32 v78, v78, v79
	v_cvt_pk_bf16_f32 v79, v80, v81
	v_add_f32_e32 v70, v70, v232
	v_add_f32_e32 v71, v71, v233
	v_add_f32_e32 v72, v72, v234
	v_add_f32_e32 v73, v73, v235
	v_cvt_pk_bf16_f32 v80, v70, v71
	v_cvt_pk_bf16_f32 v81, v72, v73
	v_lshl_add_u64 v[72:73], v[132:133], 1, v[98:99]
	s_nop 1
	v_permlane16_swap_b32 v78, v80
	v_permlane16_swap_b32 v79, v81
	v_lshl_add_u64 v[248:249], v[72:73], 0, v[246:247]
	s_nop 0
	global_store_dwordx4 v[248:249], v[78:81], off offset:128
	s_nop 1
	v_add_f32_e32 v70, v74, v236
	v_add_f32_e32 v71, v75, v237
	v_add_f32_e32 v72, v76, v238
	v_add_f32_e32 v73, v77, v239
	v_cvt_pk_bf16_f32 v70, v70, v71
	v_cvt_pk_bf16_f32 v71, v72, v73
	v_add_f32_e32 v66, v66, v240
	v_add_f32_e32 v67, v67, v241
	v_add_f32_e32 v68, v68, v242
	v_add_f32_e32 v69, v69, v243
	v_cvt_pk_bf16_f32 v72, v66, v67
	v_cvt_pk_bf16_f32 v73, v68, v69
	v_lshl_add_u64 v[68:69], v[132:133], 1, v[98:99]
	s_nop 1
	v_permlane16_swap_b32 v70, v72
	v_permlane16_swap_b32 v71, v73
	v_lshl_add_u64 v[248:249], v[68:69], 0, v[246:247]
	s_nop 0
	global_store_dwordx4 v[248:249], v[70:73], off offset:192
	s_nop 1
	v_or_b32_e32 v66, 32, v134
	v_ashrrev_i32_e32 v67, 31, v66
	v_lshl_add_u64 v[66:67], v[136:137], 0, v[66:67]
	v_lshlrev_b64 v[66:67], 11, v[66:67]
	v_lshl_add_u64 v[66:67], s[20:21], 0, v[66:67]
	v_add_f32_e32 v62, v62, v196
	v_add_f32_e32 v63, v63, v197
	v_add_f32_e32 v64, v64, v198
	v_add_f32_e32 v65, v65, v199
	v_cvt_pk_bf16_f32 v62, v62, v63
	v_cvt_pk_bf16_f32 v63, v64, v65
	v_add_f32_e32 v58, v58, v200
	v_add_f32_e32 v59, v59, v201
	v_add_f32_e32 v60, v60, v202
	v_add_f32_e32 v61, v61, v203
	v_cvt_pk_bf16_f32 v64, v58, v59
	v_cvt_pk_bf16_f32 v65, v60, v61
	v_lshl_add_u64 v[60:61], v[132:133], 1, v[66:67]
	s_nop 1
	v_permlane16_swap_b32 v62, v64
	v_permlane16_swap_b32 v63, v65
	v_lshl_add_u64 v[248:249], v[60:61], 0, v[246:247]
	s_nop 0
	global_store_dwordx4 v[248:249], v[62:65], off
	s_nop 1
	v_add_f32_e32 v54, v54, v204
	v_add_f32_e32 v55, v55, v205
	v_add_f32_e32 v56, v56, v206
	v_add_f32_e32 v57, v57, v207
	v_cvt_pk_bf16_f32 v54, v54, v55
	v_cvt_pk_bf16_f32 v55, v56, v57
	v_add_f32_e32 v50, v50, v208
	v_add_f32_e32 v51, v51, v209
	v_add_f32_e32 v52, v52, v210
	v_add_f32_e32 v53, v53, v211
	v_cvt_pk_bf16_f32 v56, v50, v51
	v_cvt_pk_bf16_f32 v57, v52, v53
	v_lshl_add_u64 v[52:53], v[132:133], 1, v[66:67]
	s_nop 1
	v_permlane16_swap_b32 v54, v56
	v_permlane16_swap_b32 v55, v57
	v_lshl_add_u64 v[248:249], v[52:53], 0, v[246:247]
	s_nop 0
	global_store_dwordx4 v[248:249], v[54:57], off offset:64
	s_nop 1
	v_add_f32_e32 v46, v46, v228
	v_add_f32_e32 v47, v47, v229
	v_add_f32_e32 v48, v48, v230
	v_add_f32_e32 v49, v49, v231
	v_cvt_pk_bf16_f32 v46, v46, v47
	v_cvt_pk_bf16_f32 v47, v48, v49
	v_add_f32_e32 v38, v38, v232
	v_add_f32_e32 v39, v39, v233
	v_add_f32_e32 v40, v40, v234
	v_add_f32_e32 v41, v41, v235
; __device__ __forceinline__ unsigned pack2(float a, float b) { unsigned r; asm("v_cvt_pk_bf16_f32 %0, %1, %2" : "=v"(r) : "v"(a), "v"(b)); return r; }
;   __device__ __forceinline__ void c4(int g, int rig, int col, f32x4 v) const {
;     const size_t row = (size_t)g * 2048 + rig;
;     const f32x4 b4 = *(const f32x4*)(bias + col);
;     uint2 u; u.x = pack2(v[0] + b4[0], v[1] + b4[1]); u.y = pack2(v[2] + b4[2], v[3] + b4[3]);
;     *(uint2*)(out + row * ld + col) = u;
;   }
; template <bool SWAP, class Epi, bool THIN = false> ...
;     ...
;         } else {
; #pragma unroll
;           for (int n = 0; n < 8; ++n) {
;             const int col = nt * 256 + wc_e * 128 + n * 16 + fq_e * 4;
;             if (col < N) epi.c4(g, rig, col, acc[m][n]);
;           }
;         }
	v_cvt_pk_bf16_f32 v48, v38, v39
	v_cvt_pk_bf16_f32 v49, v40, v41
	v_lshl_add_u64 v[40:41], v[132:133], 1, v[66:67]
	s_nop 1
	v_permlane16_swap_b32 v46, v48
	v_permlane16_swap_b32 v47, v49
	v_lshl_add_u64 v[248:249], v[40:41], 0, v[246:247]
	s_nop 0
	global_store_dwordx4 v[248:249], v[46:49], off offset:128
	s_nop 1
	v_add_f32_e32 v38, v42, v236
	v_add_f32_e32 v39, v43, v237
	v_add_f32_e32 v40, v44, v238
	v_add_f32_e32 v41, v45, v239
	v_cvt_pk_bf16_f32 v38, v38, v39
	v_cvt_pk_bf16_f32 v39, v40, v41
	v_add_f32_e32 v34, v34, v240
	v_add_f32_e32 v35, v35, v241
	v_add_f32_e32 v36, v36, v242
	v_add_f32_e32 v37, v37, v243
	v_cvt_pk_bf16_f32 v40, v34, v35
	v_cvt_pk_bf16_f32 v41, v36, v37
	v_lshl_add_u64 v[36:37], v[132:133], 1, v[66:67]
	s_nop 1
	v_permlane16_swap_b32 v38, v40
	v_permlane16_swap_b32 v39, v41
	v_lshl_add_u64 v[248:249], v[36:37], 0, v[246:247]
	s_nop 0
	global_store_dwordx4 v[248:249], v[38:41], off offset:192
	s_nop 1
	v_or_b32_e32 v34, 48, v134
	v_ashrrev_i32_e32 v35, 31, v34
	v_lshl_add_u64 v[34:35], v[136:137], 0, v[34:35]
	v_lshlrev_b64 v[34:35], 11, v[34:35]
	v_lshl_add_u64 v[34:35], s[20:21], 0, v[34:35]
	v_add_f32_e32 v30, v30, v196
	v_add_f32_e32 v31, v31, v197
	v_add_f32_e32 v32, v32, v198
	v_add_f32_e32 v33, v33, v199
	v_cvt_pk_bf16_f32 v30, v30, v31
	v_cvt_pk_bf16_f32 v31, v32, v33
	v_add_f32_e32 v26, v26, v200
	v_add_f32_e32 v27, v27, v201
	v_add_f32_e32 v28, v28, v202
	v_add_f32_e32 v29, v29, v203
	v_cvt_pk_bf16_f32 v32, v26, v27
	v_cvt_pk_bf16_f32 v33, v28, v29
	v_lshl_add_u64 v[28:29], v[132:133], 1, v[34:35]
	s_nop 1
	v_permlane16_swap_b32 v30, v32
	v_permlane16_swap_b32 v31, v33
	v_lshl_add_u64 v[248:249], v[28:29], 0, v[246:247]
	s_nop 0
	global_store_dwordx4 v[248:249], v[30:33], off
	s_nop 1
	v_add_f32_e32 v22, v22, v204
	v_add_f32_e32 v23, v23, v205
	v_add_f32_e32 v24, v24, v206
	v_add_f32_e32 v25, v25, v207
	v_cvt_pk_bf16_f32 v22, v22, v23
	v_cvt_pk_bf16_f32 v23, v24, v25
	v_add_f32_e32 v18, v18, v208
	v_add_f32_e32 v19, v19, v209
	v_add_f32_e32 v20, v20, v210
	v_add_f32_e32 v21, v21, v211
	v_cvt_pk_bf16_f32 v24, v18, v19
	v_cvt_pk_bf16_f32 v25, v20, v21
	v_lshl_add_u64 v[20:21], v[132:133], 1, v[34:35]
	s_nop 1
	v_permlane16_swap_b32 v22, v24
	v_permlane16_swap_b32 v23, v25
	v_lshl_add_u64 v[248:249], v[20:21], 0, v[246:247]
	s_nop 0
	global_store_dwordx4 v[248:249], v[22:25], off offset:64
	s_nop 1
	v_add_f32_e32 v14, v14, v228
	v_add_f32_e32 v15, v15, v229
	v_add_f32_e32 v16, v16, v230
	v_add_f32_e32 v17, v17, v231
	v_cvt_pk_bf16_f32 v14, v14, v15
	v_cvt_pk_bf16_f32 v15, v16, v17
	v_add_f32_e32 v6, v6, v232
	v_add_f32_e32 v7, v7, v233
	v_add_f32_e32 v8, v8, v234
	v_add_f32_e32 v9, v9, v235
	v_cvt_pk_bf16_f32 v16, v6, v7
	v_cvt_pk_bf16_f32 v17, v8, v9
	v_lshl_add_u64 v[8:9], v[132:133], 1, v[34:35]
	s_nop 1
	v_permlane16_swap_b32 v14, v16
	v_permlane16_swap_b32 v15, v17
	v_lshl_add_u64 v[248:249], v[8:9], 0, v[246:247]
	s_nop 0
	global_store_dwordx4 v[248:249], v[14:17], off offset:128
	s_nop 1
	v_add_f32_e32 v6, v10, v236
	v_add_f32_e32 v7, v11, v237
	v_add_f32_e32 v8, v12, v238
	v_add_f32_e32 v9, v13, v239
	v_cvt_pk_bf16_f32 v6, v6, v7
	v_cvt_pk_bf16_f32 v7, v8, v9
	v_add_f32_e32 v2, v2, v240
	v_add_f32_e32 v3, v3, v241
	v_add_f32_e32 v4, v4, v242
	v_add_f32_e32 v5, v5, v243
	v_cvt_pk_bf16_f32 v8, v2, v3
	v_cvt_pk_bf16_f32 v9, v4, v5
	v_lshl_add_u64 v[4:5], v[132:133], 1, v[34:35]
	s_nop 1
	v_permlane16_swap_b32 v6, v8
	v_permlane16_swap_b32 v7, v9
	v_lshl_add_u64 v[248:249], v[4:5], 0, v[246:247]
	s_nop 0
	global_store_dwordx4 v[248:249], v[6:9], off offset:192
	s_nop 1
	s_branch .LBB0_2641

; template <bool SWAP, class Epi, bool THIN = false> ...
;     ...
;     for (int st = 0; st < ns; ++st) {
;       asm volatile("s_waitcnt vmcnt(0)" ::: "memory");
;       __builtin_amdgcn_s_barrier();
;       asm volatile("" ::: "memory");
;       if (st + 1 < ns) {
;         char* nb = smem + ((st + 1) & 1) * 65536;
;         const int ko = (st + 1) * 64;
; #pragma unroll
;         for (int i = 0; i < 4; ++i) { GLDS16(A + (size_t)(ap[i] + ko), nb + tid * 16 + i * 8192); GLDS16(Bt + (size_t)(bp[i] + ko), nb + 32768 + tid * 16 + i * 8192); }
;       }
;       const char* sa = smem + (st & 1) * 65536 + (wr * 64 + fr) * 128;
;       const char* sb = smem + (st & 1) * 65536 + 32768 + (wc * 128 + fr) * 128;
;       if constexpr (THIN) {
;         if (wc == 0) {
; #pragma unroll
;           for (int ks = 0; ks < 2; ++ks) {
;             bf16x8 af[4], bf[2];
; #pragma unroll
;             for (int m = 0; m < 4; ++m) af[m] = *(const bf16x8*)(sa + m * 2048 + (((ks * 4 + fq) ^ swz) << 4));
; #pragma unroll
;             for (int n = 0; n < 2; ++n) bf[n] = *(const bf16x8*)(sb + n * 2048 + (((ks * 4 + fq) ^ swz) << 4));
; #pragma unroll
;             for (int m = 0; m < 4; ++m)
; #pragma unroll
;               for (int n = 0; n < 2; ++n)
;                 acc[m][n] = SWAP ? __builtin_amdgcn_mfma_f32_16x16x32_bf16(bf[n], af[m], acc[m][n], 0, 0, 0)
;                                  : __builtin_amdgcn_mfma_f32_16x16x32_bf16(af[m], bf[n], acc[m][n], 0, 0, 0);
;           }
;         }
;       } else {
;       bf16x8 afA[4], afB[4], bfb[2][2];
; #pragma unroll
;       for (int m = 0; m < 4; ++m) afA[m] = *(const bf16x8*)(sa + m * 2048 + ((fq ^ swz) << 4));
; #pragma unroll
;       for (int n = 0; n < 2; ++n) bfb[0][n] = *(const bf16x8*)(sb + n * 2048 + ((fq ^ swz) << 4));
; #pragma unroll
;       for (int gq = 0; gq < 8; ++gq) {
;         const int ks = gq >> 2, nh = gq & 3;
;         if (gq < 7) {
;           const int ks2 = (gq + 1) >> 2, nh2 = (gq + 1) & 3;
; #pragma unroll
;           for (int n = 0; n < 2; ++n) bfb[(gq + 1) & 1][n] = *(const bf16x8*)(sb + (nh2 * 2 + n) * 2048 + (((ks2 * 4 + fq) ^ swz) << 4));
;         }
;         if (gq == 3) {
; #pragma unroll
;           for (int m = 0; m < 4; ++m) afB[m] = *(const bf16x8*)(sa + m * 2048 + (((4 + fq) ^ swz) << 4));
;         }
;         __builtin_amdgcn_sched_barrier(0);
; #pragma unroll
.LBB0_2714:
	s_add_i32 s8, s7, 0x10000
	s_and_b32 s9, s8, 0x10000
	v_add_u32_e32 v167, s9, v138
	s_nop 0
	v_readfirstlane_b32 s9, v167
	s_and_b32 s7, s7, 0x10000
	v_add_u32_e32 v130, s7, v139
	v_add_u32_e32 v167, v130, v141
	s_waitcnt vmcnt(0)
	s_barrier
	ds_read_b128 v[168:171], v167
	ds_read_b128 v[172:175], v167 offset:2048
	ds_read_b128 v[176:179], v167 offset:4096
	ds_read_b128 v[180:183], v167 offset:6144
	v_or_b32_e32 v167, s7, v140
	v_add_u32_e32 v204, v167, v141
	ds_read_b128 v[184:187], v204 offset:32768
	ds_read_b128 v[188:191], v204 offset:34816
	ds_read_b128 v[192:195], v204 offset:36864
	ds_read_b128 v[196:199], v204 offset:38912
	v_add_u32_e32 v130, v130, v142
	s_waitcnt lgkmcnt(3)
	v_mfma_f32_16x16x32_bf16 v[126:129], v[168:171], v[184:187], v[126:129]
	s_mov_b32 m0, s9
	v_mfma_f32_16x16x32_bf16 v[110:113], v[172:175], v[184:187], v[110:113]
	global_load_lds_dwordx4 v166, s[18:19]
	v_add_u32_e32 v166, 0x80, v166
	v_mfma_f32_16x16x32_bf16 v[82:85], v[176:179], v[184:187], v[82:85]
	v_mfma_f32_16x16x32_bf16 v[50:53], v[180:183], v[184:187], v[50:53]
	ds_read_b128 v[184:187], v204 offset:40960
	ds_read_b128 v[200:203], v204 offset:43008
	s_waitcnt lgkmcnt(4)
	v_mfma_f32_16x16x32_bf16 v[122:125], v[168:171], v[188:191], v[122:125]
	s_add_u32 m0, s9, 0x8000
	v_mfma_f32_16x16x32_bf16 v[106:109], v[172:175], v[188:191], v[106:109]
	global_load_lds_dwordx4 v165, s[24:25]
	v_add_u32_e32 v165, 0x80, v165
	v_mfma_f32_16x16x32_bf16 v[78:81], v[176:179], v[188:191], v[78:81]
	v_mfma_f32_16x16x32_bf16 v[42:45], v[180:183], v[188:191], v[42:45]
	s_waitcnt lgkmcnt(3)
	v_mfma_f32_16x16x32_bf16 v[118:121], v[168:171], v[192:195], v[118:121]
	s_add_u32 m0, s9, 0x2000
	v_mfma_f32_16x16x32_bf16 v[94:97], v[172:175], v[192:195], v[94:97]
	global_load_lds_dwordx4 v164, s[18:19]
	v_add_u32_e32 v164, 0x80, v164
	v_mfma_f32_16x16x32_bf16 v[58:61], v[176:179], v[192:195], v[58:61]
	v_mfma_f32_16x16x32_bf16 v[26:29], v[180:183], v[192:195], v[26:29]
	ds_read_b128 v[188:191], v204 offset:45056
	ds_read_b128 v[192:195], v204 offset:47104
	s_waitcnt lgkmcnt(4)
	v_mfma_f32_16x16x32_bf16 v[114:117], v[168:171], v[196:199], v[114:117]
	s_add_u32 m0, s9, 0xa000
	v_mfma_f32_16x16x32_bf16 v[86:89], v[172:175], v[196:199], v[86:89]
	global_load_lds_dwordx4 v163, s[24:25]
	v_add_u32_e32 v163, 0x80, v163
	v_mfma_f32_16x16x32_bf16 v[54:57], v[176:179], v[196:199], v[54:57]
	v_mfma_f32_16x16x32_bf16 v[22:25], v[180:183], v[196:199], v[22:25]
	v_add_u32_e32 v167, v167, v142
	s_waitcnt lgkmcnt(3)
	v_mfma_f32_16x16x32_bf16 v[102:105], v[168:171], v[184:187], v[102:105]
	ds_read_b128 v[196:199], v167 offset:32768
	ds_read_b128 v[204:207], v167 offset:34816
	s_add_u32 m0, s9, 0x4000
	v_mfma_f32_16x16x32_bf16 v[74:77], v[172:175], v[184:187], v[74:77]
	global_load_lds_dwordx4 v135, s[18:19]
	v_add_u32_e32 v135, 0x80, v135
	v_mfma_f32_16x16x32_bf16 v[46:49], v[176:179], v[184:187], v[46:49]
	v_mfma_f32_16x16x32_bf16 v[10:13], v[180:183], v[184:187], v[10:13]
	ds_read_b128 v[184:187], v130
	ds_read_b128 v[208:211], v130 offset:2048
	ds_read_b128 v[212:215], v130 offset:4096
	ds_read_b128 v[216:219], v130 offset:6144
	s_waitcnt lgkmcnt(8)
	v_mfma_f32_16x16x32_bf16 v[98:101], v[168:171], v[200:203], v[98:101]
	s_add_u32 m0, s9, 0xc000
	v_mfma_f32_16x16x32_bf16 v[66:69], v[172:175], v[200:203], v[66:69]
	global_load_lds_dwordx4 v134, s[24:25]
	v_add_u32_e32 v134, 0x80, v134
	v_mfma_f32_16x16x32_bf16 v[30:33], v[176:179], v[200:203], v[30:33]
	v_mfma_f32_16x16x32_bf16 v[6:9], v[180:183], v[200:203], v[6:9]
	s_waitcnt lgkmcnt(7)
	v_mfma_f32_16x16x32_bf16 v[70:73], v[168:171], v[188:191], v[70:73]
	s_add_u32 m0, s9, 0x6000
	s_waitcnt lgkmcnt(6)
	v_mfma_f32_16x16x32_bf16 v[62:65], v[168:171], v[192:195], v[62:65]
	global_load_lds_dwordx4 v133, s[18:19]
	v_add_u32_e32 v133, 0x80, v133
	v_mfma_f32_16x16x32_bf16 v[38:41], v[172:175], v[188:191], v[38:41]
	v_mfma_f32_16x16x32_bf16 v[34:37], v[172:175], v[192:195], v[34:37]
	ds_read_b128 v[168:171], v167 offset:36864
	ds_read_b128 v[172:175], v167 offset:38912
	v_mfma_f32_16x16x32_bf16 v[18:21], v[176:179], v[188:191], v[18:21]
	s_add_u32 m0, s9, 0xe000
	v_mfma_f32_16x16x32_bf16 v[14:17], v[176:179], v[192:195], v[14:17]
	global_load_lds_dwordx4 v132, s[24:25]
	v_add_u32_e32 v132, 0x80, v132
	v_mfma_f32_16x16x32_bf16 v[2:5], v[180:183], v[188:191], v[2:5]
	v_mfma_f32_16x16x32_bf16 v[90:93], v[180:183], v[192:195], v[90:93]
	ds_read_b128 v[176:179], v167 offset:40960
	ds_read_b128 v[180:183], v167 offset:43008
	s_waitcnt lgkmcnt(7)
	v_mfma_f32_16x16x32_bf16 v[126:129], v[184:187], v[196:199], v[126:129]
	v_mfma_f32_16x16x32_bf16 v[122:125], v[184:187], v[204:207], v[122:125]
	s_waitcnt lgkmcnt(6)
	v_mfma_f32_16x16x32_bf16 v[110:113], v[208:211], v[196:199], v[110:113]
	v_mfma_f32_16x16x32_bf16 v[106:109], v[208:211], v[204:207], v[106:109]
	s_waitcnt lgkmcnt(5)
	v_mfma_f32_16x16x32_bf16 v[82:85], v[212:215], v[196:199], v[82:85]
	v_mfma_f32_16x16x32_bf16 v[78:81], v[212:215], v[204:207], v[78:81]
	s_waitcnt lgkmcnt(4)
	v_mfma_f32_16x16x32_bf16 v[50:53], v[216:219], v[196:199], v[50:53]
	v_mfma_f32_16x16x32_bf16 v[42:45], v[216:219], v[204:207], v[42:45]
	s_waitcnt lgkmcnt(3)
	v_mfma_f32_16x16x32_bf16 v[118:121], v[184:187], v[168:171], v[118:121]
	v_mfma_f32_16x16x32_bf16 v[94:97], v[208:211], v[168:171], v[94:97]
	v_mfma_f32_16x16x32_bf16 v[58:61], v[212:215], v[168:171], v[58:61]
	v_mfma_f32_16x16x32_bf16 v[26:29], v[216:219], v[168:171], v[26:29]
	ds_read_b128 v[168:171], v167 offset:45056
	ds_read_b128 v[188:191], v167 offset:47104
	s_waitcnt lgkmcnt(4)
; template <bool SWAP, class Epi, bool THIN = false> ...
;     ...
;       bf16x8 afA[4], afB[4], bfb[2][2];
; #pragma unroll
;       for (int m = 0; m < 4; ++m) afA[m] = *(const bf16x8*)(sa + m * 2048 + ((fq ^ swz) << 4));
; #pragma unroll
;       for (int n = 0; n < 2; ++n) bfb[0][n] = *(const bf16x8*)(sb + n * 2048 + ((fq ^ swz) << 4));
; #pragma unroll
;       for (int gq = 0; gq < 8; ++gq) {
;         const int ks = gq >> 2, nh = gq & 3;
;         if (gq < 7) {
;           const int ks2 = (gq + 1) >> 2, nh2 = (gq + 1) & 3;
; #pragma unroll
;           for (int n = 0; n < 2; ++n) bfb[(gq + 1) & 1][n] = *(const bf16x8*)(sb + (nh2 * 2 + n) * 2048 + (((ks2 * 4 + fq) ^ swz) << 4));
;         }
;         if (gq == 3) {
; #pragma unroll
;           for (int m = 0; m < 4; ++m) afB[m] = *(const bf16x8*)(sa + m * 2048 + (((4 + fq) ^ swz) << 4));
;         }
;         __builtin_amdgcn_sched_barrier(0);
; #pragma unroll
;         for (int m = 0; m < 4; ++m)
; #pragma unroll
;           for (int n = 0; n < 2; ++n) {
;             const bf16x8 av = ks ? afB[m] : afA[m];
;             acc[m][nh * 2 + n] = SWAP ? __builtin_amdgcn_mfma_f32_16x16x32_bf16(bfb[gq & 1][n], av, acc[m][nh * 2 + n], 0, 0, 0)
;                                       : __builtin_amdgcn_mfma_f32_16x16x32_bf16(av, bfb[gq & 1][n], acc[m][nh * 2 + n], 0, 0, 0);
;           }
;       }
;       }
	v_mfma_f32_16x16x32_bf16 v[114:117], v[184:187], v[172:175], v[114:117]
	v_mfma_f32_16x16x32_bf16 v[86:89], v[208:211], v[172:175], v[86:89]
	v_mfma_f32_16x16x32_bf16 v[54:57], v[212:215], v[172:175], v[54:57]
	v_mfma_f32_16x16x32_bf16 v[22:25], v[216:219], v[172:175], v[22:25]
	s_waitcnt lgkmcnt(3)
	v_mfma_f32_16x16x32_bf16 v[102:105], v[184:187], v[176:179], v[102:105]
	s_waitcnt lgkmcnt(2)
	v_mfma_f32_16x16x32_bf16 v[98:101], v[184:187], v[180:183], v[98:101]
	v_mfma_f32_16x16x32_bf16 v[74:77], v[208:211], v[176:179], v[74:77]
	v_mfma_f32_16x16x32_bf16 v[66:69], v[208:211], v[180:183], v[66:69]
	v_mfma_f32_16x16x32_bf16 v[46:49], v[212:215], v[176:179], v[46:49]
	v_mfma_f32_16x16x32_bf16 v[30:33], v[212:215], v[180:183], v[30:33]
	v_mfma_f32_16x16x32_bf16 v[10:13], v[216:219], v[176:179], v[10:13]
	v_mfma_f32_16x16x32_bf16 v[6:9], v[216:219], v[180:183], v[6:9]
	s_waitcnt lgkmcnt(1)
	v_mfma_f32_16x16x32_bf16 v[70:73], v[184:187], v[168:171], v[70:73]
	s_add_i32 s6, s6, 64
	s_cmpk_eq_i32 s6, 0x3c0
	s_mov_b32 s7, s8
	s_waitcnt lgkmcnt(0)
	v_mfma_f32_16x16x32_bf16 v[62:65], v[184:187], v[188:191], v[62:65]
	v_mfma_f32_16x16x32_bf16 v[38:41], v[208:211], v[168:171], v[38:41]
	v_mfma_f32_16x16x32_bf16 v[34:37], v[208:211], v[188:191], v[34:37]
	v_mfma_f32_16x16x32_bf16 v[18:21], v[212:215], v[168:171], v[18:21]
	v_mfma_f32_16x16x32_bf16 v[14:17], v[212:215], v[188:191], v[14:17]
	v_mfma_f32_16x16x32_bf16 v[2:5], v[216:219], v[168:171], v[2:5]
	v_mfma_f32_16x16x32_bf16 v[90:93], v[216:219], v[188:191], v[90:93]
	s_cbranch_scc0 .LBB0_2714
	s_waitcnt vmcnt(0)
	s_barrier
	v_add_u32_e32 v130, v153, v141
	ds_read_b128 v[132:135], v130
	ds_read_b128 v[164:167], v130 offset:2048
	ds_read_b128 v[168:171], v130 offset:4096
	ds_read_b128 v[172:175], v130 offset:6144
	v_add_u32_e32 v130, v154, v141
	ds_read_b128 v[176:179], v130
	ds_read_b128 v[180:183], v130 offset:2048
	ds_read_b128 v[184:187], v130 offset:4096
	ds_read_b128 v[188:191], v130 offset:6144
	s_waitcnt lgkmcnt(3)
	v_mfma_f32_16x16x32_bf16 v[126:129], v[132:135], v[176:179], v[126:129]
	v_mfma_f32_16x16x32_bf16 v[110:113], v[164:167], v[176:179], v[110:113]
	v_mfma_f32_16x16x32_bf16 v[82:85], v[168:171], v[176:179], v[82:85]
	v_mfma_f32_16x16x32_bf16 v[50:53], v[172:175], v[176:179], v[50:53]
	ds_read_b128 v[176:179], v130 offset:8192
	ds_read_b128 v[192:195], v130 offset:10240
	s_waitcnt lgkmcnt(4)
	v_mfma_f32_16x16x32_bf16 v[122:125], v[132:135], v[180:183], v[122:125]
	v_mfma_f32_16x16x32_bf16 v[106:109], v[164:167], v[180:183], v[106:109]
	v_mfma_f32_16x16x32_bf16 v[78:81], v[168:171], v[180:183], v[78:81]
	v_mfma_f32_16x16x32_bf16 v[42:45], v[172:175], v[180:183], v[42:45]
	s_waitcnt lgkmcnt(3)
	v_mfma_f32_16x16x32_bf16 v[118:121], v[132:135], v[184:187], v[118:121]
	v_mfma_f32_16x16x32_bf16 v[180:183], v[164:167], v[184:187], v[94:97]
	v_mfma_f32_16x16x32_bf16 v[200:203], v[168:171], v[184:187], v[58:61]
	s_waitcnt lgkmcnt(2)
	v_mfma_f32_16x16x32_bf16 v[204:207], v[168:171], v[188:191], v[54:57]
	v_mfma_f32_16x16x32_bf16 v[184:187], v[172:175], v[184:187], v[26:29]
	s_nop 2
	ds_read_b128 v[26:29], v130 offset:12288
	ds_read_b128 v[54:57], v130 offset:14336
	v_mfma_f32_16x16x32_bf16 v[114:117], v[132:135], v[188:191], v[114:117]
	v_mfma_f32_16x16x32_bf16 v[196:199], v[164:167], v[188:191], v[86:89]
	v_mfma_f32_16x16x32_bf16 v[188:191], v[172:175], v[188:191], v[22:25]
	v_add_u32_e32 v130, v154, v142
	s_waitcnt lgkmcnt(2)
	v_mfma_f32_16x16x32_bf16 v[208:211], v[168:171], v[192:195], v[30:33]
	ds_read_b128 v[22:25], v130
	ds_read_b128 v[86:89], v130 offset:2048
	s_nop 0
	v_add_u32_e32 v30, v153, v142
	v_mfma_f32_16x16x32_bf16 v[102:105], v[132:135], v[176:179], v[102:105]
	v_mfma_f32_16x16x32_bf16 v[74:77], v[164:167], v[176:179], v[74:77]
	v_mfma_f32_16x16x32_bf16 v[46:49], v[168:171], v[176:179], v[46:49]
	v_mfma_f32_16x16x32_bf16 v[10:13], v[172:175], v[176:179], v[10:13]
	ds_read_b128 v[176:179], v30
	ds_read_b128 v[212:215], v30 offset:2048
	ds_read_b128 v[216:219], v30 offset:4096
	ds_read_b128 v[220:223], v30 offset:6144
	v_mfma_f32_16x16x32_bf16 v[98:101], v[132:135], v[192:195], v[98:101]
	v_mfma_f32_16x16x32_bf16 v[66:69], v[164:167], v[192:195], v[66:69]
	v_mfma_f32_16x16x32_bf16 v[6:9], v[172:175], v[192:195], v[6:9]
	s_waitcnt lgkmcnt(7)
	v_mfma_f32_16x16x32_bf16 v[192:195], v[164:167], v[26:29], v[38:41]
	s_waitcnt lgkmcnt(6)
	v_mfma_f32_16x16x32_bf16 v[34:37], v[164:167], v[54:57], v[34:37]
	v_mfma_f32_16x16x32_bf16 v[164:167], v[168:171], v[26:29], v[18:21]
	v_mfma_f32_16x16x32_bf16 v[168:171], v[168:171], v[54:57], v[14:17]
	s_nop 2
	ds_read_b128 v[14:17], v130 offset:4096
	ds_read_b128 v[18:21], v130 offset:6144
	v_mfma_f32_16x16x32_bf16 v[70:73], v[132:135], v[26:29], v[70:73]
	v_mfma_f32_16x16x32_bf16 v[132:135], v[132:135], v[54:57], v[62:65]
	v_mfma_f32_16x16x32_bf16 v[2:5], v[172:175], v[26:29], v[2:5]
	v_mfma_f32_16x16x32_bf16 v[172:175], v[172:175], v[54:57], v[90:93]
	ds_read_b128 v[224:227], v130 offset:8192
	ds_read_b128 v[228:231], v130 offset:10240
	s_waitcnt lgkmcnt(7)
	v_mfma_f32_16x16x32_bf16 v[126:129], v[176:179], v[22:25], v[126:129]
	v_mfma_f32_16x16x32_bf16 v[122:125], v[176:179], v[86:89], v[122:125]
	s_waitcnt lgkmcnt(6)
	v_mfma_f32_16x16x32_bf16 v[94:97], v[212:215], v[22:25], v[110:113]
	v_mfma_f32_16x16x32_bf16 v[90:93], v[212:215], v[86:89], v[106:109]
	s_waitcnt lgkmcnt(5)
	v_mfma_f32_16x16x32_bf16 v[62:65], v[216:219], v[22:25], v[82:85]
	v_mfma_f32_16x16x32_bf16 v[58:61], v[216:219], v[86:89], v[78:81]
	s_waitcnt lgkmcnt(4)
	v_mfma_f32_16x16x32_bf16 v[30:33], v[220:223], v[22:25], v[50:53]
	v_mfma_f32_16x16x32_bf16 v[26:29], v[220:223], v[86:89], v[42:45]
	s_waitcnt lgkmcnt(3)
	v_mfma_f32_16x16x32_bf16 v[86:89], v[212:215], v[14:17], v[180:183]
	v_mfma_f32_16x16x32_bf16 v[22:25], v[220:223], v[14:17], v[184:187]
	s_nop 1
	ds_read_b128 v[180:183], v130 offset:12288
	ds_read_b128 v[184:187], v130 offset:14336
	v_mfma_f32_16x16x32_bf16 v[118:121], v[176:179], v[14:17], v[118:121]
	s_waitcnt lgkmcnt(4)
	v_mfma_f32_16x16x32_bf16 v[114:117], v[176:179], v[18:21], v[114:117]
	v_mfma_f32_16x16x32_bf16 v[82:85], v[212:215], v[18:21], v[196:199]
	v_mfma_f32_16x16x32_bf16 v[54:57], v[216:219], v[14:17], v[200:203]
	v_mfma_f32_16x16x32_bf16 v[50:53], v[216:219], v[18:21], v[204:207]
	v_mfma_f32_16x16x32_bf16 v[18:21], v[220:223], v[18:21], v[188:191]
	s_waitcnt lgkmcnt(3)
	v_mfma_f32_16x16x32_bf16 v[110:113], v[176:179], v[224:227], v[102:105]
	s_waitcnt lgkmcnt(2)
	v_mfma_f32_16x16x32_bf16 v[106:109], v[176:179], v[228:231], v[98:101]
	v_mfma_f32_16x16x32_bf16 v[78:81], v[212:215], v[224:227], v[74:77]
	v_mfma_f32_16x16x32_bf16 v[74:77], v[212:215], v[228:231], v[66:69]
	v_mfma_f32_16x16x32_bf16 v[46:49], v[216:219], v[224:227], v[46:49]
	v_mfma_f32_16x16x32_bf16 v[38:41], v[216:219], v[228:231], v[208:211]
	v_mfma_f32_16x16x32_bf16 v[14:17], v[220:223], v[224:227], v[10:13]
	v_mfma_f32_16x16x32_bf16 v[6:9], v[220:223], v[228:231], v[6:9]
	v_mov_b32_e32 v130, v1
	s_waitcnt vmcnt(0) lgkmcnt(0)
	s_barrier
; __device__ __forceinline__ unsigned pack2(float a, float b) { unsigned r; asm("v_cvt_pk_bf16_f32 %0, %1, %2" : "=v"(r) : "v"(a), "v"(b)); return r; }
;   __device__ __forceinline__ void r4(int g, int rig, int col, f32x4 v) const {
;     const float b = bias[col];
;     uint2 u; u.x = pack2(v[0] + b, v[1] + b); u.y = pack2(v[2] + b, v[3] + b);
;     *(uint2*)(out + (size_t)col * 16384 + (size_t)g * 2048 + rig) = u;
;   }
; template <bool SWAP, class Epi, bool THIN = false> ...
;     ...
;     } else if constexpr (Epi::KIND == 1) {
; #pragma unroll
;       for (int m = 0; m < 4; ++m) {
;         const int rig = rig0 + rw + m * 16 + fq_e * 4;
; #pragma unroll
;         for (int n = 0; n < 8; ++n) {
;           const int col = nt * 256 + wc_e * 128 + n * 16 + fr_e;
;           if (col < N) epi.r4(g, rig, col, acc[m][n]);
;         }
;       }
	v_mfma_f32_16x16x32_bf16 v[98:101], v[176:179], v[184:187], v[132:135]
	v_ashrrev_i32_e32 v10, 8, v130
	v_add_u32_e32 v10, s5, v10
	v_ashrrev_i32_e32 v11, 31, v10
	v_lshrrev_b32_e32 v11, 28, v11
	v_add_u32_e32 v11, v10, v11
	v_ashrrev_i32_e32 v132, 4, v11
	v_lshlrev_b32_e32 v11, 11, v132
	v_lshlrev_b32_e32 v10, 7, v10
	v_sub_u32_e32 v10, v10, v11
	v_lshrrev_b32_e32 v11, 1, v130
	v_lshrrev_b32_e32 v12, 2, v130
	v_and_b32_e32 v11, 64, v11
	v_and_b32_e32 v12, 12, v12
	v_mfma_f32_16x16x32_bf16 v[42:45], v[216:219], v[180:183], v[164:167]
	v_and_b32_e32 v133, 15, v130
	s_nop 1
	v_or3_b32 v164, v10, v11, v12
	v_mfma_f32_16x16x32_bf16 v[10:13], v[220:223], v[180:183], v[2:5]
	v_ashrrev_i32_e32 v165, 31, v164
	s_nop 1
	v_lshlrev_b32_e32 v2, 1, v130
	v_and_b32_e32 v2, 0x80, v2
	v_mfma_f32_16x16x32_bf16 v[102:105], v[176:179], v[180:183], v[70:73]
	v_or3_b32 v134, v133, v2, s4
	v_ashrrev_i32_e32 v133, 31, v132
	v_lshlrev_b64 v[132:133], 12, v[132:133]
	v_mfma_f32_16x16x32_bf16 v[70:73], v[212:215], v[180:183], v[192:195]
	v_lshl_add_u64 v[132:133], s[20:21], 0, v[132:133]
	v_lshl_add_u64 v[132:133], v[164:165], 1, v[132:133]
	v_cmp_gt_i32_e32 vcc, s30, v134
	v_mfma_f32_16x16x32_bf16 v[66:69], v[212:215], v[184:187], v[34:37]
	v_ashrrev_i32_e32 v135, 31, v134
	v_mfma_f32_16x16x32_bf16 v[34:37], v[216:219], v[184:187], v[168:171]
	v_mfma_f32_16x16x32_bf16 v[2:5], v[220:223], v[184:187], v[172:175]
	v_lshlrev_b32_e32 v236, 2, v134
	global_load_dword v237, v236, s[22:23]
	global_load_dword v238, v236, s[22:23] offset:64
	global_load_dword v239, v236, s[22:23] offset:128
	global_load_dword v240, v236, s[22:23] offset:192
	global_load_dword v241, v236, s[22:23] offset:256
	global_load_dword v242, v236, s[22:23] offset:320
	global_load_dword v243, v236, s[22:23] offset:384
	global_load_dword v244, v236, s[22:23] offset:448
	s_waitcnt vmcnt(0)
	v_bfe_u32 v246, v1, 4, 1
	v_mul_u32_u24_e32 v246, 24, v246
	v_mov_b32_e32 v247, 0
	v_lshlrev_b64 v[232:233], 15, v[134:135]
	v_lshl_add_u64 v[234:235], v[132:133], 0, v[232:233]
	v_lshl_add_u64 v[234:235], v[234:235], 0, v[246:247]
	v_add_f32_e32 v126, v126, v237
	v_add_f32_e32 v127, v127, v237
	v_add_f32_e32 v128, v128, v237
	v_add_f32_e32 v129, v129, v237
	v_add_f32_e32 v94, v94, v237
	v_add_f32_e32 v95, v95, v237
	v_add_f32_e32 v96, v96, v237
	v_add_f32_e32 v97, v97, v237
	v_cvt_pk_bf16_f32 v126, v126, v127
	v_cvt_pk_bf16_f32 v127, v128, v129
	v_cvt_pk_bf16_f32 v128, v94, v95
	v_cvt_pk_bf16_f32 v129, v96, v97
	s_nop 1
	v_permlane16_swap_b32 v126, v128
	v_permlane16_swap_b32 v127, v129
	global_store_dwordx4 v[234:235], v[126:129], off
	v_add_f32_e32 v62, v62, v237
	v_add_f32_e32 v63, v63, v237
	v_add_f32_e32 v64, v64, v237
	v_add_f32_e32 v65, v65, v237
	v_add_f32_e32 v30, v30, v237
	v_add_f32_e32 v31, v31, v237
	v_add_f32_e32 v32, v32, v237
	v_add_f32_e32 v33, v33, v237
	v_cvt_pk_bf16_f32 v62, v62, v63
	v_cvt_pk_bf16_f32 v63, v64, v65
	v_cvt_pk_bf16_f32 v64, v30, v31
	v_cvt_pk_bf16_f32 v65, v32, v33
	s_nop 1
	v_permlane16_swap_b32 v62, v64
	v_permlane16_swap_b32 v63, v65
	global_store_dwordx4 v[234:235], v[62:65], off offset:64
	s_nop 1
	v_or_b32_e32 v232, 16, v134
	v_ashrrev_i32_e32 v233, 31, v232
	v_lshlrev_b64 v[232:233], 15, v[232:233]
	v_lshl_add_u64 v[234:235], v[132:133], 0, v[232:233]
	v_lshl_add_u64 v[234:235], v[234:235], 0, v[246:247]
	v_add_f32_e32 v122, v122, v238
	v_add_f32_e32 v123, v123, v238
	v_add_f32_e32 v124, v124, v238
	v_add_f32_e32 v125, v125, v238
	v_add_f32_e32 v90, v90, v238
	v_add_f32_e32 v91, v91, v238
	v_add_f32_e32 v92, v92, v238
	v_add_f32_e32 v93, v93, v238
	v_cvt_pk_bf16_f32 v122, v122, v123
	v_cvt_pk_bf16_f32 v123, v124, v125
	v_cvt_pk_bf16_f32 v124, v90, v91
	v_cvt_pk_bf16_f32 v125, v92, v93
	s_nop 1
	v_permlane16_swap_b32 v122, v124
	v_permlane16_swap_b32 v123, v125
	global_store_dwordx4 v[234:235], v[122:125], off
	v_add_f32_e32 v58, v58, v238
	v_add_f32_e32 v59, v59, v238
	v_add_f32_e32 v60, v60, v238
	v_add_f32_e32 v61, v61, v238
	v_add_f32_e32 v26, v26, v238
	v_add_f32_e32 v27, v27, v238
	v_add_f32_e32 v28, v28, v238
	v_add_f32_e32 v29, v29, v238
	v_cvt_pk_bf16_f32 v58, v58, v59
	v_cvt_pk_bf16_f32 v59, v60, v61
	v_cvt_pk_bf16_f32 v60, v26, v27
	v_cvt_pk_bf16_f32 v61, v28, v29
	s_nop 1
	v_permlane16_swap_b32 v58, v60
	v_permlane16_swap_b32 v59, v61
	global_store_dwordx4 v[234:235], v[58:61], off offset:64
	s_nop 1
	v_or_b32_e32 v232, 32, v134
	v_ashrrev_i32_e32 v233, 31, v232
	v_lshlrev_b64 v[232:233], 15, v[232:233]
	v_lshl_add_u64 v[234:235], v[132:133], 0, v[232:233]
	v_lshl_add_u64 v[234:235], v[234:235], 0, v[246:247]
	v_add_f32_e32 v118, v118, v239
	v_add_f32_e32 v119, v119, v239
	v_add_f32_e32 v120, v120, v239
	v_add_f32_e32 v121, v121, v239
	v_add_f32_e32 v86, v86, v239
	v_add_f32_e32 v87, v87, v239
	v_add_f32_e32 v88, v88, v239
	v_add_f32_e32 v89, v89, v239
	v_cvt_pk_bf16_f32 v118, v118, v119
	v_cvt_pk_bf16_f32 v119, v120, v121
	v_cvt_pk_bf16_f32 v120, v86, v87
	v_cvt_pk_bf16_f32 v121, v88, v89
	s_nop 1
	v_permlane16_swap_b32 v118, v120
	v_permlane16_swap_b32 v119, v121
	global_store_dwordx4 v[234:235], v[118:121], off
	v_add_f32_e32 v54, v54, v239
	v_add_f32_e32 v55, v55, v239
	v_add_f32_e32 v56, v56, v239
	v_add_f32_e32 v57, v57, v239
	v_add_f32_e32 v22, v22, v239
	v_add_f32_e32 v23, v23, v239
	v_add_f32_e32 v24, v24, v239
	v_add_f32_e32 v25, v25, v239
	v_cvt_pk_bf16_f32 v54, v54, v55
	v_cvt_pk_bf16_f32 v55, v56, v57
	v_cvt_pk_bf16_f32 v56, v22, v23
	v_cvt_pk_bf16_f32 v57, v24, v25
	s_nop 1
	v_permlane16_swap_b32 v54, v56
	v_permlane16_swap_b32 v55, v57
	global_store_dwordx4 v[234:235], v[54:57], off offset:64
	s_nop 1
	v_or_b32_e32 v232, 48, v134
; __device__ __forceinline__ unsigned pack2(float a, float b) { unsigned r; asm("v_cvt_pk_bf16_f32 %0, %1, %2" : "=v"(r) : "v"(a), "v"(b)); return r; }
;   __device__ __forceinline__ void r4(int g, int rig, int col, f32x4 v) const {
;     const float b = bias[col];
;     uint2 u; u.x = pack2(v[0] + b, v[1] + b); u.y = pack2(v[2] + b, v[3] + b);
;     *(uint2*)(out + (size_t)col * 16384 + (size_t)g * 2048 + rig) = u;
;   }
; template <bool SWAP, class Epi, bool THIN = false> ...
;     ...
;     } else if constexpr (Epi::KIND == 1) {
; #pragma unroll
;       for (int m = 0; m < 4; ++m) {
;         const int rig = rig0 + rw + m * 16 + fq_e * 4;
; #pragma unroll
;         for (int n = 0; n < 8; ++n) {
;           const int col = nt * 256 + wc_e * 128 + n * 16 + fr_e;
;           if (col < N) epi.r4(g, rig, col, acc[m][n]);
;         }
;       }
	v_ashrrev_i32_e32 v233, 31, v232
	v_lshlrev_b64 v[232:233], 15, v[232:233]
	v_lshl_add_u64 v[234:235], v[132:133], 0, v[232:233]
	v_lshl_add_u64 v[234:235], v[234:235], 0, v[246:247]
	v_add_f32_e32 v114, v114, v240
	v_add_f32_e32 v115, v115, v240
	v_add_f32_e32 v116, v116, v240
	v_add_f32_e32 v117, v117, v240
	v_add_f32_e32 v82, v82, v240
	v_add_f32_e32 v83, v83, v240
	v_add_f32_e32 v84, v84, v240
	v_add_f32_e32 v85, v85, v240
	v_cvt_pk_bf16_f32 v114, v114, v115
	v_cvt_pk_bf16_f32 v115, v116, v117
	v_cvt_pk_bf16_f32 v116, v82, v83
	v_cvt_pk_bf16_f32 v117, v84, v85
	s_nop 1
	v_permlane16_swap_b32 v114, v116
	v_permlane16_swap_b32 v115, v117
	global_store_dwordx4 v[234:235], v[114:117], off
	v_add_f32_e32 v50, v50, v240
	v_add_f32_e32 v51, v51, v240
	v_add_f32_e32 v52, v52, v240
	v_add_f32_e32 v53, v53, v240
	v_add_f32_e32 v18, v18, v240
	v_add_f32_e32 v19, v19, v240
	v_add_f32_e32 v20, v20, v240
	v_add_f32_e32 v21, v21, v240
	v_cvt_pk_bf16_f32 v50, v50, v51
	v_cvt_pk_bf16_f32 v51, v52, v53
	v_cvt_pk_bf16_f32 v52, v18, v19
	v_cvt_pk_bf16_f32 v53, v20, v21
	s_nop 1
	v_permlane16_swap_b32 v50, v52
	v_permlane16_swap_b32 v51, v53
	global_store_dwordx4 v[234:235], v[50:53], off offset:64
	s_nop 1
	v_or_b32_e32 v232, 64, v134
	v_ashrrev_i32_e32 v233, 31, v232
	v_lshlrev_b64 v[232:233], 15, v[232:233]
	v_lshl_add_u64 v[234:235], v[132:133], 0, v[232:233]
	v_lshl_add_u64 v[234:235], v[234:235], 0, v[246:247]
	v_add_f32_e32 v110, v110, v241
	v_add_f32_e32 v111, v111, v241
	v_add_f32_e32 v112, v112, v241
	v_add_f32_e32 v113, v113, v241
	v_add_f32_e32 v78, v78, v241
	v_add_f32_e32 v79, v79, v241
	v_add_f32_e32 v80, v80, v241
	v_add_f32_e32 v81, v81, v241
	v_cvt_pk_bf16_f32 v110, v110, v111
	v_cvt_pk_bf16_f32 v111, v112, v113
	v_cvt_pk_bf16_f32 v112, v78, v79
	v_cvt_pk_bf16_f32 v113, v80, v81
	s_nop 1
	v_permlane16_swap_b32 v110, v112
	v_permlane16_swap_b32 v111, v113
	global_store_dwordx4 v[234:235], v[110:113], off
	v_add_f32_e32 v46, v46, v241
	v_add_f32_e32 v47, v47, v241
	v_add_f32_e32 v48, v48, v241
	v_add_f32_e32 v49, v49, v241
	v_add_f32_e32 v14, v14, v241
	v_add_f32_e32 v15, v15, v241
	v_add_f32_e32 v16, v16, v241
	v_add_f32_e32 v17, v17, v241
	v_cvt_pk_bf16_f32 v46, v46, v47
	v_cvt_pk_bf16_f32 v47, v48, v49
	v_cvt_pk_bf16_f32 v48, v14, v15
	v_cvt_pk_bf16_f32 v49, v16, v17
	s_nop 1
	v_permlane16_swap_b32 v46, v48
	v_permlane16_swap_b32 v47, v49
	global_store_dwordx4 v[234:235], v[46:49], off offset:64
	s_nop 1
	v_or_b32_e32 v232, 80, v134
	v_ashrrev_i32_e32 v233, 31, v232
	v_lshlrev_b64 v[232:233], 15, v[232:233]
	v_lshl_add_u64 v[234:235], v[132:133], 0, v[232:233]
	v_lshl_add_u64 v[234:235], v[234:235], 0, v[246:247]
	v_add_f32_e32 v106, v106, v242
	v_add_f32_e32 v107, v107, v242
	v_add_f32_e32 v108, v108, v242
	v_add_f32_e32 v109, v109, v242
	v_add_f32_e32 v74, v74, v242
	v_add_f32_e32 v75, v75, v242
	v_add_f32_e32 v76, v76, v242
	v_add_f32_e32 v77, v77, v242
	v_cvt_pk_bf16_f32 v106, v106, v107
	v_cvt_pk_bf16_f32 v107, v108, v109
	v_cvt_pk_bf16_f32 v108, v74, v75
	v_cvt_pk_bf16_f32 v109, v76, v77
	s_nop 1
	v_permlane16_swap_b32 v106, v108
	v_permlane16_swap_b32 v107, v109
	global_store_dwordx4 v[234:235], v[106:109], off
	v_add_f32_e32 v38, v38, v242
	v_add_f32_e32 v39, v39, v242
	v_add_f32_e32 v40, v40, v242
	v_add_f32_e32 v41, v41, v242
	v_add_f32_e32 v6, v6, v242
	v_add_f32_e32 v7, v7, v242
	v_add_f32_e32 v8, v8, v242
	v_add_f32_e32 v9, v9, v242
	v_cvt_pk_bf16_f32 v38, v38, v39
	v_cvt_pk_bf16_f32 v39, v40, v41
	v_cvt_pk_bf16_f32 v40, v6, v7
	v_cvt_pk_bf16_f32 v41, v8, v9
	s_nop 1
	v_permlane16_swap_b32 v38, v40
	v_permlane16_swap_b32 v39, v41
	global_store_dwordx4 v[234:235], v[38:41], off offset:64
	s_nop 1
	v_or_b32_e32 v232, 96, v134
	v_ashrrev_i32_e32 v233, 31, v232
	v_lshlrev_b64 v[232:233], 15, v[232:233]
	v_lshl_add_u64 v[234:235], v[132:133], 0, v[232:233]
	v_lshl_add_u64 v[234:235], v[234:235], 0, v[246:247]
	v_add_f32_e32 v102, v102, v243
	v_add_f32_e32 v103, v103, v243
	v_add_f32_e32 v104, v104, v243
	v_add_f32_e32 v105, v105, v243
	v_add_f32_e32 v70, v70, v243
	v_add_f32_e32 v71, v71, v243
	v_add_f32_e32 v72, v72, v243
	v_add_f32_e32 v73, v73, v243
	v_cvt_pk_bf16_f32 v102, v102, v103
	v_cvt_pk_bf16_f32 v103, v104, v105
	v_cvt_pk_bf16_f32 v104, v70, v71
	v_cvt_pk_bf16_f32 v105, v72, v73
	s_nop 1
	v_permlane16_swap_b32 v102, v104
	v_permlane16_swap_b32 v103, v105
	global_store_dwordx4 v[234:235], v[102:105], off
	v_add_f32_e32 v42, v42, v243
	v_add_f32_e32 v43, v43, v243
	v_add_f32_e32 v44, v44, v243
	v_add_f32_e32 v45, v45, v243
	v_add_f32_e32 v10, v10, v243
	v_add_f32_e32 v11, v11, v243
	v_add_f32_e32 v12, v12, v243
	v_add_f32_e32 v13, v13, v243
	v_cvt_pk_bf16_f32 v42, v42, v43
	v_cvt_pk_bf16_f32 v43, v44, v45
	v_cvt_pk_bf16_f32 v44, v10, v11
	v_cvt_pk_bf16_f32 v45, v12, v13
	s_nop 1
	v_permlane16_swap_b32 v42, v44
	v_permlane16_swap_b32 v43, v45
	global_store_dwordx4 v[234:235], v[42:45], off offset:64
	s_nop 1
	v_or_b32_e32 v232, 112, v134
	v_ashrrev_i32_e32 v233, 31, v232
	v_lshlrev_b64 v[232:233], 15, v[232:233]
	v_lshl_add_u64 v[234:235], v[132:133], 0, v[232:233]
	v_lshl_add_u64 v[234:235], v[234:235], 0, v[246:247]
	v_add_f32_e32 v98, v98, v244
	v_add_f32_e32 v99, v99, v244
	v_add_f32_e32 v100, v100, v244
	v_add_f32_e32 v101, v101, v244
	v_add_f32_e32 v66, v66, v244
	v_add_f32_e32 v67, v67, v244
	v_add_f32_e32 v68, v68, v244
	v_add_f32_e32 v69, v69, v244
	v_cvt_pk_bf16_f32 v98, v98, v99
	v_cvt_pk_bf16_f32 v99, v100, v101
	v_cvt_pk_bf16_f32 v100, v66, v67
	v_cvt_pk_bf16_f32 v101, v68, v69
	s_nop 1
	v_permlane16_swap_b32 v98, v100
	v_permlane16_swap_b32 v99, v101
	global_store_dwordx4 v[234:235], v[98:101], off
	v_add_f32_e32 v34, v34, v244
	v_add_f32_e32 v35, v35, v244
	v_add_f32_e32 v36, v36, v244
	v_add_f32_e32 v37, v37, v244
	v_add_f32_e32 v2, v2, v244
	v_add_f32_e32 v3, v3, v244
	v_add_f32_e32 v4, v4, v244
	v_add_f32_e32 v5, v5, v244
	v_cvt_pk_bf16_f32 v34, v34, v35
	v_cvt_pk_bf16_f32 v35, v36, v37
	v_cvt_pk_bf16_f32 v36, v2, v3
	v_cvt_pk_bf16_f32 v37, v4, v5
	s_nop 1
	v_permlane16_swap_b32 v34, v36
	v_permlane16_swap_b32 v35, v37
	global_store_dwordx4 v[234:235], v[34:37], off offset:64
	s_nop 1
	s_branch .LBB0_2712

; template <bool SWAP, class Epi, bool THIN = false> ...
;     ...
;     for (int st = 0; st < ns; ++st) {
;       asm volatile("s_waitcnt vmcnt(0)" ::: "memory");
;       __builtin_amdgcn_s_barrier();
;       asm volatile("" ::: "memory");
;       if (st + 1 < ns) {
;         char* nb = smem + ((st + 1) & 1) * 65536;
;         const int ko = (st + 1) * 64;
; #pragma unroll
;         for (int i = 0; i < 4; ++i) { GLDS16(A + (size_t)(ap[i] + ko), nb + tid * 16 + i * 8192); GLDS16(Bt + (size_t)(bp[i] + ko), nb + 32768 + tid * 16 + i * 8192); }
;       }
;       const char* sa = smem + (st & 1) * 65536 + (wr * 64 + fr) * 128;
;       const char* sb = smem + (st & 1) * 65536 + 32768 + (wc * 128 + fr) * 128;
;       if constexpr (THIN) {
;         if (wc == 0) {
; #pragma unroll
;           for (int ks = 0; ks < 2; ++ks) {
;             bf16x8 af[4], bf[2];
; #pragma unroll
;             for (int m = 0; m < 4; ++m) af[m] = *(const bf16x8*)(sa + m * 2048 + (((ks * 4 + fq) ^ swz) << 4));
; #pragma unroll
;             for (int n = 0; n < 2; ++n) bf[n] = *(const bf16x8*)(sb + n * 2048 + (((ks * 4 + fq) ^ swz) << 4));
; #pragma unroll
;             for (int m = 0; m < 4; ++m)
; #pragma unroll
;               for (int n = 0; n < 2; ++n)
;                 acc[m][n] = SWAP ? __builtin_amdgcn_mfma_f32_16x16x32_bf16(bf[n], af[m], acc[m][n], 0, 0, 0)
;                                  : __builtin_amdgcn_mfma_f32_16x16x32_bf16(af[m], bf[n], acc[m][n], 0, 0, 0);
;           }
;         }
;       } else {
;       bf16x8 afA[4], afB[4], bfb[2][2];
; #pragma unroll
;       for (int m = 0; m < 4; ++m) afA[m] = *(const bf16x8*)(sa + m * 2048 + ((fq ^ swz) << 4));
; #pragma unroll
;       for (int n = 0; n < 2; ++n) bfb[0][n] = *(const bf16x8*)(sb + n * 2048 + ((fq ^ swz) << 4));
; #pragma unroll
;       for (int gq = 0; gq < 8; ++gq) {
;         const int ks = gq >> 2, nh = gq & 3;
;         if (gq < 7) {
;           const int ks2 = (gq + 1) >> 2, nh2 = (gq + 1) & 3;
; #pragma unroll
;           for (int n = 0; n < 2; ++n) bfb[(gq + 1) & 1][n] = *(const bf16x8*)(sb + (nh2 * 2 + n) * 2048 + (((ks2 * 4 + fq) ^ swz) << 4));
;         }
;         if (gq == 3) {
; #pragma unroll
;           for (int m = 0; m < 4; ++m) afB[m] = *(const bf16x8*)(sa + m * 2048 + (((4 + fq) ^ swz) << 4));
;         }
;         __builtin_amdgcn_sched_barrier(0);
; #pragma unroll
.LBB0_3112:
	s_add_i32 s9, s7, 0x10000
	s_and_b32 s8, s9, 0x10000
	v_add_u32_e32 v142, s8, v156
	s_nop 0
	v_readfirstlane_b32 s10, v142
	s_and_b32 s7, s7, 0x10000
	v_add_u32_e32 v138, s7, v157
	v_add_u32_e32 v152, v138, v159
	s_waitcnt vmcnt(0)
	s_barrier
	ds_read_b128 v[140:143], v152
	ds_read_b128 v[144:147], v152 offset:2048
	ds_read_b128 v[148:151], v152 offset:4096
	ds_read_b128 v[180:183], v152 offset:6144
	v_or_b32_e32 v152, s7, v158
	v_add_u32_e32 v153, v152, v159
	ds_read_b128 v[184:187], v153 offset:32768
	ds_read_b128 v[188:191], v153 offset:34816
	ds_read_b128 v[192:195], v153 offset:36864
	ds_read_b128 v[196:199], v153 offset:38912
	v_add_u32_e32 v138, v138, v160
	s_waitcnt lgkmcnt(3)
	v_mfma_f32_16x16x32_bf16 v[126:129], v[184:187], v[140:143], v[126:129]
	s_mov_b32 m0, s10
	v_mfma_f32_16x16x32_bf16 v[110:113], v[184:187], v[144:147], v[110:113]
	global_load_lds_dwordx4 v137, s[22:23]
	v_add_u32_e32 v137, 0x80, v137
	v_mfma_f32_16x16x32_bf16 v[82:85], v[184:187], v[148:151], v[82:85]
	v_mfma_f32_16x16x32_bf16 v[50:53], v[184:187], v[180:183], v[50:53]
	ds_read_b128 v[184:187], v153 offset:40960
	ds_read_b128 v[200:203], v153 offset:43008
	s_waitcnt lgkmcnt(4)
	v_mfma_f32_16x16x32_bf16 v[122:125], v[188:191], v[140:143], v[122:125]
	s_add_u32 m0, s10, 0x8000
	v_mfma_f32_16x16x32_bf16 v[106:109], v[188:191], v[144:147], v[106:109]
	global_load_lds_dwordx4 v136, s[28:29]
	v_add_u32_e32 v136, 0x80, v136
	v_mfma_f32_16x16x32_bf16 v[78:81], v[188:191], v[148:151], v[78:81]
	v_mfma_f32_16x16x32_bf16 v[38:41], v[188:191], v[180:183], v[38:41]
	s_waitcnt lgkmcnt(3)
	v_mfma_f32_16x16x32_bf16 v[118:121], v[192:195], v[140:143], v[118:121]
	s_add_u32 m0, s10, 0x2000
	v_mfma_f32_16x16x32_bf16 v[94:97], v[192:195], v[144:147], v[94:97]
	global_load_lds_dwordx4 v135, s[22:23]
	v_add_u32_e32 v135, 0x80, v135
	v_mfma_f32_16x16x32_bf16 v[58:61], v[192:195], v[148:151], v[58:61]
	v_mfma_f32_16x16x32_bf16 v[26:29], v[192:195], v[180:183], v[26:29]
	ds_read_b128 v[188:191], v153 offset:45056
	ds_read_b128 v[192:195], v153 offset:47104
	s_waitcnt lgkmcnt(4)
	v_mfma_f32_16x16x32_bf16 v[114:117], v[196:199], v[140:143], v[114:117]
	s_add_u32 m0, s10, 0xa000
	v_mfma_f32_16x16x32_bf16 v[86:89], v[196:199], v[144:147], v[86:89]
	global_load_lds_dwordx4 v134, s[28:29]
	v_add_u32_e32 v134, 0x80, v134
	v_mfma_f32_16x16x32_bf16 v[54:57], v[196:199], v[148:151], v[54:57]
	v_mfma_f32_16x16x32_bf16 v[22:25], v[196:199], v[180:183], v[22:25]
	v_add_u32_e32 v152, v152, v160
	s_waitcnt lgkmcnt(3)
	v_mfma_f32_16x16x32_bf16 v[102:105], v[184:187], v[140:143], v[102:105]
	ds_read_b128 v[196:199], v152 offset:32768
	ds_read_b128 v[204:207], v152 offset:34816
	s_add_u32 m0, s10, 0x4000
	v_mfma_f32_16x16x32_bf16 v[74:77], v[184:187], v[144:147], v[74:77]
	global_load_lds_dwordx4 v133, s[22:23]
	v_add_u32_e32 v133, 0x80, v133
	v_mfma_f32_16x16x32_bf16 v[46:49], v[184:187], v[148:151], v[46:49]
	v_mfma_f32_16x16x32_bf16 v[10:13], v[184:187], v[180:183], v[10:13]
	ds_read_b128 v[184:187], v138
	ds_read_b128 v[208:211], v138 offset:2048
	ds_read_b128 v[212:215], v138 offset:4096
	ds_read_b128 v[216:219], v138 offset:6144
	s_waitcnt lgkmcnt(8)
	v_mfma_f32_16x16x32_bf16 v[98:101], v[200:203], v[140:143], v[98:101]
	s_add_u32 m0, s10, 0xc000
	v_mfma_f32_16x16x32_bf16 v[66:69], v[200:203], v[144:147], v[66:69]
	global_load_lds_dwordx4 v132, s[28:29]
	v_add_u32_e32 v132, 0x80, v132
	v_mfma_f32_16x16x32_bf16 v[34:37], v[200:203], v[148:151], v[34:37]
	v_mfma_f32_16x16x32_bf16 v[6:9], v[200:203], v[180:183], v[6:9]
	s_waitcnt lgkmcnt(7)
	v_mfma_f32_16x16x32_bf16 v[70:73], v[188:191], v[140:143], v[70:73]
	s_add_u32 m0, s10, 0x6000
	s_waitcnt lgkmcnt(6)
	v_mfma_f32_16x16x32_bf16 v[62:65], v[192:195], v[140:143], v[62:65]
	global_load_lds_dwordx4 v131, s[22:23]
	v_add_u32_e32 v131, 0x80, v131
	v_mfma_f32_16x16x32_bf16 v[42:45], v[188:191], v[144:147], v[42:45]
	v_mfma_f32_16x16x32_bf16 v[30:33], v[192:195], v[144:147], v[30:33]
	ds_read_b128 v[140:143], v152 offset:36864
	ds_read_b128 v[144:147], v152 offset:38912
	v_mfma_f32_16x16x32_bf16 v[18:21], v[188:191], v[148:151], v[18:21]
	s_add_u32 m0, s10, 0xe000
	v_mfma_f32_16x16x32_bf16 v[14:17], v[192:195], v[148:151], v[14:17]
	global_load_lds_dwordx4 v130, s[28:29]
	v_add_u32_e32 v130, 0x80, v130
	v_mfma_f32_16x16x32_bf16 v[2:5], v[188:191], v[180:183], v[2:5]
	v_mfma_f32_16x16x32_bf16 v[90:93], v[192:195], v[180:183], v[90:93]
	ds_read_b128 v[148:151], v152 offset:40960
	ds_read_b128 v[180:183], v152 offset:43008
	s_waitcnt lgkmcnt(7)
	v_mfma_f32_16x16x32_bf16 v[126:129], v[196:199], v[184:187], v[126:129]
	v_mfma_f32_16x16x32_bf16 v[122:125], v[204:207], v[184:187], v[122:125]
	s_waitcnt lgkmcnt(6)
	v_mfma_f32_16x16x32_bf16 v[110:113], v[196:199], v[208:211], v[110:113]
	v_mfma_f32_16x16x32_bf16 v[106:109], v[204:207], v[208:211], v[106:109]
	s_waitcnt lgkmcnt(5)
	v_mfma_f32_16x16x32_bf16 v[82:85], v[196:199], v[212:215], v[82:85]
	v_mfma_f32_16x16x32_bf16 v[78:81], v[204:207], v[212:215], v[78:81]
	s_waitcnt lgkmcnt(4)
	v_mfma_f32_16x16x32_bf16 v[50:53], v[196:199], v[216:219], v[50:53]
	v_mfma_f32_16x16x32_bf16 v[38:41], v[204:207], v[216:219], v[38:41]
	s_waitcnt lgkmcnt(3)
	v_mfma_f32_16x16x32_bf16 v[118:121], v[140:143], v[184:187], v[118:121]
	v_mfma_f32_16x16x32_bf16 v[94:97], v[140:143], v[208:211], v[94:97]
	v_mfma_f32_16x16x32_bf16 v[58:61], v[140:143], v[212:215], v[58:61]
	v_mfma_f32_16x16x32_bf16 v[26:29], v[140:143], v[216:219], v[26:29]
	ds_read_b128 v[140:143], v152 offset:45056
	ds_read_b128 v[188:191], v152 offset:47104
	s_waitcnt lgkmcnt(4)
; template <bool SWAP, class Epi, bool THIN = false> ...
;     ...
;       bf16x8 afA[4], afB[4], bfb[2][2];
; #pragma unroll
;       for (int m = 0; m < 4; ++m) afA[m] = *(const bf16x8*)(sa + m * 2048 + ((fq ^ swz) << 4));
; #pragma unroll
;       for (int n = 0; n < 2; ++n) bfb[0][n] = *(const bf16x8*)(sb + n * 2048 + ((fq ^ swz) << 4));
; #pragma unroll
;       for (int gq = 0; gq < 8; ++gq) {
;         const int ks = gq >> 2, nh = gq & 3;
;         if (gq < 7) {
;           const int ks2 = (gq + 1) >> 2, nh2 = (gq + 1) & 3;
; #pragma unroll
;           for (int n = 0; n < 2; ++n) bfb[(gq + 1) & 1][n] = *(const bf16x8*)(sb + (nh2 * 2 + n) * 2048 + (((ks2 * 4 + fq) ^ swz) << 4));
;         }
;         if (gq == 3) {
; #pragma unroll
;           for (int m = 0; m < 4; ++m) afB[m] = *(const bf16x8*)(sa + m * 2048 + (((4 + fq) ^ swz) << 4));
;         }
;         __builtin_amdgcn_sched_barrier(0);
; #pragma unroll
;         for (int m = 0; m < 4; ++m)
; #pragma unroll
;           for (int n = 0; n < 2; ++n) {
;             const bf16x8 av = ks ? afB[m] : afA[m];
;             acc[m][nh * 2 + n] = SWAP ? __builtin_amdgcn_mfma_f32_16x16x32_bf16(bfb[gq & 1][n], av, acc[m][nh * 2 + n], 0, 0, 0)
;                                       : __builtin_amdgcn_mfma_f32_16x16x32_bf16(av, bfb[gq & 1][n], acc[m][nh * 2 + n], 0, 0, 0);
;           }
;       }
;       }
	v_mfma_f32_16x16x32_bf16 v[114:117], v[144:147], v[184:187], v[114:117]
	v_mfma_f32_16x16x32_bf16 v[86:89], v[144:147], v[208:211], v[86:89]
	v_mfma_f32_16x16x32_bf16 v[54:57], v[144:147], v[212:215], v[54:57]
	v_mfma_f32_16x16x32_bf16 v[22:25], v[144:147], v[216:219], v[22:25]
	s_waitcnt lgkmcnt(3)
	v_mfma_f32_16x16x32_bf16 v[102:105], v[148:151], v[184:187], v[102:105]
	s_waitcnt lgkmcnt(2)
	v_mfma_f32_16x16x32_bf16 v[98:101], v[180:183], v[184:187], v[98:101]
	v_mfma_f32_16x16x32_bf16 v[74:77], v[148:151], v[208:211], v[74:77]
	v_mfma_f32_16x16x32_bf16 v[66:69], v[180:183], v[208:211], v[66:69]
	v_mfma_f32_16x16x32_bf16 v[46:49], v[148:151], v[212:215], v[46:49]
	v_mfma_f32_16x16x32_bf16 v[34:37], v[180:183], v[212:215], v[34:37]
	v_mfma_f32_16x16x32_bf16 v[10:13], v[148:151], v[216:219], v[10:13]
	v_mfma_f32_16x16x32_bf16 v[6:9], v[180:183], v[216:219], v[6:9]
	s_waitcnt lgkmcnt(1)
	v_mfma_f32_16x16x32_bf16 v[70:73], v[140:143], v[184:187], v[70:73]
	s_add_i32 s6, s6, 64
	s_cmpk_eq_i32 s6, 0x3c0
	s_mov_b32 s7, s9
	s_waitcnt lgkmcnt(0)
	v_mfma_f32_16x16x32_bf16 v[62:65], v[188:191], v[184:187], v[62:65]
	v_mfma_f32_16x16x32_bf16 v[42:45], v[140:143], v[208:211], v[42:45]
	v_mfma_f32_16x16x32_bf16 v[30:33], v[188:191], v[208:211], v[30:33]
	v_mfma_f32_16x16x32_bf16 v[18:21], v[140:143], v[212:215], v[18:21]
	v_mfma_f32_16x16x32_bf16 v[14:17], v[188:191], v[212:215], v[14:17]
	v_mfma_f32_16x16x32_bf16 v[2:5], v[140:143], v[216:219], v[2:5]
	v_mfma_f32_16x16x32_bf16 v[90:93], v[188:191], v[216:219], v[90:93]
	s_cbranch_scc0 .LBB0_3112
	v_add_u32_e32 v138, s8, v157
	v_add_u32_e32 v152, s8, v158
	s_waitcnt vmcnt(0)
	s_barrier
	v_add_u32_e32 v144, v138, v159
	v_add_u32_e32 v153, v152, v159
	ds_read_b128 v[130:133], v144
	ds_read_b128 v[134:137], v144 offset:2048
	ds_read_b128 v[140:143], v144 offset:4096
	ds_read_b128 v[144:147], v144 offset:6144
	ds_read_b128 v[148:151], v153 offset:32768
	ds_read_b128 v[180:183], v153 offset:34816
	ds_read_b128 v[184:187], v153 offset:36864
	ds_read_b128 v[188:191], v153 offset:38912
	v_add_u32_e32 v138, v138, v160
	s_waitcnt lgkmcnt(3)
	v_mfma_f32_16x16x32_bf16 v[126:129], v[148:151], v[130:133], v[126:129]
	v_mfma_f32_16x16x32_bf16 v[110:113], v[148:151], v[134:137], v[110:113]
	v_mfma_f32_16x16x32_bf16 v[82:85], v[148:151], v[140:143], v[82:85]
	v_mfma_f32_16x16x32_bf16 v[50:53], v[148:151], v[144:147], v[50:53]
	ds_read_b128 v[148:151], v153 offset:40960
	ds_read_b128 v[192:195], v153 offset:43008
	s_waitcnt lgkmcnt(4)
	v_mfma_f32_16x16x32_bf16 v[122:125], v[180:183], v[130:133], v[122:125]
	v_mfma_f32_16x16x32_bf16 v[106:109], v[180:183], v[134:137], v[106:109]
	v_mfma_f32_16x16x32_bf16 v[78:81], v[180:183], v[140:143], v[78:81]
	v_mfma_f32_16x16x32_bf16 v[38:41], v[180:183], v[144:147], v[38:41]
	s_waitcnt lgkmcnt(3)
	v_mfma_f32_16x16x32_bf16 v[118:121], v[184:187], v[130:133], v[118:121]
	v_mfma_f32_16x16x32_bf16 v[180:183], v[184:187], v[134:137], v[94:97]
	v_mfma_f32_16x16x32_bf16 v[200:203], v[184:187], v[140:143], v[58:61]
	s_waitcnt lgkmcnt(2)
	v_mfma_f32_16x16x32_bf16 v[204:207], v[188:191], v[140:143], v[54:57]
	v_mfma_f32_16x16x32_bf16 v[184:187], v[184:187], v[144:147], v[26:29]
	s_nop 2
	ds_read_b128 v[26:29], v153 offset:45056
	ds_read_b128 v[54:57], v153 offset:47104
	v_mfma_f32_16x16x32_bf16 v[114:117], v[188:191], v[130:133], v[114:117]
	v_mfma_f32_16x16x32_bf16 v[196:199], v[188:191], v[134:137], v[86:89]
	v_mfma_f32_16x16x32_bf16 v[188:191], v[188:191], v[144:147], v[22:25]
	v_add_u32_e32 v152, v152, v160
	s_waitcnt lgkmcnt(3)
	v_mfma_f32_16x16x32_bf16 v[102:105], v[148:151], v[130:133], v[102:105]
	ds_read_b128 v[22:25], v152 offset:32768
	ds_read_b128 v[86:89], v152 offset:34816
	v_mfma_f32_16x16x32_bf16 v[74:77], v[148:151], v[134:137], v[74:77]
	v_mfma_f32_16x16x32_bf16 v[46:49], v[148:151], v[140:143], v[46:49]
	v_mfma_f32_16x16x32_bf16 v[10:13], v[148:151], v[144:147], v[10:13]
	ds_read_b128 v[148:151], v138
	ds_read_b128 v[208:211], v138 offset:2048
	ds_read_b128 v[212:215], v138 offset:4096
	ds_read_b128 v[216:219], v138 offset:6144
	s_waitcnt lgkmcnt(8)
	v_mfma_f32_16x16x32_bf16 v[98:101], v[192:195], v[130:133], v[98:101]
	v_mfma_f32_16x16x32_bf16 v[66:69], v[192:195], v[134:137], v[66:69]
	v_mfma_f32_16x16x32_bf16 v[34:37], v[192:195], v[140:143], v[34:37]
	v_mfma_f32_16x16x32_bf16 v[6:9], v[192:195], v[144:147], v[6:9]
	s_waitcnt lgkmcnt(7)
	v_mfma_f32_16x16x32_bf16 v[220:223], v[26:29], v[140:143], v[18:21]
	s_waitcnt lgkmcnt(6)
	v_mfma_f32_16x16x32_bf16 v[140:143], v[54:57], v[140:143], v[14:17]
	s_nop 2
	ds_read_b128 v[14:17], v152 offset:36864
	ds_read_b128 v[18:21], v152 offset:38912
	v_mfma_f32_16x16x32_bf16 v[70:73], v[26:29], v[130:133], v[70:73]
	v_mfma_f32_16x16x32_bf16 v[2:5], v[26:29], v[144:147], v[2:5]
	v_mfma_f32_16x16x32_bf16 v[130:133], v[54:57], v[130:133], v[62:65]
	v_mfma_f32_16x16x32_bf16 v[192:195], v[26:29], v[134:137], v[42:45]
	v_mfma_f32_16x16x32_bf16 v[134:137], v[54:57], v[134:137], v[30:33]
	v_mfma_f32_16x16x32_bf16 v[224:227], v[54:57], v[144:147], v[90:93]
	ds_read_b128 v[144:147], v152 offset:40960
	ds_read_b128 v[228:231], v152 offset:43008
	s_waitcnt lgkmcnt(7)
; __device__ __forceinline__ unsigned pack2(float a, float b) { unsigned r; asm("v_cvt_pk_bf16_f32 %0, %1, %2" : "=v"(r) : "v"(a), "v"(b)); return r; }
; __device__ __forceinline__ float bf2f(bf16_t h) { return __uint_as_float(((unsigned)h) << 16); }
;   __device__ __forceinline__ void c4(int g, int rig, int col, f32x4 v) const {
;     const size_t o = ((size_t)g * 2048 + rig) * 1024 + col;
;     f32x4 bs;
;     if (BASE_F32) bs = __builtin_nontemporal_load((const f32x4*)((const float*)base + o));
;     else {
;       const uint2 u = *(const uint2*)((const bf16_t*)base + o);
;       bs[0] = bf2f((bf16_t)(u.x & 0xffff)); bs[1] = bf2f((bf16_t)(u.x >> 16)); bs[2] = bf2f((bf16_t)(u.y & 0xffff)); bs[3] = bf2f((bf16_t)(u.y >> 16));
;     }
;     const f32x4 gt = *(const f32x4*)(gate + (size_t)g * 6144 + col);
;     f32x4 bi = {0.f, 0.f, 0.f, 0.f};
;     if (bias) bi = *(const f32x4*)(bias + col);
;     f32x4 r;
; #pragma unroll
;     for (int j = 0; j < 4; ++j) r[j] = bs[j] + gt[j] * (v[j] + bi[j]);
;     uint2 w; w.x = pack2(r[0], r[1]); w.y = pack2(r[2], r[3]);
;     *(uint2*)(X16 + o) = w;
;   }
; template <bool SWAP, class Epi, bool THIN = false> ...
;     ...
;           const int ks2 = (gq + 1) >> 2, nh2 = (gq + 1) & 3;
; #pragma unroll
;           for (int n = 0; n < 2; ++n) bfb[(gq + 1) & 1][n] = *(const bf16x8*)(sb + (nh2 * 2 + n) * 2048 + (((ks2 * 4 + fq) ^ swz) << 4));
;         }
;         if (gq == 3) {
; #pragma unroll
;           for (int m = 0; m < 4; ++m) afB[m] = *(const bf16x8*)(sa + m * 2048 + (((4 + fq) ^ swz) << 4));
;         }
;         __builtin_amdgcn_sched_barrier(0);
; #pragma unroll
;         for (int m = 0; m < 4; ++m)
; #pragma unroll
;           for (int n = 0; n < 2; ++n) {
;             const bf16x8 av = ks ? afB[m] : afA[m];
;             acc[m][nh * 2 + n] = SWAP ? __builtin_amdgcn_mfma_f32_16x16x32_bf16(bfb[gq & 1][n], av, acc[m][nh * 2 + n], 0, 0, 0)
;                                       : __builtin_amdgcn_mfma_f32_16x16x32_bf16(av, bfb[gq & 1][n], acc[m][nh * 2 + n], 0, 0, 0);
;           }
;       }
;       }
	v_mfma_f32_16x16x32_bf16 v[126:129], v[22:25], v[148:151], v[126:129]
	v_mfma_f32_16x16x32_bf16 v[122:125], v[86:89], v[148:151], v[122:125]
	s_waitcnt lgkmcnt(6)
	v_mfma_f32_16x16x32_bf16 v[94:97], v[22:25], v[208:211], v[110:113]
	v_mfma_f32_16x16x32_bf16 v[90:93], v[86:89], v[208:211], v[106:109]
	s_waitcnt lgkmcnt(5)
	v_mfma_f32_16x16x32_bf16 v[62:65], v[22:25], v[212:215], v[82:85]
	v_mfma_f32_16x16x32_bf16 v[58:61], v[86:89], v[212:215], v[78:81]
	s_waitcnt lgkmcnt(4)
	v_mfma_f32_16x16x32_bf16 v[30:33], v[22:25], v[216:219], v[50:53]
	v_mfma_f32_16x16x32_bf16 v[26:29], v[86:89], v[216:219], v[38:41]
	s_waitcnt lgkmcnt(3)
	v_mfma_f32_16x16x32_bf16 v[86:89], v[14:17], v[208:211], v[180:183]
	v_mfma_f32_16x16x32_bf16 v[22:25], v[14:17], v[216:219], v[184:187]
	s_nop 1
	ds_read_b128 v[180:183], v152 offset:45056
	ds_read_b128 v[184:187], v152 offset:47104
	v_mfma_f32_16x16x32_bf16 v[118:121], v[14:17], v[148:151], v[118:121]
	s_waitcnt lgkmcnt(4)
	v_mfma_f32_16x16x32_bf16 v[114:117], v[18:21], v[148:151], v[114:117]
	v_mfma_f32_16x16x32_bf16 v[82:85], v[18:21], v[208:211], v[196:199]
	v_mfma_f32_16x16x32_bf16 v[54:57], v[14:17], v[212:215], v[200:203]
	v_mfma_f32_16x16x32_bf16 v[50:53], v[18:21], v[212:215], v[204:207]
	v_mfma_f32_16x16x32_bf16 v[18:21], v[18:21], v[216:219], v[188:191]
	s_waitcnt lgkmcnt(3)
	v_mfma_f32_16x16x32_bf16 v[110:113], v[144:147], v[148:151], v[102:105]
	s_waitcnt lgkmcnt(2)
	v_mfma_f32_16x16x32_bf16 v[106:109], v[228:231], v[148:151], v[98:101]
	v_mfma_f32_16x16x32_bf16 v[78:81], v[144:147], v[208:211], v[74:77]
	v_mfma_f32_16x16x32_bf16 v[74:77], v[228:231], v[208:211], v[66:69]
	v_mfma_f32_16x16x32_bf16 v[46:49], v[144:147], v[212:215], v[46:49]
	v_mfma_f32_16x16x32_bf16 v[42:45], v[228:231], v[212:215], v[34:37]
	v_mfma_f32_16x16x32_bf16 v[14:17], v[144:147], v[216:219], v[10:13]
	v_mfma_f32_16x16x32_bf16 v[10:13], v[228:231], v[216:219], v[6:9]
	v_mov_b32_e32 v138, v1
	s_waitcnt vmcnt(0) lgkmcnt(0)
	s_barrier
	v_mfma_f32_16x16x32_bf16 v[98:101], v[184:187], v[148:151], v[130:133]
	v_ashrrev_i32_e32 v7, 8, v138
	v_add_u32_e32 v7, s5, v7
	v_ashrrev_i32_e32 v8, 31, v7
	v_lshrrev_b32_e32 v8, 28, v8
	v_add_u32_e32 v8, v7, v8
	v_ashrrev_i32_e32 v130, 4, v8
	v_lshlrev_b32_e32 v8, 11, v130
	v_lshlrev_b32_e32 v7, 7, v7
	v_sub_u32_e32 v7, v7, v8
	v_lshrrev_b32_e32 v8, 1, v138
	v_and_b32_e32 v6, 15, v138
	v_and_b32_e32 v8, 64, v8
	v_or3_b32 v144, v7, v8, v6
	v_lshlrev_b32_e32 v6, 1, v138
	v_and_b32_e32 v131, 0x80, v6
	v_mfma_f32_16x16x32_bf16 v[6:9], v[180:183], v[216:219], v[2:5]
	v_ashrrev_i32_e32 v145, 31, v144
	v_lshlrev_b64 v[132:133], 10, v[144:145]
	s_nop 0
	v_lshrrev_b32_e32 v2, 2, v138
	v_and_b32_e32 v2, 12, v2
	v_mfma_f32_16x16x32_bf16 v[102:105], v[180:183], v[148:151], v[70:73]
	v_mfma_f32_16x16x32_bf16 v[70:73], v[180:183], v[208:211], v[192:195]
	v_mfma_f32_16x16x32_bf16 v[66:69], v[184:187], v[208:211], v[134:137]
	v_mfma_f32_16x16x32_bf16 v[38:41], v[180:183], v[212:215], v[220:223]
	v_mfma_f32_16x16x32_bf16 v[34:37], v[184:187], v[212:215], v[140:143]
	s_nop 2
	v_or3_b32 v140, v2, v131, s4
	v_mfma_f32_16x16x32_bf16 v[2:5], v[184:187], v[216:219], v[224:227]
	v_ashrrev_i32_e32 v131, 31, v130
	v_lshlrev_b64 v[146:147], 21, v[130:131]
	v_mad_i64_i32 v[130:131], s[4:5], v130, s39, 0
	v_lshl_add_u64 v[132:133], v[132:133], 0, v[146:147]
	v_lshl_add_u64 v[142:143], s[30:31], 0, v[130:131]
	v_cndmask_b32_e64 v130, 0, 1, s[34:35]
	v_cmp_gt_i32_e64 s[6:7], s40, v140
	v_ashrrev_i32_e32 v141, 31, v140
	v_lshl_add_u64 v[148:149], v[132:133], 1, s[24:25]
	v_cmp_ne_u32_e64 s[4:5], 1, v130
	v_bfe_u32 v248, v1, 4, 1
	v_mul_u32_u24_e32 v248, 24, v248
	v_mov_b32_e32 v249, 0
	v_lshl_add_u64 v[130:131], v[140:141], 2, v[142:143]
	global_load_dwordx4 v[180:183], v[130:131], off
	global_load_dwordx4 v[184:187], v[130:131], off offset:64
	global_load_dwordx4 v[188:191], v[130:131], off offset:128
	global_load_dwordx4 v[192:195], v[130:131], off offset:192
	global_load_dwordx4 v[196:199], v[130:131], off offset:256
	global_load_dwordx4 v[200:203], v[130:131], off offset:320
	global_load_dwordx4 v[204:207], v[130:131], off offset:384
	global_load_dwordx4 v[208:211], v[130:131], off offset:448
	s_and_b64 vcc, exec, s[4:5]
	s_cbranch_vccnz .Lhout_nobias
	v_lshl_add_u64 v[132:133], v[140:141], 2, s[26:27]
	global_load_dwordx4 v[212:215], v[132:133], off
	global_load_dwordx4 v[216:219], v[132:133], off offset:64
	global_load_dwordx4 v[220:223], v[132:133], off offset:128
	global_load_dwordx4 v[224:227], v[132:133], off offset:192
	global_load_dwordx4 v[228:231], v[132:133], off offset:256
	global_load_dwordx4 v[232:235], v[132:133], off offset:320
	global_load_dwordx4 v[236:239], v[132:133], off offset:384
	global_load_dwordx4 v[240:243], v[132:133], off offset:448
	s_branch .Lhout_bias

; template <bool SWAP, class Epi, bool THIN = false> ...
;     ...
;     for (int st = 0; st < ns; ++st) {
;       asm volatile("s_waitcnt vmcnt(0)" ::: "memory");
;       __builtin_amdgcn_s_barrier();
;       asm volatile("" ::: "memory");
;       if (st + 1 < ns) {
;         char* nb = smem + ((st + 1) & 1) * 65536;
;         const int ko = (st + 1) * 64;
; #pragma unroll
;         for (int i = 0; i < 4; ++i) { GLDS16(A + (size_t)(ap[i] + ko), nb + tid * 16 + i * 8192); GLDS16(Bt + (size_t)(bp[i] + ko), nb + 32768 + tid * 16 + i * 8192); }
;       }
;       const char* sa = smem + (st & 1) * 65536 + (wr * 64 + fr) * 128;
;       const char* sb = smem + (st & 1) * 65536 + 32768 + (wc * 128 + fr) * 128;
;       if constexpr (THIN) {
;         if (wc == 0) {
; #pragma unroll
;           for (int ks = 0; ks < 2; ++ks) {
;             bf16x8 af[4], bf[2];
; #pragma unroll
;             for (int m = 0; m < 4; ++m) af[m] = *(const bf16x8*)(sa + m * 2048 + (((ks * 4 + fq) ^ swz) << 4));
; #pragma unroll
;             for (int n = 0; n < 2; ++n) bf[n] = *(const bf16x8*)(sb + n * 2048 + (((ks * 4 + fq) ^ swz) << 4));
; #pragma unroll
;             for (int m = 0; m < 4; ++m)
; #pragma unroll
;               for (int n = 0; n < 2; ++n)
;                 acc[m][n] = SWAP ? __builtin_amdgcn_mfma_f32_16x16x32_bf16(bf[n], af[m], acc[m][n], 0, 0, 0)
;                                  : __builtin_amdgcn_mfma_f32_16x16x32_bf16(af[m], bf[n], acc[m][n], 0, 0, 0);
;           }
;         }
;       } else {
;       bf16x8 afA[4], afB[4], bfb[2][2];
; #pragma unroll
;       for (int m = 0; m < 4; ++m) afA[m] = *(const bf16x8*)(sa + m * 2048 + ((fq ^ swz) << 4));
; #pragma unroll
;       for (int n = 0; n < 2; ++n) bfb[0][n] = *(const bf16x8*)(sb + n * 2048 + ((fq ^ swz) << 4));
; #pragma unroll
;       for (int gq = 0; gq < 8; ++gq) {
;         const int ks = gq >> 2, nh = gq & 3;
;         if (gq < 7) {
;           const int ks2 = (gq + 1) >> 2, nh2 = (gq + 1) & 3;
; #pragma unroll
;           for (int n = 0; n < 2; ++n) bfb[(gq + 1) & 1][n] = *(const bf16x8*)(sb + (nh2 * 2 + n) * 2048 + (((ks2 * 4 + fq) ^ swz) << 4));
;         }
;         if (gq == 3) {
; #pragma unroll
;           for (int m = 0; m < 4; ++m) afB[m] = *(const bf16x8*)(sa + m * 2048 + (((4 + fq) ^ swz) << 4));
;         }
;         __builtin_amdgcn_sched_barrier(0);
; #pragma unroll
.LBB0_3424:
	s_add_i32 s8, s7, 0x10000
	s_and_b32 s9, s8, 0x10000
	v_add_u32_e32 v170, s9, v135
	s_nop 0
	v_readfirstlane_b32 s9, v170
	s_and_b32 s7, s7, 0x10000
	v_or_b32_e32 v204, s7, v139
	v_add_u32_e32 v205, v204, v140
	v_add_u32_e32 v136, s7, v138
	v_add_u32_e32 v180, v136, v140
	s_waitcnt vmcnt(0)
	s_barrier
	ds_read_b128 v[168:171], v180
	ds_read_b128 v[172:175], v180 offset:2048
	ds_read_b128 v[176:179], v180 offset:4096
	ds_read_b128 v[180:183], v180 offset:6144
	ds_read_b128 v[184:187], v205 offset:32768
	ds_read_b128 v[188:191], v205 offset:34816
	ds_read_b128 v[192:195], v205 offset:36864
	ds_read_b128 v[196:199], v205 offset:38912
	v_add_u32_e32 v136, v136, v141
	s_waitcnt lgkmcnt(3)
	v_mfma_f32_16x16x32_bf16 v[126:129], v[184:187], v[168:171], v[126:129]
	s_mov_b32 m0, s9
	v_mfma_f32_16x16x32_bf16 v[110:113], v[184:187], v[172:175], v[110:113]
	global_load_lds_dwordx4 v167, s[14:15]
	v_add_u32_e32 v167, 0x80, v167
	v_mfma_f32_16x16x32_bf16 v[82:85], v[184:187], v[176:179], v[82:85]
	v_mfma_f32_16x16x32_bf16 v[50:53], v[184:187], v[180:183], v[50:53]
	ds_read_b128 v[184:187], v205 offset:40960
	ds_read_b128 v[200:203], v205 offset:43008
	s_waitcnt lgkmcnt(4)
	v_mfma_f32_16x16x32_bf16 v[122:125], v[188:191], v[168:171], v[122:125]
	s_add_u32 m0, s9, 0x8000
	v_mfma_f32_16x16x32_bf16 v[106:109], v[188:191], v[172:175], v[106:109]
	global_load_lds_dwordx4 v166, s[10:11]
	v_add_u32_e32 v166, 0x80, v166
	v_mfma_f32_16x16x32_bf16 v[78:81], v[188:191], v[176:179], v[78:81]
	v_mfma_f32_16x16x32_bf16 v[42:45], v[188:191], v[180:183], v[42:45]
	s_waitcnt lgkmcnt(3)
	v_mfma_f32_16x16x32_bf16 v[118:121], v[192:195], v[168:171], v[118:121]
	s_add_u32 m0, s9, 0x2000
	v_mfma_f32_16x16x32_bf16 v[94:97], v[192:195], v[172:175], v[94:97]
	global_load_lds_dwordx4 v165, s[14:15]
	v_add_u32_e32 v165, 0x80, v165
	v_mfma_f32_16x16x32_bf16 v[58:61], v[192:195], v[176:179], v[58:61]
	v_mfma_f32_16x16x32_bf16 v[26:29], v[192:195], v[180:183], v[26:29]
	ds_read_b128 v[188:191], v205 offset:45056
	ds_read_b128 v[192:195], v205 offset:47104
	s_waitcnt lgkmcnt(4)
	v_mfma_f32_16x16x32_bf16 v[114:117], v[196:199], v[168:171], v[114:117]
	s_add_u32 m0, s9, 0xa000
	v_mfma_f32_16x16x32_bf16 v[90:93], v[196:199], v[172:175], v[90:93]
	global_load_lds_dwordx4 v164, s[10:11]
	v_add_u32_e32 v164, 0x80, v164
	v_mfma_f32_16x16x32_bf16 v[54:57], v[196:199], v[176:179], v[54:57]
	v_mfma_f32_16x16x32_bf16 v[22:25], v[196:199], v[180:183], v[22:25]
	v_add_u32_e32 v220, v204, v141
	s_waitcnt lgkmcnt(3)
	v_mfma_f32_16x16x32_bf16 v[102:105], v[184:187], v[168:171], v[102:105]
	ds_read_b128 v[196:199], v220 offset:32768
	ds_read_b128 v[204:207], v220 offset:34816
	s_add_u32 m0, s9, 0x4000
	v_mfma_f32_16x16x32_bf16 v[74:77], v[184:187], v[172:175], v[74:77]
	global_load_lds_dwordx4 v163, s[14:15]
	v_add_u32_e32 v163, 0x80, v163
	v_mfma_f32_16x16x32_bf16 v[46:49], v[184:187], v[176:179], v[46:49]
	v_mfma_f32_16x16x32_bf16 v[10:13], v[184:187], v[180:183], v[10:13]
	ds_read_b128 v[184:187], v136
	ds_read_b128 v[208:211], v136 offset:2048
	ds_read_b128 v[212:215], v136 offset:4096
	ds_read_b128 v[216:219], v136 offset:6144
	s_waitcnt lgkmcnt(8)
	v_mfma_f32_16x16x32_bf16 v[98:101], v[200:203], v[168:171], v[98:101]
	s_add_u32 m0, s9, 0xc000
	v_mfma_f32_16x16x32_bf16 v[66:69], v[200:203], v[172:175], v[66:69]
	global_load_lds_dwordx4 v162, s[10:11]
	v_add_u32_e32 v162, 0x80, v162
	v_mfma_f32_16x16x32_bf16 v[30:33], v[200:203], v[176:179], v[30:33]
	v_mfma_f32_16x16x32_bf16 v[6:9], v[200:203], v[180:183], v[6:9]
	s_waitcnt lgkmcnt(7)
	v_mfma_f32_16x16x32_bf16 v[70:73], v[188:191], v[168:171], v[70:73]
	s_add_u32 m0, s9, 0x6000
	s_waitcnt lgkmcnt(6)
	v_mfma_f32_16x16x32_bf16 v[62:65], v[192:195], v[168:171], v[62:65]
	global_load_lds_dwordx4 v161, s[14:15]
	v_add_u32_e32 v161, 0x80, v161
	v_mfma_f32_16x16x32_bf16 v[38:41], v[188:191], v[172:175], v[38:41]
	v_mfma_f32_16x16x32_bf16 v[34:37], v[192:195], v[172:175], v[34:37]
	ds_read_b128 v[168:171], v220 offset:36864
	ds_read_b128 v[172:175], v220 offset:38912
	v_mfma_f32_16x16x32_bf16 v[18:21], v[188:191], v[176:179], v[18:21]
	s_add_u32 m0, s9, 0xe000
	v_mfma_f32_16x16x32_bf16 v[14:17], v[192:195], v[176:179], v[14:17]
	global_load_lds_dwordx4 v160, s[10:11]
	v_add_u32_e32 v160, 0x80, v160
	v_mfma_f32_16x16x32_bf16 v[2:5], v[188:191], v[180:183], v[2:5]
	v_mfma_f32_16x16x32_bf16 v[86:89], v[192:195], v[180:183], v[86:89]
	ds_read_b128 v[176:179], v220 offset:40960
	ds_read_b128 v[180:183], v220 offset:43008
	s_waitcnt lgkmcnt(7)
	v_mfma_f32_16x16x32_bf16 v[126:129], v[196:199], v[184:187], v[126:129]
	v_mfma_f32_16x16x32_bf16 v[122:125], v[204:207], v[184:187], v[122:125]
	s_waitcnt lgkmcnt(6)
	v_mfma_f32_16x16x32_bf16 v[110:113], v[196:199], v[208:211], v[110:113]
	v_mfma_f32_16x16x32_bf16 v[106:109], v[204:207], v[208:211], v[106:109]
	s_waitcnt lgkmcnt(5)
	v_mfma_f32_16x16x32_bf16 v[82:85], v[196:199], v[212:215], v[82:85]
	v_mfma_f32_16x16x32_bf16 v[78:81], v[204:207], v[212:215], v[78:81]
	s_waitcnt lgkmcnt(4)
	v_mfma_f32_16x16x32_bf16 v[50:53], v[196:199], v[216:219], v[50:53]
	v_mfma_f32_16x16x32_bf16 v[42:45], v[204:207], v[216:219], v[42:45]
	s_waitcnt lgkmcnt(3)
	v_mfma_f32_16x16x32_bf16 v[118:121], v[168:171], v[184:187], v[118:121]
	v_mfma_f32_16x16x32_bf16 v[94:97], v[168:171], v[208:211], v[94:97]
	v_mfma_f32_16x16x32_bf16 v[58:61], v[168:171], v[212:215], v[58:61]
	v_mfma_f32_16x16x32_bf16 v[26:29], v[168:171], v[216:219], v[26:29]
	ds_read_b128 v[168:171], v220 offset:45056
	ds_read_b128 v[188:191], v220 offset:47104
	s_waitcnt lgkmcnt(4)
; template <bool SWAP, class Epi, bool THIN = false> ...
;     ...
;       bf16x8 afA[4], afB[4], bfb[2][2];
; #pragma unroll
;       for (int m = 0; m < 4; ++m) afA[m] = *(const bf16x8*)(sa + m * 2048 + ((fq ^ swz) << 4));
; #pragma unroll
;       for (int n = 0; n < 2; ++n) bfb[0][n] = *(const bf16x8*)(sb + n * 2048 + ((fq ^ swz) << 4));
; #pragma unroll
;       for (int gq = 0; gq < 8; ++gq) {
;         const int ks = gq >> 2, nh = gq & 3;
;         if (gq < 7) {
;           const int ks2 = (gq + 1) >> 2, nh2 = (gq + 1) & 3;
; #pragma unroll
;           for (int n = 0; n < 2; ++n) bfb[(gq + 1) & 1][n] = *(const bf16x8*)(sb + (nh2 * 2 + n) * 2048 + (((ks2 * 4 + fq) ^ swz) << 4));
;         }
;         if (gq == 3) {
; #pragma unroll
;           for (int m = 0; m < 4; ++m) afB[m] = *(const bf16x8*)(sa + m * 2048 + (((4 + fq) ^ swz) << 4));
;         }
;         __builtin_amdgcn_sched_barrier(0);
; #pragma unroll
;         for (int m = 0; m < 4; ++m)
; #pragma unroll
;           for (int n = 0; n < 2; ++n) {
;             const bf16x8 av = ks ? afB[m] : afA[m];
;             acc[m][nh * 2 + n] = SWAP ? __builtin_amdgcn_mfma_f32_16x16x32_bf16(bfb[gq & 1][n], av, acc[m][nh * 2 + n], 0, 0, 0)
;                                       : __builtin_amdgcn_mfma_f32_16x16x32_bf16(av, bfb[gq & 1][n], acc[m][nh * 2 + n], 0, 0, 0);
;           }
;       }
;       }
	v_mfma_f32_16x16x32_bf16 v[114:117], v[172:175], v[184:187], v[114:117]
	v_mfma_f32_16x16x32_bf16 v[90:93], v[172:175], v[208:211], v[90:93]
	v_mfma_f32_16x16x32_bf16 v[54:57], v[172:175], v[212:215], v[54:57]
	v_mfma_f32_16x16x32_bf16 v[22:25], v[172:175], v[216:219], v[22:25]
	s_waitcnt lgkmcnt(3)
	v_mfma_f32_16x16x32_bf16 v[102:105], v[176:179], v[184:187], v[102:105]
	s_waitcnt lgkmcnt(2)
	v_mfma_f32_16x16x32_bf16 v[98:101], v[180:183], v[184:187], v[98:101]
	v_mfma_f32_16x16x32_bf16 v[74:77], v[176:179], v[208:211], v[74:77]
	v_mfma_f32_16x16x32_bf16 v[66:69], v[180:183], v[208:211], v[66:69]
	v_mfma_f32_16x16x32_bf16 v[46:49], v[176:179], v[212:215], v[46:49]
	v_mfma_f32_16x16x32_bf16 v[30:33], v[180:183], v[212:215], v[30:33]
	v_mfma_f32_16x16x32_bf16 v[10:13], v[176:179], v[216:219], v[10:13]
	v_mfma_f32_16x16x32_bf16 v[6:9], v[180:183], v[216:219], v[6:9]
	s_waitcnt lgkmcnt(1)
	v_mfma_f32_16x16x32_bf16 v[70:73], v[168:171], v[184:187], v[70:73]
	s_add_i32 s5, s5, 64
	s_cmpk_eq_i32 s5, 0x3c0
	s_mov_b32 s7, s8
	s_waitcnt lgkmcnt(0)
	v_mfma_f32_16x16x32_bf16 v[62:65], v[188:191], v[184:187], v[62:65]
	v_mfma_f32_16x16x32_bf16 v[38:41], v[168:171], v[208:211], v[38:41]
	v_mfma_f32_16x16x32_bf16 v[34:37], v[188:191], v[208:211], v[34:37]
	v_mfma_f32_16x16x32_bf16 v[18:21], v[168:171], v[212:215], v[18:21]
	v_mfma_f32_16x16x32_bf16 v[14:17], v[188:191], v[212:215], v[14:17]
	v_mfma_f32_16x16x32_bf16 v[2:5], v[168:171], v[216:219], v[2:5]
	v_mfma_f32_16x16x32_bf16 v[86:89], v[188:191], v[216:219], v[86:89]
	s_cbranch_scc0 .LBB0_3424
	s_waitcnt vmcnt(0)
	s_barrier
	v_add_u32_e32 v136, v150, v140
	ds_read_b128 v[160:163], v136
	ds_read_b128 v[164:167], v136 offset:2048
	ds_read_b128 v[168:171], v136 offset:4096
	ds_read_b128 v[172:175], v136 offset:6144
	v_add_u32_e32 v136, v151, v140
	ds_read_b128 v[176:179], v136
	ds_read_b128 v[180:183], v136 offset:2048
	ds_read_b128 v[184:187], v136 offset:4096
	ds_read_b128 v[188:191], v136 offset:6144
	s_waitcnt lgkmcnt(3)
	v_mfma_f32_16x16x32_bf16 v[126:129], v[176:179], v[160:163], v[126:129]
	v_mfma_f32_16x16x32_bf16 v[110:113], v[176:179], v[164:167], v[110:113]
	v_mfma_f32_16x16x32_bf16 v[82:85], v[176:179], v[168:171], v[82:85]
	v_mfma_f32_16x16x32_bf16 v[50:53], v[176:179], v[172:175], v[50:53]
	ds_read_b128 v[176:179], v136 offset:8192
	ds_read_b128 v[192:195], v136 offset:10240
	s_waitcnt lgkmcnt(4)
	v_mfma_f32_16x16x32_bf16 v[122:125], v[180:183], v[160:163], v[122:125]
	v_mfma_f32_16x16x32_bf16 v[106:109], v[180:183], v[164:167], v[106:109]
	v_mfma_f32_16x16x32_bf16 v[78:81], v[180:183], v[168:171], v[78:81]
	v_mfma_f32_16x16x32_bf16 v[42:45], v[180:183], v[172:175], v[42:45]
	s_waitcnt lgkmcnt(3)
	v_mfma_f32_16x16x32_bf16 v[118:121], v[184:187], v[160:163], v[118:121]
	v_mfma_f32_16x16x32_bf16 v[94:97], v[184:187], v[164:167], v[94:97]
	v_mfma_f32_16x16x32_bf16 v[58:61], v[184:187], v[168:171], v[58:61]
	v_mfma_f32_16x16x32_bf16 v[26:29], v[184:187], v[172:175], v[26:29]
	ds_read_b128 v[180:183], v136 offset:12288
	ds_read_b128 v[184:187], v136 offset:14336
	s_waitcnt lgkmcnt(4)
	v_mfma_f32_16x16x32_bf16 v[114:117], v[188:191], v[160:163], v[114:117]
	v_mfma_f32_16x16x32_bf16 v[90:93], v[188:191], v[164:167], v[90:93]
	v_mfma_f32_16x16x32_bf16 v[54:57], v[188:191], v[168:171], v[54:57]
	v_mfma_f32_16x16x32_bf16 v[22:25], v[188:191], v[172:175], v[22:25]
	v_add_u32_e32 v136, v151, v141
	v_add_u32_e32 v208, v150, v141
	s_waitcnt lgkmcnt(3)
	v_mfma_f32_16x16x32_bf16 v[102:105], v[176:179], v[160:163], v[102:105]
	v_mfma_f32_16x16x32_bf16 v[74:77], v[176:179], v[164:167], v[74:77]
	s_waitcnt lgkmcnt(2)
	v_mfma_f32_16x16x32_bf16 v[188:191], v[192:195], v[164:167], v[66:69]
	v_mfma_f32_16x16x32_bf16 v[196:199], v[176:179], v[168:171], v[46:49]
	s_nop 2
	ds_read_b128 v[46:49], v136
	ds_read_b128 v[66:69], v136 offset:2048
	v_mfma_f32_16x16x32_bf16 v[10:13], v[176:179], v[172:175], v[10:13]
	ds_read_b128 v[176:179], v208
	ds_read_b128 v[200:203], v208 offset:2048
	ds_read_b128 v[204:207], v208 offset:4096
	ds_read_b128 v[208:211], v208 offset:6144
	v_mfma_f32_16x16x32_bf16 v[98:101], v[192:195], v[160:163], v[98:101]
	v_mfma_f32_16x16x32_bf16 v[30:33], v[192:195], v[168:171], v[30:33]
	v_mfma_f32_16x16x32_bf16 v[6:9], v[192:195], v[172:175], v[6:9]
	s_waitcnt lgkmcnt(7)
	v_mfma_f32_16x16x32_bf16 v[192:195], v[180:183], v[164:167], v[38:41]
	s_waitcnt lgkmcnt(6)
	v_mfma_f32_16x16x32_bf16 v[164:167], v[184:187], v[164:167], v[34:37]
	v_mfma_f32_16x16x32_bf16 v[18:21], v[180:183], v[168:171], v[18:21]
	v_mfma_f32_16x16x32_bf16 v[168:171], v[184:187], v[168:171], v[14:17]
	s_nop 2
	ds_read_b128 v[14:17], v136 offset:4096
	ds_read_b128 v[34:37], v136 offset:6144
	v_mfma_f32_16x16x32_bf16 v[70:73], v[180:183], v[160:163], v[70:73]
	v_mfma_f32_16x16x32_bf16 v[2:5], v[180:183], v[172:175], v[2:5]
	v_mfma_f32_16x16x32_bf16 v[160:163], v[184:187], v[160:163], v[62:65]
	v_mfma_f32_16x16x32_bf16 v[86:89], v[184:187], v[172:175], v[86:89]
	s_waitcnt lgkmcnt(2)
	v_mfma_f32_16x16x32_bf16 v[172:175], v[46:49], v[208:211], v[50:53]
	s_nop 2
	ds_read_b128 v[50:53], v136 offset:8192
	ds_read_b128 v[180:183], v136 offset:10240
	v_mfma_f32_16x16x32_bf16 v[126:129], v[46:49], v[176:179], v[126:129]
	v_mfma_f32_16x16x32_bf16 v[122:125], v[66:69], v[176:179], v[122:125]
	v_mfma_f32_16x16x32_bf16 v[110:113], v[46:49], v[200:203], v[110:113]
	v_mfma_f32_16x16x32_bf16 v[106:109], v[66:69], v[200:203], v[106:109]
	v_mfma_f32_16x16x32_bf16 v[82:85], v[46:49], v[204:207], v[82:85]
	v_mfma_f32_16x16x32_bf16 v[78:81], v[66:69], v[204:207], v[78:81]
	v_mfma_f32_16x16x32_bf16 v[184:187], v[66:69], v[208:211], v[42:45]
	ds_read_b128 v[224:227], v136 offset:12288
	ds_read_b128 v[228:231], v136 offset:14336
	s_waitcnt lgkmcnt(5)
	v_mfma_f32_16x16x32_bf16 v[118:121], v[14:17], v[176:179], v[118:121]
	s_waitcnt lgkmcnt(4)
	v_mfma_f32_16x16x32_bf16 v[114:117], v[34:37], v[176:179], v[114:117]
	v_mfma_f32_16x16x32_bf16 v[94:97], v[14:17], v[200:203], v[94:97]
	v_mfma_f32_16x16x32_bf16 v[90:93], v[34:37], v[200:203], v[90:93]
	v_mfma_f32_16x16x32_bf16 v[212:215], v[14:17], v[204:207], v[58:61]
	v_mfma_f32_16x16x32_bf16 v[216:219], v[34:37], v[204:207], v[54:57]
	v_mfma_f32_16x16x32_bf16 v[220:223], v[14:17], v[208:211], v[26:29]
	v_mfma_f32_16x16x32_bf16 v[66:69], v[34:37], v[208:211], v[22:25]
	s_waitcnt lgkmcnt(2)
	v_mfma_f32_16x16x32_bf16 v[38:41], v[180:183], v[204:207], v[30:33]
	v_mfma_f32_16x16x32_bf16 v[62:65], v[50:53], v[176:179], v[102:105]
	v_mfma_f32_16x16x32_bf16 v[46:49], v[180:183], v[176:179], v[98:101]
	v_mfma_f32_16x16x32_bf16 v[58:61], v[50:53], v[200:203], v[74:77]
	v_mfma_f32_16x16x32_bf16 v[42:45], v[180:183], v[200:203], v[188:191]
	v_mfma_f32_16x16x32_bf16 v[54:57], v[50:53], v[204:207], v[196:199]
	v_mfma_f32_16x16x32_bf16 v[50:53], v[50:53], v[208:211], v[10:13]
	v_mfma_f32_16x16x32_bf16 v[34:37], v[180:183], v[208:211], v[6:9]
	s_nop 2
	v_mov_b32_e32 v8, v1
	s_waitcnt vmcnt(0)
	s_waitcnt lgkmcnt(0)
	s_barrier
; __device__ __forceinline__ unsigned pack2(float a, float b) { unsigned r; asm("v_cvt_pk_bf16_f32 %0, %1, %2" : "=v"(r) : "v"(a), "v"(b)); return r; }
; template <bool SWAP, class Epi, bool THIN = false> ...
;     ...
;     } else {
;       bf16_t* Zw = (bf16_t*)smem + ((wr_e >> 1) * 2 + wc_e) * (128 * 132);
;       const int nt2w = nt * 2 + wc_e;
; #pragma unroll
;       for (int n = 0; n < 8; ++n) {
;         const int cl = n * 16 + fq_e * 4;
;         f32x4 b4 = {0.f, 0.f, 0.f, 0.f};
;         if (epi.pre_bias) b4 = *(const f32x4*)(epi.pre_bias + epi.norig(nt2w, cl));
; #pragma unroll
;         for (int m = 0; m < 4; ++m) {
;           const int rl = rw + m * 16 + fr_e;
;           const int pos = rig0 + rl;
;           const bool ok = pos >= 0 && pos < grows;
;           f32x4 vv = acc[m][n] + b4;
;           if (!ok) vv = (f32x4){0.f, 0.f, 0.f, 0.f};
;           uint2 u; u.x = pack2(vv[0], vv[1]); u.y = pack2(vv[2], vv[3]);
;           *(uint2*)(Zw + rl * 132 + cl) = u;
;         }
;       }
;       __syncthreads();
	v_mfma_f32_16x16x32_bf16 v[30:33], v[224:227], v[176:179], v[70:73]
	v_ashrrev_i32_e32 v98, 8, v8
	v_add_u32_e32 v6, s4, v98
	v_mul_hi_i32 v7, v6, s26
	v_lshrrev_b32_e32 v9, 31, v7
	v_ashrrev_i32_e32 v7, 3, v7
	v_add_u32_e32 v70, v7, v9
	v_and_b32_e32 v71, 15, v8
	v_mad_u64_u32 v[6:7], s[4:5], v70, s27, v[6:7]
	v_lshrrev_b32_e32 v74, 1, v8
	v_bfe_u32 v73, v8, 6, 1
	v_mul_lo_u32 v72, v6, s28
	v_and_or_b32 v71, v74, 64, v71
	v_add_u32_e32 v99, v72, v71
	v_lshl_or_b32 v73, v98, 1, v73
	v_mul_lo_u32 v73, v73, s29
	v_add_u32_e32 v100, -1, v99
	v_and_or_b32 v73, v74, 24, v73
	v_pk_add_f32 v[74:75], v[128:129], 0 op_sel_hi:[1,0]
	v_pk_add_f32 v[76:77], v[126:127], 0 op_sel_hi:[1,0]
	v_cmp_gt_u32_e32 vcc, s30, v100
	v_mfma_f32_16x16x32_bf16 v[22:25], v[224:227], v[204:207], v[18:21]
	v_mad_u32_u24 v71, v71, s31, v73
	v_add_u32_e32 v73, 15, v99
	v_cmp_gt_u32_e64 s[4:5], s30, v73
	v_mfma_f32_16x16x32_bf16 v[18:21], v[224:227], v[208:211], v[2:5]
	s_lshl_b32 s24, s6, 7
	v_cndmask_b32_e32 v75, 0, v75, vcc
	v_pk_add_f32 v[84:85], v[84:85], 0 op_sel_hi:[1,0]
	v_mfma_f32_16x16x32_bf16 v[2:5], v[228:231], v[208:211], v[86:89]
	v_add_f32_e64 v82, v82, 0
	v_add_f32_e64 v83, v83, 0
	v_pk_add_f32 v[66:67], v[66:67], 0 op_sel_hi:[1,0]
	v_pk_add_f32 v[62:63], v[62:63], 0 op_sel_hi:[1,0]
	v_cndmask_b32_e32 v86, 0, v74, vcc
	v_cndmask_b32_e32 v74, 0, v76, vcc
	v_cndmask_b32_e32 v76, 0, v77, vcc
	v_cvt_pk_bf16_f32 v74, v74, v76
	v_pk_add_f32 v[76:77], v[112:113], 0 op_sel_hi:[1,0]
	v_cvt_pk_bf16_f32 v75, v86, v75
	v_pk_add_f32 v[86:87], v[110:111], 0 op_sel_hi:[1,0]
	v_cndmask_b32_e64 v73, 0, v76, s[4:5]
	v_cndmask_b32_e64 v77, 0, v77, s[4:5]
	v_cvt_pk_bf16_f32 v77, v73, v77
	v_add_u32_e32 v73, 31, v99
	v_cmp_gt_u32_e64 s[6:7], s30, v73
	v_cndmask_b32_e64 v76, 0, v86, s[4:5]
	v_cndmask_b32_e64 v86, 0, v87, s[4:5]
	v_cndmask_b32_e64 v73, 0, v84, s[6:7]
	v_cndmask_b32_e64 v82, 0, v82, s[6:7]
	v_cndmask_b32_e64 v83, 0, v83, s[6:7]
	v_cndmask_b32_e64 v84, 0, v85, s[6:7]
	v_cvt_pk_bf16_f32 v82, v82, v83
	v_cvt_pk_bf16_f32 v83, v73, v84
	v_add_u32_e32 v73, 47, v99
	v_cvt_pk_bf16_f32 v76, v76, v86
	v_pk_add_f32 v[84:85], v[174:175], 0 op_sel_hi:[1,0]
	v_pk_add_f32 v[86:87], v[172:173], 0 op_sel_hi:[1,0]
	v_cmp_gt_u32_e64 s[8:9], s30, v73
	v_pk_add_f32 v[88:89], v[122:123], 0 op_sel_hi:[1,0]
	v_mfma_f32_16x16x32_bf16 v[26:29], v[224:227], v[200:203], v[192:195]
	v_cndmask_b32_e64 v73, 0, v84, s[8:9]
	v_cndmask_b32_e64 v84, 0, v86, s[8:9]
	v_cndmask_b32_e64 v86, 0, v87, s[8:9]
	v_cndmask_b32_e64 v85, 0, v85, s[8:9]
	v_cvt_pk_bf16_f32 v84, v84, v86
	v_pk_add_f32 v[86:87], v[124:125], 0 op_sel_hi:[1,0]
	v_cvt_pk_bf16_f32 v85, v73, v85
	v_mfma_f32_16x16x32_bf16 v[14:17], v[228:231], v[176:179], v[160:163]
	v_cndmask_b32_e32 v73, 0, v86, vcc
	v_cndmask_b32_e32 v87, 0, v87, vcc
	v_cndmask_b32_e32 v86, 0, v88, vcc
	v_cndmask_b32_e32 v88, 0, v89, vcc
	v_cvt_pk_bf16_f32 v86, v86, v88
	v_cvt_pk_bf16_f32 v87, v73, v87
	ds_write2_b64 v71, v[74:75], v[86:87] offset1:4
	v_pk_add_f32 v[74:75], v[108:109], 0 op_sel_hi:[1,0]
	v_pk_add_f32 v[86:87], v[106:107], 0 op_sel_hi:[1,0]
	v_cndmask_b32_e64 v73, 0, v74, s[4:5]
	v_cndmask_b32_e64 v75, 0, v75, s[4:5]
	v_cndmask_b32_e64 v74, 0, v86, s[4:5]
	v_cndmask_b32_e64 v86, 0, v87, s[4:5]
	v_cvt_pk_bf16_f32 v74, v74, v86
	v_cvt_pk_bf16_f32 v75, v73, v75
	v_add_u32_e32 v73, 0x1000, v71
	ds_write2_b64 v73, v[76:77], v[74:75] offset0:16 offset1:20
	v_pk_add_f32 v[74:75], v[80:81], 0 op_sel_hi:[1,0]
	v_pk_add_f32 v[76:77], v[78:79], 0 op_sel_hi:[1,0]
	v_cndmask_b32_e64 v78, 0, v74, s[6:7]
	v_cndmask_b32_e64 v75, 0, v75, s[6:7]
	v_cndmask_b32_e64 v74, 0, v76, s[6:7]
	v_cndmask_b32_e64 v76, 0, v77, s[6:7]
	v_cvt_pk_bf16_f32 v74, v74, v76
	v_cvt_pk_bf16_f32 v75, v78, v75
	v_add_u32_e32 v86, 0x2000, v71
	ds_write2_b64 v86, v[82:83], v[74:75] offset0:32 offset1:36
	v_pk_add_f32 v[74:75], v[186:187], 0 op_sel_hi:[1,0]
	v_pk_add_f32 v[76:77], v[184:185], 0 op_sel_hi:[1,0]
	v_cndmask_b32_e64 v78, 0, v74, s[8:9]
	v_cndmask_b32_e64 v75, 0, v75, s[8:9]
	v_cndmask_b32_e64 v74, 0, v76, s[8:9]
	v_cndmask_b32_e64 v76, 0, v77, s[8:9]
	v_cvt_pk_bf16_f32 v74, v74, v76
	v_cvt_pk_bf16_f32 v75, v78, v75
	v_add_u32_e32 v87, 0x3000, v71
	ds_write2_b64 v87, v[84:85], v[74:75] offset0:48 offset1:52
	v_pk_add_f32 v[74:75], v[120:121], 0 op_sel_hi:[1,0]
	v_pk_add_f32 v[76:77], v[118:119], 0 op_sel_hi:[1,0]
	v_cndmask_b32_e32 v78, 0, v74, vcc
	v_cndmask_b32_e32 v75, 0, v75, vcc
	v_cndmask_b32_e32 v74, 0, v76, vcc
	v_cndmask_b32_e32 v76, 0, v77, vcc
	v_cvt_pk_bf16_f32 v74, v74, v76
	v_cvt_pk_bf16_f32 v75, v78, v75
	v_pk_add_f32 v[76:77], v[96:97], 0 op_sel_hi:[1,0]
	v_pk_add_f32 v[78:79], v[94:95], 0 op_sel_hi:[1,0]
	v_cndmask_b32_e64 v80, 0, v76, s[4:5]
	v_cndmask_b32_e64 v77, 0, v77, s[4:5]
	v_cndmask_b32_e64 v76, 0, v78, s[4:5]
	v_cndmask_b32_e64 v78, 0, v79, s[4:5]
	v_cvt_pk_bf16_f32 v76, v76, v78
	v_cvt_pk_bf16_f32 v77, v80, v77
	v_pk_add_f32 v[78:79], v[214:215], 0 op_sel_hi:[1,0]
	v_pk_add_f32 v[80:81], v[212:213], 0 op_sel_hi:[1,0]
	v_cndmask_b32_e64 v82, 0, v78, s[6:7]
	v_cndmask_b32_e64 v79, 0, v79, s[6:7]
	v_cndmask_b32_e64 v78, 0, v80, s[6:7]
	v_cndmask_b32_e64 v80, 0, v81, s[6:7]
	v_cvt_pk_bf16_f32 v78, v78, v80
	v_cvt_pk_bf16_f32 v79, v82, v79
	v_pk_add_f32 v[80:81], v[222:223], 0 op_sel_hi:[1,0]
	v_pk_add_f32 v[82:83], v[220:221], 0 op_sel_hi:[1,0]
	v_cndmask_b32_e64 v84, 0, v80, s[8:9]
	v_cndmask_b32_e64 v81, 0, v81, s[8:9]
	v_cndmask_b32_e64 v80, 0, v82, s[8:9]
	v_cndmask_b32_e64 v82, 0, v83, s[8:9]
	v_cvt_pk_bf16_f32 v80, v80, v82
	v_cvt_pk_bf16_f32 v81, v84, v81
	v_pk_add_f32 v[82:83], v[116:117], 0 op_sel_hi:[1,0]
	v_pk_add_f32 v[84:85], v[114:115], 0 op_sel_hi:[1,0]
; __device__ __forceinline__ unsigned pack2(float a, float b) { unsigned r; asm("v_cvt_pk_bf16_f32 %0, %1, %2" : "=v"(r) : "v"(a), "v"(b)); return r; }
; template <bool SWAP, class Epi, bool THIN = false> ...
;     ...
;     } else {
;       bf16_t* Zw = (bf16_t*)smem + ((wr_e >> 1) * 2 + wc_e) * (128 * 132);
;       const int nt2w = nt * 2 + wc_e;
; #pragma unroll
;       for (int n = 0; n < 8; ++n) {
;         const int cl = n * 16 + fq_e * 4;
;         f32x4 b4 = {0.f, 0.f, 0.f, 0.f};
;         if (epi.pre_bias) b4 = *(const f32x4*)(epi.pre_bias + epi.norig(nt2w, cl));
; #pragma unroll
;         for (int m = 0; m < 4; ++m) {
;           const int rl = rw + m * 16 + fr_e;
;           const int pos = rig0 + rl;
;           const bool ok = pos >= 0 && pos < grows;
;           f32x4 vv = acc[m][n] + b4;
;           if (!ok) vv = (f32x4){0.f, 0.f, 0.f, 0.f};
;           uint2 u; u.x = pack2(vv[0], vv[1]); u.y = pack2(vv[2], vv[3]);
;           *(uint2*)(Zw + rl * 132 + cl) = u;
;         }
;       }
;       __syncthreads();
	v_cndmask_b32_e32 v88, 0, v82, vcc
	v_cndmask_b32_e32 v83, 0, v83, vcc
	v_cndmask_b32_e32 v82, 0, v84, vcc
	v_mfma_f32_16x16x32_bf16 v[10:13], v[228:231], v[200:203], v[164:167]
	v_cndmask_b32_e32 v84, 0, v85, vcc
	v_cvt_pk_bf16_f32 v82, v82, v84
	v_cvt_pk_bf16_f32 v83, v88, v83
	v_mfma_f32_16x16x32_bf16 v[6:9], v[228:231], v[204:207], v[168:171]
	ds_write2_b64 v71, v[74:75], v[82:83] offset0:8 offset1:12
	v_pk_add_f32 v[74:75], v[92:93], 0 op_sel_hi:[1,0]
	v_pk_add_f32 v[82:83], v[90:91], 0 op_sel_hi:[1,0]
	v_cndmask_b32_e64 v84, 0, v74, s[4:5]
	v_cndmask_b32_e64 v75, 0, v75, s[4:5]
	v_cndmask_b32_e64 v74, 0, v82, s[4:5]
	v_cndmask_b32_e64 v82, 0, v83, s[4:5]
	v_cvt_pk_bf16_f32 v74, v74, v82
	v_cvt_pk_bf16_f32 v75, v84, v75
	v_pk_add_f32 v[28:29], v[28:29], 0 op_sel_hi:[1,0]
	v_pk_add_f32 v[26:27], v[26:27], 0 op_sel_hi:[1,0]
	ds_write2_b64 v73, v[76:77], v[74:75] offset0:24 offset1:28
	v_pk_add_f32 v[74:75], v[218:219], 0 op_sel_hi:[1,0]
	v_pk_add_f32 v[76:77], v[216:217], 0 op_sel_hi:[1,0]
	v_pk_add_f32 v[58:59], v[58:59], 0 op_sel_hi:[1,0]
	v_pk_add_f32 v[54:55], v[54:55], 0 op_sel_hi:[1,0]
	v_pk_add_f32 v[50:51], v[50:51], 0 op_sel_hi:[1,0]
	v_pk_add_f32 v[46:47], v[46:47], 0 op_sel_hi:[1,0]
	v_pk_add_f32 v[42:43], v[42:43], 0 op_sel_hi:[1,0]
	v_pk_add_f32 v[38:39], v[38:39], 0 op_sel_hi:[1,0]
	v_pk_add_f32 v[34:35], v[34:35], 0 op_sel_hi:[1,0]
	v_pk_add_f32 v[30:31], v[30:31], 0 op_sel_hi:[1,0]
	v_cndmask_b32_e64 v28, 0, v28, s[4:5]
	v_cndmask_b32_e64 v26, 0, v26, s[4:5]
	v_cndmask_b32_e64 v27, 0, v27, s[4:5]
	v_pk_add_f32 v[22:23], v[22:23], 0 op_sel_hi:[1,0]
	v_pk_add_f32 v[18:19], v[18:19], 0 op_sel_hi:[1,0]
	v_pk_add_f32 v[14:15], v[14:15], 0 op_sel_hi:[1,0]
	v_pk_add_f32 v[10:11], v[10:11], 0 op_sel_hi:[1,0]
	v_pk_add_f32 v[6:7], v[6:7], 0 op_sel_hi:[1,0]
	v_pk_add_f32 v[2:3], v[2:3], 0 op_sel_hi:[1,0]
	v_cndmask_b32_e64 v82, 0, v74, s[6:7]
	v_cndmask_b32_e64 v75, 0, v75, s[6:7]
	v_cndmask_b32_e64 v74, 0, v76, s[6:7]
	v_pk_add_f32 v[68:69], v[68:69], 0 op_sel_hi:[1,0]
	v_cndmask_b32_e64 v66, 0, v66, s[8:9]
	v_cndmask_b32_e64 v67, 0, v67, s[8:9]
	v_pk_add_f32 v[64:65], v[64:65], 0 op_sel_hi:[1,0]
	v_cndmask_b32_e32 v62, 0, v62, vcc
	v_cndmask_b32_e32 v63, 0, v63, vcc
	v_pk_add_f32 v[60:61], v[60:61], 0 op_sel_hi:[1,0]
	v_cndmask_b32_e64 v58, 0, v58, s[4:5]
	v_cndmask_b32_e64 v59, 0, v59, s[4:5]
	v_pk_add_f32 v[56:57], v[56:57], 0 op_sel_hi:[1,0]
	v_cndmask_b32_e64 v54, 0, v54, s[6:7]
	v_cndmask_b32_e64 v55, 0, v55, s[6:7]
	v_pk_add_f32 v[52:53], v[52:53], 0 op_sel_hi:[1,0]
	v_cndmask_b32_e64 v50, 0, v50, s[8:9]
	v_cndmask_b32_e64 v51, 0, v51, s[8:9]
	v_pk_add_f32 v[48:49], v[48:49], 0 op_sel_hi:[1,0]
	v_cndmask_b32_e32 v46, 0, v46, vcc
	v_cndmask_b32_e32 v47, 0, v47, vcc
	v_pk_add_f32 v[44:45], v[44:45], 0 op_sel_hi:[1,0]
	v_cndmask_b32_e64 v42, 0, v42, s[4:5]
	v_cndmask_b32_e64 v43, 0, v43, s[4:5]
	v_pk_add_f32 v[40:41], v[40:41], 0 op_sel_hi:[1,0]
	v_cndmask_b32_e64 v38, 0, v38, s[6:7]
	v_cndmask_b32_e64 v39, 0, v39, s[6:7]
	v_pk_add_f32 v[36:37], v[36:37], 0 op_sel_hi:[1,0]
	v_cndmask_b32_e64 v34, 0, v34, s[8:9]
	v_cndmask_b32_e64 v35, 0, v35, s[8:9]
	v_pk_add_f32 v[32:33], v[32:33], 0 op_sel_hi:[1,0]
	v_cndmask_b32_e32 v30, 0, v30, vcc
	v_cndmask_b32_e32 v31, 0, v31, vcc
	v_cndmask_b32_e64 v29, 0, v29, s[4:5]
	v_cvt_pk_bf16_f32 v26, v26, v27
	v_cvt_pk_bf16_f32 v27, v28, v29
	v_pk_add_f32 v[24:25], v[24:25], 0 op_sel_hi:[1,0]
	v_cndmask_b32_e64 v22, 0, v22, s[6:7]
	v_cndmask_b32_e64 v23, 0, v23, s[6:7]
	v_pk_add_f32 v[20:21], v[20:21], 0 op_sel_hi:[1,0]
	v_cndmask_b32_e64 v18, 0, v18, s[8:9]
	v_cndmask_b32_e64 v19, 0, v19, s[8:9]
	v_pk_add_f32 v[16:17], v[16:17], 0 op_sel_hi:[1,0]
	v_cndmask_b32_e32 v14, 0, v14, vcc
	v_cndmask_b32_e32 v15, 0, v15, vcc
	v_pk_add_f32 v[12:13], v[12:13], 0 op_sel_hi:[1,0]
	v_cndmask_b32_e64 v10, 0, v10, s[4:5]
	v_cndmask_b32_e64 v11, 0, v11, s[4:5]
	v_pk_add_f32 v[8:9], v[8:9], 0 op_sel_hi:[1,0]
	v_cndmask_b32_e64 v6, 0, v6, s[6:7]
	v_cndmask_b32_e64 v7, 0, v7, s[6:7]
	v_pk_add_f32 v[4:5], v[4:5], 0 op_sel_hi:[1,0]
	v_cndmask_b32_e64 v2, 0, v2, s[8:9]
	v_cndmask_b32_e64 v3, 0, v3, s[8:9]
	v_mov_b32_e32 v28, v142
	v_cndmask_b32_e64 v76, 0, v77, s[6:7]
	v_cvt_pk_bf16_f32 v74, v74, v76
	v_cvt_pk_bf16_f32 v75, v82, v75
	ds_write2_b64 v86, v[78:79], v[74:75] offset0:40 offset1:44
	v_cndmask_b32_e64 v68, 0, v68, s[8:9]
	v_cndmask_b32_e64 v69, 0, v69, s[8:9]
	v_cvt_pk_bf16_f32 v66, v66, v67
	v_cvt_pk_bf16_f32 v67, v68, v69
	ds_write2_b64 v87, v[80:81], v[66:67] offset0:56 offset1:60
	v_cndmask_b32_e32 v64, 0, v64, vcc
	v_cndmask_b32_e32 v65, 0, v65, vcc
	v_cvt_pk_bf16_f32 v62, v62, v63
	v_cvt_pk_bf16_f32 v63, v64, v65
	v_cndmask_b32_e64 v60, 0, v60, s[4:5]
	v_cndmask_b32_e64 v61, 0, v61, s[4:5]
	v_cvt_pk_bf16_f32 v58, v58, v59
	v_cvt_pk_bf16_f32 v59, v60, v61
	v_cndmask_b32_e64 v56, 0, v56, s[6:7]
	v_cndmask_b32_e64 v57, 0, v57, s[6:7]
	v_cvt_pk_bf16_f32 v54, v54, v55
	v_cvt_pk_bf16_f32 v55, v56, v57
	v_cndmask_b32_e64 v52, 0, v52, s[8:9]
	v_cndmask_b32_e64 v53, 0, v53, s[8:9]
	v_cvt_pk_bf16_f32 v50, v50, v51
	v_cvt_pk_bf16_f32 v51, v52, v53
	v_cndmask_b32_e32 v48, 0, v48, vcc
	v_cndmask_b32_e32 v49, 0, v49, vcc
	v_cvt_pk_bf16_f32 v46, v46, v47
	v_cvt_pk_bf16_f32 v47, v48, v49
	ds_write2_b64 v71, v[62:63], v[46:47] offset0:16 offset1:20
	v_cndmask_b32_e64 v44, 0, v44, s[4:5]
	v_cndmask_b32_e64 v45, 0, v45, s[4:5]
	v_cvt_pk_bf16_f32 v42, v42, v43
; __device__ __forceinline__ int get_tid() { int t = threadIdx.x & 255; asm volatile("" : "+v"(t)); return t; }
;   template <class F>
;   __device__ __forceinline__ void finish(const bf16_t* Z, int g, int rig0, int nt, F&& pre) const {
;     typedef f32x2_t f32x2;
;     const int tid = get_tid();
;     if (MODE == 0 || nt < 8) {
;       if (MODE == 0) {
;         const int f2 = (tid & 31) * 2, q8 = tid >> 5;
;         const int q0 = 1 + 16 * q8, q1 = (q0 + 16 < 127) ? q0 + 16 : 127;
;         const int na = norig(nt, f2), ng = norig(nt, 64 + f2);
;         const f32x2 a0 = *(const f32x2*)(cw + na), a1 = *(const f32x2*)(cw + NC + na), a2 = *(const f32x2*)(cw + 2 * NC + na), ab = *(const f32x2*)(cb + na);
;         const f32x2 g0 = *(const f32x2*)(cw + ng), g1 = *(const f32x2*)(cw + NC + ng), g2 = *(const f32x2*)(cw + 2 * NC + ng), gb = *(const f32x2*)(cb + ng);
;         pre();
;         f32x2 am = ldz(Z, q0 - 1, f2), ac = ldz(Z, q0, f2);
;         f32x2 gm = ldz(Z, q0 - 1, 64 + f2), gc = ldz(Z, q0, 64 + f2);
; #pragma unroll 4
;         for (int pl = q0; pl < q1; ++pl) {
; template <bool SWAP, class Epi, bool THIN = false> ...
;     ...
;       __syncthreads();
	v_cvt_pk_bf16_f32 v43, v44, v45
	ds_write2_b64 v73, v[58:59], v[42:43] offset0:32 offset1:36
	v_cndmask_b32_e64 v40, 0, v40, s[6:7]
	v_cndmask_b32_e64 v41, 0, v41, s[6:7]
	v_cvt_pk_bf16_f32 v38, v38, v39
	v_cvt_pk_bf16_f32 v39, v40, v41
	ds_write2_b64 v86, v[54:55], v[38:39] offset0:48 offset1:52
	v_cndmask_b32_e64 v36, 0, v36, s[8:9]
	v_cndmask_b32_e64 v37, 0, v37, s[8:9]
	v_cvt_pk_bf16_f32 v34, v34, v35
	v_cvt_pk_bf16_f32 v35, v36, v37
	ds_write2_b64 v87, v[50:51], v[34:35] offset0:64 offset1:68
	v_cndmask_b32_e32 v32, 0, v32, vcc
	v_cndmask_b32_e32 v33, 0, v33, vcc
	v_cvt_pk_bf16_f32 v30, v30, v31
	v_cvt_pk_bf16_f32 v31, v32, v33
	v_cndmask_b32_e64 v24, 0, v24, s[6:7]
	v_cndmask_b32_e64 v25, 0, v25, s[6:7]
	v_cvt_pk_bf16_f32 v22, v22, v23
	v_cvt_pk_bf16_f32 v23, v24, v25
	v_cndmask_b32_e64 v20, 0, v20, s[8:9]
	v_cndmask_b32_e64 v21, 0, v21, s[8:9]
	v_cvt_pk_bf16_f32 v18, v18, v19
	v_cvt_pk_bf16_f32 v19, v20, v21
	v_cndmask_b32_e32 v16, 0, v16, vcc
	v_cndmask_b32_e32 v17, 0, v17, vcc
	v_cvt_pk_bf16_f32 v14, v14, v15
	v_cvt_pk_bf16_f32 v15, v16, v17
	ds_write2_b64 v71, v[30:31], v[14:15] offset0:24 offset1:28
	v_cndmask_b32_e64 v12, 0, v12, s[4:5]
	v_cndmask_b32_e64 v13, 0, v13, s[4:5]
	v_cvt_pk_bf16_f32 v10, v10, v11
	v_cvt_pk_bf16_f32 v11, v12, v13
	ds_write2_b64 v73, v[26:27], v[10:11] offset0:40 offset1:44
	v_cndmask_b32_e64 v8, 0, v8, s[6:7]
	v_cndmask_b32_e64 v9, 0, v9, s[6:7]
	v_cvt_pk_bf16_f32 v6, v6, v7
	v_cvt_pk_bf16_f32 v7, v8, v9
	ds_write2_b64 v86, v[22:23], v[6:7] offset0:56 offset1:60
	v_cndmask_b32_e64 v4, 0, v4, s[8:9]
	v_cndmask_b32_e64 v5, 0, v5, s[8:9]
	v_cvt_pk_bf16_f32 v2, v2, v3
	v_cvt_pk_bf16_f32 v3, v4, v5
	ds_write2_b64 v87, v[18:19], v[2:3] offset0:72 offset1:76
	s_waitcnt lgkmcnt(0)
	s_barrier
	v_mul_i32_i24_e32 v2, 0x10800, v98
	v_ashrrev_i32_e32 v29, 1, v28
	v_and_b32_e32 v38, -16, v29
	v_min_i32_e32 v3, 0x6e, v38
	v_or_b32_e32 v20, 1, v38
	v_add_u32_e32 v3, 17, v3
	v_cmp_lt_i32_e32 vcc, v20, v3
	v_ashrrev_i32_e32 v71, 31, v70
	s_and_saveexec_b64 s[4:5], vcc
	s_cbranch_execz .LBB0_3432
	v_lshlrev_b32_e32 v4, 1, v28
	v_and_b32_e32 v21, 62, v4
	v_or_b32_e32 v4, s24, v21
	s_add_i32 s6, s24, 0xb00
	v_ashrrev_i32_e32 v5, 31, v4
	v_or_b32_e32 v12, s6, v21
	v_lshlrev_b64 v[10:11], 2, v[4:5]
	v_lshl_add_u64 v[14:15], s[16:17], 0, v[10:11]
	v_lshl_add_u64 v[18:19], s[22:23], 0, v[10:11]
	v_ashrrev_i32_e32 v13, 31, v12
	v_lshl_add_u64 v[16:17], s[20:21], 0, v[10:11]
	global_load_dwordx2 v[4:5], v[14:15], off
	global_load_dwordx2 v[6:7], v[16:17], off
	global_load_dwordx2 v[8:9], v[18:19], off
	v_lshlrev_b64 v[18:19], 2, v[12:13]
	v_lshl_add_u64 v[10:11], s[18:19], 0, v[10:11]
	v_lshl_add_u64 v[22:23], s[16:17], 0, v[18:19]
	global_load_dwordx2 v[10:11], v[10:11], off
	v_lshl_add_u64 v[24:25], s[20:21], 0, v[18:19]
	v_lshl_add_u64 v[26:27], s[22:23], 0, v[18:19]
	global_load_dwordx2 v[12:13], v[22:23], off
	global_load_dwordx2 v[14:15], v[24:25], off
	global_load_dwordx2 v[16:17], v[26:27], off
	v_lshl_add_u64 v[18:19], s[18:19], 0, v[18:19]
	global_load_dwordx2 v[18:19], v[18:19], off
	v_mov_b32_e32 v117, 0
	v_lshlrev_b32_e32 v88, 1, v142
	v_and_b32_e32 v105, 62, v88
	v_add3_u32 v88, v105, s24, 64
	s_add_i32 s38, s24, 0xb40
	v_ashrrev_i32_e32 v89, 31, v88
	v_or_b32_e32 v96, s38, v105
	v_lshlrev_b64 v[94:95], 2, v[88:89]
	v_lshl_add_u64 v[98:99], s[16:17], 0, v[94:95]
	v_lshl_add_u64 v[102:103], s[22:23], 0, v[94:95]
	v_ashrrev_i32_e32 v97, 31, v96
	v_lshl_add_u64 v[100:101], s[20:21], 0, v[94:95]
	global_load_dwordx2 v[88:89], v[98:99], off
	global_load_dwordx2 v[90:91], v[100:101], off
	global_load_dwordx2 v[92:93], v[102:103], off
	v_lshlrev_b64 v[102:103], 2, v[96:97]
	v_lshl_add_u64 v[94:95], s[18:19], 0, v[94:95]
	v_lshl_add_u64 v[106:107], s[16:17], 0, v[102:103]
	global_load_dwordx2 v[94:95], v[94:95], off
	v_lshl_add_u64 v[108:109], s[20:21], 0, v[102:103]
	v_lshl_add_u64 v[110:111], s[22:23], 0, v[102:103]
	global_load_dwordx2 v[96:97], v[106:107], off
	global_load_dwordx2 v[98:99], v[108:109], off
	global_load_dwordx2 v[100:101], v[110:111], off
	v_lshl_add_u64 v[102:103], s[18:19], 0, v[102:103]
	global_load_dwordx2 v[102:103], v[102:103], off
	v_lshlrev_b32_e32 v136, 1, v21
	v_mul_lo_u32 v22, v38, s31
	v_mul_lo_u32 v20, v20, s31
	v_add3_u32 v22, v2, v22, v136
	v_add3_u32 v20, v2, v20, v136
	ds_read2_b32 v[22:23], v22 offset1:32
	ds_read2_b32 v[20:21], v20 offset1:32
	s_ashr_i32 s25, s24, 31
	s_lshl_b64 s[6:7], s[24:25], 1
	s_add_u32 s6, s12, s6
	s_addc_u32 s7, s13, s7
	v_lshrrev_b32_e32 v29, 4, v29
	v_and_b32_e32 v28, 31, v28
	s_waitcnt lgkmcnt(1)
	v_lshlrev_b32_e32 v32, 16, v23
	v_and_b32_e32 v33, 0xffff0000, v23
	v_lshlrev_b32_e32 v34, 16, v22
	v_and_b32_e32 v35, 0xffff0000, v22
	v_lshl_add_u64 v[22:23], s[6:7], 0, v[136:137]
	v_mad_u64_u32 v[30:31], s[6:7], v29, s33, v[2:3]
	v_lshlrev_b32_e32 v28, 2, v28
	s_waitcnt lgkmcnt(0)
	v_lshlrev_b32_e32 v24, 16, v21
	v_and_b32_e32 v25, 0xffff0000, v21
	v_lshlrev_b32_e32 v26, 16, v20
	v_and_b32_e32 v27, 0xffff0000, v20
	v_lshlrev_b64 v[20:21], 11, v[70:71]
	v_add3_u32 v39, v30, v28, s34
	s_mov_b32 s98, 0x1600
	s_mov_b32 s99, 0
	v_add_u32_e32 v48, v72, v38
	v_ashrrev_i32_e32 v49, 31, v48
	v_lshl_add_u64 v[48:49], v[20:21], 0, v[48:49]
	v_mad_u64_u32 v[50:51], s[38:39], v48, s35, v[22:23]
	v_mad_i32_i24 v51, v49, s35, v51
	s_mov_b64 s[6:7], 0
	s_waitcnt vmcnt(0)
	ds_read2_b32 v[44:45], v39 offset1:32
	s_branch .LBB0_3428

; template <bool SWAP, class Epi, bool THIN = false> ...
;     ...
;     for (int st = 0; st < ns; ++st) {
;       asm volatile("s_waitcnt vmcnt(0)" ::: "memory");
;       __builtin_amdgcn_s_barrier();
;       asm volatile("" ::: "memory");
;       if (st + 1 < ns) {
;         char* nb = smem + ((st + 1) & 1) * 65536;
;         const int ko = (st + 1) * 64;
; #pragma unroll
;         for (int i = 0; i < 4; ++i) { GLDS16(A + (size_t)(ap[i] + ko), nb + tid * 16 + i * 8192); GLDS16(Bt + (size_t)(bp[i] + ko), nb + 32768 + tid * 16 + i * 8192); }
;       }
;       const char* sa = smem + (st & 1) * 65536 + (wr * 64 + fr) * 128;
;       const char* sb = smem + (st & 1) * 65536 + 32768 + (wc * 128 + fr) * 128;
;       if constexpr (THIN) {
;         if (wc == 0) {
; #pragma unroll
;           for (int ks = 0; ks < 2; ++ks) {
;             bf16x8 af[4], bf[2];
; #pragma unroll
;             for (int m = 0; m < 4; ++m) af[m] = *(const bf16x8*)(sa + m * 2048 + (((ks * 4 + fq) ^ swz) << 4));
; #pragma unroll
;             for (int n = 0; n < 2; ++n) bf[n] = *(const bf16x8*)(sb + n * 2048 + (((ks * 4 + fq) ^ swz) << 4));
; #pragma unroll
;             for (int m = 0; m < 4; ++m)
; #pragma unroll
;               for (int n = 0; n < 2; ++n)
;                 acc[m][n] = SWAP ? __builtin_amdgcn_mfma_f32_16x16x32_bf16(bf[n], af[m], acc[m][n], 0, 0, 0)
;                                  : __builtin_amdgcn_mfma_f32_16x16x32_bf16(af[m], bf[n], acc[m][n], 0, 0, 0);
;           }
;         }
;       } else {
;       bf16x8 afA[4], afB[4], bfb[2][2];
; #pragma unroll
;       for (int m = 0; m < 4; ++m) afA[m] = *(const bf16x8*)(sa + m * 2048 + ((fq ^ swz) << 4));
; #pragma unroll
;       for (int n = 0; n < 2; ++n) bfb[0][n] = *(const bf16x8*)(sb + n * 2048 + ((fq ^ swz) << 4));
; #pragma unroll
;       for (int gq = 0; gq < 8; ++gq) {
;         const int ks = gq >> 2, nh = gq & 3;
;         if (gq < 7) {
;           const int ks2 = (gq + 1) >> 2, nh2 = (gq + 1) & 3;
; #pragma unroll
;           for (int n = 0; n < 2; ++n) bfb[(gq + 1) & 1][n] = *(const bf16x8*)(sb + (nh2 * 2 + n) * 2048 + (((ks2 * 4 + fq) ^ swz) << 4));
;         }
;         if (gq == 3) {
; #pragma unroll
;           for (int m = 0; m < 4; ++m) afB[m] = *(const bf16x8*)(sa + m * 2048 + (((4 + fq) ^ swz) << 4));
;         }
;         __builtin_amdgcn_sched_barrier(0);
; #pragma unroll
.LBB0_3516:
	s_add_i32 s9, s7, 0x10000
	s_and_b32 s8, s9, 0x10000
	v_add_u32_e32 v139, s8, v144
	s_nop 0
	v_readfirstlane_b32 s10, v139
	s_and_b32 s7, s7, 0x10000
	v_add_u32_e32 v130, s7, v145
	v_add_u32_e32 v139, v130, v147
	s_waitcnt vmcnt(0)
	s_barrier
	ds_read_b128 v[168:171], v139
	ds_read_b128 v[172:175], v139 offset:2048
	ds_read_b128 v[176:179], v139 offset:4096
	ds_read_b128 v[180:183], v139 offset:6144
	v_or_b32_e32 v139, s7, v146
	v_add_u32_e32 v141, v139, v147
	ds_read_b128 v[184:187], v141 offset:32768
	ds_read_b128 v[188:191], v141 offset:34816
	ds_read_b128 v[192:195], v141 offset:36864
	ds_read_b128 v[196:199], v141 offset:38912
	v_add_u32_e32 v130, v130, v148
	s_waitcnt lgkmcnt(3)
	v_mfma_f32_16x16x32_bf16 v[126:129], v[184:187], v[168:171], v[126:129]
	s_mov_b32 m0, s10
	v_mfma_f32_16x16x32_bf16 v[110:113], v[184:187], v[172:175], v[110:113]
	global_load_lds_dwordx4 v138, s[24:25]
	v_add_u32_e32 v138, 0x80, v138
	v_mfma_f32_16x16x32_bf16 v[82:85], v[184:187], v[176:179], v[82:85]
	v_mfma_f32_16x16x32_bf16 v[50:53], v[184:187], v[180:183], v[50:53]
	ds_read_b128 v[184:187], v141 offset:40960
	ds_read_b128 v[200:203], v141 offset:43008
	s_waitcnt lgkmcnt(4)
	v_mfma_f32_16x16x32_bf16 v[122:125], v[188:191], v[168:171], v[122:125]
	s_add_u32 m0, s10, 0x8000
	v_mfma_f32_16x16x32_bf16 v[106:109], v[188:191], v[172:175], v[106:109]
	global_load_lds_dwordx4 v137, s[20:21]
	v_add_u32_e32 v137, 0x80, v137
	v_mfma_f32_16x16x32_bf16 v[78:81], v[188:191], v[176:179], v[78:81]
	v_mfma_f32_16x16x32_bf16 v[38:41], v[188:191], v[180:183], v[38:41]
	s_waitcnt lgkmcnt(3)
	v_mfma_f32_16x16x32_bf16 v[118:121], v[192:195], v[168:171], v[118:121]
	s_add_u32 m0, s10, 0x2000
	v_mfma_f32_16x16x32_bf16 v[94:97], v[192:195], v[172:175], v[94:97]
	global_load_lds_dwordx4 v136, s[24:25]
	v_add_u32_e32 v136, 0x80, v136
	v_mfma_f32_16x16x32_bf16 v[58:61], v[192:195], v[176:179], v[58:61]
	v_mfma_f32_16x16x32_bf16 v[26:29], v[192:195], v[180:183], v[26:29]
	ds_read_b128 v[188:191], v141 offset:45056
	ds_read_b128 v[192:195], v141 offset:47104
	s_waitcnt lgkmcnt(4)
	v_mfma_f32_16x16x32_bf16 v[114:117], v[196:199], v[168:171], v[114:117]
	s_add_u32 m0, s10, 0xa000
	v_mfma_f32_16x16x32_bf16 v[86:89], v[196:199], v[172:175], v[86:89]
	global_load_lds_dwordx4 v135, s[20:21]
	v_add_u32_e32 v135, 0x80, v135
	v_mfma_f32_16x16x32_bf16 v[54:57], v[196:199], v[176:179], v[54:57]
	v_mfma_f32_16x16x32_bf16 v[22:25], v[196:199], v[180:183], v[22:25]
	v_add_u32_e32 v139, v139, v148
	s_waitcnt lgkmcnt(3)
	v_mfma_f32_16x16x32_bf16 v[102:105], v[184:187], v[168:171], v[102:105]
	ds_read_b128 v[196:199], v139 offset:32768
	ds_read_b128 v[204:207], v139 offset:34816
	s_add_u32 m0, s10, 0x4000
	v_mfma_f32_16x16x32_bf16 v[74:77], v[184:187], v[172:175], v[74:77]
	global_load_lds_dwordx4 v134, s[24:25]
	v_add_u32_e32 v134, 0x80, v134
	v_mfma_f32_16x16x32_bf16 v[46:49], v[184:187], v[176:179], v[46:49]
	v_mfma_f32_16x16x32_bf16 v[10:13], v[184:187], v[180:183], v[10:13]
	ds_read_b128 v[184:187], v130
	ds_read_b128 v[208:211], v130 offset:2048
	ds_read_b128 v[212:215], v130 offset:4096
	ds_read_b128 v[216:219], v130 offset:6144
	s_waitcnt lgkmcnt(8)
	v_mfma_f32_16x16x32_bf16 v[98:101], v[200:203], v[168:171], v[98:101]
	s_add_u32 m0, s10, 0xc000
	v_mfma_f32_16x16x32_bf16 v[66:69], v[200:203], v[172:175], v[66:69]
	global_load_lds_dwordx4 v133, s[20:21]
	v_add_u32_e32 v133, 0x80, v133
	v_mfma_f32_16x16x32_bf16 v[34:37], v[200:203], v[176:179], v[34:37]
	v_mfma_f32_16x16x32_bf16 v[6:9], v[200:203], v[180:183], v[6:9]
	s_waitcnt lgkmcnt(7)
	v_mfma_f32_16x16x32_bf16 v[70:73], v[188:191], v[168:171], v[70:73]
	s_add_u32 m0, s10, 0x6000
	s_waitcnt lgkmcnt(6)
	v_mfma_f32_16x16x32_bf16 v[62:65], v[192:195], v[168:171], v[62:65]
	global_load_lds_dwordx4 v132, s[24:25]
	v_add_u32_e32 v132, 0x80, v132
	v_mfma_f32_16x16x32_bf16 v[42:45], v[188:191], v[172:175], v[42:45]
	v_mfma_f32_16x16x32_bf16 v[30:33], v[192:195], v[172:175], v[30:33]
	ds_read_b128 v[168:171], v139 offset:36864
	ds_read_b128 v[172:175], v139 offset:38912
	v_mfma_f32_16x16x32_bf16 v[18:21], v[188:191], v[176:179], v[18:21]
	s_add_u32 m0, s10, 0xe000
	v_mfma_f32_16x16x32_bf16 v[14:17], v[192:195], v[176:179], v[14:17]
	global_load_lds_dwordx4 v140, s[20:21]
	v_add_u32_e32 v140, 0x80, v140
	v_mfma_f32_16x16x32_bf16 v[2:5], v[188:191], v[180:183], v[2:5]
	v_mfma_f32_16x16x32_bf16 v[90:93], v[192:195], v[180:183], v[90:93]
	ds_read_b128 v[176:179], v139 offset:40960
	ds_read_b128 v[180:183], v139 offset:43008
	s_waitcnt lgkmcnt(7)
	v_mfma_f32_16x16x32_bf16 v[126:129], v[196:199], v[184:187], v[126:129]
	v_mfma_f32_16x16x32_bf16 v[122:125], v[204:207], v[184:187], v[122:125]
	s_waitcnt lgkmcnt(6)
	v_mfma_f32_16x16x32_bf16 v[110:113], v[196:199], v[208:211], v[110:113]
	v_mfma_f32_16x16x32_bf16 v[106:109], v[204:207], v[208:211], v[106:109]
	s_waitcnt lgkmcnt(5)
	v_mfma_f32_16x16x32_bf16 v[82:85], v[196:199], v[212:215], v[82:85]
	v_mfma_f32_16x16x32_bf16 v[78:81], v[204:207], v[212:215], v[78:81]
	s_waitcnt lgkmcnt(4)
	v_mfma_f32_16x16x32_bf16 v[50:53], v[196:199], v[216:219], v[50:53]
	v_mfma_f32_16x16x32_bf16 v[38:41], v[204:207], v[216:219], v[38:41]
	s_waitcnt lgkmcnt(3)
	v_mfma_f32_16x16x32_bf16 v[118:121], v[168:171], v[184:187], v[118:121]
	v_mfma_f32_16x16x32_bf16 v[94:97], v[168:171], v[208:211], v[94:97]
	v_mfma_f32_16x16x32_bf16 v[58:61], v[168:171], v[212:215], v[58:61]
	v_mfma_f32_16x16x32_bf16 v[26:29], v[168:171], v[216:219], v[26:29]
	ds_read_b128 v[168:171], v139 offset:45056
	ds_read_b128 v[188:191], v139 offset:47104
	s_waitcnt lgkmcnt(4)
; template <bool SWAP, class Epi, bool THIN = false> ...
;     ...
;       bf16x8 afA[4], afB[4], bfb[2][2];
; #pragma unroll
;       for (int m = 0; m < 4; ++m) afA[m] = *(const bf16x8*)(sa + m * 2048 + ((fq ^ swz) << 4));
; #pragma unroll
;       for (int n = 0; n < 2; ++n) bfb[0][n] = *(const bf16x8*)(sb + n * 2048 + ((fq ^ swz) << 4));
; #pragma unroll
;       for (int gq = 0; gq < 8; ++gq) {
;         const int ks = gq >> 2, nh = gq & 3;
;         if (gq < 7) {
;           const int ks2 = (gq + 1) >> 2, nh2 = (gq + 1) & 3;
; #pragma unroll
;           for (int n = 0; n < 2; ++n) bfb[(gq + 1) & 1][n] = *(const bf16x8*)(sb + (nh2 * 2 + n) * 2048 + (((ks2 * 4 + fq) ^ swz) << 4));
;         }
;         if (gq == 3) {
; #pragma unroll
;           for (int m = 0; m < 4; ++m) afB[m] = *(const bf16x8*)(sa + m * 2048 + (((4 + fq) ^ swz) << 4));
;         }
;         __builtin_amdgcn_sched_barrier(0);
; #pragma unroll
;         for (int m = 0; m < 4; ++m)
; #pragma unroll
;           for (int n = 0; n < 2; ++n) {
;             const bf16x8 av = ks ? afB[m] : afA[m];
;             acc[m][nh * 2 + n] = SWAP ? __builtin_amdgcn_mfma_f32_16x16x32_bf16(bfb[gq & 1][n], av, acc[m][nh * 2 + n], 0, 0, 0)
;                                       : __builtin_amdgcn_mfma_f32_16x16x32_bf16(av, bfb[gq & 1][n], acc[m][nh * 2 + n], 0, 0, 0);
;           }
;       }
;       }
	v_mfma_f32_16x16x32_bf16 v[114:117], v[172:175], v[184:187], v[114:117]
	v_mfma_f32_16x16x32_bf16 v[86:89], v[172:175], v[208:211], v[86:89]
	v_mfma_f32_16x16x32_bf16 v[54:57], v[172:175], v[212:215], v[54:57]
	v_mfma_f32_16x16x32_bf16 v[22:25], v[172:175], v[216:219], v[22:25]
	s_waitcnt lgkmcnt(3)
	v_mfma_f32_16x16x32_bf16 v[102:105], v[176:179], v[184:187], v[102:105]
	s_waitcnt lgkmcnt(2)
	v_mfma_f32_16x16x32_bf16 v[98:101], v[180:183], v[184:187], v[98:101]
	v_mfma_f32_16x16x32_bf16 v[74:77], v[176:179], v[208:211], v[74:77]
	v_mfma_f32_16x16x32_bf16 v[66:69], v[180:183], v[208:211], v[66:69]
	v_mfma_f32_16x16x32_bf16 v[46:49], v[176:179], v[212:215], v[46:49]
	v_mfma_f32_16x16x32_bf16 v[34:37], v[180:183], v[212:215], v[34:37]
	v_mfma_f32_16x16x32_bf16 v[10:13], v[176:179], v[216:219], v[10:13]
	v_mfma_f32_16x16x32_bf16 v[6:9], v[180:183], v[216:219], v[6:9]
	s_waitcnt lgkmcnt(1)
	v_mfma_f32_16x16x32_bf16 v[70:73], v[168:171], v[184:187], v[70:73]
	s_add_i32 s6, s6, 64
	s_cmpk_eq_i32 s6, 0xac0
	s_mov_b32 s7, s9
	s_waitcnt lgkmcnt(0)
	v_mfma_f32_16x16x32_bf16 v[62:65], v[188:191], v[184:187], v[62:65]
	v_mfma_f32_16x16x32_bf16 v[42:45], v[168:171], v[208:211], v[42:45]
	v_mfma_f32_16x16x32_bf16 v[30:33], v[188:191], v[208:211], v[30:33]
	v_mfma_f32_16x16x32_bf16 v[18:21], v[168:171], v[212:215], v[18:21]
	v_mfma_f32_16x16x32_bf16 v[14:17], v[188:191], v[212:215], v[14:17]
	v_mfma_f32_16x16x32_bf16 v[2:5], v[168:171], v[216:219], v[2:5]
	v_mfma_f32_16x16x32_bf16 v[90:93], v[188:191], v[216:219], v[90:93]
	s_cbranch_scc0 .LBB0_3516
	v_add_u32_e32 v130, s8, v145
	s_waitcnt vmcnt(0)
	s_barrier
	v_add_u32_e32 v140, v130, v147
	ds_read_b128 v[132:135], v140
	ds_read_b128 v[136:139], v140 offset:2048
	ds_read_b128 v[168:171], v140 offset:4096
	ds_read_b128 v[172:175], v140 offset:6144
	v_add_u32_e32 v140, s8, v146
	v_add_u32_e32 v141, v140, v147
	ds_read_b128 v[176:179], v141 offset:32768
	ds_read_b128 v[180:183], v141 offset:34816
	ds_read_b128 v[184:187], v141 offset:36864
	ds_read_b128 v[188:191], v141 offset:38912
	v_add_u32_e32 v130, v130, v148
	s_waitcnt lgkmcnt(3)
	v_mfma_f32_16x16x32_bf16 v[126:129], v[176:179], v[132:135], v[126:129]
	v_mfma_f32_16x16x32_bf16 v[110:113], v[176:179], v[136:139], v[110:113]
	v_mfma_f32_16x16x32_bf16 v[82:85], v[176:179], v[168:171], v[82:85]
	v_mfma_f32_16x16x32_bf16 v[50:53], v[176:179], v[172:175], v[50:53]
	ds_read_b128 v[176:179], v141 offset:40960
	ds_read_b128 v[192:195], v141 offset:43008
	s_waitcnt lgkmcnt(4)
	v_mfma_f32_16x16x32_bf16 v[122:125], v[180:183], v[132:135], v[122:125]
	v_mfma_f32_16x16x32_bf16 v[106:109], v[180:183], v[136:139], v[106:109]
	v_mfma_f32_16x16x32_bf16 v[78:81], v[180:183], v[168:171], v[78:81]
	v_mfma_f32_16x16x32_bf16 v[38:41], v[180:183], v[172:175], v[38:41]
	s_waitcnt lgkmcnt(3)
	v_mfma_f32_16x16x32_bf16 v[118:121], v[184:187], v[132:135], v[118:121]
	v_mfma_f32_16x16x32_bf16 v[180:183], v[184:187], v[136:139], v[94:97]
	v_mfma_f32_16x16x32_bf16 v[200:203], v[184:187], v[168:171], v[58:61]
	s_waitcnt lgkmcnt(2)
	v_mfma_f32_16x16x32_bf16 v[204:207], v[188:191], v[168:171], v[54:57]
	v_mfma_f32_16x16x32_bf16 v[184:187], v[184:187], v[172:175], v[26:29]
	s_nop 2
	ds_read_b128 v[26:29], v141 offset:45056
	ds_read_b128 v[54:57], v141 offset:47104
	v_mfma_f32_16x16x32_bf16 v[114:117], v[188:191], v[132:135], v[114:117]
	v_mfma_f32_16x16x32_bf16 v[196:199], v[188:191], v[136:139], v[86:89]
	v_mfma_f32_16x16x32_bf16 v[188:191], v[188:191], v[172:175], v[22:25]
	v_add_u32_e32 v140, v140, v148
	s_waitcnt lgkmcnt(3)
	v_mfma_f32_16x16x32_bf16 v[102:105], v[176:179], v[132:135], v[102:105]
	ds_read_b128 v[22:25], v140 offset:32768
	ds_read_b128 v[86:89], v140 offset:34816
	v_mfma_f32_16x16x32_bf16 v[74:77], v[176:179], v[136:139], v[74:77]
	v_mfma_f32_16x16x32_bf16 v[46:49], v[176:179], v[168:171], v[46:49]
	v_mfma_f32_16x16x32_bf16 v[10:13], v[176:179], v[172:175], v[10:13]
	ds_read_b128 v[176:179], v130
	ds_read_b128 v[208:211], v130 offset:2048
	ds_read_b128 v[212:215], v130 offset:4096
	ds_read_b128 v[216:219], v130 offset:6144
	s_waitcnt lgkmcnt(8)
	v_mfma_f32_16x16x32_bf16 v[98:101], v[192:195], v[132:135], v[98:101]
	v_mfma_f32_16x16x32_bf16 v[66:69], v[192:195], v[136:139], v[66:69]
	v_mfma_f32_16x16x32_bf16 v[34:37], v[192:195], v[168:171], v[34:37]
	v_mfma_f32_16x16x32_bf16 v[6:9], v[192:195], v[172:175], v[6:9]
	s_waitcnt lgkmcnt(7)
	v_mfma_f32_16x16x32_bf16 v[220:223], v[26:29], v[168:171], v[18:21]
	s_waitcnt lgkmcnt(6)
	v_mfma_f32_16x16x32_bf16 v[168:171], v[54:57], v[168:171], v[14:17]
	s_nop 2
	ds_read_b128 v[14:17], v140 offset:36864
	ds_read_b128 v[18:21], v140 offset:38912
	v_mfma_f32_16x16x32_bf16 v[70:73], v[26:29], v[132:135], v[70:73]
	v_mfma_f32_16x16x32_bf16 v[132:135], v[54:57], v[132:135], v[62:65]
	v_mfma_f32_16x16x32_bf16 v[192:195], v[26:29], v[136:139], v[42:45]
	v_mfma_f32_16x16x32_bf16 v[136:139], v[54:57], v[136:139], v[30:33]
	v_mfma_f32_16x16x32_bf16 v[2:5], v[26:29], v[172:175], v[2:5]
	v_mfma_f32_16x16x32_bf16 v[172:175], v[54:57], v[172:175], v[90:93]
	ds_read_b128 v[224:227], v140 offset:40960
	ds_read_b128 v[228:231], v140 offset:43008
	s_waitcnt lgkmcnt(7)
	v_mfma_f32_16x16x32_bf16 v[126:129], v[22:25], v[176:179], v[126:129]
	v_mfma_f32_16x16x32_bf16 v[122:125], v[86:89], v[176:179], v[122:125]
	s_waitcnt lgkmcnt(6)
	v_mfma_f32_16x16x32_bf16 v[94:97], v[22:25], v[208:211], v[110:113]
	v_mfma_f32_16x16x32_bf16 v[90:93], v[86:89], v[208:211], v[106:109]
	s_waitcnt lgkmcnt(5)
	v_mfma_f32_16x16x32_bf16 v[62:65], v[22:25], v[212:215], v[82:85]
	v_mfma_f32_16x16x32_bf16 v[58:61], v[86:89], v[212:215], v[78:81]
	s_waitcnt lgkmcnt(4)
; __device__ __forceinline__ unsigned pack2(float a, float b) { unsigned r; asm("v_cvt_pk_bf16_f32 %0, %1, %2" : "=v"(r) : "v"(a), "v"(b)); return r; }
; __device__ __forceinline__ float bf2f(bf16_t h) { return __uint_as_float(((unsigned)h) << 16); }
;   __device__ __forceinline__ void c4(int g, int rig, int col, f32x4 v) const {
;     const size_t o = ((size_t)g * 2048 + rig) * 1024 + col;
;     f32x4 bs;
;     if (BASE_F32) bs = __builtin_nontemporal_load((const f32x4*)((const float*)base + o));
;     else {
;       const uint2 u = *(const uint2*)((const bf16_t*)base + o);
;       bs[0] = bf2f((bf16_t)(u.x & 0xffff)); bs[1] = bf2f((bf16_t)(u.x >> 16)); bs[2] = bf2f((bf16_t)(u.y & 0xffff)); bs[3] = bf2f((bf16_t)(u.y >> 16));
;     }
;     const f32x4 gt = *(const f32x4*)(gate + (size_t)g * 6144 + col);
;     f32x4 bi = {0.f, 0.f, 0.f, 0.f};
;     if (bias) bi = *(const f32x4*)(bias + col);
;     f32x4 r;
; #pragma unroll
;     for (int j = 0; j < 4; ++j) r[j] = bs[j] + gt[j] * (v[j] + bi[j]);
;     uint2 w; w.x = pack2(r[0], r[1]); w.y = pack2(r[2], r[3]);
;     *(uint2*)(X16 + o) = w;
;   }
; template <bool SWAP, class Epi, bool THIN = false> ...
;     ...
;           const int ks2 = (gq + 1) >> 2, nh2 = (gq + 1) & 3;
; #pragma unroll
;           for (int n = 0; n < 2; ++n) bfb[(gq + 1) & 1][n] = *(const bf16x8*)(sb + (nh2 * 2 + n) * 2048 + (((ks2 * 4 + fq) ^ swz) << 4));
;         }
;         if (gq == 3) {
; #pragma unroll
;           for (int m = 0; m < 4; ++m) afB[m] = *(const bf16x8*)(sa + m * 2048 + (((4 + fq) ^ swz) << 4));
;         }
;         __builtin_amdgcn_sched_barrier(0);
; #pragma unroll
;         for (int m = 0; m < 4; ++m)
; #pragma unroll
;           for (int n = 0; n < 2; ++n) {
;             const bf16x8 av = ks ? afB[m] : afA[m];
;             acc[m][nh * 2 + n] = SWAP ? __builtin_amdgcn_mfma_f32_16x16x32_bf16(bfb[gq & 1][n], av, acc[m][nh * 2 + n], 0, 0, 0)
;                                       : __builtin_amdgcn_mfma_f32_16x16x32_bf16(av, bfb[gq & 1][n], acc[m][nh * 2 + n], 0, 0, 0);
;           }
;       }
;       }
	v_mfma_f32_16x16x32_bf16 v[30:33], v[22:25], v[216:219], v[50:53]
	v_mfma_f32_16x16x32_bf16 v[26:29], v[86:89], v[216:219], v[38:41]
	s_waitcnt lgkmcnt(3)
	v_mfma_f32_16x16x32_bf16 v[86:89], v[14:17], v[208:211], v[180:183]
	v_mfma_f32_16x16x32_bf16 v[22:25], v[14:17], v[216:219], v[184:187]
	s_nop 1
	ds_read_b128 v[180:183], v140 offset:45056
	ds_read_b128 v[184:187], v140 offset:47104
	v_mfma_f32_16x16x32_bf16 v[118:121], v[14:17], v[176:179], v[118:121]
	s_waitcnt lgkmcnt(4)
	v_mfma_f32_16x16x32_bf16 v[114:117], v[18:21], v[176:179], v[114:117]
	v_mfma_f32_16x16x32_bf16 v[82:85], v[18:21], v[208:211], v[196:199]
	v_mfma_f32_16x16x32_bf16 v[54:57], v[14:17], v[212:215], v[200:203]
	v_mfma_f32_16x16x32_bf16 v[50:53], v[18:21], v[212:215], v[204:207]
	v_mfma_f32_16x16x32_bf16 v[18:21], v[18:21], v[216:219], v[188:191]
	s_waitcnt lgkmcnt(3)
	v_mfma_f32_16x16x32_bf16 v[110:113], v[224:227], v[176:179], v[102:105]
	s_waitcnt lgkmcnt(2)
	v_mfma_f32_16x16x32_bf16 v[106:109], v[228:231], v[176:179], v[98:101]
	v_mfma_f32_16x16x32_bf16 v[78:81], v[224:227], v[208:211], v[74:77]
	v_mfma_f32_16x16x32_bf16 v[74:77], v[228:231], v[208:211], v[66:69]
	v_mfma_f32_16x16x32_bf16 v[46:49], v[224:227], v[212:215], v[46:49]
	v_mfma_f32_16x16x32_bf16 v[42:45], v[228:231], v[212:215], v[34:37]
	v_mfma_f32_16x16x32_bf16 v[14:17], v[224:227], v[216:219], v[10:13]
	v_mfma_f32_16x16x32_bf16 v[10:13], v[228:231], v[216:219], v[6:9]
	v_mov_b32_e32 v130, v1
	s_waitcnt vmcnt(0) lgkmcnt(0)
	s_barrier
	v_mfma_f32_16x16x32_bf16 v[98:101], v[184:187], v[176:179], v[132:135]
	v_ashrrev_i32_e32 v7, 8, v130
	v_add_u32_e32 v7, s5, v7
	v_ashrrev_i32_e32 v8, 31, v7
	v_lshrrev_b32_e32 v8, 28, v8
	v_add_u32_e32 v8, v7, v8
	v_ashrrev_i32_e32 v134, 4, v8
	v_lshlrev_b32_e32 v8, 11, v134
	v_lshlrev_b32_e32 v7, 7, v7
	v_sub_u32_e32 v7, v7, v8
	v_lshrrev_b32_e32 v8, 1, v130
	v_and_b32_e32 v6, 15, v130
	v_and_b32_e32 v8, 64, v8
	v_mfma_f32_16x16x32_bf16 v[66:69], v[184:187], v[208:211], v[136:139]
	v_ashrrev_i32_e32 v135, 31, v134
	s_nop 1
	v_or3_b32 v136, v7, v8, v6
	v_lshlrev_b32_e32 v6, 1, v130
	v_and_b32_e32 v132, 0x80, v6
	v_mfma_f32_16x16x32_bf16 v[6:9], v[180:183], v[216:219], v[2:5]
	v_ashrrev_i32_e32 v137, 31, v136
	v_lshlrev_b64 v[138:139], 21, v[134:135]
	v_lshlrev_b64 v[140:141], 10, v[136:137]
	v_lshrrev_b32_e32 v2, 2, v130
	v_and_b32_e32 v2, 12, v2
	v_mfma_f32_16x16x32_bf16 v[102:105], v[180:183], v[176:179], v[70:73]
	v_or3_b32 v132, v2, v132, s4
	v_mad_i64_i32 v[134:135], s[4:5], v134, s31, 0
	v_mfma_f32_16x16x32_bf16 v[70:73], v[180:183], v[208:211], v[192:195]
	v_lshl_add_u64 v[140:141], v[140:141], 0, v[138:139]
	v_cmp_gt_i32_e32 vcc, s34, v132
	v_ashrrev_i32_e32 v133, 31, v132
	v_bfe_u32 v246, v130, 4, 1
	v_mul_u32_u24_e32 v246, 24, v246
	v_mov_b32_e32 v247, 0
	v_mfma_f32_16x16x32_bf16 v[38:41], v[180:183], v[212:215], v[220:223]
	v_lshl_add_u64 v[134:135], s[22:23], 0, v[134:135]
	v_lshl_add_u64 v[140:141], v[140:141], 1, s[18:19]
	v_mfma_f32_16x16x32_bf16 v[34:37], v[184:187], v[212:215], v[168:171]
	v_mfma_f32_16x16x32_bf16 v[2:5], v[184:187], v[216:219], v[172:175]
	v_lshl_add_u64 v[218:219], v[132:133], 2, v[134:135]
	global_load_dwordx4 v[198:201], v[218:219], off
	global_load_dwordx4 v[202:205], v[218:219], off offset:64
	global_load_dwordx4 v[206:209], v[218:219], off offset:128
	global_load_dwordx4 v[210:213], v[218:219], off offset:192
	global_load_dwordx4 v[214:217], v[218:219], off offset:256
	global_load_dwordx4 v[224:227], v[218:219], off offset:320
	global_load_dwordx4 v[228:231], v[218:219], off offset:384
	global_load_dwordx4 v[232:235], v[218:219], off offset:448
	s_nop 0
	v_lshl_add_u64 v[172:173], v[132:133], 1, v[140:141]
	v_lshl_add_u64 v[196:197], v[132:133], 1, v[140:141]
	global_load_dwordx2 v[176:177], v[196:197], off
	global_load_dwordx2 v[178:179], v[196:197], off offset:32
	global_load_dwordx2 v[180:181], v[196:197], off offset:64
	global_load_dwordx2 v[182:183], v[196:197], off offset:96
	global_load_dwordx2 v[184:185], v[196:197], off offset:128
	global_load_dwordx2 v[186:187], v[196:197], off offset:160
	global_load_dwordx2 v[188:189], v[196:197], off offset:192
	global_load_dwordx2 v[190:191], v[196:197], off offset:224
	v_add_f32_e32 v126, 0, v126
	v_add_f32_e32 v127, 0, v127
	v_add_f32_e32 v128, 0, v128
	v_add_f32_e32 v129, 0, v129
	s_waitcnt vmcnt(7)
	v_lshlrev_b32_e32 v130, 16, v176
	v_and_b32_e32 v137, 0xffff0000, v176
	v_lshlrev_b32_e32 v167, 16, v177
	v_and_b32_e32 v174, 0xffff0000, v177
	v_fmac_f32_e32 v130, v126, v198
	v_fmac_f32_e32 v137, v127, v199
	v_fmac_f32_e32 v167, v128, v200
	v_fmac_f32_e32 v174, v129, v201
	v_cvt_pk_bf16_f32 v126, v130, v137
	v_cvt_pk_bf16_f32 v127, v167, v174
	v_lshl_add_u64 v[168:169], v[132:133], 1, v[140:141]
	v_add_f32_e32 v122, 0, v122
	v_add_f32_e32 v123, 0, v123
	v_add_f32_e32 v124, 0, v124
	v_add_f32_e32 v125, 0, v125
	s_waitcnt vmcnt(6)
	v_lshlrev_b32_e32 v130, 16, v178
	v_and_b32_e32 v137, 0xffff0000, v178
	v_lshlrev_b32_e32 v167, 16, v179
	v_and_b32_e32 v170, 0xffff0000, v179
	v_fmac_f32_e32 v130, v122, v202
	v_fmac_f32_e32 v137, v123, v203
	v_fmac_f32_e32 v167, v124, v204
	v_fmac_f32_e32 v170, v125, v205
	v_cvt_pk_bf16_f32 v128, v130, v137
	v_cvt_pk_bf16_f32 v129, v167, v170
	s_nop 1
	v_permlane16_swap_b32 v126, v128
	v_permlane16_swap_b32 v127, v129
	v_lshl_add_u64 v[248:249], v[168:169], 0, v[246:247]
	s_nop 0
	global_store_dwordx4 v[248:249], v[126:129], off
	s_nop 1
	v_or_b32_e32 v122, 32, v132
	v_lshl_add_u64 v[126:127], v[132:133], 1, v[140:141]
	v_add_f32_e32 v118, 0, v118
	v_add_f32_e32 v119, 0, v119
	v_add_f32_e32 v120, 0, v120
	v_add_f32_e32 v121, 0, v121
	s_waitcnt vmcnt(6)
; __device__ __forceinline__ unsigned pack2(float a, float b) { unsigned r; asm("v_cvt_pk_bf16_f32 %0, %1, %2" : "=v"(r) : "v"(a), "v"(b)); return r; }
; __device__ __forceinline__ float bf2f(bf16_t h) { return __uint_as_float(((unsigned)h) << 16); }
;   __device__ __forceinline__ void c4(int g, int rig, int col, f32x4 v) const {
;     const size_t o = ((size_t)g * 2048 + rig) * 1024 + col;
;     f32x4 bs;
;     if (BASE_F32) bs = __builtin_nontemporal_load((const f32x4*)((const float*)base + o));
;     else {
;       const uint2 u = *(const uint2*)((const bf16_t*)base + o);
;       bs[0] = bf2f((bf16_t)(u.x & 0xffff)); bs[1] = bf2f((bf16_t)(u.x >> 16)); bs[2] = bf2f((bf16_t)(u.y & 0xffff)); bs[3] = bf2f((bf16_t)(u.y >> 16));
;     }
;     const f32x4 gt = *(const f32x4*)(gate + (size_t)g * 6144 + col);
;     f32x4 bi = {0.f, 0.f, 0.f, 0.f};
;     if (bias) bi = *(const f32x4*)(bias + col);
;     f32x4 r;
; #pragma unroll
;     for (int j = 0; j < 4; ++j) r[j] = bs[j] + gt[j] * (v[j] + bi[j]);
;     uint2 w; w.x = pack2(r[0], r[1]); w.y = pack2(r[2], r[3]);
;     *(uint2*)(X16 + o) = w;
;   }
; template <bool SWAP, class Epi, bool THIN = false> ...
;     ...
;         } else {
; #pragma unroll
;           for (int n = 0; n < 8; ++n) {
;             const int col = nt * 256 + wc_e * 128 + n * 16 + fq_e * 4;
;             if (col < N) epi.c4(g, rig, col, acc[m][n]);
;           }
;         }
	v_lshlrev_b32_e32 v130, 16, v180
	v_and_b32_e32 v128, 0xffff0000, v180
	v_lshlrev_b32_e32 v137, 16, v181
	v_and_b32_e32 v129, 0xffff0000, v181
	v_fmac_f32_e32 v130, v118, v206
	v_fmac_f32_e32 v128, v119, v207
	v_fmac_f32_e32 v137, v120, v208
	v_fmac_f32_e32 v129, v121, v209
	v_cvt_pk_bf16_f32 v118, v130, v128
	v_cvt_pk_bf16_f32 v119, v137, v129
	v_lshl_add_u64 v[122:123], v[132:133], 1, v[140:141]
	v_add_f32_e32 v114, 0, v114
	v_add_f32_e32 v115, 0, v115
	v_add_f32_e32 v116, 0, v116
	v_add_f32_e32 v117, 0, v117
	s_waitcnt vmcnt(5)
	v_lshlrev_b32_e32 v126, 16, v182
	v_and_b32_e32 v124, 0xffff0000, v182
	v_lshlrev_b32_e32 v127, 16, v183
	v_and_b32_e32 v125, 0xffff0000, v183
	v_fmac_f32_e32 v126, v114, v210
	v_fmac_f32_e32 v124, v115, v211
	v_fmac_f32_e32 v127, v116, v212
	v_fmac_f32_e32 v125, v117, v213
	v_cvt_pk_bf16_f32 v120, v126, v124
	v_cvt_pk_bf16_f32 v121, v127, v125
	s_nop 1
	v_permlane16_swap_b32 v118, v120
	v_permlane16_swap_b32 v119, v121
	v_lshl_add_u64 v[248:249], v[122:123], 0, v[246:247]
	s_nop 0
	global_store_dwordx4 v[248:249], v[118:121], off offset:64
	s_nop 1
	v_or_b32_e32 v114, 64, v132
	v_lshl_add_u64 v[118:119], v[132:133], 1, v[140:141]
	v_add_f32_e32 v110, 0, v110
	v_add_f32_e32 v111, 0, v111
	v_add_f32_e32 v112, 0, v112
	v_add_f32_e32 v113, 0, v113
	s_waitcnt vmcnt(5)
	v_lshlrev_b32_e32 v122, 16, v184
	v_and_b32_e32 v120, 0xffff0000, v184
	v_lshlrev_b32_e32 v123, 16, v185
	v_and_b32_e32 v121, 0xffff0000, v185
	v_fmac_f32_e32 v122, v110, v214
	v_fmac_f32_e32 v120, v111, v215
	v_fmac_f32_e32 v123, v112, v216
	v_fmac_f32_e32 v121, v113, v217
	v_cvt_pk_bf16_f32 v110, v122, v120
	v_cvt_pk_bf16_f32 v111, v123, v121
	v_lshl_add_u64 v[114:115], v[132:133], 1, v[140:141]
	v_add_f32_e32 v106, 0, v106
	v_add_f32_e32 v107, 0, v107
	v_add_f32_e32 v108, 0, v108
	v_add_f32_e32 v109, 0, v109
	s_waitcnt vmcnt(4)
	v_lshlrev_b32_e32 v118, 16, v186
	v_and_b32_e32 v116, 0xffff0000, v186
	v_lshlrev_b32_e32 v119, 16, v187
	v_and_b32_e32 v117, 0xffff0000, v187
	v_fmac_f32_e32 v118, v106, v224
	v_fmac_f32_e32 v116, v107, v225
	v_fmac_f32_e32 v119, v108, v226
	v_fmac_f32_e32 v117, v109, v227
	v_cvt_pk_bf16_f32 v112, v118, v116
	v_cvt_pk_bf16_f32 v113, v119, v117
	s_nop 1
	v_permlane16_swap_b32 v110, v112
	v_permlane16_swap_b32 v111, v113
	v_lshl_add_u64 v[248:249], v[114:115], 0, v[246:247]
	s_nop 0
	global_store_dwordx4 v[248:249], v[110:113], off offset:128
	s_nop 1
	v_or_b32_e32 v106, 0x60, v132
	v_lshl_add_u64 v[110:111], v[132:133], 1, v[140:141]
	v_add_f32_e32 v102, 0, v102
	v_add_f32_e32 v103, 0, v103
	v_add_f32_e32 v104, 0, v104
	v_add_f32_e32 v105, 0, v105
	s_waitcnt vmcnt(4)
	v_lshlrev_b32_e32 v114, 16, v188
	v_and_b32_e32 v112, 0xffff0000, v188
	v_lshlrev_b32_e32 v115, 16, v189
	v_and_b32_e32 v113, 0xffff0000, v189
	v_fmac_f32_e32 v114, v102, v228
	v_fmac_f32_e32 v112, v103, v229
	v_fmac_f32_e32 v115, v104, v230
	v_fmac_f32_e32 v113, v105, v231
	v_cvt_pk_bf16_f32 v102, v114, v112
	v_cvt_pk_bf16_f32 v103, v115, v113
	v_lshl_add_u64 v[106:107], v[132:133], 1, v[140:141]
	v_add_f32_e32 v98, 0, v98
	v_add_f32_e32 v99, 0, v99
	v_add_f32_e32 v100, 0, v100
	v_add_f32_e32 v101, 0, v101
	s_waitcnt vmcnt(3)
	v_lshlrev_b32_e32 v110, 16, v190
	v_and_b32_e32 v108, 0xffff0000, v190
	v_lshlrev_b32_e32 v111, 16, v191
	v_and_b32_e32 v109, 0xffff0000, v191
	v_fmac_f32_e32 v110, v98, v232
	v_fmac_f32_e32 v108, v99, v233
	v_fmac_f32_e32 v111, v100, v234
	v_fmac_f32_e32 v109, v101, v235
	v_cvt_pk_bf16_f32 v104, v110, v108
	v_cvt_pk_bf16_f32 v105, v111, v109
	s_nop 1
	v_permlane16_swap_b32 v102, v104
	v_permlane16_swap_b32 v103, v105
	v_lshl_add_u64 v[248:249], v[106:107], 0, v[246:247]
	s_nop 0
	global_store_dwordx4 v[248:249], v[102:105], off offset:192
	s_nop 1
	v_or_b32_e32 v98, 16, v136
	v_ashrrev_i32_e32 v99, 31, v98
	v_lshlrev_b64 v[98:99], 10, v[98:99]
	v_lshl_add_u64 v[98:99], v[98:99], 0, v[138:139]
	v_lshl_add_u64 v[98:99], v[98:99], 1, s[18:19]
	v_lshl_add_u64 v[104:105], v[132:133], 1, v[98:99]
	v_lshl_add_u64 v[196:197], v[132:133], 1, v[98:99]
	global_load_dwordx2 v[176:177], v[196:197], off
	global_load_dwordx2 v[178:179], v[196:197], off offset:32
	global_load_dwordx2 v[180:181], v[196:197], off offset:64
	global_load_dwordx2 v[182:183], v[196:197], off offset:96
	global_load_dwordx2 v[184:185], v[196:197], off offset:128
	global_load_dwordx2 v[186:187], v[196:197], off offset:160
	global_load_dwordx2 v[188:189], v[196:197], off offset:192
	global_load_dwordx2 v[190:191], v[196:197], off offset:224
	v_add_f32_e32 v94, 0, v94
	v_add_f32_e32 v95, 0, v95
	v_add_f32_e32 v96, 0, v96
	v_add_f32_e32 v97, 0, v97
	s_waitcnt vmcnt(7)
	v_lshlrev_b32_e32 v108, 16, v176
	v_and_b32_e32 v106, 0xffff0000, v176
	v_lshlrev_b32_e32 v109, 16, v177
	v_and_b32_e32 v107, 0xffff0000, v177
	v_fmac_f32_e32 v108, v94, v198
	v_fmac_f32_e32 v106, v95, v199
	v_fmac_f32_e32 v109, v96, v200
	v_fmac_f32_e32 v107, v97, v201
	v_cvt_pk_bf16_f32 v94, v108, v106
	v_cvt_pk_bf16_f32 v95, v109, v107
	v_lshl_add_u64 v[100:101], v[132:133], 1, v[98:99]
	v_add_f32_e32 v90, 0, v90
	v_add_f32_e32 v91, 0, v91
	v_add_f32_e32 v92, 0, v92
	v_add_f32_e32 v93, 0, v93
	s_waitcnt vmcnt(6)
	v_lshlrev_b32_e32 v104, 16, v178
	v_and_b32_e32 v102, 0xffff0000, v178
	v_lshlrev_b32_e32 v105, 16, v179
	v_and_b32_e32 v103, 0xffff0000, v179
	v_fmac_f32_e32 v104, v90, v202
	v_fmac_f32_e32 v102, v91, v203
	v_fmac_f32_e32 v105, v92, v204
	v_fmac_f32_e32 v103, v93, v205
	v_cvt_pk_bf16_f32 v96, v104, v102
	v_cvt_pk_bf16_f32 v97, v105, v103
	s_nop 1
	v_permlane16_swap_b32 v94, v96
	v_permlane16_swap_b32 v95, v97
	v_lshl_add_u64 v[248:249], v[100:101], 0, v[246:247]
	s_nop 0
	global_store_dwordx4 v[248:249], v[94:97], off
	s_nop 1
	v_lshl_add_u64 v[94:95], v[132:133], 1, v[98:99]
	v_add_f32_e32 v86, 0, v86
	v_add_f32_e32 v87, 0, v87
	v_add_f32_e32 v88, 0, v88
	v_add_f32_e32 v89, 0, v89
	s_waitcnt vmcnt(6)
; __device__ __forceinline__ unsigned pack2(float a, float b) { unsigned r; asm("v_cvt_pk_bf16_f32 %0, %1, %2" : "=v"(r) : "v"(a), "v"(b)); return r; }
; __device__ __forceinline__ float bf2f(bf16_t h) { return __uint_as_float(((unsigned)h) << 16); }
;   __device__ __forceinline__ void c4(int g, int rig, int col, f32x4 v) const {
;     const size_t o = ((size_t)g * 2048 + rig) * 1024 + col;
;     f32x4 bs;
;     if (BASE_F32) bs = __builtin_nontemporal_load((const f32x4*)((const float*)base + o));
;     else {
;       const uint2 u = *(const uint2*)((const bf16_t*)base + o);
;       bs[0] = bf2f((bf16_t)(u.x & 0xffff)); bs[1] = bf2f((bf16_t)(u.x >> 16)); bs[2] = bf2f((bf16_t)(u.y & 0xffff)); bs[3] = bf2f((bf16_t)(u.y >> 16));
;     }
;     const f32x4 gt = *(const f32x4*)(gate + (size_t)g * 6144 + col);
;     f32x4 bi = {0.f, 0.f, 0.f, 0.f};
;     if (bias) bi = *(const f32x4*)(bias + col);
;     f32x4 r;
; #pragma unroll
;     for (int j = 0; j < 4; ++j) r[j] = bs[j] + gt[j] * (v[j] + bi[j]);
;     uint2 w; w.x = pack2(r[0], r[1]); w.y = pack2(r[2], r[3]);
;     *(uint2*)(X16 + o) = w;
;   }
; template <bool SWAP, class Epi, bool THIN = false> ...
;     ...
;         } else {
; #pragma unroll
;           for (int n = 0; n < 8; ++n) {
;             const int col = nt * 256 + wc_e * 128 + n * 16 + fq_e * 4;
;             if (col < N) epi.c4(g, rig, col, acc[m][n]);
;           }
;         }
	v_lshlrev_b32_e32 v100, 16, v180
	v_and_b32_e32 v96, 0xffff0000, v180
	v_lshlrev_b32_e32 v101, 16, v181
	v_and_b32_e32 v97, 0xffff0000, v181
	v_fmac_f32_e32 v100, v86, v206
	v_fmac_f32_e32 v96, v87, v207
	v_fmac_f32_e32 v101, v88, v208
	v_fmac_f32_e32 v97, v89, v209
	v_cvt_pk_bf16_f32 v86, v100, v96
	v_cvt_pk_bf16_f32 v87, v101, v97
	v_lshl_add_u64 v[90:91], v[132:133], 1, v[98:99]
	v_add_f32_e32 v82, 0, v82
	v_add_f32_e32 v83, 0, v83
	v_add_f32_e32 v84, 0, v84
	v_add_f32_e32 v85, 0, v85
	s_waitcnt vmcnt(5)
	v_lshlrev_b32_e32 v94, 16, v182
	v_and_b32_e32 v92, 0xffff0000, v182
	v_lshlrev_b32_e32 v95, 16, v183
	v_and_b32_e32 v93, 0xffff0000, v183
	v_fmac_f32_e32 v94, v82, v210
	v_fmac_f32_e32 v92, v83, v211
	v_fmac_f32_e32 v95, v84, v212
	v_fmac_f32_e32 v93, v85, v213
	v_cvt_pk_bf16_f32 v88, v94, v92
	v_cvt_pk_bf16_f32 v89, v95, v93
	s_nop 1
	v_permlane16_swap_b32 v86, v88
	v_permlane16_swap_b32 v87, v89
	v_lshl_add_u64 v[248:249], v[90:91], 0, v[246:247]
	s_nop 0
	global_store_dwordx4 v[248:249], v[86:89], off offset:64
	s_nop 1
	v_lshl_add_u64 v[86:87], v[132:133], 1, v[98:99]
	v_add_f32_e32 v78, 0, v78
	v_add_f32_e32 v79, 0, v79
	v_add_f32_e32 v80, 0, v80
	v_add_f32_e32 v81, 0, v81
	s_waitcnt vmcnt(5)
	v_lshlrev_b32_e32 v90, 16, v184
	v_and_b32_e32 v88, 0xffff0000, v184
	v_lshlrev_b32_e32 v91, 16, v185
	v_and_b32_e32 v89, 0xffff0000, v185
	v_fmac_f32_e32 v90, v78, v214
	v_fmac_f32_e32 v88, v79, v215
	v_fmac_f32_e32 v91, v80, v216
	v_fmac_f32_e32 v89, v81, v217
	v_cvt_pk_bf16_f32 v78, v90, v88
	v_cvt_pk_bf16_f32 v79, v91, v89
	v_lshl_add_u64 v[82:83], v[132:133], 1, v[98:99]
	v_add_f32_e32 v74, 0, v74
	v_add_f32_e32 v75, 0, v75
	v_add_f32_e32 v76, 0, v76
	v_add_f32_e32 v77, 0, v77
	s_waitcnt vmcnt(4)
	v_lshlrev_b32_e32 v86, 16, v186
	v_and_b32_e32 v84, 0xffff0000, v186
	v_lshlrev_b32_e32 v87, 16, v187
	v_and_b32_e32 v85, 0xffff0000, v187
	v_fmac_f32_e32 v86, v74, v224
	v_fmac_f32_e32 v84, v75, v225
	v_fmac_f32_e32 v87, v76, v226
	v_fmac_f32_e32 v85, v77, v227
	v_cvt_pk_bf16_f32 v80, v86, v84
	v_cvt_pk_bf16_f32 v81, v87, v85
	s_nop 1
	v_permlane16_swap_b32 v78, v80
	v_permlane16_swap_b32 v79, v81
	v_lshl_add_u64 v[248:249], v[82:83], 0, v[246:247]
	s_nop 0
	global_store_dwordx4 v[248:249], v[78:81], off offset:128
	s_nop 1
	v_lshl_add_u64 v[78:79], v[132:133], 1, v[98:99]
	v_add_f32_e32 v70, 0, v70
	v_add_f32_e32 v71, 0, v71
	v_add_f32_e32 v72, 0, v72
	v_add_f32_e32 v73, 0, v73
	s_waitcnt vmcnt(4)
	v_lshlrev_b32_e32 v82, 16, v188
	v_and_b32_e32 v80, 0xffff0000, v188
	v_lshlrev_b32_e32 v83, 16, v189
	v_and_b32_e32 v81, 0xffff0000, v189
	v_fmac_f32_e32 v82, v70, v228
	v_fmac_f32_e32 v80, v71, v229
	v_fmac_f32_e32 v83, v72, v230
	v_fmac_f32_e32 v81, v73, v231
	v_cvt_pk_bf16_f32 v70, v82, v80
	v_cvt_pk_bf16_f32 v71, v83, v81
	v_lshl_add_u64 v[74:75], v[132:133], 1, v[98:99]
	v_add_f32_e32 v66, 0, v66
	v_add_f32_e32 v67, 0, v67
	v_add_f32_e32 v68, 0, v68
	v_add_f32_e32 v69, 0, v69
	s_waitcnt vmcnt(3)
	v_lshlrev_b32_e32 v78, 16, v190
	v_and_b32_e32 v76, 0xffff0000, v190
	v_lshlrev_b32_e32 v79, 16, v191
	v_and_b32_e32 v77, 0xffff0000, v191
	v_fmac_f32_e32 v78, v66, v232
	v_fmac_f32_e32 v76, v67, v233
	v_fmac_f32_e32 v79, v68, v234
	v_fmac_f32_e32 v77, v69, v235
	v_cvt_pk_bf16_f32 v72, v78, v76
	v_cvt_pk_bf16_f32 v73, v79, v77
	s_nop 1
	v_permlane16_swap_b32 v70, v72
	v_permlane16_swap_b32 v71, v73
	v_lshl_add_u64 v[248:249], v[74:75], 0, v[246:247]
	s_nop 0
	global_store_dwordx4 v[248:249], v[70:73], off offset:192
	s_nop 1
	v_or_b32_e32 v66, 32, v136
	v_ashrrev_i32_e32 v67, 31, v66
	v_lshlrev_b64 v[66:67], 10, v[66:67]
	v_lshl_add_u64 v[66:67], v[66:67], 0, v[138:139]
	v_lshl_add_u64 v[66:67], v[66:67], 1, s[18:19]
	v_lshl_add_u64 v[72:73], v[132:133], 1, v[66:67]
	v_lshl_add_u64 v[196:197], v[132:133], 1, v[66:67]
	global_load_dwordx2 v[176:177], v[196:197], off
	global_load_dwordx2 v[178:179], v[196:197], off offset:32
	global_load_dwordx2 v[180:181], v[196:197], off offset:64
	global_load_dwordx2 v[182:183], v[196:197], off offset:96
	global_load_dwordx2 v[184:185], v[196:197], off offset:128
	global_load_dwordx2 v[186:187], v[196:197], off offset:160
	global_load_dwordx2 v[188:189], v[196:197], off offset:192
	global_load_dwordx2 v[190:191], v[196:197], off offset:224
	v_add_f32_e32 v62, 0, v62
	v_add_f32_e32 v63, 0, v63
	v_add_f32_e32 v64, 0, v64
	v_add_f32_e32 v65, 0, v65
	s_waitcnt vmcnt(7)
	v_lshlrev_b32_e32 v76, 16, v176
	v_and_b32_e32 v74, 0xffff0000, v176
	v_lshlrev_b32_e32 v77, 16, v177
	v_and_b32_e32 v75, 0xffff0000, v177
	v_fmac_f32_e32 v76, v62, v198
	v_fmac_f32_e32 v74, v63, v199
	v_fmac_f32_e32 v77, v64, v200
	v_fmac_f32_e32 v75, v65, v201
	v_cvt_pk_bf16_f32 v62, v76, v74
	v_cvt_pk_bf16_f32 v63, v77, v75
	v_lshl_add_u64 v[68:69], v[132:133], 1, v[66:67]
	v_add_f32_e32 v58, 0, v58
	v_add_f32_e32 v59, 0, v59
	v_add_f32_e32 v60, 0, v60
	v_add_f32_e32 v61, 0, v61
	s_waitcnt vmcnt(6)
	v_lshlrev_b32_e32 v72, 16, v178
	v_and_b32_e32 v70, 0xffff0000, v178
	v_lshlrev_b32_e32 v73, 16, v179
	v_and_b32_e32 v71, 0xffff0000, v179
	v_fmac_f32_e32 v72, v58, v202
	v_fmac_f32_e32 v70, v59, v203
	v_fmac_f32_e32 v73, v60, v204
	v_fmac_f32_e32 v71, v61, v205
	v_cvt_pk_bf16_f32 v64, v72, v70
	v_cvt_pk_bf16_f32 v65, v73, v71
	s_nop 1
	v_permlane16_swap_b32 v62, v64
	v_permlane16_swap_b32 v63, v65
	v_lshl_add_u64 v[248:249], v[68:69], 0, v[246:247]
	s_nop 0
	global_store_dwordx4 v[248:249], v[62:65], off
	s_nop 1
	v_lshl_add_u64 v[62:63], v[132:133], 1, v[66:67]
	v_add_f32_e32 v54, 0, v54
	v_add_f32_e32 v55, 0, v55
	v_add_f32_e32 v56, 0, v56
	v_add_f32_e32 v57, 0, v57
	s_waitcnt vmcnt(6)
; __device__ __forceinline__ unsigned pack2(float a, float b) { unsigned r; asm("v_cvt_pk_bf16_f32 %0, %1, %2" : "=v"(r) : "v"(a), "v"(b)); return r; }
; __device__ __forceinline__ float bf2f(bf16_t h) { return __uint_as_float(((unsigned)h) << 16); }
;   __device__ __forceinline__ void c4(int g, int rig, int col, f32x4 v) const {
;     const size_t o = ((size_t)g * 2048 + rig) * 1024 + col;
;     f32x4 bs;
;     if (BASE_F32) bs = __builtin_nontemporal_load((const f32x4*)((const float*)base + o));
;     else {
;       const uint2 u = *(const uint2*)((const bf16_t*)base + o);
;       bs[0] = bf2f((bf16_t)(u.x & 0xffff)); bs[1] = bf2f((bf16_t)(u.x >> 16)); bs[2] = bf2f((bf16_t)(u.y & 0xffff)); bs[3] = bf2f((bf16_t)(u.y >> 16));
;     }
;     const f32x4 gt = *(const f32x4*)(gate + (size_t)g * 6144 + col);
;     f32x4 bi = {0.f, 0.f, 0.f, 0.f};
;     if (bias) bi = *(const f32x4*)(bias + col);
;     f32x4 r;
; #pragma unroll
;     for (int j = 0; j < 4; ++j) r[j] = bs[j] + gt[j] * (v[j] + bi[j]);
;     uint2 w; w.x = pack2(r[0], r[1]); w.y = pack2(r[2], r[3]);
;     *(uint2*)(X16 + o) = w;
;   }
; template <bool SWAP, class Epi, bool THIN = false> ...
;     ...
; #pragma unroll
;           for (int n = 0; n < 8; ++n) {
;             const int col = nt * 256 + wc_e * 128 + n * 16 + fq_e * 4;
;             if (col < N) epi.c4(g, rig, col, acc[m][n]);
;           }
	v_lshlrev_b32_e32 v68, 16, v180
	v_and_b32_e32 v64, 0xffff0000, v180
	v_lshlrev_b32_e32 v69, 16, v181
	v_and_b32_e32 v65, 0xffff0000, v181
	v_fmac_f32_e32 v68, v54, v206
	v_fmac_f32_e32 v64, v55, v207
	v_fmac_f32_e32 v69, v56, v208
	v_fmac_f32_e32 v65, v57, v209
	v_cvt_pk_bf16_f32 v54, v68, v64
	v_cvt_pk_bf16_f32 v55, v69, v65
	v_lshl_add_u64 v[58:59], v[132:133], 1, v[66:67]
	v_add_f32_e32 v50, 0, v50
	v_add_f32_e32 v51, 0, v51
	v_add_f32_e32 v52, 0, v52
	v_add_f32_e32 v53, 0, v53
	s_waitcnt vmcnt(5)
	v_lshlrev_b32_e32 v62, 16, v182
	v_and_b32_e32 v60, 0xffff0000, v182
	v_lshlrev_b32_e32 v63, 16, v183
	v_and_b32_e32 v61, 0xffff0000, v183
	v_fmac_f32_e32 v62, v50, v210
	v_fmac_f32_e32 v60, v51, v211
	v_fmac_f32_e32 v63, v52, v212
	v_fmac_f32_e32 v61, v53, v213
	v_cvt_pk_bf16_f32 v56, v62, v60
	v_cvt_pk_bf16_f32 v57, v63, v61
	s_nop 1
	v_permlane16_swap_b32 v54, v56
	v_permlane16_swap_b32 v55, v57
	v_lshl_add_u64 v[248:249], v[58:59], 0, v[246:247]
	s_nop 0
	global_store_dwordx4 v[248:249], v[54:57], off offset:64
	s_nop 1
	v_lshl_add_u64 v[54:55], v[132:133], 1, v[66:67]
	v_add_f32_e32 v46, 0, v46
	v_add_f32_e32 v47, 0, v47
	v_add_f32_e32 v48, 0, v48
	v_add_f32_e32 v49, 0, v49
	s_waitcnt vmcnt(5)
	v_lshlrev_b32_e32 v58, 16, v184
	v_and_b32_e32 v56, 0xffff0000, v184
	v_lshlrev_b32_e32 v59, 16, v185
	v_and_b32_e32 v57, 0xffff0000, v185
	v_fmac_f32_e32 v58, v46, v214
	v_fmac_f32_e32 v56, v47, v215
	v_fmac_f32_e32 v59, v48, v216
	v_fmac_f32_e32 v57, v49, v217
	v_cvt_pk_bf16_f32 v46, v58, v56
	v_cvt_pk_bf16_f32 v47, v59, v57
	v_lshl_add_u64 v[50:51], v[132:133], 1, v[66:67]
	v_add_f32_e32 v42, 0, v42
	v_add_f32_e32 v43, 0, v43
	v_add_f32_e32 v44, 0, v44
	v_add_f32_e32 v45, 0, v45
	s_waitcnt vmcnt(4)
	v_lshlrev_b32_e32 v54, 16, v186
	v_and_b32_e32 v52, 0xffff0000, v186
	v_lshlrev_b32_e32 v55, 16, v187
	v_and_b32_e32 v53, 0xffff0000, v187
	v_fmac_f32_e32 v54, v42, v224
	v_fmac_f32_e32 v52, v43, v225
	v_fmac_f32_e32 v55, v44, v226
	v_fmac_f32_e32 v53, v45, v227
	v_cvt_pk_bf16_f32 v48, v54, v52
	v_cvt_pk_bf16_f32 v49, v55, v53
	s_nop 1
	v_permlane16_swap_b32 v46, v48
	v_permlane16_swap_b32 v47, v49
	v_lshl_add_u64 v[248:249], v[50:51], 0, v[246:247]
	s_nop 0
	global_store_dwordx4 v[248:249], v[46:49], off offset:128
	s_nop 1
	v_lshl_add_u64 v[46:47], v[132:133], 1, v[66:67]
	v_add_f32_e32 v38, 0, v38
	v_add_f32_e32 v39, 0, v39
	v_add_f32_e32 v40, 0, v40
	v_add_f32_e32 v41, 0, v41
	s_waitcnt vmcnt(4)
	v_lshlrev_b32_e32 v50, 16, v188
	v_and_b32_e32 v48, 0xffff0000, v188
	v_lshlrev_b32_e32 v51, 16, v189
	v_and_b32_e32 v49, 0xffff0000, v189
	v_fmac_f32_e32 v50, v38, v228
	v_fmac_f32_e32 v48, v39, v229
	v_fmac_f32_e32 v51, v40, v230
	v_fmac_f32_e32 v49, v41, v231
	v_cvt_pk_bf16_f32 v38, v50, v48
	v_cvt_pk_bf16_f32 v39, v51, v49
	v_lshl_add_u64 v[42:43], v[132:133], 1, v[66:67]
	v_add_f32_e32 v34, 0, v34
	v_add_f32_e32 v35, 0, v35
	v_add_f32_e32 v36, 0, v36
	v_add_f32_e32 v37, 0, v37
	s_waitcnt vmcnt(3)
	v_lshlrev_b32_e32 v46, 16, v190
	v_and_b32_e32 v44, 0xffff0000, v190
	v_lshlrev_b32_e32 v47, 16, v191
	v_and_b32_e32 v45, 0xffff0000, v191
	v_fmac_f32_e32 v46, v34, v232
	v_fmac_f32_e32 v44, v35, v233
	v_fmac_f32_e32 v47, v36, v234
	v_fmac_f32_e32 v45, v37, v235
	v_cvt_pk_bf16_f32 v40, v46, v44
	v_cvt_pk_bf16_f32 v41, v47, v45
	s_nop 1
	v_permlane16_swap_b32 v38, v40
	v_permlane16_swap_b32 v39, v41
	v_lshl_add_u64 v[248:249], v[42:43], 0, v[246:247]
	s_nop 0
	global_store_dwordx4 v[248:249], v[38:41], off offset:192
	s_nop 1
	v_or_b32_e32 v34, 48, v136
	v_ashrrev_i32_e32 v35, 31, v34
	v_lshlrev_b64 v[34:35], 10, v[34:35]
	v_lshl_add_u64 v[34:35], v[34:35], 0, v[138:139]
	v_lshl_add_u64 v[34:35], v[34:35], 1, s[18:19]
	v_lshl_add_u64 v[40:41], v[132:133], 1, v[34:35]
	v_lshl_add_u64 v[196:197], v[132:133], 1, v[34:35]
	global_load_dwordx2 v[176:177], v[196:197], off
	global_load_dwordx2 v[178:179], v[196:197], off offset:32
	global_load_dwordx2 v[180:181], v[196:197], off offset:64
	global_load_dwordx2 v[182:183], v[196:197], off offset:96
	global_load_dwordx2 v[184:185], v[196:197], off offset:128
	global_load_dwordx2 v[186:187], v[196:197], off offset:160
	global_load_dwordx2 v[188:189], v[196:197], off offset:192
	global_load_dwordx2 v[190:191], v[196:197], off offset:224
	v_add_f32_e32 v30, 0, v30
	v_add_f32_e32 v31, 0, v31
	v_add_f32_e32 v32, 0, v32
	v_add_f32_e32 v33, 0, v33
	s_waitcnt vmcnt(7)
; __device__ __forceinline__ unsigned pack2(float a, float b) { unsigned r; asm("v_cvt_pk_bf16_f32 %0, %1, %2" : "=v"(r) : "v"(a), "v"(b)); return r; }
; __device__ __forceinline__ float bf2f(bf16_t h) { return __uint_as_float(((unsigned)h) << 16); }
;   __device__ __forceinline__ void c4(int g, int rig, int col, f32x4 v) const {
;     const size_t o = ((size_t)g * 2048 + rig) * 1024 + col;
;     f32x4 bs;
;     if (BASE_F32) bs = __builtin_nontemporal_load((const f32x4*)((const float*)base + o));
;     else {
;       const uint2 u = *(const uint2*)((const bf16_t*)base + o);
;       bs[0] = bf2f((bf16_t)(u.x & 0xffff)); bs[1] = bf2f((bf16_t)(u.x >> 16)); bs[2] = bf2f((bf16_t)(u.y & 0xffff)); bs[3] = bf2f((bf16_t)(u.y >> 16));
;     }
;     const f32x4 gt = *(const f32x4*)(gate + (size_t)g * 6144 + col);
;     f32x4 bi = {0.f, 0.f, 0.f, 0.f};
;     if (bias) bi = *(const f32x4*)(bias + col);
;     f32x4 r;
; #pragma unroll
;     for (int j = 0; j < 4; ++j) r[j] = bs[j] + gt[j] * (v[j] + bi[j]);
;     uint2 w; w.x = pack2(r[0], r[1]); w.y = pack2(r[2], r[3]);
;     *(uint2*)(X16 + o) = w;
;   }
; template <bool SWAP, class Epi, bool THIN = false> ...
;     ...
; #pragma unroll
;           for (int n = 0; n < 8; ++n) {
;             const int col = nt * 256 + wc_e * 128 + n * 16 + fq_e * 4;
;             if (col < N) epi.c4(g, rig, col, acc[m][n]);
;           }
	v_lshlrev_b32_e32 v44, 16, v176
	v_and_b32_e32 v42, 0xffff0000, v176
	v_lshlrev_b32_e32 v45, 16, v177
	v_and_b32_e32 v43, 0xffff0000, v177
	v_fmac_f32_e32 v44, v30, v198
	v_fmac_f32_e32 v42, v31, v199
	v_fmac_f32_e32 v45, v32, v200
	v_fmac_f32_e32 v43, v33, v201
	v_cvt_pk_bf16_f32 v30, v44, v42
	v_cvt_pk_bf16_f32 v31, v45, v43
	v_lshl_add_u64 v[36:37], v[132:133], 1, v[34:35]
	v_add_f32_e32 v26, 0, v26
	v_add_f32_e32 v27, 0, v27
	v_add_f32_e32 v28, 0, v28
	v_add_f32_e32 v29, 0, v29
	s_waitcnt vmcnt(6)
	v_lshlrev_b32_e32 v40, 16, v178
	v_and_b32_e32 v38, 0xffff0000, v178
	v_lshlrev_b32_e32 v41, 16, v179
	v_and_b32_e32 v39, 0xffff0000, v179
	v_fmac_f32_e32 v40, v26, v202
	v_fmac_f32_e32 v38, v27, v203
	v_fmac_f32_e32 v41, v28, v204
	v_fmac_f32_e32 v39, v29, v205
	v_cvt_pk_bf16_f32 v32, v40, v38
	v_cvt_pk_bf16_f32 v33, v41, v39
	s_nop 1
	v_permlane16_swap_b32 v30, v32
	v_permlane16_swap_b32 v31, v33
	v_lshl_add_u64 v[248:249], v[36:37], 0, v[246:247]
	s_nop 0
	global_store_dwordx4 v[248:249], v[30:33], off
	s_nop 1
	v_lshl_add_u64 v[30:31], v[132:133], 1, v[34:35]
	v_add_f32_e32 v22, 0, v22
	v_add_f32_e32 v23, 0, v23
	v_add_f32_e32 v24, 0, v24
	v_add_f32_e32 v25, 0, v25
	s_waitcnt vmcnt(6)
	v_lshlrev_b32_e32 v36, 16, v180
	v_and_b32_e32 v32, 0xffff0000, v180
	v_lshlrev_b32_e32 v37, 16, v181
	v_and_b32_e32 v33, 0xffff0000, v181
	v_fmac_f32_e32 v36, v22, v206
	v_fmac_f32_e32 v32, v23, v207
	v_fmac_f32_e32 v37, v24, v208
	v_fmac_f32_e32 v33, v25, v209
	v_cvt_pk_bf16_f32 v22, v36, v32
	v_cvt_pk_bf16_f32 v23, v37, v33
	v_lshl_add_u64 v[26:27], v[132:133], 1, v[34:35]
	v_add_f32_e32 v18, 0, v18
	v_add_f32_e32 v19, 0, v19
	v_add_f32_e32 v20, 0, v20
	v_add_f32_e32 v21, 0, v21
	s_waitcnt vmcnt(5)
	v_lshlrev_b32_e32 v30, 16, v182
	v_and_b32_e32 v28, 0xffff0000, v182
	v_lshlrev_b32_e32 v31, 16, v183
	v_and_b32_e32 v29, 0xffff0000, v183
	v_fmac_f32_e32 v30, v18, v210
	v_fmac_f32_e32 v28, v19, v211
	v_fmac_f32_e32 v31, v20, v212
	v_fmac_f32_e32 v29, v21, v213
	v_cvt_pk_bf16_f32 v24, v30, v28
	v_cvt_pk_bf16_f32 v25, v31, v29
	s_nop 1
	v_permlane16_swap_b32 v22, v24
	v_permlane16_swap_b32 v23, v25
	v_lshl_add_u64 v[248:249], v[26:27], 0, v[246:247]
	s_nop 0
	global_store_dwordx4 v[248:249], v[22:25], off offset:64
	s_nop 1
	v_lshl_add_u64 v[22:23], v[132:133], 1, v[34:35]
	v_add_f32_e32 v14, 0, v14
	v_add_f32_e32 v15, 0, v15
	v_add_f32_e32 v16, 0, v16
	v_add_f32_e32 v17, 0, v17
	s_waitcnt vmcnt(5)
	v_lshlrev_b32_e32 v26, 16, v184
	v_and_b32_e32 v24, 0xffff0000, v184
	v_lshlrev_b32_e32 v27, 16, v185
	v_and_b32_e32 v25, 0xffff0000, v185
	v_fmac_f32_e32 v26, v14, v214
	v_fmac_f32_e32 v24, v15, v215
	v_fmac_f32_e32 v27, v16, v216
	v_fmac_f32_e32 v25, v17, v217
	v_cvt_pk_bf16_f32 v14, v26, v24
	v_cvt_pk_bf16_f32 v15, v27, v25
	v_lshl_add_u64 v[18:19], v[132:133], 1, v[34:35]
	v_add_f32_e32 v10, 0, v10
	v_add_f32_e32 v11, 0, v11
	v_add_f32_e32 v12, 0, v12
	v_add_f32_e32 v13, 0, v13
	s_waitcnt vmcnt(4)
	v_lshlrev_b32_e32 v22, 16, v186
	v_and_b32_e32 v20, 0xffff0000, v186
	v_lshlrev_b32_e32 v23, 16, v187
	v_and_b32_e32 v21, 0xffff0000, v187
	v_fmac_f32_e32 v22, v10, v224
	v_fmac_f32_e32 v20, v11, v225
	v_fmac_f32_e32 v23, v12, v226
	v_fmac_f32_e32 v21, v13, v227
	v_cvt_pk_bf16_f32 v16, v22, v20
	v_cvt_pk_bf16_f32 v17, v23, v21
	s_nop 1
	v_permlane16_swap_b32 v14, v16
	v_permlane16_swap_b32 v15, v17
	v_lshl_add_u64 v[248:249], v[18:19], 0, v[246:247]
	s_nop 0
	global_store_dwordx4 v[248:249], v[14:17], off offset:128
	s_nop 1
	v_lshl_add_u64 v[14:15], v[132:133], 1, v[34:35]
	v_add_f32_e32 v6, 0, v6
	v_add_f32_e32 v7, 0, v7
	v_add_f32_e32 v8, 0, v8
	v_add_f32_e32 v9, 0, v9
	s_waitcnt vmcnt(4)
	v_lshlrev_b32_e32 v18, 16, v188
	v_and_b32_e32 v16, 0xffff0000, v188
	v_lshlrev_b32_e32 v19, 16, v189
	v_and_b32_e32 v17, 0xffff0000, v189
	v_fmac_f32_e32 v18, v6, v228
	v_fmac_f32_e32 v16, v7, v229
	v_fmac_f32_e32 v19, v8, v230
	v_fmac_f32_e32 v17, v9, v231
	v_cvt_pk_bf16_f32 v6, v18, v16
	v_cvt_pk_bf16_f32 v7, v19, v17
	v_lshl_add_u64 v[10:11], v[132:133], 1, v[34:35]
	v_add_f32_e32 v2, 0, v2
	v_add_f32_e32 v3, 0, v3
	v_add_f32_e32 v4, 0, v4
	v_add_f32_e32 v5, 0, v5
	s_waitcnt vmcnt(3)
	v_lshlrev_b32_e32 v14, 16, v190
	v_and_b32_e32 v12, 0xffff0000, v190
	v_lshlrev_b32_e32 v15, 16, v191
	v_and_b32_e32 v13, 0xffff0000, v191
	v_fmac_f32_e32 v14, v2, v232
	v_fmac_f32_e32 v12, v3, v233
	v_fmac_f32_e32 v15, v4, v234
	v_fmac_f32_e32 v13, v5, v235
	v_cvt_pk_bf16_f32 v8, v14, v12
	v_cvt_pk_bf16_f32 v9, v15, v13
	s_nop 1
	v_permlane16_swap_b32 v6, v8
	v_permlane16_swap_b32 v7, v9
	v_lshl_add_u64 v[248:249], v[10:11], 0, v[246:247]
	s_nop 0
	global_store_dwordx4 v[248:249], v[6:9], off offset:192
	s_nop 1
	s_branch .LBB0_3514
